# LDS-DMA loads in all GEMM loops converted from 64-bit VGPR address (v_lshl_add_u64 + off) to SGPR base + 32-bit VGPR offset form
# speedup vs baseline: 1.0267x; 1.0074x over previous
; #define PG8_STAGE(bufoff, gbase, voff) do { const char* gb_ = (const char*)(gbase); asm volatile("" : "+s"(gb_));   \
;         _Pragma("unroll") for (int _i = 0; _i < 2; ++_i) \
;         __builtin_amdgcn_global_load_lds((const unsigned*)(gb_ + (voff)[_i]), (PG8_LAS unsigned*)(lds + (bufoff) + ldsw + _i * 8192), 16, 0, 0); } while (0)
; #define PG8_WAIT_V(n) asm volatile("s_waitcnt vmcnt(" #n ")" ::: "memory")
; #define PG8_WAIT_V8_RELAX() do { if constexpr (Epi::NSTORES + Epi::NPRE == 10) asm volatile("s_waitcnt vmcnt(18)" ::: "memory"); else if constexpr (Epi::NSTORES + Epi::NPRE == 18) asm volatile("s_waitcnt vmcnt(26)" ::: "memory"); else asm volatile("s_waitcnt vmcnt(8)" ::: "memory"); } while (0)
; #define PG8_BAR __builtin_amdgcn_s_barrier()
; template <class Epi, class Sched, bool ALIGN_EPI = false, bool SP2 = false>
; __device__ __forceinline__ void gemm_phase(PG8_LAS unsigned char* lds, const Gemm g, const Sched& S, const Epi& E, int wave_s) {
;     ...
;         PG8_WAIT_V(2); PG8_BAR;
;         PG8_STAGE(PG8_SB(1, 0), cB + kstep, voffB); PG8_STAGE(PG8_SA(1, 0), cA + kstep, voffA); PG8_STAGE(PG8_SB(1, 1), cB + hstep + kstep, voffB);
;         PG8_WAIT_V(6); PG8_BAR;
;     ...
;         if constexpr (Epi::NPRE > 0) E.prefetch(lds, wid, cur, wr, fr, fq);
;         if constexpr (SP2 && Epi::NSTORES > 0 && !Epi::AFTER_DRAIN) {
;             const char* a1 = cA + kstep; const char* a2 = cA + 2 * kstep; const char* b2 = cB + 2 * kstep; const char* a3 = a2 + kstep; const char* b3 = b2 + kstep;
;             PG8_SP2_PAIR(PG8_WAIT_V8_RELAX);
.LBB0_101:
	s_lshl_b32 s11, s11, 5
	s_and_b32 s18, s11, 0x60
	s_lshl_b32 s3, s16, 13
	s_lshl_b32 s11, s18, 7
	s_add_u32 s16, s22, 0x80
	s_addc_u32 s17, s23, 0
	s_waitcnt vmcnt(2)
	s_barrier
	s_add_i32 m0, s42, 0x18000
	s_nop 0
	global_load_lds_dwordx4 v136, s[16:17]
	s_add_i32 m0, s42, 0x1a000
	s_nop 0
	global_load_lds_dwordx4 v132, s[16:17]
	s_add_u32 s16, s24, 0x80
	s_addc_u32 s17, s25, 0
	s_add_i32 s55, s42, 0x8000
	s_mov_b32 m0, s55
	s_add_i32 s58, s42, 0xa000
	global_load_lds_dwordx4 v138, s[16:17]
	s_mov_b64 s[98:99], s[16:17]
	s_add_u32 s16, s22, 0x40080
	s_mov_b32 m0, s58
	s_addc_u32 s17, s23, 0
	global_load_lds_dwordx4 v134, s[98:99]
	s_add_i32 m0, s42, 0x1c000
	s_nop 0
	global_load_lds_dwordx4 v136, s[16:17]
	s_add_i32 m0, s42, 0x1e000
	v_and_b32_e32 v0, 15, v2
	global_load_lds_dwordx4 v132, s[16:17]
	v_lshrrev_b32_e32 v2, 1, v2
	v_or_b32_e32 v144, s2, v0
	v_and_b32_e32 v2, 24, v2
	v_lshlrev_b32_e32 v3, 6, v144
	v_lshlrev_b32_e32 v4, 1, v2
	s_movk_i32 s2, 0x3c0
	v_lshlrev_b32_e32 v5, 2, v144
	v_and_or_b32 v3, v3, s2, v4
	v_and_b32_e32 v5, 32, v5
	v_lshlrev_b32_e32 v145, 2, v0
	v_bitop3_b32 v5, v3, s3, v5 bitop3:0xde
	v_lshl_or_b32 v3, v0, 6, v4
	v_and_b32_e32 v0, 32, v145
	v_bitop3_b32 v146, v3, s11, v0 bitop3:0xde
	s_waitcnt vmcnt(6)
	s_cmpk_lt_u32 s10, 0x100
	v_or_b32_e32 v147, s18, v2
	v_mov_b32_e32 v2, v1
	v_mov_b32_e32 v3, v1
	s_cselect_b64 s[10:11], -1, 0
	s_add_u32 s60, s14, s12
	v_mov_b32_e32 v0, v1
	v_add_u32_e32 v149, 0, v5
	v_mov_b64_e32 v[10:11], v[2:3]
	v_mov_b64_e32 v[14:15], v[2:3]
	v_mov_b64_e32 v[22:23], v[2:3]
	v_mov_b64_e32 v[30:31], v[2:3]
	v_mov_b64_e32 v[38:39], v[2:3]
	v_mov_b64_e32 v[46:47], v[2:3]
	v_mov_b64_e32 v[54:55], v[2:3]
	v_mov_b64_e32 v[66:67], v[2:3]
	v_mov_b64_e32 v[6:7], v[2:3]
	v_mov_b64_e32 v[18:19], v[2:3]
	v_mov_b64_e32 v[26:27], v[2:3]
	v_mov_b64_e32 v[34:35], v[2:3]
	v_mov_b64_e32 v[42:43], v[2:3]
	v_mov_b64_e32 v[50:51], v[2:3]
	v_mov_b64_e32 v[58:59], v[2:3]
	v_mov_b64_e32 v[70:71], v[2:3]
	v_mov_b64_e32 v[74:75], v[2:3]
	v_mov_b64_e32 v[82:83], v[2:3]
	v_mov_b64_e32 v[90:91], v[2:3]
	v_mov_b64_e32 v[98:99], v[2:3]
	v_mov_b64_e32 v[106:107], v[2:3]
	v_mov_b64_e32 v[114:115], v[2:3]
	v_mov_b64_e32 v[122:123], v[2:3]
	v_mov_b64_e32 v[130:131], v[2:3]
	v_mov_b64_e32 v[62:63], v[2:3]
	v_mov_b64_e32 v[78:79], v[2:3]
	v_mov_b64_e32 v[86:87], v[2:3]
	v_mov_b64_e32 v[94:95], v[2:3]
	v_mov_b64_e32 v[102:103], v[2:3]
	v_mov_b64_e32 v[110:111], v[2:3]
	v_mov_b64_e32 v[118:119], v[2:3]
	v_mov_b64_e32 v[126:127], v[2:3]
	s_sext_i32_i16 s21, s6
	s_mov_b32 s59, s46
	s_addc_u32 s61, s15, s13
	v_mov_b64_e32 v[140:141], 0x580
	v_mov_b64_e32 v[142:143], 0x57f
	s_add_i32 s63, 0, 0x10000
	s_add_i32 s64, 0, 0x14000
	s_movk_i32 s65, 0x1600
	v_mov_b32_e32 v148, 0x358637bd
	v_mov_b64_e32 v[8:9], v[0:1]
	v_mov_b64_e32 v[12:13], v[0:1]
	v_mov_b64_e32 v[20:21], v[0:1]
	v_mov_b64_e32 v[28:29], v[0:1]
	v_mov_b64_e32 v[36:37], v[0:1]
	v_mov_b64_e32 v[44:45], v[0:1]
	v_mov_b64_e32 v[52:53], v[0:1]
	v_mov_b64_e32 v[64:65], v[0:1]
	v_mov_b64_e32 v[4:5], v[0:1]
	s_mov_b32 s6, s7
	s_mov_b32 s66, s7
	v_mov_b64_e32 v[16:17], v[0:1]
	v_mov_b64_e32 v[24:25], v[0:1]
	v_mov_b64_e32 v[32:33], v[0:1]
	v_mov_b64_e32 v[40:41], v[0:1]
	v_mov_b64_e32 v[48:49], v[0:1]
	v_mov_b64_e32 v[56:57], v[0:1]
	v_mov_b64_e32 v[68:69], v[0:1]
	v_mov_b64_e32 v[72:73], v[0:1]
	v_mov_b64_e32 v[80:81], v[0:1]
	v_mov_b64_e32 v[88:89], v[0:1]
	v_mov_b64_e32 v[96:97], v[0:1]
	v_mov_b64_e32 v[104:105], v[0:1]
	v_mov_b64_e32 v[112:113], v[0:1]
	v_mov_b64_e32 v[120:121], v[0:1]
	v_mov_b64_e32 v[128:129], v[0:1]
	v_mov_b64_e32 v[60:61], v[0:1]
	v_mov_b64_e32 v[76:77], v[0:1]
	v_mov_b64_e32 v[84:85], v[0:1]
	v_mov_b64_e32 v[92:93], v[0:1]
	v_mov_b64_e32 v[100:101], v[0:1]
	v_mov_b64_e32 v[108:109], v[0:1]
	v_mov_b64_e32 v[116:117], v[0:1]
	v_mov_b64_e32 v[124:125], v[0:1]
	s_barrier
	s_branch .LBB0_104
.LBB0_102:
	s_lshl_b32 s2, s14, 8
	s_ashr_i32 s3, s2, 31
	s_lshl_b64 s[2:3], s[2:3], 2
	v_mbcnt_lo_u32_b32 v6, -1, 0
	v_mbcnt_hi_u32_b32 v6, -1, v6
	s_add_u32 s2, s60, s2
	v_and_b32_e32 v0, 15, v6
	v_lshlrev_b32_e32 v2, 2, v6
	v_and_b32_e32 v2, 0xffffff80, v2
	s_addc_u32 s3, s61, s3
	v_lshlrev_b32_e32 v0, 2, v0
	v_ashrrev_i32_e32 v3, 31, v2
	v_lshl_add_u64 v[4:5], s[2:3], 0, v[0:1]
	v_lshlrev_b32_e32 v0, 3, v6
	v_lshl_add_u64 v[2:3], v[2:3], 2, v[4:5]
	v_and_b32_e32 v0, 0x80, v0
	s_mov_b32 m0, s41
	v_lshl_add_u64 v[2:3], v[2:3], 0, v[0:1]
	global_load_lds_dword v[2:3], off
	v_lshl_add_u64 v[2:3], v[2:3], 0, 64
	s_add_i32 m0, s41, 0x100
	s_add_u32 s20, s16, 0x100
	global_load_lds_dword v[2:3], off
	ds_read_b128 v[2:5], v151
	ds_read_b128 v[6:9], v151 offset:1024
	ds_read_b128 v[10:13], v151 offset:2048
	ds_read_b128 v[14:17], v151 offset:3072
	ds_read_b128 v[18:21], v150
	ds_read_b128 v[22:25], v150 offset:1024
	ds_read_b128 v[26:29], v150 offset:2048
	ds_read_b128 v[30:33], v150 offset:3072
	s_addc_u32 s21, s17, 0
	s_add_u32 s2, s16, 0x180
	s_addc_u32 s3, s17, 0
	s_add_u32 s22, s18, 0x100
	s_addc_u32 s23, s19, 0
	s_add_u32 s24, s16, 0x40080
	s_addc_u32 s25, s17, 0
	s_mov_b32 m0, s69
	ds_read_b128 v[34:37], v149
	ds_read_b128 v[38:41], v149 offset:1024
	ds_read_b128 v[42:45], v149 offset:2048
	ds_read_b128 v[46:49], v149 offset:3072
	ds_read_b128 v[50:53], v149 offset:4096
	ds_read_b128 v[54:57], v149 offset:5120
	ds_read_b128 v[58:61], v149 offset:6144
	ds_read_b128 v[62:65], v149 offset:7168
	s_nop 0
	global_load_lds_dwordx4 v138, s[24:25]
	s_mov_b32 m0, s6
	s_nop 0
	global_load_lds_dwordx4 v134, s[24:25]
	s_waitcnt vmcnt(18)
	s_waitcnt lgkmcnt(0)
	s_barrier
	s_setprio 1
	s_waitcnt lgkmcnt(0)
	v_mfma_f32_16x16x32_bf16 v[90:93], v[2:5], v[58:61], 0
	v_mfma_f32_16x16x32_bf16 v[66:69], v[2:5], v[34:37], 0
	v_mfma_f32_16x16x32_bf16 v[70:73], v[10:13], v[34:37], 0
	v_mfma_f32_16x16x32_bf16 v[74:77], v[2:5], v[42:45], 0
	v_mfma_f32_16x16x32_bf16 v[78:81], v[10:13], v[42:45], 0
	v_mfma_f32_16x16x32_bf16 v[82:85], v[2:5], v[50:53], 0
	v_mfma_f32_16x16x32_bf16 v[86:89], v[10:13], v[50:53], 0
	v_mfma_f32_16x16x32_bf16 v[96:99], v[6:9], v[62:65], v[90:93]
	v_mfma_f32_16x16x32_bf16 v[90:93], v[10:13], v[58:61], 0
	v_mfma_f32_16x16x32_bf16 v[66:69], v[6:9], v[38:41], v[66:69]
	v_mfma_f32_16x16x32_bf16 v[70:73], v[14:17], v[38:41], v[70:73]
	v_mfma_f32_16x16x32_bf16 v[74:77], v[6:9], v[46:49], v[74:77]
	v_mfma_f32_16x16x32_bf16 v[78:81], v[14:17], v[46:49], v[78:81]
	v_mfma_f32_16x16x32_bf16 v[82:85], v[6:9], v[54:57], v[82:85]
	v_mfma_f32_16x16x32_bf16 v[86:89], v[14:17], v[54:57], v[86:89]
	v_mfma_f32_16x16x32_bf16 v[104:107], v[14:17], v[62:65], v[90:93]
	s_setprio 0
	s_setprio 1
	v_mfma_f32_16x16x32_bf16 v[90:93], v[18:21], v[34:37], 0
	v_mfma_f32_16x16x32_bf16 v[34:37], v[26:29], v[34:37], 0
	v_mfma_f32_16x16x32_bf16 v[112:115], v[22:25], v[38:41], v[90:93]
	v_mfma_f32_16x16x32_bf16 v[34:37], v[30:33], v[38:41], v[34:37]
	v_mfma_f32_16x16x32_bf16 v[38:41], v[18:21], v[42:45], 0
	v_mfma_f32_16x16x32_bf16 v[42:45], v[26:29], v[42:45], 0
	v_mfma_f32_16x16x32_bf16 v[38:41], v[22:25], v[46:49], v[38:41]
	v_mfma_f32_16x16x32_bf16 v[42:45], v[30:33], v[46:49], v[42:45]
	v_mfma_f32_16x16x32_bf16 v[46:49], v[18:21], v[50:53], 0
	v_mfma_f32_16x16x32_bf16 v[50:53], v[26:29], v[50:53], 0
	v_mfma_f32_16x16x32_bf16 v[46:49], v[22:25], v[54:57], v[46:49]
	v_mfma_f32_16x16x32_bf16 v[50:53], v[30:33], v[54:57], v[50:53]
	v_mfma_f32_16x16x32_bf16 v[54:57], v[18:21], v[58:61], 0
	v_mfma_f32_16x16x32_bf16 v[54:57], v[22:25], v[62:65], v[54:57]
	v_mfma_f32_16x16x32_bf16 v[58:61], v[26:29], v[58:61], 0
	v_mfma_f32_16x16x32_bf16 v[154:157], v[30:33], v[62:65], v[58:61]
	s_setprio 0
	s_barrier
	s_mov_b32 m0, s68
	s_nop 3
	ds_read_b128 v[58:61], v149 offset:16384
	ds_read_b128 v[62:65], v149 offset:17408
	ds_read_b128 v[90:93], v149 offset:18432
	ds_read_b128 v[100:103], v149 offset:19456
	ds_read_b128 v[108:111], v149 offset:20480
	ds_read_b128 v[116:119], v149 offset:21504
	ds_read_b128 v[120:123], v149 offset:22528
	ds_read_b128 v[124:127], v149 offset:23552
	s_nop 0
	global_load_lds_dwordx4 v136, s[22:23]
	s_mov_b64 s[98:99], s[22:23]
	s_add_u32 s22, s18, 0x40100
	s_mov_b32 m0, s13
	s_addc_u32 s23, s19, 0
	global_load_lds_dwordx4 v132, s[98:99]
	s_mov_b32 m0, s15
	s_nop 0
	global_load_lds_dwordx4 v136, s[22:23]
	s_mov_b32 m0, s67
	s_nop 0
	global_load_lds_dwordx4 v132, s[22:23]
	s_mov_b32 m0, s42
	s_nop 0
	global_load_lds_dwordx4 v138, s[20:21]
	s_mov_b32 m0, s43
	s_nop 0
	global_load_lds_dwordx4 v134, s[20:21]
	s_waitcnt vmcnt(18)
	s_waitcnt lgkmcnt(0)
	s_barrier
	s_setprio 1
	s_waitcnt lgkmcnt(0)
	v_mfma_f32_16x16x32_bf16 v[128:131], v[2:5], v[58:61], 0
	v_mfma_f32_16x16x32_bf16 v[158:161], v[6:9], v[62:65], v[128:131]
	v_mfma_f32_16x16x32_bf16 v[128:131], v[10:13], v[58:61], 0
	v_mfma_f32_16x16x32_bf16 v[162:165], v[14:17], v[62:65], v[128:131]
	v_mfma_f32_16x16x32_bf16 v[128:131], v[2:5], v[90:93], 0
	v_mfma_f32_16x16x32_bf16 v[166:169], v[6:9], v[100:103], v[128:131]
	v_mfma_f32_16x16x32_bf16 v[128:131], v[10:13], v[90:93], 0
	v_mfma_f32_16x16x32_bf16 v[170:173], v[14:17], v[100:103], v[128:131]
	v_mfma_f32_16x16x32_bf16 v[128:131], v[2:5], v[108:111], 0
	v_mfma_f32_16x16x32_bf16 v[2:5], v[2:5], v[120:123], 0
	v_mfma_f32_16x16x32_bf16 v[176:179], v[6:9], v[116:119], v[128:131]
	v_mfma_f32_16x16x32_bf16 v[2:5], v[6:9], v[124:127], v[2:5]
	v_mfma_f32_16x16x32_bf16 v[6:9], v[10:13], v[120:123], 0
	v_mfma_f32_16x16x32_bf16 v[128:131], v[10:13], v[108:111], 0
	v_mfma_f32_16x16x32_bf16 v[6:9], v[14:17], v[124:127], v[6:9]
	v_mfma_f32_16x16x32_bf16 v[180:183], v[14:17], v[116:119], v[128:131]
	s_setprio 0
	s_setprio 1
	v_mfma_f32_16x16x32_bf16 v[14:17], v[26:29], v[58:61], 0
	v_mfma_f32_16x16x32_bf16 v[184:187], v[30:33], v[62:65], v[14:17]
	v_mfma_f32_16x16x32_bf16 v[14:17], v[18:21], v[90:93], 0
	v_mfma_f32_16x16x32_bf16 v[188:191], v[22:25], v[100:103], v[14:17]
	v_mfma_f32_16x16x32_bf16 v[14:17], v[26:29], v[90:93], 0
	v_mfma_f32_16x16x32_bf16 v[192:195], v[30:33], v[100:103], v[14:17]
	v_mfma_f32_16x16x32_bf16 v[14:17], v[18:21], v[108:111], 0
	v_mfma_f32_16x16x32_bf16 v[196:199], v[22:25], v[116:119], v[14:17]
	v_mfma_f32_16x16x32_bf16 v[14:17], v[26:29], v[108:111], 0
	v_mfma_f32_16x16x32_bf16 v[10:13], v[18:21], v[58:61], 0
	v_mfma_f32_16x16x32_bf16 v[200:203], v[30:33], v[116:119], v[14:17]
	v_mfma_f32_16x16x32_bf16 v[14:17], v[18:21], v[120:123], 0
	v_mfma_f32_16x16x32_bf16 v[10:13], v[22:25], v[62:65], v[10:13]
	v_mfma_f32_16x16x32_bf16 v[204:207], v[22:25], v[124:127], v[14:17]
	v_mfma_f32_16x16x32_bf16 v[14:17], v[26:29], v[120:123], 0
	v_mfma_f32_16x16x32_bf16 v[208:211], v[30:33], v[124:127], v[14:17]
	s_setprio 0
	s_barrier
	s_nop 4
	ds_read_b128 v[14:17], v152
	ds_read_b128 v[18:21], v152 offset:1024
	ds_read_b128 v[28:31], v152 offset:2048
	ds_read_b128 v[212:215], v152 offset:3072
	ds_read_b128 v[216:219], v153
	ds_read_b128 v[220:223], v153 offset:1024
	ds_read_b128 v[224:227], v153 offset:2048
	ds_read_b128 v[150:153], v153 offset:3072
	s_add_u32 s20, s16, 0x40100
	s_addc_u32 s21, s17, 0
	s_mov_b32 m0, s52
	ds_read_b128 v[22:25], v149 offset:32768
	ds_read_b128 v[120:123], v149 offset:33792
	ds_read_b128 v[228:231], v149 offset:34816
	ds_read_b128 v[232:235], v149 offset:35840
	ds_read_b128 v[236:239], v149 offset:36864
	ds_read_b128 v[240:243], v149 offset:37888
	ds_read_b128 v[244:247], v149 offset:38912
	ds_read_b128 v[248:251], v149 offset:39936
	s_nop 0
	global_load_lds_dwordx4 v138, s[20:21]
	s_mov_b32 m0, s53
	s_nop 0
	global_load_lds_dwordx4 v134, s[20:21]
	s_waitcnt vmcnt(18)
	s_waitcnt lgkmcnt(0)
	s_barrier
	s_setprio 1
	s_waitcnt lgkmcnt(0)
	v_mfma_f32_16x16x32_bf16 v[58:61], v[14:17], v[22:25], v[66:69]
	v_mfma_f32_16x16x32_bf16 v[124:127], v[18:21], v[120:123], v[58:61]
	v_mfma_f32_16x16x32_bf16 v[58:61], v[28:31], v[22:25], v[70:73]
	v_mfma_f32_16x16x32_bf16 v[116:119], v[212:215], v[120:123], v[58:61]
	v_mfma_f32_16x16x32_bf16 v[58:61], v[14:17], v[228:231], v[74:77]
	v_mfma_f32_16x16x32_bf16 v[108:111], v[18:21], v[232:235], v[58:61]
	v_mfma_f32_16x16x32_bf16 v[58:61], v[28:31], v[228:231], v[78:81]
	v_mfma_f32_16x16x32_bf16 v[100:103], v[212:215], v[232:235], v[58:61]
	v_mfma_f32_16x16x32_bf16 v[58:61], v[14:17], v[236:239], v[82:85]
	v_mfma_f32_16x16x32_bf16 v[92:95], v[18:21], v[240:243], v[58:61]
	v_mfma_f32_16x16x32_bf16 v[58:61], v[28:31], v[236:239], v[86:89]
	v_mfma_f32_16x16x32_bf16 v[84:87], v[212:215], v[240:243], v[58:61]
	v_mfma_f32_16x16x32_bf16 v[58:61], v[14:17], v[244:247], v[96:99]
	v_mfma_f32_16x16x32_bf16 v[76:79], v[18:21], v[248:251], v[58:61]
	v_mfma_f32_16x16x32_bf16 v[58:61], v[28:31], v[244:247], v[104:107]
	v_mfma_f32_16x16x32_bf16 v[60:63], v[212:215], v[248:251], v[58:61]
	s_setprio 0
	s_setprio 1
	v_mfma_f32_16x16x32_bf16 v[64:67], v[216:219], v[22:25], v[112:115]
	v_mfma_f32_16x16x32_bf16 v[22:25], v[224:227], v[22:25], v[34:37]
	v_mfma_f32_16x16x32_bf16 v[128:131], v[220:223], v[120:123], v[64:67]
	v_mfma_f32_16x16x32_bf16 v[120:123], v[150:153], v[120:123], v[22:25]
	v_mfma_f32_16x16x32_bf16 v[22:25], v[216:219], v[228:231], v[38:41]
	v_mfma_f32_16x16x32_bf16 v[112:115], v[220:223], v[232:235], v[22:25]
	v_mfma_f32_16x16x32_bf16 v[22:25], v[224:227], v[228:231], v[42:45]
	v_mfma_f32_16x16x32_bf16 v[104:107], v[150:153], v[232:235], v[22:25]
	v_mfma_f32_16x16x32_bf16 v[22:25], v[216:219], v[236:239], v[46:49]
	v_mfma_f32_16x16x32_bf16 v[96:99], v[220:223], v[240:243], v[22:25]
	v_mfma_f32_16x16x32_bf16 v[22:25], v[224:227], v[236:239], v[50:53]
	v_mfma_f32_16x16x32_bf16 v[88:91], v[150:153], v[240:243], v[22:25]
	v_mfma_f32_16x16x32_bf16 v[22:25], v[216:219], v[244:247], v[54:57]
	v_mfma_f32_16x16x32_bf16 v[80:83], v[220:223], v[248:251], v[22:25]
	v_mfma_f32_16x16x32_bf16 v[22:25], v[224:227], v[244:247], v[154:157]
	v_mfma_f32_16x16x32_bf16 v[72:75], v[150:153], v[248:251], v[22:25]
	s_setprio 0
	s_barrier
	s_add_u32 s20, s18, 0x180
	s_addc_u32 s21, s19, 0
	s_mov_b32 m0, s29
	ds_read_b128 v[36:39], v149 offset:49152
	ds_read_b128 v[44:47], v149 offset:50176
	ds_read_b128 v[154:157], v149 offset:51200
	ds_read_b128 v[228:231], v149 offset:52224
	ds_read_b128 v[232:235], v149 offset:53248
	ds_read_b128 v[236:239], v149 offset:54272
	ds_read_b128 v[240:243], v149 offset:55296
	ds_read_b128 v[244:247], v149 offset:56320
	s_nop 0
	global_load_lds_dwordx4 v136, s[20:21]
	s_mov_b64 s[98:99], s[20:21]
	s_add_u32 s20, s18, 0x40180
	s_mov_b32 m0, s28
	s_addc_u32 s21, s19, 0
	global_load_lds_dwordx4 v132, s[98:99]
	s_mov_b32 m0, s26
	s_nop 0
	global_load_lds_dwordx4 v136, s[20:21]
	s_mov_b32 m0, s27
	s_nop 0
	global_load_lds_dwordx4 v132, s[20:21]
	s_mov_b32 m0, s55
	s_nop 0
	global_load_lds_dwordx4 v138, s[2:3]
	s_mov_b32 m0, s58
	s_nop 0
	global_load_lds_dwordx4 v134, s[2:3]
	s_waitcnt vmcnt(18)
	s_waitcnt lgkmcnt(0)
	s_barrier
	s_setprio 1
	s_waitcnt lgkmcnt(0)
	v_mfma_f32_16x16x32_bf16 v[22:25], v[14:17], v[36:39], v[158:161]
	v_mfma_f32_16x16x32_bf16 v[68:71], v[18:21], v[44:47], v[22:25]
	v_mfma_f32_16x16x32_bf16 v[22:25], v[28:31], v[36:39], v[162:165]
	v_mfma_f32_16x16x32_bf16 v[56:59], v[212:215], v[44:47], v[22:25]
	v_mfma_f32_16x16x32_bf16 v[22:25], v[14:17], v[154:157], v[166:169]
	v_mfma_f32_16x16x32_bf16 v[48:51], v[18:21], v[228:231], v[22:25]
	v_mfma_f32_16x16x32_bf16 v[22:25], v[28:31], v[154:157], v[170:173]
	v_mfma_f32_16x16x32_bf16 v[40:43], v[212:215], v[228:231], v[22:25]
	v_mfma_f32_16x16x32_bf16 v[22:25], v[14:17], v[232:235], v[176:179]
	v_mfma_f32_16x16x32_bf16 v[2:5], v[14:17], v[240:243], v[2:5]
	v_mfma_f32_16x16x32_bf16 v[32:35], v[18:21], v[236:239], v[22:25]
	v_mfma_f32_16x16x32_bf16 v[22:25], v[28:31], v[232:235], v[180:183]
	v_mfma_f32_16x16x32_bf16 v[16:19], v[18:21], v[244:247], v[2:5]
	v_mfma_f32_16x16x32_bf16 v[2:5], v[28:31], v[240:243], v[6:9]
	v_mfma_f32_16x16x32_bf16 v[24:27], v[212:215], v[236:239], v[22:25]
	v_mfma_f32_16x16x32_bf16 v[4:7], v[212:215], v[244:247], v[2:5]
	s_setprio 0
	s_setprio 1
	v_mfma_f32_16x16x32_bf16 v[8:11], v[216:219], v[36:39], v[10:13]
	v_mfma_f32_16x16x32_bf16 v[64:67], v[220:223], v[44:47], v[8:11]
	v_mfma_f32_16x16x32_bf16 v[8:11], v[224:227], v[36:39], v[184:187]
	v_mfma_f32_16x16x32_bf16 v[52:55], v[150:153], v[44:47], v[8:11]
	v_mfma_f32_16x16x32_bf16 v[8:11], v[216:219], v[154:157], v[188:191]
	v_mfma_f32_16x16x32_bf16 v[44:47], v[220:223], v[228:231], v[8:11]
	v_mfma_f32_16x16x32_bf16 v[8:11], v[224:227], v[154:157], v[192:195]
	v_mfma_f32_16x16x32_bf16 v[36:39], v[150:153], v[228:231], v[8:11]
	v_mfma_f32_16x16x32_bf16 v[8:11], v[216:219], v[232:235], v[196:199]
	v_mfma_f32_16x16x32_bf16 v[28:31], v[220:223], v[236:239], v[8:11]
	v_mfma_f32_16x16x32_bf16 v[8:11], v[224:227], v[232:235], v[200:203]
	v_mfma_f32_16x16x32_bf16 v[20:23], v[150:153], v[236:239], v[8:11]
	v_mfma_f32_16x16x32_bf16 v[8:11], v[216:219], v[240:243], v[204:207]
	v_mfma_f32_16x16x32_bf16 v[12:15], v[220:223], v[244:247], v[8:11]
	v_mfma_f32_16x16x32_bf16 v[8:11], v[224:227], v[240:243], v[208:211]
	v_mfma_f32_16x16x32_bf16 v[8:11], v[150:153], v[244:247], v[8:11]
	s_setprio 0
	s_barrier
	s_mov_b64 s[2:3], 0

; #define PG8_WAIT_V8_STRICT() asm volatile("s_waitcnt vmcnt(8)" ::: "memory")
; template <class Epi, class Sched, bool ALIGN_EPI = false, bool SP2 = false>
; __device__ __forceinline__ void gemm_phase(PG8_LAS unsigned char* lds, const Gemm g, const Sched& S, const Epi& E, int wave_s) {
;     ...
;         for (int t = peeled ? 2 : 0; t < nt; t += 2) {
;             const bool last = (t == nt - 2);
;             const char* a1 = cA + (size_t)(t + 1) * kstep;
;             const char* a2 = last ? nA : cA + (size_t)(t + 2) * kstep; const char* b2 = last ? nB : cB + (size_t)(t + 2) * kstep;
;             const char* a3 = a2 + kstep; const char* b3 = b2 + kstep;
;             if (last && has_next) S.a_ready(nxt);
;             if constexpr (SP2) {
;             PG8_SP2_PAIR(PG8_WAIT_V8_STRICT);
.LBB0_107:
	v_add_u32_e32 v151, s63, v146
	v_add_u32_e32 v150, s64, v146
	ds_read_b128 v[152:155], v151
	ds_read_b128 v[156:159], v151 offset:1024
	ds_read_b128 v[160:163], v151 offset:2048
	ds_read_b128 v[164:167], v151 offset:3072
	ds_read_b128 v[168:171], v150
	ds_read_b128 v[176:179], v150 offset:1024
	ds_read_b128 v[180:183], v150 offset:2048
	ds_read_b128 v[184:187], v150 offset:3072
	s_add_u32 s22, s30, 0x100
	s_addc_u32 s23, s31, 0
	s_cmp_eq_u32 s76, 12
	s_cselect_b32 s28, s73, s22
	s_cselect_b32 s29, s72, s23
	s_cselect_b32 s26, s75, s77
	s_cselect_b32 s27, s74, s78
	s_add_u32 s24, s28, 0x80
	s_addc_u32 s25, s29, 0
	s_add_u32 s30, s30, 0x40080
	s_addc_u32 s31, s31, 0
	s_add_i32 s69, s42, 0xc000
	ds_read_b128 v[188:191], v149
	ds_read_b128 v[192:195], v149 offset:1024
	ds_read_b128 v[196:199], v149 offset:2048
	ds_read_b128 v[200:203], v149 offset:3072
	ds_read_b128 v[204:207], v149 offset:4096
	ds_read_b128 v[208:211], v149 offset:5120
	ds_read_b128 v[212:215], v149 offset:6144
	ds_read_b128 v[216:219], v149 offset:7168
	s_mov_b32 m0, s69
	s_add_i32 s6, s42, 0xe000
	global_load_lds_dwordx4 v138, s[30:31]
	s_mov_b32 m0, s6
	s_nop 0
	global_load_lds_dwordx4 v134, s[30:31]
	s_waitcnt vmcnt(8)
	s_waitcnt lgkmcnt(0)
	s_barrier
	s_setprio 1
	s_waitcnt lgkmcnt(0)
	v_mfma_f32_16x16x32_bf16 v[124:127], v[152:155], v[188:191], v[124:127]
	v_mfma_f32_16x16x32_bf16 v[116:119], v[160:163], v[188:191], v[116:119]
	v_mfma_f32_16x16x32_bf16 v[108:111], v[152:155], v[196:199], v[108:111]
	v_mfma_f32_16x16x32_bf16 v[100:103], v[160:163], v[196:199], v[100:103]
	v_mfma_f32_16x16x32_bf16 v[92:95], v[152:155], v[204:207], v[92:95]
	v_mfma_f32_16x16x32_bf16 v[84:87], v[160:163], v[204:207], v[84:87]
	v_mfma_f32_16x16x32_bf16 v[76:79], v[152:155], v[212:215], v[76:79]
	v_mfma_f32_16x16x32_bf16 v[60:63], v[160:163], v[212:215], v[60:63]
	v_mfma_f32_16x16x32_bf16 v[124:127], v[156:159], v[192:195], v[124:127]
	v_mfma_f32_16x16x32_bf16 v[116:119], v[164:167], v[192:195], v[116:119]
	v_mfma_f32_16x16x32_bf16 v[108:111], v[156:159], v[200:203], v[108:111]
	v_mfma_f32_16x16x32_bf16 v[100:103], v[164:167], v[200:203], v[100:103]
	v_mfma_f32_16x16x32_bf16 v[92:95], v[156:159], v[208:211], v[92:95]
	v_mfma_f32_16x16x32_bf16 v[84:87], v[164:167], v[208:211], v[84:87]
	v_mfma_f32_16x16x32_bf16 v[76:79], v[156:159], v[216:219], v[76:79]
	v_mfma_f32_16x16x32_bf16 v[60:63], v[164:167], v[216:219], v[60:63]
	s_setprio 0
	s_setprio 1
	v_mfma_f32_16x16x32_bf16 v[128:131], v[168:171], v[188:191], v[128:131]
	v_mfma_f32_16x16x32_bf16 v[120:123], v[180:183], v[188:191], v[120:123]
	v_mfma_f32_16x16x32_bf16 v[112:115], v[168:171], v[196:199], v[112:115]
	v_mfma_f32_16x16x32_bf16 v[104:107], v[180:183], v[196:199], v[104:107]
	v_mfma_f32_16x16x32_bf16 v[96:99], v[168:171], v[204:207], v[96:99]
	v_mfma_f32_16x16x32_bf16 v[88:91], v[180:183], v[204:207], v[88:91]
	v_mfma_f32_16x16x32_bf16 v[80:83], v[168:171], v[212:215], v[80:83]
	v_mfma_f32_16x16x32_bf16 v[72:75], v[180:183], v[212:215], v[72:75]
	v_mfma_f32_16x16x32_bf16 v[128:131], v[176:179], v[192:195], v[128:131]
	v_mfma_f32_16x16x32_bf16 v[120:123], v[184:187], v[192:195], v[120:123]
	v_mfma_f32_16x16x32_bf16 v[112:115], v[176:179], v[200:203], v[112:115]
	v_mfma_f32_16x16x32_bf16 v[104:107], v[184:187], v[200:203], v[104:107]
	v_mfma_f32_16x16x32_bf16 v[96:99], v[176:179], v[208:211], v[96:99]
	v_mfma_f32_16x16x32_bf16 v[88:91], v[184:187], v[208:211], v[88:91]
	v_mfma_f32_16x16x32_bf16 v[80:83], v[176:179], v[216:219], v[80:83]
	v_mfma_f32_16x16x32_bf16 v[72:75], v[184:187], v[216:219], v[72:75]
	s_setprio 0
	s_barrier
	s_mov_b64 s[30:31], s[26:27]
	s_add_i32 s68, s63, s38
	ds_read_b128 v[188:191], v149 offset:16384
	ds_read_b128 v[192:195], v149 offset:17408
	ds_read_b128 v[196:199], v149 offset:18432
	ds_read_b128 v[200:203], v149 offset:19456
	ds_read_b128 v[204:207], v149 offset:20480
	ds_read_b128 v[208:211], v149 offset:21504
	ds_read_b128 v[212:215], v149 offset:22528
	ds_read_b128 v[216:219], v149 offset:23552
	s_mov_b32 m0, s68
	s_add_i32 s13, s68, 0x2000
	global_load_lds_dwordx4 v136, s[30:31]
	s_mov_b64 s[98:99], s[30:31]
	s_add_u32 s30, s26, 0x40000
	s_mov_b32 m0, s13
	s_addc_u32 s31, s27, 0
	s_add_i32 s15, s64, s38
	global_load_lds_dwordx4 v132, s[98:99]
	s_mov_b32 m0, s15
	s_add_i32 s67, s15, 0x2000
	global_load_lds_dwordx4 v136, s[30:31]
	s_mov_b64 s[98:99], s[30:31]
	s_mov_b32 m0, s67
	s_mov_b64 s[30:31], s[28:29]
	global_load_lds_dwordx4 v132, s[98:99]
	s_mov_b32 m0, s42
	s_nop 0
	global_load_lds_dwordx4 v138, s[30:31]
	s_mov_b32 m0, s43
	s_nop 0
	global_load_lds_dwordx4 v134, s[30:31]
	s_waitcnt vmcnt(8)
	s_waitcnt lgkmcnt(0)
	s_barrier
	s_setprio 1
	s_waitcnt lgkmcnt(0)
	v_mfma_f32_16x16x32_bf16 v[68:71], v[152:155], v[188:191], v[68:71]
	v_mfma_f32_16x16x32_bf16 v[56:59], v[160:163], v[188:191], v[56:59]
	v_mfma_f32_16x16x32_bf16 v[48:51], v[152:155], v[196:199], v[48:51]
	v_mfma_f32_16x16x32_bf16 v[40:43], v[160:163], v[196:199], v[40:43]
	v_mfma_f32_16x16x32_bf16 v[32:35], v[152:155], v[204:207], v[32:35]
	v_mfma_f32_16x16x32_bf16 v[24:27], v[160:163], v[204:207], v[24:27]
	v_mfma_f32_16x16x32_bf16 v[16:19], v[152:155], v[212:215], v[16:19]
	v_mfma_f32_16x16x32_bf16 v[2:5], v[160:163], v[212:215], v[4:7]
	v_mfma_f32_16x16x32_bf16 v[68:71], v[156:159], v[192:195], v[68:71]
	v_mfma_f32_16x16x32_bf16 v[56:59], v[164:167], v[192:195], v[56:59]
	v_mfma_f32_16x16x32_bf16 v[48:51], v[156:159], v[200:203], v[48:51]
	v_mfma_f32_16x16x32_bf16 v[40:43], v[164:167], v[200:203], v[40:43]
	v_mfma_f32_16x16x32_bf16 v[32:35], v[156:159], v[208:211], v[32:35]
	v_mfma_f32_16x16x32_bf16 v[24:27], v[164:167], v[208:211], v[24:27]
	v_mfma_f32_16x16x32_bf16 v[16:19], v[156:159], v[216:219], v[16:19]
	v_mfma_f32_16x16x32_bf16 v[2:5], v[164:167], v[216:219], v[2:5]
	s_setprio 0
	s_setprio 1
	v_mfma_f32_16x16x32_bf16 v[64:67], v[168:171], v[188:191], v[64:67]
	v_mfma_f32_16x16x32_bf16 v[52:55], v[180:183], v[188:191], v[52:55]
	v_mfma_f32_16x16x32_bf16 v[44:47], v[168:171], v[196:199], v[44:47]
	v_mfma_f32_16x16x32_bf16 v[36:39], v[180:183], v[196:199], v[36:39]
	v_mfma_f32_16x16x32_bf16 v[28:31], v[168:171], v[204:207], v[28:31]
	v_mfma_f32_16x16x32_bf16 v[20:23], v[180:183], v[204:207], v[20:23]
	v_mfma_f32_16x16x32_bf16 v[12:15], v[168:171], v[212:215], v[12:15]
	v_mfma_f32_16x16x32_bf16 v[6:9], v[180:183], v[212:215], v[8:11]
	v_mfma_f32_16x16x32_bf16 v[64:67], v[176:179], v[192:195], v[64:67]
	v_mfma_f32_16x16x32_bf16 v[52:55], v[184:187], v[192:195], v[52:55]
	v_mfma_f32_16x16x32_bf16 v[44:47], v[176:179], v[200:203], v[44:47]
	v_mfma_f32_16x16x32_bf16 v[36:39], v[184:187], v[200:203], v[36:39]
	v_mfma_f32_16x16x32_bf16 v[28:31], v[176:179], v[208:211], v[28:31]
	v_mfma_f32_16x16x32_bf16 v[20:23], v[184:187], v[208:211], v[20:23]
	v_mfma_f32_16x16x32_bf16 v[12:15], v[176:179], v[216:219], v[12:15]
	v_mfma_f32_16x16x32_bf16 v[8:11], v[184:187], v[216:219], v[6:9]
	s_setprio 0
	s_barrier
	s_add_i32 s79, 0, 0x18000
	s_add_i32 s82, 0, 0x1c000
	v_add_u32_e32 v152, s79, v146
	v_add_u32_e32 v153, s82, v146
	ds_read_b128 v[154:157], v152
	ds_read_b128 v[158:161], v152 offset:1024
	ds_read_b128 v[162:165], v152 offset:2048
	ds_read_b128 v[166:169], v152 offset:3072
	ds_read_b128 v[170:173], v153
	ds_read_b128 v[176:179], v153 offset:1024
	ds_read_b128 v[180:183], v153 offset:2048
	ds_read_b128 v[184:187], v153 offset:3072
	s_add_u32 s28, s28, 0x40000
	s_addc_u32 s29, s29, 0
	s_mov_b32 m0, s52
	ds_read_b128 v[188:191], v149 offset:32768
	ds_read_b128 v[192:195], v149 offset:33792
	ds_read_b128 v[196:199], v149 offset:34816
	ds_read_b128 v[200:203], v149 offset:35840
	ds_read_b128 v[204:207], v149 offset:36864
	ds_read_b128 v[208:211], v149 offset:37888
	ds_read_b128 v[212:215], v149 offset:38912
	ds_read_b128 v[216:219], v149 offset:39936
	s_nop 0
	global_load_lds_dwordx4 v138, s[28:29]
	s_mov_b32 m0, s53
	s_nop 0
	global_load_lds_dwordx4 v134, s[28:29]
	s_waitcnt vmcnt(8)
	s_waitcnt lgkmcnt(0)
	s_barrier
	s_setprio 1
	s_waitcnt lgkmcnt(0)
	v_mfma_f32_16x16x32_bf16 v[124:127], v[154:157], v[188:191], v[124:127]
	v_mfma_f32_16x16x32_bf16 v[116:119], v[162:165], v[188:191], v[116:119]
	v_mfma_f32_16x16x32_bf16 v[108:111], v[154:157], v[196:199], v[108:111]
	v_mfma_f32_16x16x32_bf16 v[100:103], v[162:165], v[196:199], v[100:103]
	v_mfma_f32_16x16x32_bf16 v[92:95], v[154:157], v[204:207], v[92:95]
	v_mfma_f32_16x16x32_bf16 v[84:87], v[162:165], v[204:207], v[84:87]
	v_mfma_f32_16x16x32_bf16 v[76:79], v[154:157], v[212:215], v[76:79]
	v_mfma_f32_16x16x32_bf16 v[60:63], v[162:165], v[212:215], v[60:63]
	v_mfma_f32_16x16x32_bf16 v[124:127], v[158:161], v[192:195], v[124:127]
	v_mfma_f32_16x16x32_bf16 v[116:119], v[166:169], v[192:195], v[116:119]
	v_mfma_f32_16x16x32_bf16 v[108:111], v[158:161], v[200:203], v[108:111]
	v_mfma_f32_16x16x32_bf16 v[100:103], v[166:169], v[200:203], v[100:103]
	v_mfma_f32_16x16x32_bf16 v[92:95], v[158:161], v[208:211], v[92:95]
	v_mfma_f32_16x16x32_bf16 v[84:87], v[166:169], v[208:211], v[84:87]
	v_mfma_f32_16x16x32_bf16 v[76:79], v[158:161], v[216:219], v[76:79]
	v_mfma_f32_16x16x32_bf16 v[60:63], v[166:169], v[216:219], v[60:63]
	s_setprio 0
	s_setprio 1
	v_mfma_f32_16x16x32_bf16 v[128:131], v[170:173], v[188:191], v[128:131]
	v_mfma_f32_16x16x32_bf16 v[120:123], v[180:183], v[188:191], v[120:123]
	v_mfma_f32_16x16x32_bf16 v[112:115], v[170:173], v[196:199], v[112:115]
	v_mfma_f32_16x16x32_bf16 v[104:107], v[180:183], v[196:199], v[104:107]
	v_mfma_f32_16x16x32_bf16 v[96:99], v[170:173], v[204:207], v[96:99]
	v_mfma_f32_16x16x32_bf16 v[88:91], v[180:183], v[204:207], v[88:91]
	v_mfma_f32_16x16x32_bf16 v[80:83], v[170:173], v[212:215], v[80:83]
	v_mfma_f32_16x16x32_bf16 v[72:75], v[180:183], v[212:215], v[72:75]
	v_mfma_f32_16x16x32_bf16 v[128:131], v[176:179], v[192:195], v[128:131]
	v_mfma_f32_16x16x32_bf16 v[120:123], v[184:187], v[192:195], v[120:123]
	v_mfma_f32_16x16x32_bf16 v[112:115], v[176:179], v[200:203], v[112:115]
	v_mfma_f32_16x16x32_bf16 v[104:107], v[184:187], v[200:203], v[104:107]
	v_mfma_f32_16x16x32_bf16 v[96:99], v[176:179], v[208:211], v[96:99]
	v_mfma_f32_16x16x32_bf16 v[88:91], v[184:187], v[208:211], v[88:91]
	v_mfma_f32_16x16x32_bf16 v[80:83], v[176:179], v[216:219], v[80:83]
	v_mfma_f32_16x16x32_bf16 v[72:75], v[184:187], v[216:219], v[72:75]
	s_setprio 0
	s_barrier
; template <class Epi, class Sched, bool ALIGN_EPI = false, bool SP2 = false>
; __device__ __forceinline__ void gemm_phase(PG8_LAS unsigned char* lds, const Gemm g, const Sched& S, const Epi& E, int wave_s) {
;     ...
;         for (int t = peeled ? 2 : 0; t < nt; t += 2) {
	s_add_u32 s30, s26, 0x80
	s_addc_u32 s31, s27, 0
	s_add_i32 s29, s79, s38
	ds_read_b128 v[188:191], v149 offset:49152
	ds_read_b128 v[192:195], v149 offset:50176
	ds_read_b128 v[196:199], v149 offset:51200
	ds_read_b128 v[200:203], v149 offset:52224
	ds_read_b128 v[204:207], v149 offset:53248
	ds_read_b128 v[208:211], v149 offset:54272
	ds_read_b128 v[212:215], v149 offset:55296
	ds_read_b128 v[216:219], v149 offset:56320
	s_mov_b32 m0, s29
	s_add_i32 s28, s29, 0x2000
	global_load_lds_dwordx4 v136, s[30:31]
	s_mov_b64 s[98:99], s[30:31]
	s_add_u32 s30, s26, 0x40080
	s_mov_b32 m0, s28
	s_addc_u32 s31, s27, 0
	s_add_i32 s26, s82, s38
	global_load_lds_dwordx4 v132, s[98:99]
	s_mov_b32 m0, s26
	s_add_i32 s27, s26, 0x2000
	global_load_lds_dwordx4 v136, s[30:31]
	s_mov_b32 m0, s27
	s_nop 0
	global_load_lds_dwordx4 v132, s[30:31]
	s_mov_b32 m0, s55
	s_nop 0
	global_load_lds_dwordx4 v138, s[24:25]
	s_mov_b32 m0, s58
	s_nop 0
	global_load_lds_dwordx4 v134, s[24:25]
	s_waitcnt vmcnt(8)
	s_waitcnt lgkmcnt(0)
	s_barrier
	s_setprio 1
	s_waitcnt lgkmcnt(0)
	v_mfma_f32_16x16x32_bf16 v[68:71], v[154:157], v[188:191], v[68:71]
	v_mfma_f32_16x16x32_bf16 v[56:59], v[162:165], v[188:191], v[56:59]
	v_mfma_f32_16x16x32_bf16 v[48:51], v[154:157], v[196:199], v[48:51]
	v_mfma_f32_16x16x32_bf16 v[40:43], v[162:165], v[196:199], v[40:43]
	v_mfma_f32_16x16x32_bf16 v[32:35], v[154:157], v[204:207], v[32:35]
	v_mfma_f32_16x16x32_bf16 v[24:27], v[162:165], v[204:207], v[24:27]
	v_mfma_f32_16x16x32_bf16 v[16:19], v[154:157], v[212:215], v[16:19]
	v_mfma_f32_16x16x32_bf16 v[2:5], v[162:165], v[212:215], v[2:5]
	v_mfma_f32_16x16x32_bf16 v[68:71], v[158:161], v[192:195], v[68:71]
	v_mfma_f32_16x16x32_bf16 v[56:59], v[166:169], v[192:195], v[56:59]
	v_mfma_f32_16x16x32_bf16 v[48:51], v[158:161], v[200:203], v[48:51]
	v_mfma_f32_16x16x32_bf16 v[40:43], v[166:169], v[200:203], v[40:43]
	v_mfma_f32_16x16x32_bf16 v[32:35], v[158:161], v[208:211], v[32:35]
	v_mfma_f32_16x16x32_bf16 v[24:27], v[166:169], v[208:211], v[24:27]
	v_mfma_f32_16x16x32_bf16 v[16:19], v[158:161], v[216:219], v[16:19]
	v_mfma_f32_16x16x32_bf16 v[4:7], v[166:169], v[216:219], v[2:5]
	s_setprio 0
	s_setprio 1
	v_mfma_f32_16x16x32_bf16 v[64:67], v[170:173], v[188:191], v[64:67]
	v_mfma_f32_16x16x32_bf16 v[52:55], v[180:183], v[188:191], v[52:55]
	v_mfma_f32_16x16x32_bf16 v[44:47], v[170:173], v[196:199], v[44:47]
	v_mfma_f32_16x16x32_bf16 v[36:39], v[180:183], v[196:199], v[36:39]
	v_mfma_f32_16x16x32_bf16 v[28:31], v[170:173], v[204:207], v[28:31]
	v_mfma_f32_16x16x32_bf16 v[20:23], v[180:183], v[204:207], v[20:23]
	v_mfma_f32_16x16x32_bf16 v[12:15], v[170:173], v[212:215], v[12:15]
	v_mfma_f32_16x16x32_bf16 v[8:11], v[180:183], v[212:215], v[8:11]
	v_mfma_f32_16x16x32_bf16 v[64:67], v[176:179], v[192:195], v[64:67]
	v_mfma_f32_16x16x32_bf16 v[52:55], v[184:187], v[192:195], v[52:55]
	v_mfma_f32_16x16x32_bf16 v[44:47], v[176:179], v[200:203], v[44:47]
	v_mfma_f32_16x16x32_bf16 v[36:39], v[184:187], v[200:203], v[36:39]
	v_mfma_f32_16x16x32_bf16 v[28:31], v[176:179], v[208:211], v[28:31]
	v_mfma_f32_16x16x32_bf16 v[20:23], v[184:187], v[208:211], v[20:23]
	v_mfma_f32_16x16x32_bf16 v[12:15], v[176:179], v[216:219], v[12:15]
	v_mfma_f32_16x16x32_bf16 v[8:11], v[184:187], v[216:219], v[8:11]
	s_setprio 0
	s_barrier
	s_add_i32 s76, s76, 2
	s_add_u32 s77, s77, 0x100
	s_addc_u32 s78, s78, 0
	s_cmp_gt_u32 s76, 13
	s_mov_b64 s[30:31], s[22:23]
	s_cbranch_scc0 .LBB0_107
	s_and_b64 vcc, exec, s[10:11]
	s_cbranch_vccz .LBB0_110
	s_barrier

; __device__ __forceinline__ int lane_id_() { int l; asm volatile("v_mbcnt_lo_u32_b32 %0, -1, 0\n\tv_mbcnt_hi_u32_b32 %0, -1, %0" : "=v"(l)); return l; }
; __device__ __forceinline__ unsigned xb_ld(unsigned* p)              { return __hip_atomic_load(p, __ATOMIC_RELAXED, __HIP_MEMORY_SCOPE_AGENT); }
; __device__ __forceinline__ unsigned xb_add(unsigned* p, unsigned v) { return __hip_atomic_fetch_add(p, v, __ATOMIC_RELAXED, __HIP_MEMORY_SCOPE_AGENT); }
; #define XB_SPIN(cond, bar) do { unsigned _sp = 0; while (cond) { __builtin_amdgcn_s_sleep(1); \
;     if ((++_sp & 255u) == 0u) { if (xb_ld(&(bar)[XB_TMO])) break; if (_sp > XB_SPIN_CAP) { atomicAdd(&(bar)[XB_TMO], 1u); break; } } } } while (0)
; __device__ __forceinline__ void xcd_barrier(const XcdBarrier& b, int wave_s) {
;     asm volatile("s_waitcnt vmcnt(0)" ::: "memory");
;     __syncthreads();
;     if (wave_s == 0 && lane_id_() == 0) {
;         unsigned* bar = b.bar;
;         __builtin_amdgcn_s_waitcnt(0);
;         unsigned nloc = b.st[0], nx = b.st[1];
;         if (nloc == 0u) { xcd_barrier_complete(bar, b.x, nloc, nx); b.st[0] = nloc; b.st[1] = nx; }
;         const unsigned old = xb_add(&bar[XB_XSUB(b.x)], 1u);
;         const unsigned gen = old / nloc;
;         if (old + 1u == (gen + 1u) * nloc) {
;             __builtin_amdgcn_fence(__ATOMIC_RELEASE, "agent");
;             asm volatile("s_waitcnt vmcnt(0)" ::: "memory");
;             const unsigned og = xb_add(&bar[XB_TOP], 1u);
;             const unsigned tg = og / nx;
;             if (og + 1u == (tg + 1u) * nx) xb_add(&bar[XB_TOPGEN], 1u);
;             else XB_SPIN(xb_ld(&bar[XB_TOPGEN]) == tg, bar);
;             __builtin_amdgcn_fence(__ATOMIC_ACQUIRE, "agent");
;             xb_add(&bar[XB_XGEN(b.x)], 1u);
;             asm volatile("s_waitcnt vmcnt(0)" ::: "memory");
;         } else {
;             XB_SPIN(xb_ld(&bar[XB_XGEN(b.x)]) == gen, bar);
;             __builtin_amdgcn_fence(__ATOMIC_ACQUIRE, "agent");
;             asm volatile("s_waitcnt vmcnt(0)" ::: "memory");
;         }
;     }
;     __syncthreads();
; }
.LBB0_252:
	s_waitcnt vmcnt(0)
	v_cndmask_b32_e64 v0, 0, 1, s[4:5]
	v_cmp_ne_u32_e64 s[2:3], 1, v0
	s_andn2_b64 vcc, exec, s[4:5]
	s_waitcnt vmcnt(0)
	s_barrier
	s_cbranch_vccnz .LBB0_306
	v_mbcnt_lo_u32_b32 v0, -1, 0
	v_mbcnt_hi_u32_b32 v0, -1, v0
	s_nop 0
	v_cmp_eq_u32_e32 vcc, 0, v0
	s_and_saveexec_b64 s[4:5], vcc
	s_cbranch_execz .LBB0_305
	s_cmp_eq_u32 s101, 1
	s_cbranch_scc0 .Lglob_S2
	s_and_b32 s98, s33, 7
	s_lshl_b32 s99, s98, 2
	s_addk_i32 s99, 0x4800
	v_mov_b32_e32 v3, s99
	s_lshl_b32 s98, s98, 8
	s_addk_i32 s98, 0x4000
	v_mov_b32_e32 v0, s98
	v_mov_b32_e32 v1, 1
	global_atomic_add v2, v0, v1, s[44:45] sc0
	buffer_inv sc1
	s_waitcnt vmcnt(1)
	v_readfirstlane_b32 s98, v2
	s_nop 3
	s_add_u32 s99, s98, 1
	s_and_b32 s99, s99, 31
	s_lshr_b32 s98, s98, 5
	s_cmp_eq_u32 s99, 0
	s_cbranch_scc0 .Llw_S2
	global_atomic_add v3, v1, s[44:45]
	s_branch .Lrvp_S2
.Llw_S2:
.Lrvp_S2:
	s_add_u32 s98, s98, 1
	s_mov_b64 exec, 0xff
	v_mbcnt_lo_u32_b32 v0, -1, 0
	v_lshlrev_b32_e32 v0, 2, v0
	v_add_u32_e32 v0, 0x4800, v0
	s_mov_b32 s99, 0

; #define PG8_STAGE(bufoff, gbase, voff) do { const char* gb_ = (const char*)(gbase); asm volatile("" : "+s"(gb_));   \
;         _Pragma("unroll") for (int _i = 0; _i < 2; ++_i) \
;         __builtin_amdgcn_global_load_lds((const unsigned*)(gb_ + (voff)[_i]), (PG8_LAS unsigned*)(lds + (bufoff) + ldsw + _i * 8192), 16, 0, 0); } while (0)
; #define PG8_WAIT_V(n) asm volatile("s_waitcnt vmcnt(" #n ")" ::: "memory")
; #define PG8_BAR __builtin_amdgcn_s_barrier()
; template <class Epi, class Sched, bool ALIGN_EPI = false, bool SP2 = false>
; __device__ __forceinline__ void gemm_phase(PG8_LAS unsigned char* lds, const Gemm g, const Sched& S, const Epi& E, int wave_s) {
;     ...
;     if constexpr (SP2) {
;         PG8_STAGE(PG8_SB(0, 0), cB, voffB); PG8_STAGE(PG8_SB(0, 1), cB + hstep, voffB); PG8_STAGE(PG8_SA(0, 0), cA, voffA); PG8_STAGE(PG8_SA(0, 1), cA + hstep, voffA);
;         if (wr == 1) PG8_BAR;
;         PG8_WAIT_V(2); PG8_BAR;
;         PG8_STAGE(PG8_SB(1, 0), cB + kstep, voffB); PG8_STAGE(PG8_SA(1, 0), cA + kstep, voffA); PG8_STAGE(PG8_SB(1, 1), cB + hstep + kstep, voffB);
;         PG8_WAIT_V(6); PG8_BAR;
.LBB0_315:
	s_and_b32 s9, s8, 3
	s_lshl_b32 s7, s6, 13
	s_lshl_b32 s14, s9, 12
	s_add_u32 s10, s30, 0x80
	s_addc_u32 s11, s31, 0
	s_waitcnt vmcnt(2)
	s_barrier
	s_add_i32 m0, s43, 0x18000
	s_nop 0
	global_load_lds_dwordx4 v130, s[10:11]
	s_add_i32 m0, s43, 0x1a000
	s_nop 0
	global_load_lds_dwordx4 v134, s[10:11]
	s_add_u32 s10, s28, 0x80
	s_addc_u32 s11, s29, 0
	s_add_i32 s60, s43, 0x8000
	s_mov_b32 m0, s60
	s_add_i32 s61, s43, 0xa000
	global_load_lds_dwordx4 v128, s[10:11]
	s_mov_b64 s[98:99], s[10:11]
	s_add_u32 s10, s30, 0xb0080
	s_mov_b32 m0, s61
	s_addc_u32 s11, s31, 0
	global_load_lds_dwordx4 v132, s[98:99]
	s_add_i32 m0, s43, 0x1c000
	s_nop 0
	global_load_lds_dwordx4 v130, s[10:11]
	s_add_i32 m0, s43, 0x1e000
	v_and_b32_e32 v1, 15, v0
	global_load_lds_dwordx4 v134, s[10:11]
	v_bfe_u32 v2, v0, 4, 2
	v_lshlrev_b32_e32 v4, 4, v2
	v_lshlrev_b32_e32 v0, 2, v0
	v_lshl_or_b32 v144, s6, 6, v1
	v_lshl_or_b32 v1, v1, 6, v4
	v_and_b32_e32 v0, 32, v0
	s_cmpk_lt_u32 s63, 0x100
	v_bitop3_b32 v4, v1, s7, v0 bitop3:0xde
	v_bitop3_b32 v145, v1, s14, v0 bitop3:0xde
	s_cselect_b64 s[14:15], -1, 0
	v_lshlrev_b32_e32 v0, 4, v144
	s_add_i32 s10, 0, 0x22400
	v_add_u32_e32 v1, s10, v0
	s_add_i32 s10, 0, 0x22500
	v_lshlrev_b32_e32 v3, 3, v2
	v_cmp_eq_u32_e64 s[6:7], 0, v2
	v_add_u32_e32 v2, s10, v0
	s_add_i32 s10, 0, 0x22600
	v_lshl_or_b32 v146, s9, 5, v3
	v_add_u32_e32 v3, s10, v0
	s_add_i32 s10, 0, 0x22700
	v_add_u32_e32 v5, s10, v0
	s_add_i32 s10, 0, 0x22c00
	v_add_u32_e32 v6, s10, v0
	s_add_i32 s10, 0, 0x22d00
	v_add_u32_e32 v7, s10, v0
	s_add_i32 s10, 0, 0x22e00
	s_lshl_b32 s9, s9, 2
	v_add_u32_e32 v8, s10, v0
	s_add_i32 s10, 0, 0x22f00
	s_waitcnt vmcnt(6)
	s_cmp_lt_i32 s8, 4
	v_add_u32_e32 v0, s10, v0
	s_cselect_b64 s[16:17], -1, 0
	s_add_i32 s72, 0, 0x10000
	s_add_i32 s73, 0, 0x14000
	s_andn2_b32 s63, s63, 63
	s_mov_b32 s68, s46
	s_ashr_i32 s69, s33, 31
	v_mov_b64_e32 v[136:137], 0x100
	v_mov_b64_e32 v[138:139], 0xff
	v_add_u32_e32 v147, s72, v145
	v_add_u32_e32 v148, s73, v145
	v_add_u32_e32 v149, 0, v4
	v_mbcnt_hi_u32_b32 v150, -1, v254
	v_add_u32_e32 v151, s9, v1
	v_add_u32_e32 v152, s9, v2
	v_add_u32_e32 v153, s9, v3
	v_add_u32_e32 v154, s9, v5
	s_mov_b64 s[18:19], 0x40000
	v_add_u32_e32 v155, s9, v6
	s_mov_b64 s[20:21], 0x48000
	v_add_u32_e32 v156, s9, v7
	s_mov_b64 s[22:23], 0x50000
	v_add_u32_e32 v157, s9, v8
	s_mov_b64 s[24:25], 0x58000
	v_add_u32_e32 v158, s9, v0
	s_barrier
	s_branch .LBB0_318

; #define PG8_WAIT_V8_STRICT() asm volatile("s_waitcnt vmcnt(8)" ::: "memory")
; template <class Epi, class Sched, bool ALIGN_EPI = false, bool SP2 = false>
; __device__ __forceinline__ void gemm_phase(PG8_LAS unsigned char* lds, const Gemm g, const Sched& S, const Epi& E, int wave_s) {
;     ...
;         for (int t = peeled ? 2 : 0; t < nt; t += 2) {
;             const bool last = (t == nt - 2);
;             const char* a1 = cA + (size_t)(t + 1) * kstep;
;             const char* a2 = last ? nA : cA + (size_t)(t + 2) * kstep; const char* b2 = last ? nB : cB + (size_t)(t + 2) * kstep;
;             const char* a3 = a2 + kstep; const char* b3 = b2 + kstep;
;             if (last && has_next) S.a_ready(nxt);
;             if constexpr (SP2) {
;             PG8_SP2_PAIR(PG8_WAIT_V8_STRICT);
.LBB0_329:
	ds_read_b128 v[140:143], v147
	ds_read_b128 v[160:163], v147 offset:1024
	ds_read_b128 v[164:167], v147 offset:2048
	ds_read_b128 v[168:171], v147 offset:3072
	ds_read_b128 v[176:179], v148
	ds_read_b128 v[180:183], v148 offset:1024
	ds_read_b128 v[184:187], v148 offset:2048
	ds_read_b128 v[188:191], v148 offset:3072
	s_add_u32 s30, s28, 0x100
	s_addc_u32 s31, s29, 0
	s_cmp_eq_u32 s82, 40
	s_cselect_b32 s38, s10, s30
	s_cselect_b32 s39, s11, s31
	s_cselect_b32 s36, s26, s78
	s_cselect_b32 s37, s27, s79
	s_add_u32 s34, s38, 0x80
	s_addc_u32 s35, s39, 0
	s_add_u32 s28, s28, 0xb0080
	s_addc_u32 s29, s29, 0
	ds_read_b128 v[192:195], v149
	ds_read_b128 v[196:199], v149 offset:1024
	ds_read_b128 v[200:203], v149 offset:2048
	ds_read_b128 v[204:207], v149 offset:3072
	ds_read_b128 v[208:211], v149 offset:4096
	ds_read_b128 v[212:215], v149 offset:5120
	ds_read_b128 v[216:219], v149 offset:6144
	ds_read_b128 v[220:223], v149 offset:7168
	s_add_i32 m0, s43, 0xc000
	s_nop 0
	global_load_lds_dwordx4 v128, s[28:29]
	s_add_i32 m0, s43, 0xe000
	s_nop 0
	global_load_lds_dwordx4 v132, s[28:29]
	s_waitcnt vmcnt(8)
	s_waitcnt lgkmcnt(0)
	s_barrier
	s_setprio 1
	s_waitcnt lgkmcnt(0)
	v_mfma_f32_16x16x32_bf16 v[124:127], v[140:143], v[192:195], v[124:127]
	v_mfma_f32_16x16x32_bf16 v[120:123], v[164:167], v[192:195], v[120:123]
	v_mfma_f32_16x16x32_bf16 v[108:111], v[140:143], v[200:203], v[108:111]
	v_mfma_f32_16x16x32_bf16 v[104:107], v[164:167], v[200:203], v[104:107]
	v_mfma_f32_16x16x32_bf16 v[92:95], v[140:143], v[208:211], v[92:95]
	v_mfma_f32_16x16x32_bf16 v[88:91], v[164:167], v[208:211], v[88:91]
	v_mfma_f32_16x16x32_bf16 v[76:79], v[140:143], v[216:219], v[76:79]
	v_mfma_f32_16x16x32_bf16 v[72:75], v[164:167], v[216:219], v[72:75]
	v_mfma_f32_16x16x32_bf16 v[124:127], v[160:163], v[196:199], v[124:127]
	v_mfma_f32_16x16x32_bf16 v[120:123], v[168:171], v[196:199], v[120:123]
	v_mfma_f32_16x16x32_bf16 v[108:111], v[160:163], v[204:207], v[108:111]
	v_mfma_f32_16x16x32_bf16 v[104:107], v[168:171], v[204:207], v[104:107]
	v_mfma_f32_16x16x32_bf16 v[92:95], v[160:163], v[212:215], v[92:95]
	v_mfma_f32_16x16x32_bf16 v[88:91], v[168:171], v[212:215], v[88:91]
	v_mfma_f32_16x16x32_bf16 v[76:79], v[160:163], v[220:223], v[76:79]
	v_mfma_f32_16x16x32_bf16 v[72:75], v[168:171], v[220:223], v[72:75]
	s_setprio 0
	s_setprio 1
	v_mfma_f32_16x16x32_bf16 v[116:119], v[176:179], v[192:195], v[116:119]
	v_mfma_f32_16x16x32_bf16 v[112:115], v[184:187], v[192:195], v[112:115]
	v_mfma_f32_16x16x32_bf16 v[100:103], v[176:179], v[200:203], v[100:103]
	v_mfma_f32_16x16x32_bf16 v[96:99], v[184:187], v[200:203], v[96:99]
	v_mfma_f32_16x16x32_bf16 v[84:87], v[176:179], v[208:211], v[84:87]
	v_mfma_f32_16x16x32_bf16 v[80:83], v[184:187], v[208:211], v[80:83]
	v_mfma_f32_16x16x32_bf16 v[68:71], v[176:179], v[216:219], v[68:71]
	v_mfma_f32_16x16x32_bf16 v[64:67], v[184:187], v[216:219], v[64:67]
	v_mfma_f32_16x16x32_bf16 v[116:119], v[180:183], v[196:199], v[116:119]
	v_mfma_f32_16x16x32_bf16 v[112:115], v[188:191], v[196:199], v[112:115]
	v_mfma_f32_16x16x32_bf16 v[100:103], v[180:183], v[204:207], v[100:103]
	v_mfma_f32_16x16x32_bf16 v[96:99], v[188:191], v[204:207], v[96:99]
	v_mfma_f32_16x16x32_bf16 v[84:87], v[180:183], v[212:215], v[84:87]
	v_mfma_f32_16x16x32_bf16 v[80:83], v[188:191], v[212:215], v[80:83]
	v_mfma_f32_16x16x32_bf16 v[68:71], v[180:183], v[220:223], v[68:71]
	v_mfma_f32_16x16x32_bf16 v[64:67], v[188:191], v[220:223], v[64:67]
	s_setprio 0
	s_barrier
	s_mov_b64 s[28:29], s[36:37]
	s_add_i32 s87, s72, s42
	ds_read_b128 v[192:195], v149 offset:16384
	ds_read_b128 v[196:199], v149 offset:17408
	ds_read_b128 v[200:203], v149 offset:18432
	ds_read_b128 v[204:207], v149 offset:19456
	ds_read_b128 v[208:211], v149 offset:20480
	ds_read_b128 v[212:215], v149 offset:21504
	ds_read_b128 v[216:219], v149 offset:22528
	ds_read_b128 v[220:223], v149 offset:23552
	s_mov_b32 m0, s87
	s_nop 0
	global_load_lds_dwordx4 v130, s[28:29]
	s_add_i32 m0, s87, 0x2000
	s_nop 0
	global_load_lds_dwordx4 v134, s[28:29]
	s_add_u32 s28, s36, 0xb0000
	s_addc_u32 s29, s37, 0
	s_add_i32 s87, s73, s42
	s_mov_b32 m0, s87
	s_nop 0
	global_load_lds_dwordx4 v130, s[28:29]
	s_mov_b64 s[98:99], s[28:29]
	s_add_i32 m0, s87, 0x2000
	s_mov_b64 s[28:29], s[38:39]
	global_load_lds_dwordx4 v134, s[98:99]
	s_mov_b32 m0, s43
	s_nop 0
	global_load_lds_dwordx4 v128, s[28:29]
	s_mov_b32 m0, s52
	s_nop 0
	global_load_lds_dwordx4 v132, s[28:29]
	s_waitcnt vmcnt(8)
	s_waitcnt lgkmcnt(0)
	s_barrier
	s_setprio 1
	s_waitcnt lgkmcnt(0)
	v_mfma_f32_16x16x32_bf16 v[60:63], v[140:143], v[192:195], v[60:63]
	v_mfma_f32_16x16x32_bf16 v[56:59], v[164:167], v[192:195], v[56:59]
	v_mfma_f32_16x16x32_bf16 v[44:47], v[140:143], v[200:203], v[44:47]
	v_mfma_f32_16x16x32_bf16 v[40:43], v[164:167], v[200:203], v[40:43]
	v_mfma_f32_16x16x32_bf16 v[28:31], v[140:143], v[208:211], v[28:31]
	v_mfma_f32_16x16x32_bf16 v[24:27], v[164:167], v[208:211], v[24:27]
	v_mfma_f32_16x16x32_bf16 v[12:15], v[140:143], v[216:219], v[12:15]
	v_mfma_f32_16x16x32_bf16 v[8:11], v[164:167], v[216:219], v[8:11]
	v_mfma_f32_16x16x32_bf16 v[60:63], v[160:163], v[196:199], v[60:63]
	v_mfma_f32_16x16x32_bf16 v[56:59], v[168:171], v[196:199], v[56:59]
	v_mfma_f32_16x16x32_bf16 v[44:47], v[160:163], v[204:207], v[44:47]
	v_mfma_f32_16x16x32_bf16 v[40:43], v[168:171], v[204:207], v[40:43]
	v_mfma_f32_16x16x32_bf16 v[28:31], v[160:163], v[212:215], v[28:31]
	v_mfma_f32_16x16x32_bf16 v[24:27], v[168:171], v[212:215], v[24:27]
	v_mfma_f32_16x16x32_bf16 v[12:15], v[160:163], v[220:223], v[12:15]
	v_mfma_f32_16x16x32_bf16 v[8:11], v[168:171], v[220:223], v[8:11]
	s_setprio 0
	s_setprio 1
	v_mfma_f32_16x16x32_bf16 v[52:55], v[176:179], v[192:195], v[52:55]
	v_mfma_f32_16x16x32_bf16 v[48:51], v[184:187], v[192:195], v[48:51]
	v_mfma_f32_16x16x32_bf16 v[36:39], v[176:179], v[200:203], v[36:39]
	v_mfma_f32_16x16x32_bf16 v[32:35], v[184:187], v[200:203], v[32:35]
	v_mfma_f32_16x16x32_bf16 v[20:23], v[176:179], v[208:211], v[20:23]
	v_mfma_f32_16x16x32_bf16 v[16:19], v[184:187], v[208:211], v[16:19]
	v_mfma_f32_16x16x32_bf16 v[4:7], v[176:179], v[216:219], v[4:7]
	v_mfma_f32_16x16x32_bf16 v[0:3], v[184:187], v[216:219], v[0:3]
	v_mfma_f32_16x16x32_bf16 v[52:55], v[180:183], v[196:199], v[52:55]
	v_mfma_f32_16x16x32_bf16 v[48:51], v[188:191], v[196:199], v[48:51]
	v_mfma_f32_16x16x32_bf16 v[36:39], v[180:183], v[204:207], v[36:39]
	v_mfma_f32_16x16x32_bf16 v[32:35], v[188:191], v[204:207], v[32:35]
	v_mfma_f32_16x16x32_bf16 v[20:23], v[180:183], v[212:215], v[20:23]
	v_mfma_f32_16x16x32_bf16 v[16:19], v[188:191], v[212:215], v[16:19]
	v_mfma_f32_16x16x32_bf16 v[4:7], v[180:183], v[220:223], v[4:7]
	v_mfma_f32_16x16x32_bf16 v[0:3], v[188:191], v[220:223], v[0:3]
	s_setprio 0
	s_barrier
	s_add_i32 s87, 0, 0x18000
	v_add_u32_e32 v159, s87, v145
	s_add_i32 s88, 0, 0x1c000
	ds_read_b128 v[140:143], v159
	ds_read_b128 v[160:163], v159 offset:1024
	ds_read_b128 v[164:167], v159 offset:2048
	ds_read_b128 v[168:171], v159 offset:3072
	v_add_u32_e32 v159, s88, v145
	ds_read_b128 v[176:179], v159
	ds_read_b128 v[180:183], v159 offset:1024
	ds_read_b128 v[184:187], v159 offset:2048
	ds_read_b128 v[188:191], v159 offset:3072
	s_add_u32 s28, s38, 0xb0000
	s_addc_u32 s29, s39, 0
	s_mov_b32 m0, s53
	ds_read_b128 v[192:195], v149 offset:32768
	ds_read_b128 v[196:199], v149 offset:33792
	ds_read_b128 v[200:203], v149 offset:34816
	ds_read_b128 v[204:207], v149 offset:35840
	ds_read_b128 v[208:211], v149 offset:36864
	ds_read_b128 v[212:215], v149 offset:37888
	ds_read_b128 v[216:219], v149 offset:38912
	ds_read_b128 v[220:223], v149 offset:39936
	s_nop 0
	global_load_lds_dwordx4 v128, s[28:29]
	s_mov_b32 m0, s58
	s_nop 0
	global_load_lds_dwordx4 v132, s[28:29]
	s_waitcnt vmcnt(8)
	s_waitcnt lgkmcnt(0)
	s_barrier
	s_setprio 1
	s_waitcnt lgkmcnt(0)
	v_mfma_f32_16x16x32_bf16 v[124:127], v[140:143], v[192:195], v[124:127]
	v_mfma_f32_16x16x32_bf16 v[120:123], v[164:167], v[192:195], v[120:123]
	v_mfma_f32_16x16x32_bf16 v[108:111], v[140:143], v[200:203], v[108:111]
	v_mfma_f32_16x16x32_bf16 v[104:107], v[164:167], v[200:203], v[104:107]
	v_mfma_f32_16x16x32_bf16 v[92:95], v[140:143], v[208:211], v[92:95]
	v_mfma_f32_16x16x32_bf16 v[88:91], v[164:167], v[208:211], v[88:91]
	v_mfma_f32_16x16x32_bf16 v[76:79], v[140:143], v[216:219], v[76:79]
	v_mfma_f32_16x16x32_bf16 v[72:75], v[164:167], v[216:219], v[72:75]
	v_mfma_f32_16x16x32_bf16 v[124:127], v[160:163], v[196:199], v[124:127]
	v_mfma_f32_16x16x32_bf16 v[120:123], v[168:171], v[196:199], v[120:123]
	v_mfma_f32_16x16x32_bf16 v[108:111], v[160:163], v[204:207], v[108:111]
	v_mfma_f32_16x16x32_bf16 v[104:107], v[168:171], v[204:207], v[104:107]
	v_mfma_f32_16x16x32_bf16 v[92:95], v[160:163], v[212:215], v[92:95]
	v_mfma_f32_16x16x32_bf16 v[88:91], v[168:171], v[212:215], v[88:91]
	v_mfma_f32_16x16x32_bf16 v[76:79], v[160:163], v[220:223], v[76:79]
	v_mfma_f32_16x16x32_bf16 v[72:75], v[168:171], v[220:223], v[72:75]
	s_setprio 0
	s_setprio 1
	v_mfma_f32_16x16x32_bf16 v[116:119], v[176:179], v[192:195], v[116:119]
	v_mfma_f32_16x16x32_bf16 v[112:115], v[184:187], v[192:195], v[112:115]
	v_mfma_f32_16x16x32_bf16 v[100:103], v[176:179], v[200:203], v[100:103]
	v_mfma_f32_16x16x32_bf16 v[96:99], v[184:187], v[200:203], v[96:99]
	v_mfma_f32_16x16x32_bf16 v[84:87], v[176:179], v[208:211], v[84:87]
	v_mfma_f32_16x16x32_bf16 v[80:83], v[184:187], v[208:211], v[80:83]
	v_mfma_f32_16x16x32_bf16 v[68:71], v[176:179], v[216:219], v[68:71]
	v_mfma_f32_16x16x32_bf16 v[64:67], v[184:187], v[216:219], v[64:67]
	v_mfma_f32_16x16x32_bf16 v[116:119], v[180:183], v[196:199], v[116:119]
	v_mfma_f32_16x16x32_bf16 v[112:115], v[188:191], v[196:199], v[112:115]
	v_mfma_f32_16x16x32_bf16 v[100:103], v[180:183], v[204:207], v[100:103]
	v_mfma_f32_16x16x32_bf16 v[96:99], v[188:191], v[204:207], v[96:99]
	v_mfma_f32_16x16x32_bf16 v[84:87], v[180:183], v[212:215], v[84:87]
	v_mfma_f32_16x16x32_bf16 v[80:83], v[188:191], v[212:215], v[80:83]
	v_mfma_f32_16x16x32_bf16 v[68:71], v[180:183], v[220:223], v[68:71]
	v_mfma_f32_16x16x32_bf16 v[64:67], v[188:191], v[220:223], v[64:67]
	s_setprio 0
	s_barrier
; template <class Epi, class Sched, bool ALIGN_EPI = false, bool SP2 = false>
; __device__ __forceinline__ void gemm_phase(PG8_LAS unsigned char* lds, const Gemm g, const Sched& S, const Epi& E, int wave_s) {
;     ...
;         for (int t = peeled ? 2 : 0; t < nt; t += 2) {
	s_add_u32 s28, s36, 0x80
	s_addc_u32 s29, s37, 0
	s_add_i32 s38, s87, s42
	ds_read_b128 v[192:195], v149 offset:49152
	ds_read_b128 v[196:199], v149 offset:50176
	ds_read_b128 v[200:203], v149 offset:51200
	ds_read_b128 v[204:207], v149 offset:52224
	ds_read_b128 v[208:211], v149 offset:53248
	ds_read_b128 v[212:215], v149 offset:54272
	ds_read_b128 v[216:219], v149 offset:55296
	ds_read_b128 v[220:223], v149 offset:56320
	s_mov_b32 m0, s38
	s_nop 0
	global_load_lds_dwordx4 v130, s[28:29]
	s_add_i32 m0, s38, 0x2000
	s_nop 0
	global_load_lds_dwordx4 v134, s[28:29]
	s_add_u32 s28, s36, 0xb0080
	s_addc_u32 s29, s37, 0
	s_add_i32 s36, s88, s42
	s_mov_b32 m0, s36
	s_nop 0
	global_load_lds_dwordx4 v130, s[28:29]
	s_add_i32 m0, s36, 0x2000
	s_nop 0
	global_load_lds_dwordx4 v134, s[28:29]
	s_mov_b32 m0, s60
	s_nop 0
	global_load_lds_dwordx4 v128, s[34:35]
	s_mov_b32 m0, s61
	s_nop 0
	global_load_lds_dwordx4 v132, s[34:35]
	s_waitcnt vmcnt(8)
	s_waitcnt lgkmcnt(0)
	s_barrier
	s_setprio 1
	s_waitcnt lgkmcnt(0)
	v_mfma_f32_16x16x32_bf16 v[60:63], v[140:143], v[192:195], v[60:63]
	v_mfma_f32_16x16x32_bf16 v[56:59], v[164:167], v[192:195], v[56:59]
	v_mfma_f32_16x16x32_bf16 v[44:47], v[140:143], v[200:203], v[44:47]
	v_mfma_f32_16x16x32_bf16 v[40:43], v[164:167], v[200:203], v[40:43]
	v_mfma_f32_16x16x32_bf16 v[28:31], v[140:143], v[208:211], v[28:31]
	v_mfma_f32_16x16x32_bf16 v[24:27], v[164:167], v[208:211], v[24:27]
	v_mfma_f32_16x16x32_bf16 v[12:15], v[140:143], v[216:219], v[12:15]
	v_mfma_f32_16x16x32_bf16 v[8:11], v[164:167], v[216:219], v[8:11]
	v_mfma_f32_16x16x32_bf16 v[60:63], v[160:163], v[196:199], v[60:63]
	v_mfma_f32_16x16x32_bf16 v[56:59], v[168:171], v[196:199], v[56:59]
	v_mfma_f32_16x16x32_bf16 v[44:47], v[160:163], v[204:207], v[44:47]
	v_mfma_f32_16x16x32_bf16 v[40:43], v[168:171], v[204:207], v[40:43]
	v_mfma_f32_16x16x32_bf16 v[28:31], v[160:163], v[212:215], v[28:31]
	v_mfma_f32_16x16x32_bf16 v[24:27], v[168:171], v[212:215], v[24:27]
	v_mfma_f32_16x16x32_bf16 v[12:15], v[160:163], v[220:223], v[12:15]
	v_mfma_f32_16x16x32_bf16 v[8:11], v[168:171], v[220:223], v[8:11]
	s_setprio 0
	s_setprio 1
	v_mfma_f32_16x16x32_bf16 v[52:55], v[176:179], v[192:195], v[52:55]
	v_mfma_f32_16x16x32_bf16 v[48:51], v[184:187], v[192:195], v[48:51]
	v_mfma_f32_16x16x32_bf16 v[36:39], v[176:179], v[200:203], v[36:39]
	v_mfma_f32_16x16x32_bf16 v[32:35], v[184:187], v[200:203], v[32:35]
	v_mfma_f32_16x16x32_bf16 v[20:23], v[176:179], v[208:211], v[20:23]
	v_mfma_f32_16x16x32_bf16 v[16:19], v[184:187], v[208:211], v[16:19]
	v_mfma_f32_16x16x32_bf16 v[4:7], v[176:179], v[216:219], v[4:7]
	v_mfma_f32_16x16x32_bf16 v[0:3], v[184:187], v[216:219], v[0:3]
	v_mfma_f32_16x16x32_bf16 v[52:55], v[180:183], v[196:199], v[52:55]
	v_mfma_f32_16x16x32_bf16 v[48:51], v[188:191], v[196:199], v[48:51]
	v_mfma_f32_16x16x32_bf16 v[36:39], v[180:183], v[204:207], v[36:39]
	v_mfma_f32_16x16x32_bf16 v[32:35], v[188:191], v[204:207], v[32:35]
	v_mfma_f32_16x16x32_bf16 v[20:23], v[180:183], v[212:215], v[20:23]
	v_mfma_f32_16x16x32_bf16 v[16:19], v[188:191], v[212:215], v[16:19]
	v_mfma_f32_16x16x32_bf16 v[4:7], v[180:183], v[220:223], v[4:7]
	v_mfma_f32_16x16x32_bf16 v[0:3], v[188:191], v[220:223], v[0:3]
	s_setprio 0
	s_barrier
	s_add_i32 s82, s82, 2
	s_add_u32 s78, s78, 0x100
	s_addc_u32 s79, s79, 0
	s_cmp_gt_u32 s82, 41
	s_mov_b64 s[28:29], s[30:31]
	s_cbranch_scc0 .LBB0_329
	s_and_b64 vcc, exec, s[14:15]
	s_cbranch_vccz .LBB0_332
	s_barrier

; __device__ __forceinline__ int lane_id_() { int l; asm volatile("v_mbcnt_lo_u32_b32 %0, -1, 0\n\tv_mbcnt_hi_u32_b32 %0, -1, %0" : "=v"(l)); return l; }
; __device__ __forceinline__ unsigned xb_ld(unsigned* p)              { return __hip_atomic_load(p, __ATOMIC_RELAXED, __HIP_MEMORY_SCOPE_AGENT); }
; __device__ __forceinline__ unsigned xb_add(unsigned* p, unsigned v) { return __hip_atomic_fetch_add(p, v, __ATOMIC_RELAXED, __HIP_MEMORY_SCOPE_AGENT); }
; #define XB_SPIN(cond, bar) do { unsigned _sp = 0; while (cond) { __builtin_amdgcn_s_sleep(1); \
;     if ((++_sp & 255u) == 0u) { if (xb_ld(&(bar)[XB_TMO])) break; if (_sp > XB_SPIN_CAP) { atomicAdd(&(bar)[XB_TMO], 1u); break; } } } } while (0)
; __device__ __forceinline__ void xcd_barrier(const XcdBarrier& b, int wave_s) {
;     asm volatile("s_waitcnt vmcnt(0)" ::: "memory");
;     __syncthreads();
;     if (wave_s == 0 && lane_id_() == 0) {
;         unsigned* bar = b.bar;
;         __builtin_amdgcn_s_waitcnt(0);
;         unsigned nloc = b.st[0], nx = b.st[1];
;         if (nloc == 0u) { xcd_barrier_complete(bar, b.x, nloc, nx); b.st[0] = nloc; b.st[1] = nx; }
;         const unsigned old = xb_add(&bar[XB_XSUB(b.x)], 1u);
;         const unsigned gen = old / nloc;
;         if (old + 1u == (gen + 1u) * nloc) {
;             __builtin_amdgcn_fence(__ATOMIC_RELEASE, "agent");
;             asm volatile("s_waitcnt vmcnt(0)" ::: "memory");
;             const unsigned og = xb_add(&bar[XB_TOP], 1u);
;             const unsigned tg = og / nx;
;             if (og + 1u == (tg + 1u) * nx) xb_add(&bar[XB_TOPGEN], 1u);
;             else XB_SPIN(xb_ld(&bar[XB_TOPGEN]) == tg, bar);
;             __builtin_amdgcn_fence(__ATOMIC_ACQUIRE, "agent");
;             xb_add(&bar[XB_XGEN(b.x)], 1u);
;             asm volatile("s_waitcnt vmcnt(0)" ::: "memory");
;         } else {
;             XB_SPIN(xb_ld(&bar[XB_XGEN(b.x)]) == gen, bar);
;             __builtin_amdgcn_fence(__ATOMIC_ACQUIRE, "agent");
;             asm volatile("s_waitcnt vmcnt(0)" ::: "memory");
;         }
;     }
;     __syncthreads();
; }
.LBB0_354:
	s_waitcnt vmcnt(0)
	s_and_b64 vcc, exec, s[2:3]
	s_waitcnt lgkmcnt(0)
	s_barrier
	s_cbranch_vccnz .LBB0_408
	v_mbcnt_lo_u32_b32 v0, -1, 0
	v_mbcnt_hi_u32_b32 v0, -1, v0
	s_nop 0
	v_cmp_eq_u32_e32 vcc, 0, v0
	s_and_saveexec_b64 s[6:7], vcc
	s_cbranch_execz .LBB0_407
	s_cmp_eq_u32 s101, 1
	s_cbranch_scc0 .Lglob_S3
	s_and_b32 s98, s33, 7
	s_lshl_b32 s99, s98, 2
	s_addk_i32 s99, 0x4800
	v_mov_b32_e32 v3, s99
	s_lshl_b32 s98, s98, 8
	s_addk_i32 s98, 0x4000
	v_mov_b32_e32 v0, s98
	v_mov_b32_e32 v1, 1
	global_atomic_add v2, v0, v1, s[44:45] sc0
	buffer_inv sc1
	s_waitcnt vmcnt(1)
	v_readfirstlane_b32 s98, v2
	s_nop 3
	s_add_u32 s99, s98, 1
	s_and_b32 s99, s99, 31
	s_lshr_b32 s98, s98, 5
	s_cmp_eq_u32 s99, 0
	s_cbranch_scc0 .Llw_S3
	global_atomic_add v3, v1, s[44:45]
	s_branch .Lrvp_S3

; #define PG8_STAGE(bufoff, gbase, voff) do { const char* gb_ = (const char*)(gbase); asm volatile("" : "+s"(gb_));   \
;         _Pragma("unroll") for (int _i = 0; _i < 2; ++_i) \
;         __builtin_amdgcn_global_load_lds((const unsigned*)(gb_ + (voff)[_i]), (PG8_LAS unsigned*)(lds + (bufoff) + ldsw + _i * 8192), 16, 0, 0); } while (0)
; #define PG8_WAIT_V(n) asm volatile("s_waitcnt vmcnt(" #n ")" ::: "memory")
; #define PG8_WAIT_V8_RELAX() do { if constexpr (Epi::NSTORES + Epi::NPRE == 10) asm volatile("s_waitcnt vmcnt(18)" ::: "memory"); else if constexpr (Epi::NSTORES + Epi::NPRE == 18) asm volatile("s_waitcnt vmcnt(26)" ::: "memory"); else asm volatile("s_waitcnt vmcnt(8)" ::: "memory"); } while (0)
; #define PG8_BAR __builtin_amdgcn_s_barrier()
; template <class Epi, class Sched, bool ALIGN_EPI = false, bool SP2 = false>
; __device__ __forceinline__ void gemm_phase(PG8_LAS unsigned char* lds, const Gemm g, const Sched& S, const Epi& E, int wave_s) {
;     ...
;     if constexpr (SP2) {
;         PG8_STAGE(PG8_SB(0, 0), cB, voffB); PG8_STAGE(PG8_SB(0, 1), cB + hstep, voffB); PG8_STAGE(PG8_SA(0, 0), cA, voffA); PG8_STAGE(PG8_SA(0, 1), cA + hstep, voffA);
;         if (wr == 1) PG8_BAR;
;         PG8_WAIT_V(2); PG8_BAR;
;         PG8_STAGE(PG8_SB(1, 0), cB + kstep, voffB); PG8_STAGE(PG8_SA(1, 0), cA + kstep, voffA); PG8_STAGE(PG8_SB(1, 1), cB + hstep + kstep, voffB);
;         PG8_WAIT_V(6); PG8_BAR;
;     ...
;         if constexpr (Epi::NPRE > 0) E.prefetch(lds, wid, cur, wr, fr, fq);
;         if constexpr (SP2 && Epi::NSTORES > 0 && !Epi::AFTER_DRAIN) {
;             const char* a1 = cA + kstep; const char* a2 = cA + 2 * kstep; const char* b2 = cB + 2 * kstep; const char* a3 = a2 + kstep; const char* b3 = b2 + kstep;
;             PG8_SP2_PAIR(PG8_WAIT_V8_RELAX);
.LBB0_413:
	s_lshl_b32 s18, s18, 5
	s_and_b32 s20, s18, 0x60
	s_lshl_b32 s17, s17, 13
	s_lshl_b32 s21, s20, 7
	s_add_u32 s18, s8, 0x80
	s_addc_u32 s19, s9, 0
	s_waitcnt vmcnt(2)
	s_barrier
	s_add_i32 m0, s35, 0x18000
	s_nop 0
	global_load_lds_dwordx4 v134, s[18:19]
	s_add_i32 m0, s35, 0x1a000
	s_nop 0
	global_load_lds_dwordx4 v138, s[18:19]
	s_add_u32 s18, s38, 0x80
	s_addc_u32 s19, s39, 0
	s_add_i32 s63, s35, 0x8000
	s_mov_b32 m0, s63
	s_add_i32 s72, s35, 0xa000
	global_load_lds_dwordx4 v132, s[18:19]
	s_mov_b64 s[98:99], s[18:19]
	s_add_u32 s18, s8, 0x40080
	s_mov_b32 m0, s72
	s_addc_u32 s19, s9, 0
	global_load_lds_dwordx4 v136, s[98:99]
	s_add_i32 m0, s35, 0x1c000
	s_nop 0
	global_load_lds_dwordx4 v134, s[18:19]
	s_add_i32 m0, s35, 0x1e000
	v_and_b32_e32 v0, 15, v2
	global_load_lds_dwordx4 v138, s[18:19]
	v_lshrrev_b32_e32 v2, 1, v2
	v_or_b32_e32 v144, s10, v0
	v_and_b32_e32 v2, 24, v2
	v_lshlrev_b32_e32 v3, 6, v144
	v_lshlrev_b32_e32 v4, 1, v2
	s_movk_i32 s10, 0x3c0
	v_lshlrev_b32_e32 v5, 2, v144
	v_and_or_b32 v3, v3, s10, v4
	v_and_b32_e32 v5, 32, v5
	v_lshlrev_b32_e32 v145, 2, v0
	v_bitop3_b32 v5, v3, s17, v5 bitop3:0xde
	v_lshl_or_b32 v3, v0, 6, v4
	v_and_b32_e32 v0, 32, v145
	s_cmpk_lt_u32 s16, 0x100
	v_bitop3_b32 v146, v3, s21, v0 bitop3:0xde
	s_waitcnt vmcnt(6)
	s_cselect_b64 s[16:17], -1, 0
	s_ashr_i32 s74, s33, 31
	v_or_b32_e32 v147, s20, v2
	v_mov_b32_e32 v2, v1
	v_mov_b32_e32 v3, v1
	s_add_u32 s75, s40, s6
	v_mov_b32_e32 v0, v1
	v_add_u32_e32 v149, 0, v5
	v_mov_b64_e32 v[6:7], v[2:3]
	v_mov_b64_e32 v[10:11], v[2:3]
	v_mov_b64_e32 v[22:23], v[2:3]
	v_mov_b64_e32 v[26:27], v[2:3]
	v_mov_b64_e32 v[38:39], v[2:3]
	v_mov_b64_e32 v[42:43], v[2:3]
	v_mov_b64_e32 v[54:55], v[2:3]
	v_mov_b64_e32 v[58:59], v[2:3]
	v_mov_b64_e32 v[14:15], v[2:3]
	v_mov_b64_e32 v[18:19], v[2:3]
	v_mov_b64_e32 v[30:31], v[2:3]
	v_mov_b64_e32 v[34:35], v[2:3]
	v_mov_b64_e32 v[46:47], v[2:3]
	v_mov_b64_e32 v[50:51], v[2:3]
	v_mov_b64_e32 v[62:63], v[2:3]
	v_mov_b64_e32 v[66:67], v[2:3]
	v_mov_b64_e32 v[70:71], v[2:3]
	v_mov_b64_e32 v[74:75], v[2:3]
	v_mov_b64_e32 v[86:87], v[2:3]
	v_mov_b64_e32 v[90:91], v[2:3]
	v_mov_b64_e32 v[102:103], v[2:3]
	v_mov_b64_e32 v[106:107], v[2:3]
	v_mov_b64_e32 v[118:119], v[2:3]
	v_mov_b64_e32 v[122:123], v[2:3]
	v_mov_b64_e32 v[78:79], v[2:3]
	v_mov_b64_e32 v[82:83], v[2:3]
	v_mov_b64_e32 v[94:95], v[2:3]
	v_mov_b64_e32 v[98:99], v[2:3]
	v_mov_b64_e32 v[110:111], v[2:3]
	v_mov_b64_e32 v[114:115], v[2:3]
	v_mov_b64_e32 v[126:127], v[2:3]
	v_mov_b64_e32 v[130:131], v[2:3]
	s_mov_b32 s73, s46
	s_addc_u32 s76, s41, s7
	v_mov_b64_e32 v[140:141], 0x300
	v_mov_b64_e32 v[142:143], 0x2ff
	s_movk_i32 s77, 0x61
	s_add_i32 s78, 0, 0x10000
	s_add_i32 s79, 0, 0x14000
	v_mov_b32_e32 v148, 0x358637bd
	s_mov_b64 s[18:19], 0x48000
	s_mov_b64 s[20:21], 0x50000
	s_mov_b64 s[22:23], 0x58000
	v_mov_b64_e32 v[4:5], v[0:1]
	v_mov_b64_e32 v[8:9], v[0:1]
	v_mov_b64_e32 v[20:21], v[0:1]
	v_mov_b64_e32 v[24:25], v[0:1]
	v_mov_b64_e32 v[36:37], v[0:1]
	v_mov_b64_e32 v[40:41], v[0:1]
	v_mov_b64_e32 v[52:53], v[0:1]
	v_mov_b64_e32 v[56:57], v[0:1]
	v_mov_b64_e32 v[12:13], v[0:1]
	v_mov_b64_e32 v[16:17], v[0:1]
	v_mov_b64_e32 v[28:29], v[0:1]
	v_mov_b64_e32 v[32:33], v[0:1]
	v_mov_b64_e32 v[44:45], v[0:1]
	v_mov_b64_e32 v[48:49], v[0:1]
	v_mov_b64_e32 v[60:61], v[0:1]
	v_mov_b64_e32 v[64:65], v[0:1]
	v_mov_b64_e32 v[68:69], v[0:1]
	v_mov_b64_e32 v[72:73], v[0:1]
	v_mov_b64_e32 v[84:85], v[0:1]
	v_mov_b64_e32 v[88:89], v[0:1]
	v_mov_b64_e32 v[100:101], v[0:1]
	v_mov_b64_e32 v[104:105], v[0:1]
	v_mov_b64_e32 v[116:117], v[0:1]
	v_mov_b64_e32 v[120:121], v[0:1]
	v_mov_b64_e32 v[76:77], v[0:1]
	v_mov_b64_e32 v[80:81], v[0:1]
	v_mov_b64_e32 v[92:93], v[0:1]
	v_mov_b64_e32 v[96:97], v[0:1]
	v_mov_b64_e32 v[108:109], v[0:1]
	v_mov_b64_e32 v[112:113], v[0:1]
	v_mov_b64_e32 v[124:125], v[0:1]
	v_mov_b64_e32 v[128:129], v[0:1]
	s_mov_b32 s10, s11
	s_mov_b32 s87, s11
	s_barrier
	s_branch .LBB0_416
.LBB0_414:
	s_lshl_b32 s6, s26, 8
	s_ashr_i32 s7, s6, 31
	s_lshl_b64 s[6:7], s[6:7], 2
	v_mbcnt_lo_u32_b32 v6, -1, 0
	v_mbcnt_hi_u32_b32 v6, -1, v6
	s_add_u32 s6, s75, s6
	v_and_b32_e32 v0, 15, v6
	v_lshlrev_b32_e32 v2, 2, v6
	v_and_b32_e32 v2, 0xffffff80, v2
	s_addc_u32 s7, s76, s7
	v_lshlrev_b32_e32 v0, 2, v0
	v_ashrrev_i32_e32 v3, 31, v2
	v_lshl_add_u64 v[4:5], s[6:7], 0, v[0:1]
	v_lshlrev_b32_e32 v0, 3, v6
	v_lshl_add_u64 v[2:3], v[2:3], 2, v[4:5]
	v_and_b32_e32 v0, 0x80, v0
	s_mov_b32 m0, s59
	v_lshl_add_u64 v[2:3], v[2:3], 0, v[0:1]
	global_load_lds_dword v[2:3], off
	v_lshl_add_u64 v[2:3], v[2:3], 0, 64
	s_add_i32 m0, s59, 0x100
	s_add_u32 s8, s28, 0x100
	global_load_lds_dword v[2:3], off
	ds_read_b128 v[2:5], v151
	ds_read_b128 v[6:9], v151 offset:1024
	ds_read_b128 v[10:13], v151 offset:2048
	ds_read_b128 v[14:17], v151 offset:3072
	ds_read_b128 v[18:21], v150
	ds_read_b128 v[22:25], v150 offset:1024
	ds_read_b128 v[26:29], v150 offset:2048
	ds_read_b128 v[30:33], v150 offset:3072
	s_addc_u32 s9, s29, 0
	s_add_u32 s6, s28, 0x180
	s_addc_u32 s7, s29, 0
	s_add_u32 s38, s30, 0x100
	s_addc_u32 s39, s31, 0
	s_add_u32 s40, s28, 0x40080
	s_addc_u32 s41, s29, 0
	s_mov_b32 m0, s91
	ds_read_b128 v[34:37], v149
	ds_read_b128 v[38:41], v149 offset:1024
	ds_read_b128 v[42:45], v149 offset:2048
	ds_read_b128 v[46:49], v149 offset:3072
	ds_read_b128 v[50:53], v149 offset:4096
	ds_read_b128 v[54:57], v149 offset:5120
	ds_read_b128 v[58:61], v149 offset:6144
	ds_read_b128 v[62:65], v149 offset:7168
	s_nop 0
	global_load_lds_dwordx4 v132, s[40:41]
	s_mov_b32 m0, s10
	s_nop 0
	global_load_lds_dwordx4 v136, s[40:41]
	s_waitcnt vmcnt(26)
	s_waitcnt lgkmcnt(0)
	s_barrier
	s_setprio 1
	s_waitcnt lgkmcnt(0)
	v_mfma_f32_16x16x32_bf16 v[90:93], v[2:5], v[58:61], 0
	v_mfma_f32_16x16x32_bf16 v[66:69], v[2:5], v[34:37], 0
	v_mfma_f32_16x16x32_bf16 v[70:73], v[10:13], v[34:37], 0
	v_mfma_f32_16x16x32_bf16 v[74:77], v[2:5], v[42:45], 0
	v_mfma_f32_16x16x32_bf16 v[78:81], v[10:13], v[42:45], 0
	v_mfma_f32_16x16x32_bf16 v[82:85], v[2:5], v[50:53], 0
	v_mfma_f32_16x16x32_bf16 v[86:89], v[10:13], v[50:53], 0
	v_mfma_f32_16x16x32_bf16 v[100:103], v[6:9], v[62:65], v[90:93]
	v_mfma_f32_16x16x32_bf16 v[90:93], v[10:13], v[58:61], 0
	v_mfma_f32_16x16x32_bf16 v[66:69], v[6:9], v[38:41], v[66:69]
	v_mfma_f32_16x16x32_bf16 v[70:73], v[14:17], v[38:41], v[70:73]
	v_mfma_f32_16x16x32_bf16 v[74:77], v[6:9], v[46:49], v[74:77]
	v_mfma_f32_16x16x32_bf16 v[78:81], v[14:17], v[46:49], v[78:81]
	v_mfma_f32_16x16x32_bf16 v[82:85], v[6:9], v[54:57], v[82:85]
	v_mfma_f32_16x16x32_bf16 v[86:89], v[14:17], v[54:57], v[86:89]
	v_mfma_f32_16x16x32_bf16 v[104:107], v[14:17], v[62:65], v[90:93]
	s_setprio 0
	s_setprio 1
	v_mfma_f32_16x16x32_bf16 v[90:93], v[18:21], v[34:37], 0
	v_mfma_f32_16x16x32_bf16 v[34:37], v[26:29], v[34:37], 0
	v_mfma_f32_16x16x32_bf16 v[116:119], v[22:25], v[38:41], v[90:93]
	v_mfma_f32_16x16x32_bf16 v[34:37], v[30:33], v[38:41], v[34:37]
	v_mfma_f32_16x16x32_bf16 v[38:41], v[18:21], v[42:45], 0
	v_mfma_f32_16x16x32_bf16 v[42:45], v[26:29], v[42:45], 0
	v_mfma_f32_16x16x32_bf16 v[38:41], v[22:25], v[46:49], v[38:41]
	v_mfma_f32_16x16x32_bf16 v[42:45], v[30:33], v[46:49], v[42:45]
	v_mfma_f32_16x16x32_bf16 v[46:49], v[18:21], v[50:53], 0
	v_mfma_f32_16x16x32_bf16 v[50:53], v[26:29], v[50:53], 0
	v_mfma_f32_16x16x32_bf16 v[46:49], v[22:25], v[54:57], v[46:49]
	v_mfma_f32_16x16x32_bf16 v[50:53], v[30:33], v[54:57], v[50:53]
	v_mfma_f32_16x16x32_bf16 v[54:57], v[18:21], v[58:61], 0
	v_mfma_f32_16x16x32_bf16 v[58:61], v[26:29], v[58:61], 0
	v_mfma_f32_16x16x32_bf16 v[54:57], v[22:25], v[62:65], v[54:57]
	v_mfma_f32_16x16x32_bf16 v[58:61], v[30:33], v[62:65], v[58:61]
	s_setprio 0
	s_barrier
	s_mov_b32 m0, s90
	ds_read_b128 v[62:65], v149 offset:16384
	ds_read_b128 v[90:93], v149 offset:17408
	ds_read_b128 v[94:97], v149 offset:18432
	ds_read_b128 v[108:111], v149 offset:19456
	ds_read_b128 v[112:115], v149 offset:20480
	ds_read_b128 v[120:123], v149 offset:21504
	ds_read_b128 v[124:127], v149 offset:22528
	ds_read_b128 v[128:131], v149 offset:23552
	s_nop 0
	global_load_lds_dwordx4 v134, s[38:39]
	s_mov_b64 s[98:99], s[38:39]
	s_add_u32 s38, s30, 0x40100
	s_mov_b32 m0, s25
	s_addc_u32 s39, s31, 0
	global_load_lds_dwordx4 v138, s[98:99]
	s_mov_b32 m0, s27
	s_nop 0
	global_load_lds_dwordx4 v134, s[38:39]
	s_mov_b32 m0, s88
	s_nop 0
	global_load_lds_dwordx4 v138, s[38:39]
	s_mov_b32 m0, s35
	s_nop 0
	global_load_lds_dwordx4 v132, s[8:9]
	s_mov_b32 m0, s37
	s_nop 0
	global_load_lds_dwordx4 v136, s[8:9]
	s_waitcnt vmcnt(26)
	s_waitcnt lgkmcnt(0)
	s_barrier
	s_setprio 1
	s_waitcnt lgkmcnt(0)
	v_mfma_f32_16x16x32_bf16 v[154:157], v[2:5], v[62:65], 0
	v_mfma_f32_16x16x32_bf16 v[162:165], v[2:5], v[94:97], 0
	v_mfma_f32_16x16x32_bf16 v[170:173], v[2:5], v[112:115], 0
	v_mfma_f32_16x16x32_bf16 v[2:5], v[2:5], v[124:127], 0
	v_mfma_f32_16x16x32_bf16 v[154:157], v[6:9], v[90:93], v[154:157]
	v_mfma_f32_16x16x32_bf16 v[162:165], v[6:9], v[108:111], v[162:165]
	v_mfma_f32_16x16x32_bf16 v[170:173], v[6:9], v[120:123], v[170:173]
	v_mfma_f32_16x16x32_bf16 v[2:5], v[6:9], v[128:131], v[2:5]
	v_mfma_f32_16x16x32_bf16 v[6:9], v[10:13], v[124:127], 0
	v_mfma_f32_16x16x32_bf16 v[158:161], v[10:13], v[62:65], 0
	v_mfma_f32_16x16x32_bf16 v[166:169], v[10:13], v[94:97], 0
	v_mfma_f32_16x16x32_bf16 v[176:179], v[10:13], v[112:115], 0
	v_mfma_f32_16x16x32_bf16 v[6:9], v[14:17], v[128:131], v[6:9]
	v_mfma_f32_16x16x32_bf16 v[158:161], v[14:17], v[90:93], v[158:161]
	v_mfma_f32_16x16x32_bf16 v[166:169], v[14:17], v[108:111], v[166:169]
	v_mfma_f32_16x16x32_bf16 v[176:179], v[14:17], v[120:123], v[176:179]
	s_setprio 0
	s_setprio 1
	v_mfma_f32_16x16x32_bf16 v[10:13], v[18:21], v[62:65], 0
	v_mfma_f32_16x16x32_bf16 v[180:183], v[22:25], v[90:93], v[10:13]
	v_mfma_f32_16x16x32_bf16 v[10:13], v[26:29], v[62:65], 0
	v_mfma_f32_16x16x32_bf16 v[184:187], v[30:33], v[90:93], v[10:13]
	v_mfma_f32_16x16x32_bf16 v[10:13], v[18:21], v[94:97], 0
	v_mfma_f32_16x16x32_bf16 v[188:191], v[22:25], v[108:111], v[10:13]
	v_mfma_f32_16x16x32_bf16 v[10:13], v[26:29], v[94:97], 0
	v_mfma_f32_16x16x32_bf16 v[192:195], v[30:33], v[108:111], v[10:13]
	v_mfma_f32_16x16x32_bf16 v[10:13], v[18:21], v[112:115], 0
	v_mfma_f32_16x16x32_bf16 v[196:199], v[22:25], v[120:123], v[10:13]
	v_mfma_f32_16x16x32_bf16 v[10:13], v[26:29], v[112:115], 0
	v_mfma_f32_16x16x32_bf16 v[200:203], v[30:33], v[120:123], v[10:13]
	v_mfma_f32_16x16x32_bf16 v[10:13], v[18:21], v[124:127], 0
	v_mfma_f32_16x16x32_bf16 v[204:207], v[22:25], v[128:131], v[10:13]
	v_mfma_f32_16x16x32_bf16 v[10:13], v[26:29], v[124:127], 0
	v_mfma_f32_16x16x32_bf16 v[208:211], v[30:33], v[128:131], v[10:13]
	s_setprio 0
	s_barrier
	s_nop 4
	ds_read_b128 v[10:13], v152
	ds_read_b128 v[14:17], v152 offset:1024
	ds_read_b128 v[20:23], v152 offset:2048
	ds_read_b128 v[24:27], v152 offset:3072
	ds_read_b128 v[212:215], v153
	ds_read_b128 v[216:219], v153 offset:1024
	ds_read_b128 v[220:223], v153 offset:2048
	ds_read_b128 v[150:153], v153 offset:3072
	s_add_u32 s8, s28, 0x40100
	s_addc_u32 s9, s29, 0
	s_mov_b32 m0, s60
	ds_read_b128 v[28:31], v149 offset:32768
	ds_read_b128 v[62:65], v149 offset:33792
	ds_read_b128 v[224:227], v149 offset:34816
	ds_read_b128 v[228:231], v149 offset:35840
	ds_read_b128 v[232:235], v149 offset:36864
	ds_read_b128 v[236:239], v149 offset:37888
	ds_read_b128 v[240:243], v149 offset:38912
	ds_read_b128 v[244:247], v149 offset:39936
	s_nop 0
	global_load_lds_dwordx4 v132, s[8:9]
	s_mov_b32 m0, s61
	s_nop 0
	global_load_lds_dwordx4 v136, s[8:9]
	s_waitcnt vmcnt(26)
	s_waitcnt lgkmcnt(0)
	s_barrier
	s_setprio 1
	s_waitcnt lgkmcnt(0)
	v_mfma_f32_16x16x32_bf16 v[66:69], v[10:13], v[28:31], v[66:69]
	v_mfma_f32_16x16x32_bf16 v[128:131], v[14:17], v[62:65], v[66:69]
	v_mfma_f32_16x16x32_bf16 v[66:69], v[20:23], v[28:31], v[70:73]
	v_mfma_f32_16x16x32_bf16 v[124:127], v[24:27], v[62:65], v[66:69]
	v_mfma_f32_16x16x32_bf16 v[66:69], v[10:13], v[224:227], v[74:77]
	v_mfma_f32_16x16x32_bf16 v[112:115], v[14:17], v[228:231], v[66:69]
	v_mfma_f32_16x16x32_bf16 v[66:69], v[20:23], v[224:227], v[78:81]
	v_mfma_f32_16x16x32_bf16 v[108:111], v[24:27], v[228:231], v[66:69]
	v_mfma_f32_16x16x32_bf16 v[66:69], v[10:13], v[232:235], v[82:85]
	v_mfma_f32_16x16x32_bf16 v[96:99], v[14:17], v[236:239], v[66:69]
	v_mfma_f32_16x16x32_bf16 v[66:69], v[20:23], v[232:235], v[86:89]
	v_mfma_f32_16x16x32_bf16 v[92:95], v[24:27], v[236:239], v[66:69]
	v_mfma_f32_16x16x32_bf16 v[66:69], v[10:13], v[240:243], v[100:103]
	v_mfma_f32_16x16x32_bf16 v[80:83], v[14:17], v[244:247], v[66:69]
	v_mfma_f32_16x16x32_bf16 v[66:69], v[20:23], v[240:243], v[104:107]
	v_mfma_f32_16x16x32_bf16 v[76:79], v[24:27], v[244:247], v[66:69]
	s_setprio 0
	s_setprio 1
	v_mfma_f32_16x16x32_bf16 v[66:69], v[212:215], v[28:31], v[116:119]
	v_mfma_f32_16x16x32_bf16 v[28:31], v[220:223], v[28:31], v[34:37]
	v_mfma_f32_16x16x32_bf16 v[116:119], v[150:153], v[62:65], v[28:31]
	v_mfma_f32_16x16x32_bf16 v[28:31], v[212:215], v[224:227], v[38:41]
	v_mfma_f32_16x16x32_bf16 v[104:107], v[216:219], v[228:231], v[28:31]
	v_mfma_f32_16x16x32_bf16 v[28:31], v[220:223], v[224:227], v[42:45]
	v_mfma_f32_16x16x32_bf16 v[100:103], v[150:153], v[228:231], v[28:31]
	v_mfma_f32_16x16x32_bf16 v[28:31], v[212:215], v[232:235], v[46:49]
	v_mfma_f32_16x16x32_bf16 v[88:91], v[216:219], v[236:239], v[28:31]
	v_mfma_f32_16x16x32_bf16 v[28:31], v[220:223], v[232:235], v[50:53]
	v_mfma_f32_16x16x32_bf16 v[84:87], v[150:153], v[236:239], v[28:31]
	v_mfma_f32_16x16x32_bf16 v[28:31], v[212:215], v[240:243], v[54:57]
	v_mfma_f32_16x16x32_bf16 v[72:75], v[216:219], v[244:247], v[28:31]
	v_mfma_f32_16x16x32_bf16 v[28:31], v[220:223], v[240:243], v[58:61]
	v_mfma_f32_16x16x32_bf16 v[120:123], v[216:219], v[62:65], v[66:69]
	v_mfma_f32_16x16x32_bf16 v[68:71], v[150:153], v[244:247], v[28:31]
	s_setprio 0
	s_barrier
	s_add_u32 s8, s30, 0x180
	s_addc_u32 s9, s31, 0
	s_mov_b32 m0, s92
	ds_read_b128 v[36:39], v149 offset:49152
	ds_read_b128 v[40:43], v149 offset:50176
	ds_read_b128 v[224:227], v149 offset:51200
	ds_read_b128 v[228:231], v149 offset:52224
	ds_read_b128 v[232:235], v149 offset:53248
	ds_read_b128 v[236:239], v149 offset:54272
	ds_read_b128 v[240:243], v149 offset:55296
	ds_read_b128 v[244:247], v149 offset:56320
	s_nop 0
	global_load_lds_dwordx4 v134, s[8:9]
	s_mov_b64 s[98:99], s[8:9]
	s_add_u32 s8, s30, 0x40180
	s_mov_b32 m0, s42
	s_addc_u32 s9, s31, 0
	global_load_lds_dwordx4 v138, s[98:99]
	s_mov_b32 m0, s43
	s_nop 0
	global_load_lds_dwordx4 v134, s[8:9]
	s_mov_b32 m0, s89
	s_nop 0
	global_load_lds_dwordx4 v138, s[8:9]
	s_mov_b32 m0, s63
	s_nop 0
	global_load_lds_dwordx4 v132, s[6:7]
	s_mov_b32 m0, s72
	s_nop 0
	global_load_lds_dwordx4 v136, s[6:7]
	s_waitcnt vmcnt(26)
	s_waitcnt lgkmcnt(0)
	s_barrier
	s_setprio 1
	s_waitcnt lgkmcnt(0)
	v_mfma_f32_16x16x32_bf16 v[28:31], v[10:13], v[36:39], v[154:157]
	v_mfma_f32_16x16x32_bf16 v[64:67], v[14:17], v[40:43], v[28:31]
	v_mfma_f32_16x16x32_bf16 v[28:31], v[20:23], v[36:39], v[158:161]
	v_mfma_f32_16x16x32_bf16 v[60:63], v[24:27], v[40:43], v[28:31]
	v_mfma_f32_16x16x32_bf16 v[28:31], v[10:13], v[224:227], v[162:165]
	v_mfma_f32_16x16x32_bf16 v[48:51], v[14:17], v[228:231], v[28:31]
	v_mfma_f32_16x16x32_bf16 v[28:31], v[20:23], v[224:227], v[166:169]
	v_mfma_f32_16x16x32_bf16 v[44:47], v[24:27], v[228:231], v[28:31]
	v_mfma_f32_16x16x32_bf16 v[28:31], v[10:13], v[232:235], v[170:173]
	v_mfma_f32_16x16x32_bf16 v[2:5], v[10:13], v[240:243], v[2:5]
	v_mfma_f32_16x16x32_bf16 v[32:35], v[14:17], v[236:239], v[28:31]
	v_mfma_f32_16x16x32_bf16 v[28:31], v[20:23], v[232:235], v[176:179]
	v_mfma_f32_16x16x32_bf16 v[16:19], v[14:17], v[244:247], v[2:5]
	v_mfma_f32_16x16x32_bf16 v[2:5], v[20:23], v[240:243], v[6:9]
	v_mfma_f32_16x16x32_bf16 v[28:31], v[24:27], v[236:239], v[28:31]
	v_mfma_f32_16x16x32_bf16 v[12:15], v[24:27], v[244:247], v[2:5]
	s_setprio 0
	s_setprio 1
	v_mfma_f32_16x16x32_bf16 v[2:5], v[212:215], v[36:39], v[180:183]
	v_mfma_f32_16x16x32_bf16 v[56:59], v[216:219], v[40:43], v[2:5]
	v_mfma_f32_16x16x32_bf16 v[2:5], v[220:223], v[36:39], v[184:187]
	v_mfma_f32_16x16x32_bf16 v[52:55], v[150:153], v[40:43], v[2:5]
	v_mfma_f32_16x16x32_bf16 v[2:5], v[212:215], v[224:227], v[188:191]
	v_mfma_f32_16x16x32_bf16 v[40:43], v[216:219], v[228:231], v[2:5]
	v_mfma_f32_16x16x32_bf16 v[2:5], v[220:223], v[224:227], v[192:195]
	v_mfma_f32_16x16x32_bf16 v[36:39], v[150:153], v[228:231], v[2:5]
	v_mfma_f32_16x16x32_bf16 v[2:5], v[212:215], v[232:235], v[196:199]
	v_mfma_f32_16x16x32_bf16 v[24:27], v[216:219], v[236:239], v[2:5]
	v_mfma_f32_16x16x32_bf16 v[2:5], v[220:223], v[232:235], v[200:203]
	v_mfma_f32_16x16x32_bf16 v[20:23], v[150:153], v[236:239], v[2:5]
	v_mfma_f32_16x16x32_bf16 v[2:5], v[212:215], v[240:243], v[204:207]
	v_mfma_f32_16x16x32_bf16 v[8:11], v[216:219], v[244:247], v[2:5]
	v_mfma_f32_16x16x32_bf16 v[2:5], v[220:223], v[240:243], v[208:211]
	v_mfma_f32_16x16x32_bf16 v[4:7], v[150:153], v[244:247], v[2:5]
	s_setprio 0
	s_barrier
	s_mov_b64 s[6:7], 0

; #define PG8_WAIT_V8_STRICT() asm volatile("s_waitcnt vmcnt(8)" ::: "memory")
; template <class Epi, class Sched, bool ALIGN_EPI = false, bool SP2 = false>
; __device__ __forceinline__ void gemm_phase(PG8_LAS unsigned char* lds, const Gemm g, const Sched& S, const Epi& E, int wave_s) {
;     ...
;         for (int t = peeled ? 2 : 0; t < nt; t += 2) {
;             const bool last = (t == nt - 2);
;             const char* a1 = cA + (size_t)(t + 1) * kstep;
;             const char* a2 = last ? nA : cA + (size_t)(t + 2) * kstep; const char* b2 = last ? nB : cB + (size_t)(t + 2) * kstep;
;             const char* a3 = a2 + kstep; const char* b3 = b2 + kstep;
;             if (last && has_next) S.a_ready(nxt);
;             if constexpr (SP2) {
;             PG8_SP2_PAIR(PG8_WAIT_V8_STRICT);
.LBB0_419:
	v_add_u32_e32 v151, s78, v146
	v_add_u32_e32 v150, s79, v146
	ds_read_b128 v[152:155], v151
	ds_read_b128 v[156:159], v151 offset:1024
	ds_read_b128 v[160:163], v151 offset:2048
	ds_read_b128 v[164:167], v151 offset:3072
	ds_read_b128 v[168:171], v150
	ds_read_b128 v[176:179], v150 offset:1024
	ds_read_b128 v[180:183], v150 offset:2048
	ds_read_b128 v[184:187], v150 offset:3072
	s_add_u32 s8, s52, 0x100
	s_addc_u32 s9, s53, 0
	s_cmp_eq_u32 s96, 12
	s_cselect_b32 s42, s93, s8
	s_cselect_b32 s43, s82, s9
	s_cselect_b32 s40, s95, s97
	s_cselect_b32 s41, s94, vcc_lo
	s_add_u32 s38, s42, 0x80
	s_addc_u32 s39, s43, 0
	s_add_u32 s52, s52, 0x40080
	s_addc_u32 s53, s53, 0
	s_add_i32 s91, s35, 0xc000
	ds_read_b128 v[188:191], v149
	ds_read_b128 v[192:195], v149 offset:1024
	ds_read_b128 v[196:199], v149 offset:2048
	ds_read_b128 v[200:203], v149 offset:3072
	ds_read_b128 v[204:207], v149 offset:4096
	ds_read_b128 v[208:211], v149 offset:5120
	ds_read_b128 v[212:215], v149 offset:6144
	ds_read_b128 v[216:219], v149 offset:7168
	s_mov_b32 m0, s91
	s_add_i32 s10, s35, 0xe000
	global_load_lds_dwordx4 v132, s[52:53]
	s_mov_b32 m0, s10
	s_nop 0
	global_load_lds_dwordx4 v136, s[52:53]
	s_waitcnt vmcnt(8)
	s_waitcnt lgkmcnt(0)
	s_barrier
	s_setprio 1
	s_waitcnt lgkmcnt(0)
	v_mfma_f32_16x16x32_bf16 v[128:131], v[152:155], v[188:191], v[128:131]
	v_mfma_f32_16x16x32_bf16 v[124:127], v[160:163], v[188:191], v[124:127]
	v_mfma_f32_16x16x32_bf16 v[112:115], v[152:155], v[196:199], v[112:115]
	v_mfma_f32_16x16x32_bf16 v[108:111], v[160:163], v[196:199], v[108:111]
	v_mfma_f32_16x16x32_bf16 v[96:99], v[152:155], v[204:207], v[96:99]
	v_mfma_f32_16x16x32_bf16 v[92:95], v[160:163], v[204:207], v[92:95]
	v_mfma_f32_16x16x32_bf16 v[80:83], v[152:155], v[212:215], v[80:83]
	v_mfma_f32_16x16x32_bf16 v[76:79], v[160:163], v[212:215], v[76:79]
	v_mfma_f32_16x16x32_bf16 v[128:131], v[156:159], v[192:195], v[128:131]
	v_mfma_f32_16x16x32_bf16 v[124:127], v[164:167], v[192:195], v[124:127]
	v_mfma_f32_16x16x32_bf16 v[112:115], v[156:159], v[200:203], v[112:115]
	v_mfma_f32_16x16x32_bf16 v[108:111], v[164:167], v[200:203], v[108:111]
	v_mfma_f32_16x16x32_bf16 v[96:99], v[156:159], v[208:211], v[96:99]
	v_mfma_f32_16x16x32_bf16 v[92:95], v[164:167], v[208:211], v[92:95]
	v_mfma_f32_16x16x32_bf16 v[80:83], v[156:159], v[216:219], v[80:83]
	v_mfma_f32_16x16x32_bf16 v[76:79], v[164:167], v[216:219], v[76:79]
	s_setprio 0
	s_setprio 1
	v_mfma_f32_16x16x32_bf16 v[120:123], v[168:171], v[188:191], v[120:123]
	v_mfma_f32_16x16x32_bf16 v[116:119], v[180:183], v[188:191], v[116:119]
	v_mfma_f32_16x16x32_bf16 v[104:107], v[168:171], v[196:199], v[104:107]
	v_mfma_f32_16x16x32_bf16 v[100:103], v[180:183], v[196:199], v[100:103]
	v_mfma_f32_16x16x32_bf16 v[88:91], v[168:171], v[204:207], v[88:91]
	v_mfma_f32_16x16x32_bf16 v[84:87], v[180:183], v[204:207], v[84:87]
	v_mfma_f32_16x16x32_bf16 v[72:75], v[168:171], v[212:215], v[72:75]
	v_mfma_f32_16x16x32_bf16 v[68:71], v[180:183], v[212:215], v[68:71]
	v_mfma_f32_16x16x32_bf16 v[120:123], v[176:179], v[192:195], v[120:123]
	v_mfma_f32_16x16x32_bf16 v[116:119], v[184:187], v[192:195], v[116:119]
	v_mfma_f32_16x16x32_bf16 v[104:107], v[176:179], v[200:203], v[104:107]
	v_mfma_f32_16x16x32_bf16 v[100:103], v[184:187], v[200:203], v[100:103]
	v_mfma_f32_16x16x32_bf16 v[88:91], v[176:179], v[208:211], v[88:91]
	v_mfma_f32_16x16x32_bf16 v[84:87], v[184:187], v[208:211], v[84:87]
	v_mfma_f32_16x16x32_bf16 v[72:75], v[176:179], v[216:219], v[72:75]
	v_mfma_f32_16x16x32_bf16 v[68:71], v[184:187], v[216:219], v[68:71]
	s_setprio 0
	s_barrier
	s_mov_b64 s[52:53], s[40:41]
	s_add_i32 s90, s78, s58
	ds_read_b128 v[188:191], v149 offset:16384
	ds_read_b128 v[192:195], v149 offset:17408
	ds_read_b128 v[196:199], v149 offset:18432
	ds_read_b128 v[200:203], v149 offset:19456
	ds_read_b128 v[204:207], v149 offset:20480
	ds_read_b128 v[208:211], v149 offset:21504
	ds_read_b128 v[212:215], v149 offset:22528
	ds_read_b128 v[216:219], v149 offset:23552
	s_mov_b32 m0, s90
	s_add_i32 s25, s90, 0x2000
	global_load_lds_dwordx4 v134, s[52:53]
	s_mov_b64 s[98:99], s[52:53]
	s_add_u32 s52, s40, 0x40000
	s_mov_b32 m0, s25
	s_addc_u32 s53, s41, 0
	s_add_i32 s27, s79, s58
	global_load_lds_dwordx4 v138, s[98:99]
	s_mov_b32 m0, s27
	s_add_i32 s88, s27, 0x2000
	global_load_lds_dwordx4 v134, s[52:53]
	s_mov_b64 s[98:99], s[52:53]
	s_mov_b32 m0, s88
	s_mov_b64 s[52:53], s[42:43]
	global_load_lds_dwordx4 v138, s[98:99]
	s_mov_b32 m0, s35
	s_nop 0
	global_load_lds_dwordx4 v132, s[52:53]
	s_mov_b32 m0, s37
	s_nop 0
	global_load_lds_dwordx4 v136, s[52:53]
	s_waitcnt vmcnt(8)
	s_waitcnt lgkmcnt(0)
	s_barrier
	s_setprio 1
	s_waitcnt lgkmcnt(0)
	v_mfma_f32_16x16x32_bf16 v[64:67], v[152:155], v[188:191], v[64:67]
	v_mfma_f32_16x16x32_bf16 v[60:63], v[160:163], v[188:191], v[60:63]
	v_mfma_f32_16x16x32_bf16 v[48:51], v[152:155], v[196:199], v[48:51]
	v_mfma_f32_16x16x32_bf16 v[44:47], v[160:163], v[196:199], v[44:47]
	v_mfma_f32_16x16x32_bf16 v[32:35], v[152:155], v[204:207], v[32:35]
	v_mfma_f32_16x16x32_bf16 v[28:31], v[160:163], v[204:207], v[28:31]
	v_mfma_f32_16x16x32_bf16 v[16:19], v[152:155], v[212:215], v[16:19]
	v_mfma_f32_16x16x32_bf16 v[12:15], v[160:163], v[212:215], v[12:15]
	v_mfma_f32_16x16x32_bf16 v[64:67], v[156:159], v[192:195], v[64:67]
	v_mfma_f32_16x16x32_bf16 v[60:63], v[164:167], v[192:195], v[60:63]
	v_mfma_f32_16x16x32_bf16 v[48:51], v[156:159], v[200:203], v[48:51]
	v_mfma_f32_16x16x32_bf16 v[44:47], v[164:167], v[200:203], v[44:47]
	v_mfma_f32_16x16x32_bf16 v[32:35], v[156:159], v[208:211], v[32:35]
	v_mfma_f32_16x16x32_bf16 v[28:31], v[164:167], v[208:211], v[28:31]
	v_mfma_f32_16x16x32_bf16 v[16:19], v[156:159], v[216:219], v[16:19]
	v_mfma_f32_16x16x32_bf16 v[12:15], v[164:167], v[216:219], v[12:15]
	s_setprio 0
	s_setprio 1
	v_mfma_f32_16x16x32_bf16 v[56:59], v[168:171], v[188:191], v[56:59]
	v_mfma_f32_16x16x32_bf16 v[52:55], v[180:183], v[188:191], v[52:55]
	v_mfma_f32_16x16x32_bf16 v[40:43], v[168:171], v[196:199], v[40:43]
	v_mfma_f32_16x16x32_bf16 v[36:39], v[180:183], v[196:199], v[36:39]
	v_mfma_f32_16x16x32_bf16 v[24:27], v[168:171], v[204:207], v[24:27]
	v_mfma_f32_16x16x32_bf16 v[20:23], v[180:183], v[204:207], v[20:23]
	v_mfma_f32_16x16x32_bf16 v[8:11], v[168:171], v[212:215], v[8:11]
	v_mfma_f32_16x16x32_bf16 v[2:5], v[180:183], v[212:215], v[4:7]
	v_mfma_f32_16x16x32_bf16 v[56:59], v[176:179], v[192:195], v[56:59]
	v_mfma_f32_16x16x32_bf16 v[52:55], v[184:187], v[192:195], v[52:55]
	v_mfma_f32_16x16x32_bf16 v[40:43], v[176:179], v[200:203], v[40:43]
	v_mfma_f32_16x16x32_bf16 v[36:39], v[184:187], v[200:203], v[36:39]
	v_mfma_f32_16x16x32_bf16 v[24:27], v[176:179], v[208:211], v[24:27]
	v_mfma_f32_16x16x32_bf16 v[20:23], v[184:187], v[208:211], v[20:23]
	v_mfma_f32_16x16x32_bf16 v[8:11], v[176:179], v[216:219], v[8:11]
	v_mfma_f32_16x16x32_bf16 v[2:5], v[184:187], v[216:219], v[2:5]
	s_setprio 0
	s_barrier
	s_add_i32 s92, 0, 0x18000
	s_add_i32 s52, 0, 0x1c000
	v_add_u32_e32 v152, s92, v146
	v_add_u32_e32 v153, s52, v146
	ds_read_b128 v[154:157], v152
	ds_read_b128 v[158:161], v152 offset:1024
	ds_read_b128 v[162:165], v152 offset:2048
	ds_read_b128 v[166:169], v152 offset:3072
	ds_read_b128 v[170:173], v153
	ds_read_b128 v[176:179], v153 offset:1024
	ds_read_b128 v[180:183], v153 offset:2048
	ds_read_b128 v[184:187], v153 offset:3072
	s_add_u32 s42, s42, 0x40000
	s_addc_u32 s43, s43, 0
	s_mov_b32 m0, s60
	ds_read_b128 v[188:191], v149 offset:32768
	ds_read_b128 v[192:195], v149 offset:33792
	ds_read_b128 v[196:199], v149 offset:34816
	ds_read_b128 v[200:203], v149 offset:35840
	ds_read_b128 v[204:207], v149 offset:36864
	ds_read_b128 v[208:211], v149 offset:37888
	ds_read_b128 v[212:215], v149 offset:38912
	ds_read_b128 v[216:219], v149 offset:39936
	s_nop 0
	global_load_lds_dwordx4 v132, s[42:43]
	s_mov_b32 m0, s61
	s_nop 0
	global_load_lds_dwordx4 v136, s[42:43]
	s_waitcnt vmcnt(8)
	s_waitcnt lgkmcnt(0)
	s_barrier
	s_setprio 1
	s_waitcnt lgkmcnt(0)
	v_mfma_f32_16x16x32_bf16 v[128:131], v[154:157], v[188:191], v[128:131]
	v_mfma_f32_16x16x32_bf16 v[124:127], v[162:165], v[188:191], v[124:127]
	v_mfma_f32_16x16x32_bf16 v[112:115], v[154:157], v[196:199], v[112:115]
	v_mfma_f32_16x16x32_bf16 v[108:111], v[162:165], v[196:199], v[108:111]
	v_mfma_f32_16x16x32_bf16 v[96:99], v[154:157], v[204:207], v[96:99]
	v_mfma_f32_16x16x32_bf16 v[92:95], v[162:165], v[204:207], v[92:95]
	v_mfma_f32_16x16x32_bf16 v[80:83], v[154:157], v[212:215], v[80:83]
	v_mfma_f32_16x16x32_bf16 v[76:79], v[162:165], v[212:215], v[76:79]
	v_mfma_f32_16x16x32_bf16 v[128:131], v[158:161], v[192:195], v[128:131]
	v_mfma_f32_16x16x32_bf16 v[124:127], v[166:169], v[192:195], v[124:127]
	v_mfma_f32_16x16x32_bf16 v[112:115], v[158:161], v[200:203], v[112:115]
	v_mfma_f32_16x16x32_bf16 v[108:111], v[166:169], v[200:203], v[108:111]
	v_mfma_f32_16x16x32_bf16 v[96:99], v[158:161], v[208:211], v[96:99]
	v_mfma_f32_16x16x32_bf16 v[92:95], v[166:169], v[208:211], v[92:95]
	v_mfma_f32_16x16x32_bf16 v[80:83], v[158:161], v[216:219], v[80:83]
	v_mfma_f32_16x16x32_bf16 v[76:79], v[166:169], v[216:219], v[76:79]
	s_setprio 0
	s_setprio 1
	v_mfma_f32_16x16x32_bf16 v[120:123], v[170:173], v[188:191], v[120:123]
	v_mfma_f32_16x16x32_bf16 v[116:119], v[180:183], v[188:191], v[116:119]
	v_mfma_f32_16x16x32_bf16 v[104:107], v[170:173], v[196:199], v[104:107]
	v_mfma_f32_16x16x32_bf16 v[100:103], v[180:183], v[196:199], v[100:103]
	v_mfma_f32_16x16x32_bf16 v[88:91], v[170:173], v[204:207], v[88:91]
	v_mfma_f32_16x16x32_bf16 v[84:87], v[180:183], v[204:207], v[84:87]
	v_mfma_f32_16x16x32_bf16 v[72:75], v[170:173], v[212:215], v[72:75]
	v_mfma_f32_16x16x32_bf16 v[68:71], v[180:183], v[212:215], v[68:71]
	v_mfma_f32_16x16x32_bf16 v[120:123], v[176:179], v[192:195], v[120:123]
	v_mfma_f32_16x16x32_bf16 v[116:119], v[184:187], v[192:195], v[116:119]
	v_mfma_f32_16x16x32_bf16 v[104:107], v[176:179], v[200:203], v[104:107]
	v_mfma_f32_16x16x32_bf16 v[100:103], v[184:187], v[200:203], v[100:103]
	v_mfma_f32_16x16x32_bf16 v[88:91], v[176:179], v[208:211], v[88:91]
	v_mfma_f32_16x16x32_bf16 v[84:87], v[184:187], v[208:211], v[84:87]
	v_mfma_f32_16x16x32_bf16 v[72:75], v[176:179], v[216:219], v[72:75]
	v_mfma_f32_16x16x32_bf16 v[68:71], v[184:187], v[216:219], v[68:71]
	s_setprio 0
	s_barrier
; template <class Epi, class Sched, bool ALIGN_EPI = false, bool SP2 = false>
; __device__ __forceinline__ void gemm_phase(PG8_LAS unsigned char* lds, const Gemm g, const Sched& S, const Epi& E, int wave_s) {
;     ...
;         for (int t = peeled ? 2 : 0; t < nt; t += 2) {
	s_add_u32 s42, s40, 0x80
	s_addc_u32 s43, s41, 0
	s_add_i32 s92, s92, s58
	ds_read_b128 v[188:191], v149 offset:49152
	ds_read_b128 v[192:195], v149 offset:50176
	ds_read_b128 v[196:199], v149 offset:51200
	ds_read_b128 v[200:203], v149 offset:52224
	ds_read_b128 v[204:207], v149 offset:53248
	ds_read_b128 v[208:211], v149 offset:54272
	ds_read_b128 v[212:215], v149 offset:55296
	ds_read_b128 v[216:219], v149 offset:56320
	s_mov_b32 m0, s92
	s_nop 0
	global_load_lds_dwordx4 v134, s[42:43]
	s_mov_b64 s[98:99], s[42:43]
	s_add_i32 s42, s92, 0x2000
	s_add_u32 s40, s40, 0x40080
	s_mov_b32 m0, s42
	s_addc_u32 s41, s41, 0
	s_add_i32 s43, s52, s58
	global_load_lds_dwordx4 v138, s[98:99]
	s_mov_b32 m0, s43
	s_add_i32 s89, s43, 0x2000
	global_load_lds_dwordx4 v134, s[40:41]
	s_mov_b32 m0, s89
	s_nop 0
	global_load_lds_dwordx4 v138, s[40:41]
	s_mov_b32 m0, s63
	s_nop 0
	global_load_lds_dwordx4 v132, s[38:39]
	s_mov_b32 m0, s72
	s_nop 0
	global_load_lds_dwordx4 v136, s[38:39]
	s_waitcnt vmcnt(8)
	s_waitcnt lgkmcnt(0)
	s_barrier
	s_setprio 1
	s_waitcnt lgkmcnt(0)
	v_mfma_f32_16x16x32_bf16 v[64:67], v[154:157], v[188:191], v[64:67]
	v_mfma_f32_16x16x32_bf16 v[60:63], v[162:165], v[188:191], v[60:63]
	v_mfma_f32_16x16x32_bf16 v[48:51], v[154:157], v[196:199], v[48:51]
	v_mfma_f32_16x16x32_bf16 v[44:47], v[162:165], v[196:199], v[44:47]
	v_mfma_f32_16x16x32_bf16 v[32:35], v[154:157], v[204:207], v[32:35]
	v_mfma_f32_16x16x32_bf16 v[28:31], v[162:165], v[204:207], v[28:31]
	v_mfma_f32_16x16x32_bf16 v[16:19], v[154:157], v[212:215], v[16:19]
	v_mfma_f32_16x16x32_bf16 v[12:15], v[162:165], v[212:215], v[12:15]
	v_mfma_f32_16x16x32_bf16 v[64:67], v[158:161], v[192:195], v[64:67]
	v_mfma_f32_16x16x32_bf16 v[60:63], v[166:169], v[192:195], v[60:63]
	v_mfma_f32_16x16x32_bf16 v[48:51], v[158:161], v[200:203], v[48:51]
	v_mfma_f32_16x16x32_bf16 v[44:47], v[166:169], v[200:203], v[44:47]
	v_mfma_f32_16x16x32_bf16 v[32:35], v[158:161], v[208:211], v[32:35]
	v_mfma_f32_16x16x32_bf16 v[28:31], v[166:169], v[208:211], v[28:31]
	v_mfma_f32_16x16x32_bf16 v[16:19], v[158:161], v[216:219], v[16:19]
	v_mfma_f32_16x16x32_bf16 v[12:15], v[166:169], v[216:219], v[12:15]
	s_setprio 0
	s_setprio 1
	v_mfma_f32_16x16x32_bf16 v[56:59], v[170:173], v[188:191], v[56:59]
	v_mfma_f32_16x16x32_bf16 v[52:55], v[180:183], v[188:191], v[52:55]
	v_mfma_f32_16x16x32_bf16 v[40:43], v[170:173], v[196:199], v[40:43]
	v_mfma_f32_16x16x32_bf16 v[36:39], v[180:183], v[196:199], v[36:39]
	v_mfma_f32_16x16x32_bf16 v[24:27], v[170:173], v[204:207], v[24:27]
	v_mfma_f32_16x16x32_bf16 v[20:23], v[180:183], v[204:207], v[20:23]
	v_mfma_f32_16x16x32_bf16 v[6:9], v[170:173], v[212:215], v[8:11]
	v_mfma_f32_16x16x32_bf16 v[2:5], v[180:183], v[212:215], v[2:5]
	v_mfma_f32_16x16x32_bf16 v[56:59], v[176:179], v[192:195], v[56:59]
	v_mfma_f32_16x16x32_bf16 v[52:55], v[184:187], v[192:195], v[52:55]
	v_mfma_f32_16x16x32_bf16 v[40:43], v[176:179], v[200:203], v[40:43]
	v_mfma_f32_16x16x32_bf16 v[36:39], v[184:187], v[200:203], v[36:39]
	v_mfma_f32_16x16x32_bf16 v[24:27], v[176:179], v[208:211], v[24:27]
	v_mfma_f32_16x16x32_bf16 v[20:23], v[184:187], v[208:211], v[20:23]
	v_mfma_f32_16x16x32_bf16 v[8:11], v[176:179], v[216:219], v[6:9]
	v_mfma_f32_16x16x32_bf16 v[4:7], v[184:187], v[216:219], v[2:5]
	s_setprio 0
	s_barrier
	s_add_i32 s96, s96, 2
	s_add_u32 s97, s97, 0x100
	s_addc_u32 vcc_lo, vcc_lo, 0
	s_cmp_gt_u32 s96, 13
	s_mov_b64 s[52:53], s[8:9]
	s_cbranch_scc0 .LBB0_419
	s_and_b64 vcc, exec, s[16:17]
	s_cbranch_vccz .LBB0_422
	s_barrier

; __device__ __forceinline__ int lane_id_() { int l; asm volatile("v_mbcnt_lo_u32_b32 %0, -1, 0\n\tv_mbcnt_hi_u32_b32 %0, -1, %0" : "=v"(l)); return l; }
; #define PG8_LAS __attribute__((address_space(3)))
; #define PG8_STAGE(bufoff, gbase, voff) do { const char* gb_ = (const char*)(gbase); asm volatile("" : "+s"(gb_));   \
;         _Pragma("unroll") for (int _i = 0; _i < 2; ++_i) \
;         __builtin_amdgcn_global_load_lds((const unsigned*)(gb_ + (voff)[_i]), (PG8_LAS unsigned*)(lds + (bufoff) + ldsw + _i * 8192), 16, 0, 0); } while (0)
; #define PG8_WAIT_V(n) asm volatile("s_waitcnt vmcnt(" #n ")" ::: "memory")
; #define PG8_BAR __builtin_amdgcn_s_barrier()
;     __device__ __forceinline__ void operator()(const f32x4 (&acc)[2][2][4][2], const Unit& u, int wr, int wc, int fr, int fq, PG8_LAS unsigned char* lds, int wid) const {
;     ...
;                     if (fq == 0) *(PG8_LAS float*)(lds + PRE_SLOT + 4096 + ((wr * 64 + fr + ai * HALF + m * 16) * 4 + wc) * 4) = s; }
;             }
;         if (!LAST) {
;             asm volatile("s_waitcnt lgkmcnt(0)" ::: "memory"); __builtin_amdgcn_s_barrier(); asm volatile("" ::: "memory");
;             if (wid < 4) { const int r = wid * 64 + lane_id_();
;                 const f32x4 p = *(const PG8_LAS f32x4*)(lds + PRE_SLOT + 4096 + r * 16);
;                 __hip_atomic_fetch_add(ssq + u.pm * BM + r, (p[0] + p[1]) + (p[2] + p[3]), __ATOMIC_RELAXED, __HIP_MEMORY_SCOPE_AGENT); }
; template <class Epi, class Sched, bool ALIGN_EPI = false, bool SP2 = false>
; __device__ __forceinline__ void gemm_phase(PG8_LAS unsigned char* lds, const Gemm g, const Sched& S, const Epi& E, int wave_s) {
;     ...
;         PG8_STAGE(PG8_SB(0, 0), cB, voffB); PG8_STAGE(PG8_SB(0, 1), cB + hstep, voffB); PG8_STAGE(PG8_SA(0, 0), cA, voffA); PG8_STAGE(PG8_SA(0, 1), cA + hstep, voffA);
;         if (wr == 1) PG8_BAR;
;         PG8_WAIT_V(2); PG8_BAR;
;         PG8_STAGE(PG8_SB(1, 0), cB + kstep, voffB); PG8_STAGE(PG8_SA(1, 0), cA + kstep, voffA); PG8_STAGE(PG8_SB(1, 1), cB + hstep + kstep, voffB);
;         PG8_WAIT_V(6); PG8_BAR;
.LBB0_812:
	s_and_b32 s9, s8, 3
	s_lshl_b32 s7, s6, 13
	s_lshl_b32 s18, s9, 12
	s_add_u32 s16, s42, 0x80
	s_addc_u32 s17, s43, 0
	s_waitcnt vmcnt(2)
	s_barrier
	s_add_i32 m0, s87, 0x18000
	s_nop 0
	global_load_lds_dwordx4 v130, s[16:17]
	s_add_i32 m0, s87, 0x1a000
	s_nop 0
	global_load_lds_dwordx4 v134, s[16:17]
	s_add_u32 s16, s40, 0x80
	s_addc_u32 s17, s41, 0
	s_add_i32 s92, s87, 0x8000
	s_mov_b32 m0, s92
	s_add_i32 s93, s87, 0xa000
	global_load_lds_dwordx4 v128, s[16:17]
	s_mov_b64 s[98:99], s[16:17]
	s_add_u32 s16, s42, 0x40080
	s_mov_b32 m0, s93
	s_addc_u32 s17, s43, 0
	global_load_lds_dwordx4 v132, s[98:99]
	s_add_i32 m0, s87, 0x1c000
	s_nop 0
	global_load_lds_dwordx4 v130, s[16:17]
	s_add_i32 m0, s87, 0x1e000
	v_and_b32_e32 v1, 15, v0
	global_load_lds_dwordx4 v134, s[16:17]
	v_bfe_u32 v2, v0, 4, 2
	v_lshlrev_b32_e32 v4, 4, v2
	v_lshlrev_b32_e32 v0, 2, v0
	s_waitcnt vmcnt(0)
	v_lshl_or_b32 v144, s6, 6, v1
	v_lshl_or_b32 v1, v1, 6, v4
	v_and_b32_e32 v0, 32, v0
	s_cmpk_lt_u32 s94, 0x100
	v_bitop3_b32 v4, v1, s7, v0 bitop3:0xde
	v_bitop3_b32 v145, v1, s18, v0 bitop3:0xde
	s_cselect_b64 s[16:17], -1, 0
	v_lshlrev_b32_e32 v0, 4, v144
	s_add_i32 s18, 0, 0x22400
	v_add_u32_e32 v1, s18, v0
	s_add_i32 s18, 0, 0x22500
	v_lshlrev_b32_e32 v3, 3, v2
	v_cmp_eq_u32_e64 s[6:7], 0, v2
	v_add_u32_e32 v2, s18, v0
	s_add_i32 s18, 0, 0x22600
	v_lshl_or_b32 v146, s9, 5, v3
	v_add_u32_e32 v3, s18, v0
	s_add_i32 s18, 0, 0x22700
	v_add_u32_e32 v5, s18, v0
	s_add_i32 s18, 0, 0x22c00
	v_add_u32_e32 v6, s18, v0
	s_add_i32 s18, 0, 0x22d00
	v_add_u32_e32 v7, s18, v0
	s_add_i32 s18, 0, 0x22e00
	s_lshl_b32 s9, s9, 2
	v_add_u32_e32 v8, s18, v0
	s_add_i32 s18, 0, 0x22f00
	s_waitcnt vmcnt(6)
	s_cmp_lt_i32 s8, 4
	v_add_u32_e32 v0, s18, v0
	s_cselect_b64 s[18:19], -1, 0
	s_add_i32 s97, 0, 0x10000
	s_add_i32 s82, 0, 0x14000
	s_andn2_b32 s94, s94, 63
	s_mov_b32 s95, s46
	s_ashr_i32 s96, s33, 31
	v_mov_b64_e32 v[136:137], 0x100
	v_mov_b64_e32 v[138:139], 0xff
	v_add_u32_e32 v147, s97, v145
	v_add_u32_e32 v148, s82, v145
	v_add_u32_e32 v149, 0, v4
	v_mbcnt_hi_u32_b32 v150, -1, v254
	v_add_u32_e32 v151, s9, v1
	v_add_u32_e32 v152, s9, v2
	v_add_u32_e32 v153, s9, v3
	v_add_u32_e32 v154, s9, v5
	v_add_u32_e32 v155, s9, v6
	s_mov_b64 s[20:21], 0x48000
	v_add_u32_e32 v156, s9, v7
	s_mov_b64 s[22:23], 0x50000
	v_add_u32_e32 v157, s9, v8
	s_mov_b64 s[24:25], 0x58000
	v_add_u32_e32 v158, s9, v0
	s_barrier
	s_branch .LBB0_815

; template <class Epi, class Sched, bool ALIGN_EPI = false, bool SP2 = false>
; __device__ __forceinline__ void gemm_phase(PG8_LAS unsigned char* lds, const Gemm g, const Sched& S, const Epi& E, int wave_s) {
;     ...
;         const bool has_next = S.next(ui + 1, nxt);
;         const char* nA = has_next ? (const char*)g.A + (size_t)nxt.pm * tstep : cA; const char* nB = has_next ? (const char*)g.Bt + (size_t)nxt.pn * tstep : cB;
;         for (int t = peeled ? 2 : 0; t < nt; t += 2) {
;             const bool last = (t == nt - 2);
;             const char* a1 = cA + (size_t)(t + 1) * kstep;
;             const char* a2 = last ? nA : cA + (size_t)(t + 2) * kstep; const char* b2 = last ? nB : cB + (size_t)(t + 2) * kstep;
;             const char* a3 = a2 + kstep; const char* b3 = b2 + kstep;
;             if (last && has_next) S.a_ready(nxt);
.LBB0_822:
	ds_read_b128 v[140:143], v147
	ds_read_b128 v[160:163], v147 offset:1024
	ds_read_b128 v[164:167], v147 offset:2048
	ds_read_b128 v[168:171], v147 offset:3072
	ds_read_b128 v[176:179], v148
	ds_read_b128 v[180:183], v148 offset:1024
	ds_read_b128 v[184:187], v148 offset:2048
	ds_read_b128 v[188:191], v148 offset:3072
	s_add_u32 s42, s40, 0x100
	s_addc_u32 s43, s41, 0
	s_cmp_eq_u32 vcc_lo, 12
	s_cselect_b32 s76, s37, s42
	s_cselect_b32 s77, s29, s43
	s_cselect_b32 s74, s39, s60
	s_cselect_b32 s75, s27, s61
	s_add_u32 s72, s76, 0x80
	s_addc_u32 s73, s77, 0
	s_add_u32 s40, s40, 0x40080
	s_addc_u32 s41, s41, 0
	ds_read_b128 v[192:195], v149
	ds_read_b128 v[196:199], v149 offset:1024
	ds_read_b128 v[200:203], v149 offset:2048
	ds_read_b128 v[204:207], v149 offset:3072
	ds_read_b128 v[208:211], v149 offset:4096
	ds_read_b128 v[212:215], v149 offset:5120
	ds_read_b128 v[216:219], v149 offset:6144
	ds_read_b128 v[220:223], v149 offset:7168
	s_add_i32 m0, s87, 0xc000
	s_nop 0
	global_load_lds_dwordx4 v128, s[40:41]
	s_add_i32 m0, s87, 0xe000
	s_nop 0
	global_load_lds_dwordx4 v132, s[40:41]
	s_waitcnt vmcnt(8)
	s_waitcnt lgkmcnt(0)
	s_barrier
	s_setprio 1
	s_waitcnt lgkmcnt(0)
	v_mfma_f32_16x16x32_bf16 v[124:127], v[140:143], v[192:195], v[124:127]
	v_mfma_f32_16x16x32_bf16 v[120:123], v[164:167], v[192:195], v[120:123]
	v_mfma_f32_16x16x32_bf16 v[108:111], v[140:143], v[200:203], v[108:111]
	v_mfma_f32_16x16x32_bf16 v[104:107], v[164:167], v[200:203], v[104:107]
	v_mfma_f32_16x16x32_bf16 v[92:95], v[140:143], v[208:211], v[92:95]
	v_mfma_f32_16x16x32_bf16 v[88:91], v[164:167], v[208:211], v[88:91]
	v_mfma_f32_16x16x32_bf16 v[76:79], v[140:143], v[216:219], v[76:79]
	v_mfma_f32_16x16x32_bf16 v[72:75], v[164:167], v[216:219], v[72:75]
	v_mfma_f32_16x16x32_bf16 v[124:127], v[160:163], v[196:199], v[124:127]
	v_mfma_f32_16x16x32_bf16 v[120:123], v[168:171], v[196:199], v[120:123]
	v_mfma_f32_16x16x32_bf16 v[108:111], v[160:163], v[204:207], v[108:111]
	v_mfma_f32_16x16x32_bf16 v[104:107], v[168:171], v[204:207], v[104:107]
	v_mfma_f32_16x16x32_bf16 v[92:95], v[160:163], v[212:215], v[92:95]
	v_mfma_f32_16x16x32_bf16 v[88:91], v[168:171], v[212:215], v[88:91]
	v_mfma_f32_16x16x32_bf16 v[76:79], v[160:163], v[220:223], v[76:79]
	v_mfma_f32_16x16x32_bf16 v[72:75], v[168:171], v[220:223], v[72:75]
	s_setprio 0
	s_setprio 1
	v_mfma_f32_16x16x32_bf16 v[116:119], v[176:179], v[192:195], v[116:119]
	v_mfma_f32_16x16x32_bf16 v[112:115], v[184:187], v[192:195], v[112:115]
	v_mfma_f32_16x16x32_bf16 v[100:103], v[176:179], v[200:203], v[100:103]
	v_mfma_f32_16x16x32_bf16 v[96:99], v[184:187], v[200:203], v[96:99]
	v_mfma_f32_16x16x32_bf16 v[84:87], v[176:179], v[208:211], v[84:87]
	v_mfma_f32_16x16x32_bf16 v[80:83], v[184:187], v[208:211], v[80:83]
	v_mfma_f32_16x16x32_bf16 v[68:71], v[176:179], v[216:219], v[68:71]
	v_mfma_f32_16x16x32_bf16 v[64:67], v[184:187], v[216:219], v[64:67]
	v_mfma_f32_16x16x32_bf16 v[116:119], v[180:183], v[196:199], v[116:119]
	v_mfma_f32_16x16x32_bf16 v[112:115], v[188:191], v[196:199], v[112:115]
	v_mfma_f32_16x16x32_bf16 v[100:103], v[180:183], v[204:207], v[100:103]
	v_mfma_f32_16x16x32_bf16 v[96:99], v[188:191], v[204:207], v[96:99]
	v_mfma_f32_16x16x32_bf16 v[84:87], v[180:183], v[212:215], v[84:87]
	v_mfma_f32_16x16x32_bf16 v[80:83], v[188:191], v[212:215], v[80:83]
	v_mfma_f32_16x16x32_bf16 v[68:71], v[180:183], v[220:223], v[68:71]
	v_mfma_f32_16x16x32_bf16 v[64:67], v[188:191], v[220:223], v[64:67]
	s_setprio 0
	s_barrier
	s_mov_b64 s[40:41], s[74:75]
	s_add_i32 vcc_hi, s97, s79
	ds_read_b128 v[192:195], v149 offset:16384
	ds_read_b128 v[196:199], v149 offset:17408
	ds_read_b128 v[200:203], v149 offset:18432
	ds_read_b128 v[204:207], v149 offset:19456
	ds_read_b128 v[208:211], v149 offset:20480
	ds_read_b128 v[212:215], v149 offset:21504
	ds_read_b128 v[216:219], v149 offset:22528
	ds_read_b128 v[220:223], v149 offset:23552
	s_mov_b32 m0, vcc_hi
	s_nop 0
	global_load_lds_dwordx4 v130, s[40:41]
	s_add_i32 m0, vcc_hi, 0x2000
	s_nop 0
	global_load_lds_dwordx4 v134, s[40:41]
	s_add_u32 s40, s74, 0x40000
	s_addc_u32 s41, s75, 0
	s_add_i32 vcc_hi, s82, s79
	s_mov_b32 m0, vcc_hi
	s_nop 0
	global_load_lds_dwordx4 v130, s[40:41]
	s_mov_b64 s[98:99], s[40:41]
	s_add_i32 m0, vcc_hi, 0x2000
	s_mov_b64 s[40:41], s[76:77]
	global_load_lds_dwordx4 v134, s[98:99]
	s_mov_b32 m0, s87
	s_nop 0
	global_load_lds_dwordx4 v128, s[40:41]
	s_mov_b32 m0, s88
	s_nop 0
	global_load_lds_dwordx4 v132, s[40:41]
	s_waitcnt vmcnt(8)
	s_waitcnt lgkmcnt(0)
	s_barrier
	s_setprio 1
	s_waitcnt lgkmcnt(0)
	v_mfma_f32_16x16x32_bf16 v[60:63], v[140:143], v[192:195], v[60:63]
	v_mfma_f32_16x16x32_bf16 v[56:59], v[164:167], v[192:195], v[56:59]
	v_mfma_f32_16x16x32_bf16 v[44:47], v[140:143], v[200:203], v[44:47]
	v_mfma_f32_16x16x32_bf16 v[40:43], v[164:167], v[200:203], v[40:43]
	v_mfma_f32_16x16x32_bf16 v[28:31], v[140:143], v[208:211], v[28:31]
	v_mfma_f32_16x16x32_bf16 v[24:27], v[164:167], v[208:211], v[24:27]
	v_mfma_f32_16x16x32_bf16 v[12:15], v[140:143], v[216:219], v[12:15]
	v_mfma_f32_16x16x32_bf16 v[8:11], v[164:167], v[216:219], v[8:11]
	v_mfma_f32_16x16x32_bf16 v[60:63], v[160:163], v[196:199], v[60:63]
	v_mfma_f32_16x16x32_bf16 v[56:59], v[168:171], v[196:199], v[56:59]
	v_mfma_f32_16x16x32_bf16 v[44:47], v[160:163], v[204:207], v[44:47]
	v_mfma_f32_16x16x32_bf16 v[40:43], v[168:171], v[204:207], v[40:43]
	v_mfma_f32_16x16x32_bf16 v[28:31], v[160:163], v[212:215], v[28:31]
	v_mfma_f32_16x16x32_bf16 v[24:27], v[168:171], v[212:215], v[24:27]
	v_mfma_f32_16x16x32_bf16 v[12:15], v[160:163], v[220:223], v[12:15]
	v_mfma_f32_16x16x32_bf16 v[8:11], v[168:171], v[220:223], v[8:11]
	s_setprio 0
	s_setprio 1
	v_mfma_f32_16x16x32_bf16 v[52:55], v[176:179], v[192:195], v[52:55]
	v_mfma_f32_16x16x32_bf16 v[48:51], v[184:187], v[192:195], v[48:51]
	v_mfma_f32_16x16x32_bf16 v[36:39], v[176:179], v[200:203], v[36:39]
	v_mfma_f32_16x16x32_bf16 v[32:35], v[184:187], v[200:203], v[32:35]
	v_mfma_f32_16x16x32_bf16 v[20:23], v[176:179], v[208:211], v[20:23]
	v_mfma_f32_16x16x32_bf16 v[16:19], v[184:187], v[208:211], v[16:19]
	v_mfma_f32_16x16x32_bf16 v[4:7], v[176:179], v[216:219], v[4:7]
	v_mfma_f32_16x16x32_bf16 v[0:3], v[184:187], v[216:219], v[0:3]
	v_mfma_f32_16x16x32_bf16 v[52:55], v[180:183], v[196:199], v[52:55]
	v_mfma_f32_16x16x32_bf16 v[48:51], v[188:191], v[196:199], v[48:51]
	v_mfma_f32_16x16x32_bf16 v[36:39], v[180:183], v[204:207], v[36:39]
	v_mfma_f32_16x16x32_bf16 v[32:35], v[188:191], v[204:207], v[32:35]
	v_mfma_f32_16x16x32_bf16 v[20:23], v[180:183], v[212:215], v[20:23]
	v_mfma_f32_16x16x32_bf16 v[16:19], v[188:191], v[212:215], v[16:19]
	v_mfma_f32_16x16x32_bf16 v[4:7], v[180:183], v[220:223], v[4:7]
	v_mfma_f32_16x16x32_bf16 v[0:3], v[188:191], v[220:223], v[0:3]
	s_setprio 0
	s_barrier
	s_add_i32 vcc_hi, 0, 0x18000
	v_add_u32_e32 v159, vcc_hi, v145
	s_add_i32 s86, 0, 0x1c000
	ds_read_b128 v[140:143], v159
	ds_read_b128 v[160:163], v159 offset:1024
	ds_read_b128 v[164:167], v159 offset:2048
	ds_read_b128 v[168:171], v159 offset:3072
	v_add_u32_e32 v159, s86, v145
	ds_read_b128 v[176:179], v159
	ds_read_b128 v[180:183], v159 offset:1024
	ds_read_b128 v[184:187], v159 offset:2048
	ds_read_b128 v[188:191], v159 offset:3072
	s_add_u32 s40, s76, 0x40000
	s_addc_u32 s41, s77, 0
	s_mov_b32 m0, s89
	ds_read_b128 v[192:195], v149 offset:32768
	ds_read_b128 v[196:199], v149 offset:33792
	ds_read_b128 v[200:203], v149 offset:34816
	ds_read_b128 v[204:207], v149 offset:35840
	ds_read_b128 v[208:211], v149 offset:36864
	ds_read_b128 v[212:215], v149 offset:37888
	ds_read_b128 v[216:219], v149 offset:38912
	ds_read_b128 v[220:223], v149 offset:39936
	s_nop 0
	global_load_lds_dwordx4 v128, s[40:41]
	s_mov_b32 m0, s90
	s_nop 0
	global_load_lds_dwordx4 v132, s[40:41]
	s_waitcnt vmcnt(8)
	s_waitcnt lgkmcnt(0)
	s_barrier
	s_setprio 1
	s_waitcnt lgkmcnt(0)
	v_mfma_f32_16x16x32_bf16 v[124:127], v[140:143], v[192:195], v[124:127]
	v_mfma_f32_16x16x32_bf16 v[120:123], v[164:167], v[192:195], v[120:123]
	v_mfma_f32_16x16x32_bf16 v[108:111], v[140:143], v[200:203], v[108:111]
	v_mfma_f32_16x16x32_bf16 v[104:107], v[164:167], v[200:203], v[104:107]
	v_mfma_f32_16x16x32_bf16 v[92:95], v[140:143], v[208:211], v[92:95]
	v_mfma_f32_16x16x32_bf16 v[88:91], v[164:167], v[208:211], v[88:91]
	v_mfma_f32_16x16x32_bf16 v[76:79], v[140:143], v[216:219], v[76:79]
	v_mfma_f32_16x16x32_bf16 v[72:75], v[164:167], v[216:219], v[72:75]
	v_mfma_f32_16x16x32_bf16 v[124:127], v[160:163], v[196:199], v[124:127]
	v_mfma_f32_16x16x32_bf16 v[120:123], v[168:171], v[196:199], v[120:123]
	v_mfma_f32_16x16x32_bf16 v[108:111], v[160:163], v[204:207], v[108:111]
	v_mfma_f32_16x16x32_bf16 v[104:107], v[168:171], v[204:207], v[104:107]
	v_mfma_f32_16x16x32_bf16 v[92:95], v[160:163], v[212:215], v[92:95]
	v_mfma_f32_16x16x32_bf16 v[88:91], v[168:171], v[212:215], v[88:91]
	v_mfma_f32_16x16x32_bf16 v[76:79], v[160:163], v[220:223], v[76:79]
	v_mfma_f32_16x16x32_bf16 v[72:75], v[168:171], v[220:223], v[72:75]
	s_setprio 0
	s_setprio 1
	v_mfma_f32_16x16x32_bf16 v[116:119], v[176:179], v[192:195], v[116:119]
	v_mfma_f32_16x16x32_bf16 v[112:115], v[184:187], v[192:195], v[112:115]
	v_mfma_f32_16x16x32_bf16 v[100:103], v[176:179], v[200:203], v[100:103]
	v_mfma_f32_16x16x32_bf16 v[96:99], v[184:187], v[200:203], v[96:99]
	v_mfma_f32_16x16x32_bf16 v[84:87], v[176:179], v[208:211], v[84:87]
	v_mfma_f32_16x16x32_bf16 v[80:83], v[184:187], v[208:211], v[80:83]
	v_mfma_f32_16x16x32_bf16 v[68:71], v[176:179], v[216:219], v[68:71]
	v_mfma_f32_16x16x32_bf16 v[64:67], v[184:187], v[216:219], v[64:67]
	v_mfma_f32_16x16x32_bf16 v[116:119], v[180:183], v[196:199], v[116:119]
	v_mfma_f32_16x16x32_bf16 v[112:115], v[188:191], v[196:199], v[112:115]
	v_mfma_f32_16x16x32_bf16 v[100:103], v[180:183], v[204:207], v[100:103]
	v_mfma_f32_16x16x32_bf16 v[96:99], v[188:191], v[204:207], v[96:99]
	v_mfma_f32_16x16x32_bf16 v[84:87], v[180:183], v[212:215], v[84:87]
	v_mfma_f32_16x16x32_bf16 v[80:83], v[188:191], v[212:215], v[80:83]
	v_mfma_f32_16x16x32_bf16 v[68:71], v[180:183], v[220:223], v[68:71]
	v_mfma_f32_16x16x32_bf16 v[64:67], v[188:191], v[220:223], v[64:67]
	s_setprio 0
	s_barrier
; template <class Epi, class Sched, bool ALIGN_EPI = false, bool SP2 = false>
; __device__ __forceinline__ void gemm_phase(PG8_LAS unsigned char* lds, const Gemm g, const Sched& S, const Epi& E, int wave_s) {
;     ...
;         for (int t = peeled ? 2 : 0; t < nt; t += 2) {
	s_add_u32 s40, s74, 0x80
	s_addc_u32 s41, s75, 0
	s_add_i32 s76, vcc_hi, s79
	ds_read_b128 v[192:195], v149 offset:49152
	ds_read_b128 v[196:199], v149 offset:50176
	ds_read_b128 v[200:203], v149 offset:51200
	ds_read_b128 v[204:207], v149 offset:52224
	ds_read_b128 v[208:211], v149 offset:53248
	ds_read_b128 v[212:215], v149 offset:54272
	ds_read_b128 v[216:219], v149 offset:55296
	ds_read_b128 v[220:223], v149 offset:56320
	s_mov_b32 m0, s76
	s_nop 0
	global_load_lds_dwordx4 v130, s[40:41]
	s_add_i32 m0, s76, 0x2000
	s_nop 0
	global_load_lds_dwordx4 v134, s[40:41]
	s_add_u32 s40, s74, 0x40080
	s_addc_u32 s41, s75, 0
	s_add_i32 s74, s86, s79
	s_mov_b32 m0, s74
	s_nop 0
	global_load_lds_dwordx4 v130, s[40:41]
	s_add_i32 m0, s74, 0x2000
	s_nop 0
	global_load_lds_dwordx4 v134, s[40:41]
	s_mov_b32 m0, s92
	s_nop 0
	global_load_lds_dwordx4 v128, s[72:73]
	s_mov_b32 m0, s93
	s_nop 0
	global_load_lds_dwordx4 v132, s[72:73]
	s_waitcnt vmcnt(8)
	s_waitcnt lgkmcnt(0)
	s_barrier
	s_setprio 1
	s_waitcnt lgkmcnt(0)
	v_mfma_f32_16x16x32_bf16 v[60:63], v[140:143], v[192:195], v[60:63]
	v_mfma_f32_16x16x32_bf16 v[56:59], v[164:167], v[192:195], v[56:59]
	v_mfma_f32_16x16x32_bf16 v[44:47], v[140:143], v[200:203], v[44:47]
	v_mfma_f32_16x16x32_bf16 v[40:43], v[164:167], v[200:203], v[40:43]
	v_mfma_f32_16x16x32_bf16 v[28:31], v[140:143], v[208:211], v[28:31]
	v_mfma_f32_16x16x32_bf16 v[24:27], v[164:167], v[208:211], v[24:27]
	v_mfma_f32_16x16x32_bf16 v[12:15], v[140:143], v[216:219], v[12:15]
	v_mfma_f32_16x16x32_bf16 v[8:11], v[164:167], v[216:219], v[8:11]
	v_mfma_f32_16x16x32_bf16 v[60:63], v[160:163], v[196:199], v[60:63]
	v_mfma_f32_16x16x32_bf16 v[56:59], v[168:171], v[196:199], v[56:59]
	v_mfma_f32_16x16x32_bf16 v[44:47], v[160:163], v[204:207], v[44:47]
	v_mfma_f32_16x16x32_bf16 v[40:43], v[168:171], v[204:207], v[40:43]
	v_mfma_f32_16x16x32_bf16 v[28:31], v[160:163], v[212:215], v[28:31]
	v_mfma_f32_16x16x32_bf16 v[24:27], v[168:171], v[212:215], v[24:27]
	v_mfma_f32_16x16x32_bf16 v[12:15], v[160:163], v[220:223], v[12:15]
	v_mfma_f32_16x16x32_bf16 v[8:11], v[168:171], v[220:223], v[8:11]
	s_setprio 0
	s_setprio 1
	v_mfma_f32_16x16x32_bf16 v[52:55], v[176:179], v[192:195], v[52:55]
	v_mfma_f32_16x16x32_bf16 v[48:51], v[184:187], v[192:195], v[48:51]
	v_mfma_f32_16x16x32_bf16 v[36:39], v[176:179], v[200:203], v[36:39]
	v_mfma_f32_16x16x32_bf16 v[32:35], v[184:187], v[200:203], v[32:35]
	v_mfma_f32_16x16x32_bf16 v[20:23], v[176:179], v[208:211], v[20:23]
	v_mfma_f32_16x16x32_bf16 v[16:19], v[184:187], v[208:211], v[16:19]
	v_mfma_f32_16x16x32_bf16 v[4:7], v[176:179], v[216:219], v[4:7]
	v_mfma_f32_16x16x32_bf16 v[0:3], v[184:187], v[216:219], v[0:3]
	v_mfma_f32_16x16x32_bf16 v[52:55], v[180:183], v[196:199], v[52:55]
	v_mfma_f32_16x16x32_bf16 v[48:51], v[188:191], v[196:199], v[48:51]
	v_mfma_f32_16x16x32_bf16 v[36:39], v[180:183], v[204:207], v[36:39]
	v_mfma_f32_16x16x32_bf16 v[32:35], v[188:191], v[204:207], v[32:35]
	v_mfma_f32_16x16x32_bf16 v[20:23], v[180:183], v[212:215], v[20:23]
	v_mfma_f32_16x16x32_bf16 v[16:19], v[188:191], v[212:215], v[16:19]
	v_mfma_f32_16x16x32_bf16 v[4:7], v[180:183], v[220:223], v[4:7]
	v_mfma_f32_16x16x32_bf16 v[0:3], v[188:191], v[220:223], v[0:3]
	s_setprio 0
	s_barrier
	s_add_i32 vcc_lo, vcc_lo, 2
	s_add_u32 s60, s60, 0x100
	s_addc_u32 s61, s61, 0
	s_cmp_gt_u32 vcc_lo, 13
	s_mov_b64 s[40:41], s[42:43]
	s_cbranch_scc0 .LBB0_822
	s_and_b64 vcc, exec, s[16:17]
	s_cbranch_vccz .LBB0_825
	s_barrier

; #define PG8_STAGE(bufoff, gbase, voff) do { const char* gb_ = (const char*)(gbase); asm volatile("" : "+s"(gb_));   \
;         _Pragma("unroll") for (int _i = 0; _i < 2; ++_i) \
;         __builtin_amdgcn_global_load_lds((const unsigned*)(gb_ + (voff)[_i]), (PG8_LAS unsigned*)(lds + (bufoff) + ldsw + _i * 8192), 16, 0, 0); } while (0)
; #define PG8_WAIT_V(n) asm volatile("s_waitcnt vmcnt(" #n ")" ::: "memory")
; #define PG8_WAIT_V8_RELAX() do { if constexpr (Epi::NSTORES + Epi::NPRE == 10) asm volatile("s_waitcnt vmcnt(18)" ::: "memory"); else if constexpr (Epi::NSTORES + Epi::NPRE == 18) asm volatile("s_waitcnt vmcnt(26)" ::: "memory"); else asm volatile("s_waitcnt vmcnt(8)" ::: "memory"); } while (0)
; #define PG8_BAR __builtin_amdgcn_s_barrier()
; template <class Epi, class Sched, bool ALIGN_EPI = false, bool SP2 = false>
; __device__ __forceinline__ void gemm_phase(PG8_LAS unsigned char* lds, const Gemm g, const Sched& S, const Epi& E, int wave_s) {
;     ...
;         PG8_STAGE(PG8_SB(0, 0), cB, voffB); PG8_STAGE(PG8_SB(0, 1), cB + hstep, voffB); PG8_STAGE(PG8_SA(0, 0), cA, voffA); PG8_STAGE(PG8_SA(0, 1), cA + hstep, voffA);
;         if (wr == 1) PG8_BAR;
;         PG8_WAIT_V(2); PG8_BAR;
;         PG8_STAGE(PG8_SB(1, 0), cB + kstep, voffB); PG8_STAGE(PG8_SA(1, 0), cA + kstep, voffA); PG8_STAGE(PG8_SB(1, 1), cB + hstep + kstep, voffB);
;         PG8_WAIT_V(6); PG8_BAR;
;     ...
;         cur = nxt; cA = nA; cB = nB; ++ui;
;         if constexpr (ALIGN_EPI) { if (wr == 1) PG8_BAR; }
;         if constexpr (Epi::NPRE > 0) E.prefetch(lds, wid, cur, wr, fr, fq);
;         if constexpr (SP2 && Epi::NSTORES > 0 && !Epi::AFTER_DRAIN) {
;             const char* a1 = cA + kstep; const char* a2 = cA + 2 * kstep; const char* b2 = cB + 2 * kstep; const char* a3 = a2 + kstep; const char* b3 = b2 + kstep;
;             PG8_SP2_PAIR(PG8_WAIT_V8_RELAX);
.LBB0_906:
	s_lshl_b32 s7, s7, 5
	s_and_b32 s7, s7, 0x60
	s_lshl_b32 s9, s18, 13
	s_lshl_b32 s22, s7, 7
	s_add_u32 s18, s30, 0x80
	s_addc_u32 s19, s31, 0
	s_waitcnt vmcnt(2)
	s_barrier
	s_add_i32 m0, s72, 0x18000
	s_nop 0
	global_load_lds_dwordx4 v136, s[18:19]
	s_add_i32 m0, s72, 0x1a000
	s_nop 0
	global_load_lds_dwordx4 v132, s[18:19]
	s_add_u32 s18, s34, 0x80
	s_addc_u32 s19, s35, 0
	s_add_i32 s76, s72, 0x8000
	s_mov_b32 m0, s76
	s_add_i32 s77, s72, 0xa000
	global_load_lds_dwordx4 v138, s[18:19]
	s_mov_b64 s[98:99], s[18:19]
	s_add_u32 s18, s30, 0x40080
	s_mov_b32 m0, s77
	s_addc_u32 s19, s31, 0
	global_load_lds_dwordx4 v134, s[98:99]
	s_add_i32 m0, s72, 0x1c000
	s_nop 0
	global_load_lds_dwordx4 v136, s[18:19]
	s_add_i32 m0, s72, 0x1e000
	v_and_b32_e32 v0, 15, v2
	global_load_lds_dwordx4 v132, s[18:19]
	v_lshrrev_b32_e32 v2, 1, v2
	s_waitcnt vmcnt(0)
	v_or_b32_e32 v144, s8, v0
	v_and_b32_e32 v2, 24, v2
	v_lshlrev_b32_e32 v3, 6, v144
	v_lshlrev_b32_e32 v4, 1, v2
	s_movk_i32 s8, 0x3c0
	v_lshlrev_b32_e32 v5, 2, v144
	v_and_or_b32 v3, v3, s8, v4
	v_and_b32_e32 v5, 32, v5
	v_lshlrev_b32_e32 v145, 2, v0
	v_bitop3_b32 v5, v3, s9, v5 bitop3:0xde
	v_lshl_or_b32 v3, v0, 6, v4
	v_and_b32_e32 v0, 32, v145
	v_bitop3_b32 v146, v3, s22, v0 bitop3:0xde
	s_waitcnt vmcnt(6)
	s_cmpk_lt_u32 s6, 0x100
	v_or_b32_e32 v147, s7, v2
	v_mov_b32_e32 v2, v1
	v_mov_b32_e32 v3, v1
	s_cselect_b64 s[18:19], -1, 0
	s_add_u32 s63, s63, s20
	v_mov_b32_e32 v0, v1
	v_add_u32_e32 v149, 0, v5
	v_mov_b64_e32 v[10:11], v[2:3]
	v_mov_b64_e32 v[18:19], v[2:3]
	v_mov_b64_e32 v[26:27], v[2:3]
	v_mov_b64_e32 v[34:35], v[2:3]
	v_mov_b64_e32 v[42:43], v[2:3]
	v_mov_b64_e32 v[50:51], v[2:3]
	v_mov_b64_e32 v[58:59], v[2:3]
	v_mov_b64_e32 v[74:75], v[2:3]
	v_mov_b64_e32 v[6:7], v[2:3]
	v_mov_b64_e32 v[14:15], v[2:3]
	v_mov_b64_e32 v[22:23], v[2:3]
	v_mov_b64_e32 v[30:31], v[2:3]
	v_mov_b64_e32 v[38:39], v[2:3]
	v_mov_b64_e32 v[46:47], v[2:3]
	v_mov_b64_e32 v[54:55], v[2:3]
	v_mov_b64_e32 v[66:67], v[2:3]
	v_mov_b64_e32 v[70:71], v[2:3]
	v_mov_b64_e32 v[82:83], v[2:3]
	v_mov_b64_e32 v[90:91], v[2:3]
	v_mov_b64_e32 v[98:99], v[2:3]
	v_mov_b64_e32 v[106:107], v[2:3]
	v_mov_b64_e32 v[114:115], v[2:3]
	v_mov_b64_e32 v[122:123], v[2:3]
	v_mov_b64_e32 v[130:131], v[2:3]
	v_mov_b64_e32 v[62:63], v[2:3]
	v_mov_b64_e32 v[78:79], v[2:3]
	v_mov_b64_e32 v[86:87], v[2:3]
	v_mov_b64_e32 v[94:95], v[2:3]
	v_mov_b64_e32 v[102:103], v[2:3]
	v_mov_b64_e32 v[110:111], v[2:3]
	v_mov_b64_e32 v[118:119], v[2:3]
	v_mov_b64_e32 v[126:127], v[2:3]
	s_sext_i32_i16 s29, s10
	s_mov_b32 s79, s46
	s_addc_u32 s78, s78, s21
	v_mov_b64_e32 v[252:253], 0x580
	v_mov_b64_e32 v[174:175], 0x57f
	s_add_i32 s82, 0, 0x10000
	s_add_i32 s87, 0, 0x14000
	s_movk_i32 s88, 0x1600
	v_mov_b32_e32 v148, 0x358637bd
	v_mov_b64_e32 v[8:9], v[0:1]
	v_mov_b64_e32 v[16:17], v[0:1]
	v_mov_b64_e32 v[24:25], v[0:1]
	v_mov_b64_e32 v[32:33], v[0:1]
	v_mov_b64_e32 v[40:41], v[0:1]
	v_mov_b64_e32 v[48:49], v[0:1]
	v_mov_b64_e32 v[56:57], v[0:1]
	v_mov_b64_e32 v[72:73], v[0:1]
	v_mov_b64_e32 v[4:5], v[0:1]
	v_mov_b64_e32 v[12:13], v[0:1]
	v_mov_b64_e32 v[20:21], v[0:1]
	v_mov_b64_e32 v[28:29], v[0:1]
	v_mov_b64_e32 v[36:37], v[0:1]
	v_mov_b64_e32 v[44:45], v[0:1]
	v_mov_b64_e32 v[52:53], v[0:1]
	v_mov_b64_e32 v[64:65], v[0:1]
	v_mov_b64_e32 v[68:69], v[0:1]
	v_mov_b64_e32 v[80:81], v[0:1]
	v_mov_b64_e32 v[88:89], v[0:1]
	v_mov_b64_e32 v[96:97], v[0:1]
	v_mov_b64_e32 v[104:105], v[0:1]
	v_mov_b64_e32 v[112:113], v[0:1]
	v_mov_b64_e32 v[120:121], v[0:1]
	v_mov_b64_e32 v[128:129], v[0:1]
	v_mov_b64_e32 v[60:61], v[0:1]
	v_mov_b64_e32 v[76:77], v[0:1]
	v_mov_b64_e32 v[84:85], v[0:1]
	v_mov_b64_e32 v[92:93], v[0:1]
	v_mov_b64_e32 v[100:101], v[0:1]
	v_mov_b64_e32 v[108:109], v[0:1]
	v_mov_b64_e32 v[116:117], v[0:1]
	v_mov_b64_e32 v[124:125], v[0:1]
	s_mov_b32 s10, s11
	s_mov_b32 s89, s11
	s_barrier
	s_branch .LBB0_909
.LBB0_907:
	s_lshl_b32 s6, s22, 8
	s_ashr_i32 s7, s6, 31
	s_lshl_b64 s[6:7], s[6:7], 2
	v_mbcnt_lo_u32_b32 v6, -1, 0
	v_mbcnt_hi_u32_b32 v6, -1, v6
	s_add_u32 s6, s63, s6
	v_and_b32_e32 v0, 15, v6
	v_lshlrev_b32_e32 v2, 2, v6
	v_and_b32_e32 v2, 0xffffff80, v2
	s_addc_u32 s7, s78, s7
	v_lshlrev_b32_e32 v0, 2, v0
	v_ashrrev_i32_e32 v3, 31, v2
	v_lshl_add_u64 v[4:5], s[6:7], 0, v[0:1]
	v_lshlrev_b32_e32 v0, 3, v6
	v_lshl_add_u64 v[2:3], v[2:3], 2, v[4:5]
	v_and_b32_e32 v0, 0x80, v0
	s_mov_b32 m0, s71
	v_lshl_add_u64 v[2:3], v[2:3], 0, v[0:1]
	global_load_lds_dword v[2:3], off
	v_lshl_add_u64 v[2:3], v[2:3], 0, 64
	s_add_i32 m0, s71, 0x100
	s_add_u32 s28, s24, 0x100
	global_load_lds_dword v[2:3], off
	ds_read_b128 v[2:5], v151
	ds_read_b128 v[6:9], v151 offset:1024
	ds_read_b128 v[10:13], v151 offset:2048
	ds_read_b128 v[14:17], v151 offset:3072
	ds_read_b128 v[18:21], v150
	ds_read_b128 v[22:25], v150 offset:1024
	ds_read_b128 v[26:29], v150 offset:2048
	ds_read_b128 v[30:33], v150 offset:3072
	s_addc_u32 s29, s25, 0
	s_add_u32 s8, s24, 0x180
	s_addc_u32 s9, s25, 0
	s_add_u32 s6, s26, 0x100
	s_addc_u32 s7, s27, 0
	s_add_u32 s30, s24, 0x40080
	s_addc_u32 s31, s25, 0
	s_mov_b32 m0, s90
	ds_read_b128 v[34:37], v149
	ds_read_b128 v[38:41], v149 offset:1024
	ds_read_b128 v[42:45], v149 offset:2048
	ds_read_b128 v[46:49], v149 offset:3072
	ds_read_b128 v[50:53], v149 offset:4096
	ds_read_b128 v[54:57], v149 offset:5120
	ds_read_b128 v[58:61], v149 offset:6144
	ds_read_b128 v[62:65], v149 offset:7168
	s_nop 0
	global_load_lds_dwordx4 v138, s[30:31]
	s_mov_b32 m0, s10
	s_nop 0
	global_load_lds_dwordx4 v134, s[30:31]
	s_waitcnt vmcnt(18)
	s_waitcnt lgkmcnt(0)
	s_barrier
	s_setprio 1
	s_waitcnt lgkmcnt(0)
	v_mfma_f32_16x16x32_bf16 v[90:93], v[2:5], v[58:61], 0
	v_mfma_f32_16x16x32_bf16 v[66:69], v[2:5], v[34:37], 0
	v_mfma_f32_16x16x32_bf16 v[70:73], v[10:13], v[34:37], 0
	v_mfma_f32_16x16x32_bf16 v[74:77], v[2:5], v[42:45], 0
	v_mfma_f32_16x16x32_bf16 v[78:81], v[10:13], v[42:45], 0
	v_mfma_f32_16x16x32_bf16 v[82:85], v[2:5], v[50:53], 0
	v_mfma_f32_16x16x32_bf16 v[86:89], v[10:13], v[50:53], 0
	v_mfma_f32_16x16x32_bf16 v[96:99], v[6:9], v[62:65], v[90:93]
	v_mfma_f32_16x16x32_bf16 v[90:93], v[10:13], v[58:61], 0
	v_mfma_f32_16x16x32_bf16 v[66:69], v[6:9], v[38:41], v[66:69]
	v_mfma_f32_16x16x32_bf16 v[70:73], v[14:17], v[38:41], v[70:73]
	v_mfma_f32_16x16x32_bf16 v[74:77], v[6:9], v[46:49], v[74:77]
	v_mfma_f32_16x16x32_bf16 v[78:81], v[14:17], v[46:49], v[78:81]
	v_mfma_f32_16x16x32_bf16 v[82:85], v[6:9], v[54:57], v[82:85]
	v_mfma_f32_16x16x32_bf16 v[86:89], v[14:17], v[54:57], v[86:89]
	v_mfma_f32_16x16x32_bf16 v[104:107], v[14:17], v[62:65], v[90:93]
	s_setprio 0
	s_setprio 1
	v_mfma_f32_16x16x32_bf16 v[90:93], v[18:21], v[34:37], 0
	v_mfma_f32_16x16x32_bf16 v[34:37], v[26:29], v[34:37], 0
	v_mfma_f32_16x16x32_bf16 v[112:115], v[22:25], v[38:41], v[90:93]
	v_mfma_f32_16x16x32_bf16 v[34:37], v[30:33], v[38:41], v[34:37]
	v_mfma_f32_16x16x32_bf16 v[38:41], v[18:21], v[42:45], 0
	v_mfma_f32_16x16x32_bf16 v[42:45], v[26:29], v[42:45], 0
	v_mfma_f32_16x16x32_bf16 v[38:41], v[22:25], v[46:49], v[38:41]
	v_mfma_f32_16x16x32_bf16 v[42:45], v[30:33], v[46:49], v[42:45]
	v_mfma_f32_16x16x32_bf16 v[46:49], v[18:21], v[50:53], 0
	v_mfma_f32_16x16x32_bf16 v[50:53], v[26:29], v[50:53], 0
	v_mfma_f32_16x16x32_bf16 v[46:49], v[22:25], v[54:57], v[46:49]
	v_mfma_f32_16x16x32_bf16 v[50:53], v[30:33], v[54:57], v[50:53]
	v_mfma_f32_16x16x32_bf16 v[54:57], v[18:21], v[58:61], 0
	v_mfma_f32_16x16x32_bf16 v[54:57], v[22:25], v[62:65], v[54:57]
	v_mfma_f32_16x16x32_bf16 v[58:61], v[26:29], v[58:61], 0
	v_mfma_f32_16x16x32_bf16 v[154:157], v[30:33], v[62:65], v[58:61]
	s_setprio 0
	s_barrier
	s_mov_b32 m0, s61
	s_nop 3
	ds_read_b128 v[58:61], v149 offset:16384
	ds_read_b128 v[62:65], v149 offset:17408
	ds_read_b128 v[90:93], v149 offset:18432
	ds_read_b128 v[100:103], v149 offset:19456
	ds_read_b128 v[108:111], v149 offset:20480
	ds_read_b128 v[116:119], v149 offset:21504
	ds_read_b128 v[120:123], v149 offset:22528
	ds_read_b128 v[124:127], v149 offset:23552
	s_nop 0
	global_load_lds_dwordx4 v136, s[6:7]
	s_mov_b64 s[98:99], s[6:7]
	s_add_u32 s6, s26, 0x40100
	s_mov_b32 m0, s21
	s_addc_u32 s7, s27, 0
	global_load_lds_dwordx4 v132, s[98:99]
	s_mov_b32 m0, s23
	s_nop 0
	global_load_lds_dwordx4 v136, s[6:7]
	s_mov_b32 m0, s60
	s_nop 0
	global_load_lds_dwordx4 v132, s[6:7]
	s_mov_b32 m0, s72
	s_nop 0
	global_load_lds_dwordx4 v138, s[28:29]
	s_mov_b32 m0, s73
	s_nop 0
	global_load_lds_dwordx4 v134, s[28:29]
	s_waitcnt vmcnt(18)
	s_waitcnt lgkmcnt(0)
	s_barrier
	s_setprio 1
	s_waitcnt lgkmcnt(0)
	v_mfma_f32_16x16x32_bf16 v[128:131], v[2:5], v[58:61], 0
	v_mfma_f32_16x16x32_bf16 v[158:161], v[6:9], v[62:65], v[128:131]
	v_mfma_f32_16x16x32_bf16 v[128:131], v[10:13], v[58:61], 0
	v_mfma_f32_16x16x32_bf16 v[162:165], v[14:17], v[62:65], v[128:131]
	v_mfma_f32_16x16x32_bf16 v[128:131], v[2:5], v[90:93], 0
	v_mfma_f32_16x16x32_bf16 v[166:169], v[6:9], v[100:103], v[128:131]
	v_mfma_f32_16x16x32_bf16 v[128:131], v[10:13], v[90:93], 0
	v_mfma_f32_16x16x32_bf16 v[170:173], v[14:17], v[100:103], v[128:131]
	v_mfma_f32_16x16x32_bf16 v[128:131], v[2:5], v[108:111], 0
	v_mfma_f32_16x16x32_bf16 v[2:5], v[2:5], v[120:123], 0
	v_mfma_f32_16x16x32_bf16 v[176:179], v[6:9], v[116:119], v[128:131]
	v_mfma_f32_16x16x32_bf16 v[2:5], v[6:9], v[124:127], v[2:5]
	v_mfma_f32_16x16x32_bf16 v[6:9], v[10:13], v[120:123], 0
	v_mfma_f32_16x16x32_bf16 v[128:131], v[10:13], v[108:111], 0
	v_mfma_f32_16x16x32_bf16 v[6:9], v[14:17], v[124:127], v[6:9]
	v_mfma_f32_16x16x32_bf16 v[180:183], v[14:17], v[116:119], v[128:131]
	s_setprio 0
	s_setprio 1
	v_mfma_f32_16x16x32_bf16 v[10:13], v[18:21], v[58:61], 0
	v_mfma_f32_16x16x32_bf16 v[184:187], v[22:25], v[62:65], v[10:13]
	v_mfma_f32_16x16x32_bf16 v[10:13], v[26:29], v[58:61], 0
	v_mfma_f32_16x16x32_bf16 v[188:191], v[30:33], v[62:65], v[10:13]
	v_mfma_f32_16x16x32_bf16 v[10:13], v[18:21], v[90:93], 0
	v_mfma_f32_16x16x32_bf16 v[192:195], v[22:25], v[100:103], v[10:13]
	v_mfma_f32_16x16x32_bf16 v[10:13], v[26:29], v[90:93], 0
	v_mfma_f32_16x16x32_bf16 v[196:199], v[30:33], v[100:103], v[10:13]
	v_mfma_f32_16x16x32_bf16 v[10:13], v[18:21], v[108:111], 0
	v_mfma_f32_16x16x32_bf16 v[200:203], v[22:25], v[116:119], v[10:13]
	v_mfma_f32_16x16x32_bf16 v[10:13], v[26:29], v[108:111], 0
	v_mfma_f32_16x16x32_bf16 v[204:207], v[30:33], v[116:119], v[10:13]
	v_mfma_f32_16x16x32_bf16 v[10:13], v[18:21], v[120:123], 0
	v_mfma_f32_16x16x32_bf16 v[16:19], v[22:25], v[124:127], v[10:13]
	v_mfma_f32_16x16x32_bf16 v[10:13], v[26:29], v[120:123], 0
	v_mfma_f32_16x16x32_bf16 v[208:211], v[30:33], v[124:127], v[10:13]
	s_setprio 0
	s_barrier
	s_nop 4
	ds_read_b128 v[10:13], v152
	ds_read_b128 v[24:27], v152 offset:1024
	ds_read_b128 v[212:215], v152 offset:2048
	ds_read_b128 v[216:219], v152 offset:3072
	ds_read_b128 v[220:223], v153
	ds_read_b128 v[224:227], v153 offset:1024
	ds_read_b128 v[228:231], v153 offset:2048
	ds_read_b128 v[150:153], v153 offset:3072
	s_add_u32 s6, s24, 0x40100
	s_addc_u32 s7, s25, 0
	s_mov_b32 m0, s74
	ds_read_b128 v[20:23], v149 offset:32768
	ds_read_b128 v[28:31], v149 offset:33792
	ds_read_b128 v[232:235], v149 offset:34816
	ds_read_b128 v[236:239], v149 offset:35840
	ds_read_b128 v[240:243], v149 offset:36864
	ds_read_b128 v[244:247], v149 offset:37888
	ds_read_b128 v[248:251], v149 offset:38912
	ds_read_b128 v[140:143], v149 offset:39936
	s_nop 0
	global_load_lds_dwordx4 v138, s[6:7]
	s_mov_b32 m0, s75
	s_nop 0
	global_load_lds_dwordx4 v134, s[6:7]
	s_waitcnt vmcnt(18)
	s_waitcnt lgkmcnt(0)
	s_barrier
	s_setprio 1
	s_waitcnt lgkmcnt(0)
	v_mfma_f32_16x16x32_bf16 v[58:61], v[10:13], v[20:23], v[66:69]
	v_mfma_f32_16x16x32_bf16 v[124:127], v[24:27], v[28:31], v[58:61]
	v_mfma_f32_16x16x32_bf16 v[58:61], v[212:215], v[20:23], v[70:73]
	v_mfma_f32_16x16x32_bf16 v[116:119], v[216:219], v[28:31], v[58:61]
	v_mfma_f32_16x16x32_bf16 v[58:61], v[10:13], v[232:235], v[74:77]
	v_mfma_f32_16x16x32_bf16 v[108:111], v[24:27], v[236:239], v[58:61]
	v_mfma_f32_16x16x32_bf16 v[58:61], v[212:215], v[232:235], v[78:81]
	v_mfma_f32_16x16x32_bf16 v[100:103], v[216:219], v[236:239], v[58:61]
	v_mfma_f32_16x16x32_bf16 v[58:61], v[10:13], v[240:243], v[82:85]
	v_mfma_f32_16x16x32_bf16 v[92:95], v[24:27], v[244:247], v[58:61]
	v_mfma_f32_16x16x32_bf16 v[58:61], v[212:215], v[240:243], v[86:89]
	v_mfma_f32_16x16x32_bf16 v[84:87], v[216:219], v[244:247], v[58:61]
	v_mfma_f32_16x16x32_bf16 v[58:61], v[10:13], v[248:251], v[96:99]
	v_mfma_f32_16x16x32_bf16 v[76:79], v[24:27], v[140:143], v[58:61]
	v_mfma_f32_16x16x32_bf16 v[58:61], v[212:215], v[248:251], v[104:107]
	v_mfma_f32_16x16x32_bf16 v[60:63], v[216:219], v[140:143], v[58:61]
	s_setprio 0
	s_setprio 1
	v_mfma_f32_16x16x32_bf16 v[64:67], v[220:223], v[20:23], v[112:115]
	v_mfma_f32_16x16x32_bf16 v[20:23], v[228:231], v[20:23], v[34:37]
	v_mfma_f32_16x16x32_bf16 v[120:123], v[150:153], v[28:31], v[20:23]
	v_mfma_f32_16x16x32_bf16 v[20:23], v[220:223], v[232:235], v[38:41]
	v_mfma_f32_16x16x32_bf16 v[112:115], v[224:227], v[236:239], v[20:23]
	v_mfma_f32_16x16x32_bf16 v[20:23], v[228:231], v[232:235], v[42:45]
	v_mfma_f32_16x16x32_bf16 v[104:107], v[150:153], v[236:239], v[20:23]
	v_mfma_f32_16x16x32_bf16 v[20:23], v[220:223], v[240:243], v[46:49]
	v_mfma_f32_16x16x32_bf16 v[96:99], v[224:227], v[244:247], v[20:23]
	v_mfma_f32_16x16x32_bf16 v[20:23], v[228:231], v[240:243], v[50:53]
	v_mfma_f32_16x16x32_bf16 v[88:91], v[150:153], v[244:247], v[20:23]
	v_mfma_f32_16x16x32_bf16 v[20:23], v[220:223], v[248:251], v[54:57]
	v_mfma_f32_16x16x32_bf16 v[80:83], v[224:227], v[140:143], v[20:23]
	v_mfma_f32_16x16x32_bf16 v[20:23], v[228:231], v[248:251], v[154:157]
	v_mfma_f32_16x16x32_bf16 v[128:131], v[224:227], v[28:31], v[64:67]
	v_mfma_f32_16x16x32_bf16 v[68:71], v[150:153], v[140:143], v[20:23]
	s_setprio 0
	s_barrier
	s_add_u32 s6, s26, 0x180
	s_addc_u32 s7, s27, 0
	s_mov_b32 m0, s39
	ds_read_b128 v[32:35], v149 offset:49152
	ds_read_b128 v[40:43], v149 offset:50176
	ds_read_b128 v[140:143], v149 offset:51200
	ds_read_b128 v[154:157], v149 offset:52224
	ds_read_b128 v[232:235], v149 offset:53248
	ds_read_b128 v[236:239], v149 offset:54272
	ds_read_b128 v[240:243], v149 offset:55296
	ds_read_b128 v[244:247], v149 offset:56320
	s_nop 0
	global_load_lds_dwordx4 v136, s[6:7]
	s_mov_b64 s[98:99], s[6:7]
	s_add_u32 s6, s26, 0x40180
	s_mov_b32 m0, s38
	s_addc_u32 s7, s27, 0
	global_load_lds_dwordx4 v132, s[98:99]
	s_mov_b32 m0, s36
	s_nop 0
	global_load_lds_dwordx4 v136, s[6:7]
	s_mov_b32 m0, s37
	s_nop 0
	global_load_lds_dwordx4 v132, s[6:7]
	s_mov_b32 m0, s76
	s_nop 0
	global_load_lds_dwordx4 v138, s[8:9]
	s_mov_b32 m0, s77
	s_nop 0
	global_load_lds_dwordx4 v134, s[8:9]
	s_waitcnt vmcnt(18)
	s_waitcnt lgkmcnt(0)
	s_barrier
	s_setprio 1
	s_waitcnt lgkmcnt(0)
	v_mfma_f32_16x16x32_bf16 v[20:23], v[10:13], v[32:35], v[158:161]
	v_mfma_f32_16x16x32_bf16 v[64:67], v[24:27], v[40:43], v[20:23]
	v_mfma_f32_16x16x32_bf16 v[20:23], v[212:215], v[32:35], v[162:165]
	v_mfma_f32_16x16x32_bf16 v[52:55], v[216:219], v[40:43], v[20:23]
	v_mfma_f32_16x16x32_bf16 v[20:23], v[10:13], v[140:143], v[166:169]
	v_mfma_f32_16x16x32_bf16 v[44:47], v[24:27], v[154:157], v[20:23]
	v_mfma_f32_16x16x32_bf16 v[20:23], v[212:215], v[140:143], v[170:173]
	v_mfma_f32_16x16x32_bf16 v[36:39], v[216:219], v[154:157], v[20:23]
	v_mfma_f32_16x16x32_bf16 v[20:23], v[10:13], v[232:235], v[176:179]
	v_mfma_f32_16x16x32_bf16 v[2:5], v[10:13], v[240:243], v[2:5]
	v_mfma_f32_16x16x32_bf16 v[28:31], v[24:27], v[236:239], v[20:23]
	v_mfma_f32_16x16x32_bf16 v[20:23], v[212:215], v[232:235], v[180:183]
	v_mfma_f32_16x16x32_bf16 v[12:15], v[24:27], v[244:247], v[2:5]
	v_mfma_f32_16x16x32_bf16 v[2:5], v[212:215], v[240:243], v[6:9]
	v_mfma_f32_16x16x32_bf16 v[20:23], v[216:219], v[236:239], v[20:23]
	v_mfma_f32_16x16x32_bf16 v[4:7], v[216:219], v[244:247], v[2:5]
	s_setprio 0
	s_setprio 1
	v_mfma_f32_16x16x32_bf16 v[8:11], v[220:223], v[32:35], v[184:187]
	v_mfma_f32_16x16x32_bf16 v[72:75], v[224:227], v[40:43], v[8:11]
	v_mfma_f32_16x16x32_bf16 v[8:11], v[228:231], v[32:35], v[188:191]
	v_mfma_f32_16x16x32_bf16 v[56:59], v[150:153], v[40:43], v[8:11]
	v_mfma_f32_16x16x32_bf16 v[8:11], v[220:223], v[140:143], v[192:195]
	v_mfma_f32_16x16x32_bf16 v[48:51], v[224:227], v[154:157], v[8:11]
	v_mfma_f32_16x16x32_bf16 v[8:11], v[228:231], v[140:143], v[196:199]
	v_mfma_f32_16x16x32_bf16 v[40:43], v[150:153], v[154:157], v[8:11]
	v_mfma_f32_16x16x32_bf16 v[8:11], v[220:223], v[232:235], v[200:203]
	v_mfma_f32_16x16x32_bf16 v[32:35], v[224:227], v[236:239], v[8:11]
	v_mfma_f32_16x16x32_bf16 v[8:11], v[228:231], v[232:235], v[204:207]
	v_mfma_f32_16x16x32_bf16 v[24:27], v[150:153], v[236:239], v[8:11]
	v_mfma_f32_16x16x32_bf16 v[8:11], v[220:223], v[240:243], v[16:19]
	v_mfma_f32_16x16x32_bf16 v[16:19], v[224:227], v[244:247], v[8:11]
	v_mfma_f32_16x16x32_bf16 v[8:11], v[228:231], v[240:243], v[208:211]
	v_mfma_f32_16x16x32_bf16 v[8:11], v[150:153], v[244:247], v[8:11]
	s_setprio 0
	s_barrier
	s_mov_b64 s[8:9], 0

; template <class Epi, class Sched, bool ALIGN_EPI = false, bool SP2 = false>
; __device__ __forceinline__ void gemm_phase(PG8_LAS unsigned char* lds, const Gemm g, const Sched& S, const Epi& E, int wave_s) {
;     ...
;         const bool has_next = S.next(ui + 1, nxt);
;         const char* nA = has_next ? (const char*)g.A + (size_t)nxt.pm * tstep : cA; const char* nB = has_next ? (const char*)g.Bt + (size_t)nxt.pn * tstep : cB;
;         for (int t = peeled ? 2 : 0; t < nt; t += 2) {
;             const bool last = (t == nt - 2);
;             const char* a1 = cA + (size_t)(t + 1) * kstep;
;             const char* a2 = last ? nA : cA + (size_t)(t + 2) * kstep; const char* b2 = last ? nB : cB + (size_t)(t + 2) * kstep;
;             const char* a3 = a2 + kstep; const char* b3 = b2 + kstep;
;             if (last && has_next) S.a_ready(nxt);
.LBB0_912:
	v_add_u32_e32 v151, s82, v146
	v_add_u32_e32 v150, s87, v146
	ds_read_b128 v[152:155], v151
	ds_read_b128 v[156:159], v151 offset:1024
	ds_read_b128 v[160:163], v151 offset:2048
	ds_read_b128 v[164:167], v151 offset:3072
	ds_read_b128 v[168:171], v150
	ds_read_b128 v[176:179], v150 offset:1024
	ds_read_b128 v[180:183], v150 offset:2048
	ds_read_b128 v[184:187], v150 offset:3072
	s_add_u32 s30, s40, 0x100
	s_addc_u32 s31, s41, 0
	s_cmp_eq_u32 s95, 12
	s_cselect_b32 s38, s92, s30
	s_cselect_b32 s39, s91, s31
	s_cselect_b32 s36, s94, s96
	s_cselect_b32 s37, s93, s6
	s_add_u32 s34, s38, 0x80
	s_addc_u32 s35, s39, 0
	s_add_u32 s40, s40, 0x40080
	s_addc_u32 s41, s41, 0
	s_add_i32 s90, s72, 0xc000
	ds_read_b128 v[188:191], v149
	ds_read_b128 v[192:195], v149 offset:1024
	ds_read_b128 v[196:199], v149 offset:2048
	ds_read_b128 v[200:203], v149 offset:3072
	ds_read_b128 v[204:207], v149 offset:4096
	ds_read_b128 v[208:211], v149 offset:5120
	ds_read_b128 v[212:215], v149 offset:6144
	ds_read_b128 v[216:219], v149 offset:7168
	s_mov_b32 m0, s90
	s_add_i32 s10, s72, 0xe000
	global_load_lds_dwordx4 v138, s[40:41]
	s_mov_b32 m0, s10
	s_nop 0
	global_load_lds_dwordx4 v134, s[40:41]
	s_waitcnt vmcnt(8)
	s_waitcnt lgkmcnt(0)
	s_barrier
	s_setprio 1
	s_waitcnt lgkmcnt(0)
	v_mfma_f32_16x16x32_bf16 v[124:127], v[152:155], v[188:191], v[124:127]
	v_mfma_f32_16x16x32_bf16 v[116:119], v[160:163], v[188:191], v[116:119]
	v_mfma_f32_16x16x32_bf16 v[108:111], v[152:155], v[196:199], v[108:111]
	v_mfma_f32_16x16x32_bf16 v[100:103], v[160:163], v[196:199], v[100:103]
	v_mfma_f32_16x16x32_bf16 v[92:95], v[152:155], v[204:207], v[92:95]
	v_mfma_f32_16x16x32_bf16 v[84:87], v[160:163], v[204:207], v[84:87]
	v_mfma_f32_16x16x32_bf16 v[76:79], v[152:155], v[212:215], v[76:79]
	v_mfma_f32_16x16x32_bf16 v[60:63], v[160:163], v[212:215], v[60:63]
	v_mfma_f32_16x16x32_bf16 v[124:127], v[156:159], v[192:195], v[124:127]
	v_mfma_f32_16x16x32_bf16 v[116:119], v[164:167], v[192:195], v[116:119]
	v_mfma_f32_16x16x32_bf16 v[108:111], v[156:159], v[200:203], v[108:111]
	v_mfma_f32_16x16x32_bf16 v[100:103], v[164:167], v[200:203], v[100:103]
	v_mfma_f32_16x16x32_bf16 v[92:95], v[156:159], v[208:211], v[92:95]
	v_mfma_f32_16x16x32_bf16 v[84:87], v[164:167], v[208:211], v[84:87]
	v_mfma_f32_16x16x32_bf16 v[76:79], v[156:159], v[216:219], v[76:79]
	v_mfma_f32_16x16x32_bf16 v[60:63], v[164:167], v[216:219], v[60:63]
	s_setprio 0
	s_setprio 1
	v_mfma_f32_16x16x32_bf16 v[128:131], v[168:171], v[188:191], v[128:131]
	v_mfma_f32_16x16x32_bf16 v[120:123], v[180:183], v[188:191], v[120:123]
	v_mfma_f32_16x16x32_bf16 v[112:115], v[168:171], v[196:199], v[112:115]
	v_mfma_f32_16x16x32_bf16 v[104:107], v[180:183], v[196:199], v[104:107]
	v_mfma_f32_16x16x32_bf16 v[96:99], v[168:171], v[204:207], v[96:99]
	v_mfma_f32_16x16x32_bf16 v[88:91], v[180:183], v[204:207], v[88:91]
	v_mfma_f32_16x16x32_bf16 v[80:83], v[168:171], v[212:215], v[80:83]
	v_mfma_f32_16x16x32_bf16 v[68:71], v[180:183], v[212:215], v[68:71]
	v_mfma_f32_16x16x32_bf16 v[128:131], v[176:179], v[192:195], v[128:131]
	v_mfma_f32_16x16x32_bf16 v[120:123], v[184:187], v[192:195], v[120:123]
	v_mfma_f32_16x16x32_bf16 v[112:115], v[176:179], v[200:203], v[112:115]
	v_mfma_f32_16x16x32_bf16 v[104:107], v[184:187], v[200:203], v[104:107]
	v_mfma_f32_16x16x32_bf16 v[96:99], v[176:179], v[208:211], v[96:99]
	v_mfma_f32_16x16x32_bf16 v[88:91], v[184:187], v[208:211], v[88:91]
	v_mfma_f32_16x16x32_bf16 v[80:83], v[176:179], v[216:219], v[80:83]
	v_mfma_f32_16x16x32_bf16 v[68:71], v[184:187], v[216:219], v[68:71]
	s_setprio 0
	s_barrier
	s_mov_b64 s[40:41], s[36:37]
	s_add_i32 s61, s82, s42
	ds_read_b128 v[188:191], v149 offset:16384
	ds_read_b128 v[192:195], v149 offset:17408
	ds_read_b128 v[196:199], v149 offset:18432
	ds_read_b128 v[200:203], v149 offset:19456
	ds_read_b128 v[204:207], v149 offset:20480
	ds_read_b128 v[208:211], v149 offset:21504
	ds_read_b128 v[212:215], v149 offset:22528
	ds_read_b128 v[216:219], v149 offset:23552
	s_mov_b32 m0, s61
	s_add_i32 s21, s61, 0x2000
	global_load_lds_dwordx4 v136, s[40:41]
	s_mov_b64 s[98:99], s[40:41]
	s_add_u32 s40, s36, 0x40000
	s_mov_b32 m0, s21
	s_addc_u32 s41, s37, 0
	s_add_i32 s23, s87, s42
	global_load_lds_dwordx4 v132, s[98:99]
	s_mov_b32 m0, s23
	s_add_i32 s60, s23, 0x2000
	global_load_lds_dwordx4 v136, s[40:41]
	s_mov_b64 s[98:99], s[40:41]
	s_mov_b32 m0, s60
	s_mov_b64 s[40:41], s[38:39]
	global_load_lds_dwordx4 v132, s[98:99]
	s_mov_b32 m0, s72
	s_nop 0
	global_load_lds_dwordx4 v138, s[40:41]
	s_mov_b32 m0, s73
	s_nop 0
	global_load_lds_dwordx4 v134, s[40:41]
	s_waitcnt vmcnt(8)
	s_waitcnt lgkmcnt(0)
	s_barrier
	s_setprio 1
	s_waitcnt lgkmcnt(0)
	v_mfma_f32_16x16x32_bf16 v[64:67], v[152:155], v[188:191], v[64:67]
	v_mfma_f32_16x16x32_bf16 v[52:55], v[160:163], v[188:191], v[52:55]
	v_mfma_f32_16x16x32_bf16 v[44:47], v[152:155], v[196:199], v[44:47]
	v_mfma_f32_16x16x32_bf16 v[36:39], v[160:163], v[196:199], v[36:39]
	v_mfma_f32_16x16x32_bf16 v[28:31], v[152:155], v[204:207], v[28:31]
	v_mfma_f32_16x16x32_bf16 v[20:23], v[160:163], v[204:207], v[20:23]
	v_mfma_f32_16x16x32_bf16 v[12:15], v[152:155], v[212:215], v[12:15]
	v_mfma_f32_16x16x32_bf16 v[2:5], v[160:163], v[212:215], v[4:7]
	v_mfma_f32_16x16x32_bf16 v[64:67], v[156:159], v[192:195], v[64:67]
	v_mfma_f32_16x16x32_bf16 v[52:55], v[164:167], v[192:195], v[52:55]
	v_mfma_f32_16x16x32_bf16 v[44:47], v[156:159], v[200:203], v[44:47]
	v_mfma_f32_16x16x32_bf16 v[36:39], v[164:167], v[200:203], v[36:39]
	v_mfma_f32_16x16x32_bf16 v[28:31], v[156:159], v[208:211], v[28:31]
	v_mfma_f32_16x16x32_bf16 v[20:23], v[164:167], v[208:211], v[20:23]
	v_mfma_f32_16x16x32_bf16 v[12:15], v[156:159], v[216:219], v[12:15]
	v_mfma_f32_16x16x32_bf16 v[2:5], v[164:167], v[216:219], v[2:5]
	s_setprio 0
	s_setprio 1
	v_mfma_f32_16x16x32_bf16 v[72:75], v[168:171], v[188:191], v[72:75]
	v_mfma_f32_16x16x32_bf16 v[56:59], v[180:183], v[188:191], v[56:59]
	v_mfma_f32_16x16x32_bf16 v[48:51], v[168:171], v[196:199], v[48:51]
	v_mfma_f32_16x16x32_bf16 v[40:43], v[180:183], v[196:199], v[40:43]
	v_mfma_f32_16x16x32_bf16 v[32:35], v[168:171], v[204:207], v[32:35]
	v_mfma_f32_16x16x32_bf16 v[24:27], v[180:183], v[204:207], v[24:27]
	v_mfma_f32_16x16x32_bf16 v[16:19], v[168:171], v[212:215], v[16:19]
	v_mfma_f32_16x16x32_bf16 v[6:9], v[180:183], v[212:215], v[8:11]
	v_mfma_f32_16x16x32_bf16 v[72:75], v[176:179], v[192:195], v[72:75]
	v_mfma_f32_16x16x32_bf16 v[56:59], v[184:187], v[192:195], v[56:59]
	v_mfma_f32_16x16x32_bf16 v[48:51], v[176:179], v[200:203], v[48:51]
	v_mfma_f32_16x16x32_bf16 v[40:43], v[184:187], v[200:203], v[40:43]
	v_mfma_f32_16x16x32_bf16 v[32:35], v[176:179], v[208:211], v[32:35]
	v_mfma_f32_16x16x32_bf16 v[24:27], v[184:187], v[208:211], v[24:27]
	v_mfma_f32_16x16x32_bf16 v[16:19], v[176:179], v[216:219], v[16:19]
	v_mfma_f32_16x16x32_bf16 v[8:11], v[184:187], v[216:219], v[6:9]
	s_setprio 0
	s_barrier
	s_add_i32 s7, 0, 0x18000
	s_add_i32 s86, 0, 0x1c000
	v_add_u32_e32 v152, s7, v146
	v_add_u32_e32 v153, s86, v146
	ds_read_b128 v[154:157], v152
	ds_read_b128 v[158:161], v152 offset:1024
	ds_read_b128 v[162:165], v152 offset:2048
	ds_read_b128 v[166:169], v152 offset:3072
	ds_read_b128 v[170:173], v153
	ds_read_b128 v[176:179], v153 offset:1024
	ds_read_b128 v[180:183], v153 offset:2048
	ds_read_b128 v[184:187], v153 offset:3072
	s_add_u32 s38, s38, 0x40000
	s_addc_u32 s39, s39, 0
	s_mov_b32 m0, s74
	ds_read_b128 v[188:191], v149 offset:32768
	ds_read_b128 v[192:195], v149 offset:33792
	ds_read_b128 v[196:199], v149 offset:34816
	ds_read_b128 v[200:203], v149 offset:35840
	ds_read_b128 v[204:207], v149 offset:36864
	ds_read_b128 v[208:211], v149 offset:37888
	ds_read_b128 v[212:215], v149 offset:38912
	ds_read_b128 v[216:219], v149 offset:39936
	s_nop 0
	global_load_lds_dwordx4 v138, s[38:39]
	s_mov_b32 m0, s75
	s_nop 0
	global_load_lds_dwordx4 v134, s[38:39]
	s_waitcnt vmcnt(8)
	s_waitcnt lgkmcnt(0)
	s_barrier
	s_setprio 1
	s_waitcnt lgkmcnt(0)
	v_mfma_f32_16x16x32_bf16 v[124:127], v[154:157], v[188:191], v[124:127]
	v_mfma_f32_16x16x32_bf16 v[116:119], v[162:165], v[188:191], v[116:119]
	v_mfma_f32_16x16x32_bf16 v[108:111], v[154:157], v[196:199], v[108:111]
	v_mfma_f32_16x16x32_bf16 v[100:103], v[162:165], v[196:199], v[100:103]
	v_mfma_f32_16x16x32_bf16 v[92:95], v[154:157], v[204:207], v[92:95]
	v_mfma_f32_16x16x32_bf16 v[84:87], v[162:165], v[204:207], v[84:87]
	v_mfma_f32_16x16x32_bf16 v[76:79], v[154:157], v[212:215], v[76:79]
	v_mfma_f32_16x16x32_bf16 v[60:63], v[162:165], v[212:215], v[60:63]
	v_mfma_f32_16x16x32_bf16 v[124:127], v[158:161], v[192:195], v[124:127]
	v_mfma_f32_16x16x32_bf16 v[116:119], v[166:169], v[192:195], v[116:119]
	v_mfma_f32_16x16x32_bf16 v[108:111], v[158:161], v[200:203], v[108:111]
	v_mfma_f32_16x16x32_bf16 v[100:103], v[166:169], v[200:203], v[100:103]
	v_mfma_f32_16x16x32_bf16 v[92:95], v[158:161], v[208:211], v[92:95]
	v_mfma_f32_16x16x32_bf16 v[84:87], v[166:169], v[208:211], v[84:87]
	v_mfma_f32_16x16x32_bf16 v[76:79], v[158:161], v[216:219], v[76:79]
	v_mfma_f32_16x16x32_bf16 v[60:63], v[166:169], v[216:219], v[60:63]
	s_setprio 0
	s_setprio 1
	v_mfma_f32_16x16x32_bf16 v[128:131], v[170:173], v[188:191], v[128:131]
	v_mfma_f32_16x16x32_bf16 v[120:123], v[180:183], v[188:191], v[120:123]
	v_mfma_f32_16x16x32_bf16 v[112:115], v[170:173], v[196:199], v[112:115]
	v_mfma_f32_16x16x32_bf16 v[104:107], v[180:183], v[196:199], v[104:107]
	v_mfma_f32_16x16x32_bf16 v[96:99], v[170:173], v[204:207], v[96:99]
	v_mfma_f32_16x16x32_bf16 v[88:91], v[180:183], v[204:207], v[88:91]
	v_mfma_f32_16x16x32_bf16 v[80:83], v[170:173], v[212:215], v[80:83]
	v_mfma_f32_16x16x32_bf16 v[68:71], v[180:183], v[212:215], v[68:71]
	v_mfma_f32_16x16x32_bf16 v[128:131], v[176:179], v[192:195], v[128:131]
	v_mfma_f32_16x16x32_bf16 v[120:123], v[184:187], v[192:195], v[120:123]
	v_mfma_f32_16x16x32_bf16 v[112:115], v[176:179], v[200:203], v[112:115]
	v_mfma_f32_16x16x32_bf16 v[104:107], v[184:187], v[200:203], v[104:107]
	v_mfma_f32_16x16x32_bf16 v[96:99], v[176:179], v[208:211], v[96:99]
	v_mfma_f32_16x16x32_bf16 v[88:91], v[184:187], v[208:211], v[88:91]
	v_mfma_f32_16x16x32_bf16 v[80:83], v[176:179], v[216:219], v[80:83]
	v_mfma_f32_16x16x32_bf16 v[68:71], v[184:187], v[216:219], v[68:71]
	s_setprio 0
	s_barrier
	s_add_u32 s40, s36, 0x80
	s_addc_u32 s41, s37, 0
	s_add_i32 s39, s7, s42
	ds_read_b128 v[188:191], v149 offset:49152
	ds_read_b128 v[192:195], v149 offset:50176
	ds_read_b128 v[196:199], v149 offset:51200
	ds_read_b128 v[200:203], v149 offset:52224
	ds_read_b128 v[204:207], v149 offset:53248
	ds_read_b128 v[208:211], v149 offset:54272
	ds_read_b128 v[212:215], v149 offset:55296
	ds_read_b128 v[216:219], v149 offset:56320
	s_mov_b32 m0, s39
	s_add_i32 s38, s39, 0x2000
	global_load_lds_dwordx4 v136, s[40:41]
	s_mov_b64 s[98:99], s[40:41]
	s_add_u32 s40, s36, 0x40080
	s_mov_b32 m0, s38
	s_addc_u32 s41, s37, 0
	s_add_i32 s36, s86, s42
	global_load_lds_dwordx4 v132, s[98:99]
	s_mov_b32 m0, s36
	s_add_i32 s37, s36, 0x2000
	global_load_lds_dwordx4 v136, s[40:41]
	s_mov_b32 m0, s37
	s_nop 0
	global_load_lds_dwordx4 v132, s[40:41]
	s_mov_b32 m0, s76
	s_nop 0
	global_load_lds_dwordx4 v138, s[34:35]
	s_mov_b32 m0, s77
	s_nop 0
	global_load_lds_dwordx4 v134, s[34:35]
	s_waitcnt vmcnt(8)
	s_waitcnt lgkmcnt(0)
	s_barrier
	s_setprio 1
	s_waitcnt lgkmcnt(0)
	v_mfma_f32_16x16x32_bf16 v[64:67], v[154:157], v[188:191], v[64:67]
	v_mfma_f32_16x16x32_bf16 v[52:55], v[162:165], v[188:191], v[52:55]
	v_mfma_f32_16x16x32_bf16 v[44:47], v[154:157], v[196:199], v[44:47]
	v_mfma_f32_16x16x32_bf16 v[36:39], v[162:165], v[196:199], v[36:39]
	v_mfma_f32_16x16x32_bf16 v[28:31], v[154:157], v[204:207], v[28:31]
	v_mfma_f32_16x16x32_bf16 v[20:23], v[162:165], v[204:207], v[20:23]
	v_mfma_f32_16x16x32_bf16 v[12:15], v[154:157], v[212:215], v[12:15]
	v_mfma_f32_16x16x32_bf16 v[2:5], v[162:165], v[212:215], v[2:5]
	v_mfma_f32_16x16x32_bf16 v[64:67], v[158:161], v[192:195], v[64:67]
	v_mfma_f32_16x16x32_bf16 v[52:55], v[166:169], v[192:195], v[52:55]
	v_mfma_f32_16x16x32_bf16 v[44:47], v[158:161], v[200:203], v[44:47]
	v_mfma_f32_16x16x32_bf16 v[36:39], v[166:169], v[200:203], v[36:39]
	v_mfma_f32_16x16x32_bf16 v[28:31], v[158:161], v[208:211], v[28:31]
	v_mfma_f32_16x16x32_bf16 v[20:23], v[166:169], v[208:211], v[20:23]
	v_mfma_f32_16x16x32_bf16 v[12:15], v[158:161], v[216:219], v[12:15]
	v_mfma_f32_16x16x32_bf16 v[4:7], v[166:169], v[216:219], v[2:5]
	s_setprio 0
	s_setprio 1
	v_mfma_f32_16x16x32_bf16 v[72:75], v[170:173], v[188:191], v[72:75]
	v_mfma_f32_16x16x32_bf16 v[56:59], v[180:183], v[188:191], v[56:59]
	v_mfma_f32_16x16x32_bf16 v[48:51], v[170:173], v[196:199], v[48:51]
	v_mfma_f32_16x16x32_bf16 v[40:43], v[180:183], v[196:199], v[40:43]
	v_mfma_f32_16x16x32_bf16 v[32:35], v[170:173], v[204:207], v[32:35]
	v_mfma_f32_16x16x32_bf16 v[24:27], v[180:183], v[204:207], v[24:27]
	v_mfma_f32_16x16x32_bf16 v[16:19], v[170:173], v[212:215], v[16:19]
	v_mfma_f32_16x16x32_bf16 v[8:11], v[180:183], v[212:215], v[8:11]
	v_mfma_f32_16x16x32_bf16 v[72:75], v[176:179], v[192:195], v[72:75]
	v_mfma_f32_16x16x32_bf16 v[56:59], v[184:187], v[192:195], v[56:59]
	v_mfma_f32_16x16x32_bf16 v[48:51], v[176:179], v[200:203], v[48:51]
	v_mfma_f32_16x16x32_bf16 v[40:43], v[184:187], v[200:203], v[40:43]
	v_mfma_f32_16x16x32_bf16 v[32:35], v[176:179], v[208:211], v[32:35]
	v_mfma_f32_16x16x32_bf16 v[24:27], v[184:187], v[208:211], v[24:27]
	v_mfma_f32_16x16x32_bf16 v[16:19], v[176:179], v[216:219], v[16:19]
	v_mfma_f32_16x16x32_bf16 v[8:11], v[184:187], v[216:219], v[8:11]
	s_setprio 0
	s_barrier
	s_add_i32 s95, s95, 2
	s_add_u32 s96, s96, 0x100
	s_addc_u32 s6, s6, 0
	s_cmp_gt_u32 s95, 13
	s_mov_b64 s[40:41], s[30:31]
	s_cbranch_scc0 .LBB0_912
	s_and_b64 vcc, exec, s[18:19]
	s_cbranch_vccz .LBB0_915
	s_barrier

; __device__ __forceinline__ int lane_id_() { int l; asm volatile("v_mbcnt_lo_u32_b32 %0, -1, 0\n\tv_mbcnt_hi_u32_b32 %0, -1, %0" : "=v"(l)); return l; }
; __device__ __forceinline__ unsigned xb_ld(unsigned* p)              { return __hip_atomic_load(p, __ATOMIC_RELAXED, __HIP_MEMORY_SCOPE_AGENT); }
; __device__ __forceinline__ unsigned xb_add(unsigned* p, unsigned v) { return __hip_atomic_fetch_add(p, v, __ATOMIC_RELAXED, __HIP_MEMORY_SCOPE_AGENT); }
; #define XB_SPIN(cond, bar) do { unsigned _sp = 0; while (cond) { __builtin_amdgcn_s_sleep(1); \
;     if ((++_sp & 255u) == 0u) { if (xb_ld(&(bar)[XB_TMO])) break; if (_sp > XB_SPIN_CAP) { atomicAdd(&(bar)[XB_TMO], 1u); break; } } } } while (0)
; __device__ __forceinline__ void xcd_barrier(const XcdBarrier& b, int wave_s) {
;     asm volatile("s_waitcnt vmcnt(0)" ::: "memory");
;     __syncthreads();
;     if (wave_s == 0 && lane_id_() == 0) {
;         unsigned* bar = b.bar;
;         __builtin_amdgcn_s_waitcnt(0);
;         unsigned nloc = b.st[0], nx = b.st[1];
;         if (nloc == 0u) { xcd_barrier_complete(bar, b.x, nloc, nx); b.st[0] = nloc; b.st[1] = nx; }
;         const unsigned old = xb_add(&bar[XB_XSUB(b.x)], 1u);
;         const unsigned gen = old / nloc;
;         if (old + 1u == (gen + 1u) * nloc) {
;             __builtin_amdgcn_fence(__ATOMIC_RELEASE, "agent");
;             asm volatile("s_waitcnt vmcnt(0)" ::: "memory");
;             const unsigned og = xb_add(&bar[XB_TOP], 1u);
;             const unsigned tg = og / nx;
;             if (og + 1u == (tg + 1u) * nx) xb_add(&bar[XB_TOPGEN], 1u);
;             else XB_SPIN(xb_ld(&bar[XB_TOPGEN]) == tg, bar);
;             __builtin_amdgcn_fence(__ATOMIC_ACQUIRE, "agent");
;             xb_add(&bar[XB_XGEN(b.x)], 1u);
;             asm volatile("s_waitcnt vmcnt(0)" ::: "memory");
;         } else {
;             XB_SPIN(xb_ld(&bar[XB_XGEN(b.x)]) == gen, bar);
;             __builtin_amdgcn_fence(__ATOMIC_ACQUIRE, "agent");
;             asm volatile("s_waitcnt vmcnt(0)" ::: "memory");
;         }
;     }
;     __syncthreads();
; }
.LBB0_1109:
	v_add_u32_e32 v28, 56, v28
	v_mad_i64_i32 v[28:29], s[20:21], v28, s38, v[30:31]
	global_load_dwordx4 v[28:31], v[28:29], off
	s_and_b64 vcc, exec, s[8:9]
	s_cbranch_vccnz .LBB0_1018
	global_load_dword v64, v[60:61], off offset:224
	s_branch .LBB0_1018
.LBB0_1111:
	s_waitcnt vmcnt(0)
	s_and_b64 vcc, exec, s[2:3]
	s_waitcnt vmcnt(0)
	s_barrier
	s_cbranch_vccnz .LBB0_1165
	v_mbcnt_lo_u32_b32 v0, -1, 0
	v_mbcnt_hi_u32_b32 v0, -1, v0
	s_nop 0
	v_cmp_eq_u32_e32 vcc, 0, v0
	s_and_saveexec_b64 s[8:9], vcc
	s_cbranch_execz .LBB0_1164
	s_cmp_eq_u32 s101, 1
	s_cbranch_scc0 .Lglob_S7
	s_and_b32 s98, s33, 7
	s_lshl_b32 s99, s98, 2
	s_addk_i32 s99, 0x4800
	v_mov_b32_e32 v3, s99
	s_lshl_b32 s98, s98, 8
	s_addk_i32 s98, 0x4000
	v_mov_b32_e32 v0, s98
	v_mov_b32_e32 v1, 1
	global_atomic_add v2, v0, v1, s[44:45] sc0
	buffer_inv sc1
	s_waitcnt vmcnt(1)
	v_readfirstlane_b32 s98, v2
	s_nop 3
	s_add_u32 s99, s98, 1
	s_and_b32 s99, s99, 31
	s_lshr_b32 s98, s98, 5
	s_cmp_eq_u32 s99, 0
	s_cbranch_scc0 .Llw_S7
	global_atomic_add v3, v1, s[44:45]
	s_branch .Lrvp_S7

; __device__ __forceinline__ int lane_id_() { int l; asm volatile("v_mbcnt_lo_u32_b32 %0, -1, 0\n\tv_mbcnt_hi_u32_b32 %0, -1, %0" : "=v"(l)); return l; }
; #define PG8_LAS __attribute__((address_space(3)))
; #define PG8_STAGE(bufoff, gbase, voff) do { const char* gb_ = (const char*)(gbase); asm volatile("" : "+s"(gb_));   \
;         _Pragma("unroll") for (int _i = 0; _i < 2; ++_i) \
;         __builtin_amdgcn_global_load_lds((const unsigned*)(gb_ + (voff)[_i]), (PG8_LAS unsigned*)(lds + (bufoff) + ldsw + _i * 8192), 16, 0, 0); } while (0)
; #define PG8_WAIT_V(n) asm volatile("s_waitcnt vmcnt(" #n ")" ::: "memory")
; #define PG8_BAR __builtin_amdgcn_s_barrier()
;     __device__ __forceinline__ void operator()(const f32x4 (&acc)[2][2][4][2], const Unit& u, int wr, int wc, int fr, int fq, PG8_LAS unsigned char* lds, int wid) const {
;     ...
;                     if (fq == 0) *(PG8_LAS float*)(lds + PRE_SLOT + 4096 + ((wr * 64 + fr + ai * HALF + m * 16) * 4 + wc) * 4) = s; }
;             }
;         if (!LAST) {
;             asm volatile("s_waitcnt lgkmcnt(0)" ::: "memory"); __builtin_amdgcn_s_barrier(); asm volatile("" ::: "memory");
;             if (wid < 4) { const int r = wid * 64 + lane_id_();
;                 const f32x4 p = *(const PG8_LAS f32x4*)(lds + PRE_SLOT + 4096 + r * 16);
;                 __hip_atomic_fetch_add(ssq + u.pm * BM + r, (p[0] + p[1]) + (p[2] + p[3]), __ATOMIC_RELAXED, __HIP_MEMORY_SCOPE_AGENT); }
; template <class Epi, class Sched, bool ALIGN_EPI = false, bool SP2 = false>
; __device__ __forceinline__ void gemm_phase(PG8_LAS unsigned char* lds, const Gemm g, const Sched& S, const Epi& E, int wave_s) {
;     ...
;         PG8_STAGE(PG8_SB(0, 0), cB, voffB); PG8_STAGE(PG8_SB(0, 1), cB + hstep, voffB); PG8_STAGE(PG8_SA(0, 0), cA, voffA); PG8_STAGE(PG8_SA(0, 1), cA + hstep, voffA);
;         if (wr == 1) PG8_BAR;
;         PG8_WAIT_V(2); PG8_BAR;
;         PG8_STAGE(PG8_SB(1, 0), cB + kstep, voffB); PG8_STAGE(PG8_SA(1, 0), cA + kstep, voffA); PG8_STAGE(PG8_SB(1, 1), cB + hstep + kstep, voffB);
;         PG8_WAIT_V(6); PG8_BAR;
.LBB0_1174:
	s_and_b32 s10, s6, 3
	s_lshl_b32 s11, s7, 13
	s_lshl_b32 s12, s10, 12
	s_add_u32 s8, s40, 0x80
	s_addc_u32 s9, s41, 0
	s_waitcnt vmcnt(2)
	s_barrier
	s_add_i32 m0, s76, 0x18000
	s_nop 0
	global_load_lds_dwordx4 v130, s[8:9]
	s_add_i32 m0, s76, 0x1a000
	s_nop 0
	global_load_lds_dwordx4 v134, s[8:9]
	s_add_u32 s8, s38, 0x80
	s_addc_u32 s9, s39, 0
	s_add_i32 s88, s76, 0x8000
	s_mov_b32 m0, s88
	s_add_i32 s89, s76, 0xa000
	global_load_lds_dwordx4 v128, s[8:9]
	s_mov_b64 s[98:99], s[8:9]
	s_add_u32 s8, s40, 0xb0080
	s_mov_b32 m0, s89
	s_addc_u32 s9, s41, 0
	global_load_lds_dwordx4 v132, s[98:99]
	s_add_i32 m0, s76, 0x1c000
	s_nop 0
	global_load_lds_dwordx4 v130, s[8:9]
	s_add_i32 m0, s76, 0x1e000
	v_and_b32_e32 v1, 15, v0
	global_load_lds_dwordx4 v134, s[8:9]
	v_bfe_u32 v2, v0, 4, 2
	v_lshlrev_b32_e32 v4, 4, v2
	v_lshlrev_b32_e32 v0, 2, v0
	v_lshl_or_b32 v144, s7, 6, v1
	v_lshl_or_b32 v1, v1, 6, v4
	v_and_b32_e32 v0, 32, v0
	s_cmpk_lt_u32 s90, 0x100
	v_lshlrev_b32_e32 v3, 3, v2
	v_bitop3_b32 v4, v1, s11, v0 bitop3:0xde
	v_bitop3_b32 v145, v1, s12, v0 bitop3:0xde
	s_cselect_b64 s[22:23], -1, 0
	v_lshlrev_b32_e32 v0, 4, v144
	s_add_i32 s7, 0, 0x22400
	v_lshl_or_b32 v146, s10, 5, v3
	v_add_u32_e32 v1, s7, v0
	s_lshl_b32 s7, s10, 2
	s_add_i32 s10, 0, 0x22500
	v_cmp_eq_u32_e64 s[8:9], 0, v2
	v_add_u32_e32 v2, s10, v0
	s_add_i32 s10, 0, 0x22600
	v_add_u32_e32 v3, s10, v0
	s_add_i32 s10, 0, 0x22700
	v_add_u32_e32 v5, s10, v0
	s_add_i32 s10, 0, 0x22c00
	v_add_u32_e32 v6, s10, v0
	s_add_i32 s10, 0, 0x22d00
	v_add_u32_e32 v7, s10, v0
	s_add_i32 s10, 0, 0x22e00
	v_add_u32_e32 v8, s10, v0
	s_add_i32 s10, 0, 0x22f00
	s_waitcnt vmcnt(6)
	s_cmp_lt_i32 s6, 4
	v_add_u32_e32 v0, s10, v0
	s_cselect_b64 s[24:25], -1, 0
	s_add_i32 s93, 0, 0x10000
	s_add_i32 s94, 0, 0x14000
	s_andn2_b32 s90, s90, 63
	s_mov_b32 s91, s46
	s_ashr_i32 s92, s33, 31
	v_mov_b64_e32 v[136:137], 0x100
	v_mov_b64_e32 v[138:139], 0xff
	v_add_u32_e32 v147, s93, v145
	v_add_u32_e32 v148, s94, v145
	v_add_u32_e32 v149, 0, v4
	v_mbcnt_hi_u32_b32 v150, -1, v254
	v_add_u32_e32 v151, s7, v1
	v_add_u32_e32 v152, s7, v2
	v_add_u32_e32 v153, s7, v3
	v_add_u32_e32 v154, s7, v5
	s_mov_b64 s[26:27], 0x40000
	v_add_u32_e32 v155, s7, v6
	s_mov_b64 s[28:29], 0x48000
	v_add_u32_e32 v156, s7, v7
	s_mov_b64 s[30:31], 0x50000
	v_add_u32_e32 v157, s7, v8
	s_mov_b64 s[34:35], 0x58000
	v_add_u32_e32 v158, s7, v0
	s_barrier
	s_branch .LBB0_1177

.LBB0_1188:
	ds_read_b128 v[140:143], v147
	ds_read_b128 v[160:163], v147 offset:1024
	ds_read_b128 v[164:167], v147 offset:2048
	ds_read_b128 v[168:171], v147 offset:3072
	ds_read_b128 v[172:175], v148
	ds_read_b128 v[176:179], v148 offset:1024
	ds_read_b128 v[180:183], v148 offset:2048
	ds_read_b128 v[184:187], v148 offset:3072
	s_add_u32 s40, s38, 0x100
	s_addc_u32 s41, s39, 0
	s_cmp_eq_u32 vcc_lo, 40
	s_cselect_b32 s72, s12, s40
	s_cselect_b32 s73, s13, s41
	s_cselect_b32 s70, s36, s60
	s_cselect_b32 s71, s37, s61
	s_add_u32 s42, s72, 0x80
	s_addc_u32 s43, s73, 0
	s_add_u32 s6, s38, 0xb0080
	s_addc_u32 s7, s39, 0
	ds_read_b128 v[188:191], v149
	ds_read_b128 v[192:195], v149 offset:1024
	ds_read_b128 v[196:199], v149 offset:2048
	ds_read_b128 v[200:203], v149 offset:3072
	ds_read_b128 v[204:207], v149 offset:4096
	ds_read_b128 v[208:211], v149 offset:5120
	ds_read_b128 v[212:215], v149 offset:6144
	ds_read_b128 v[216:219], v149 offset:7168
	s_add_i32 m0, s76, 0xc000
	s_nop 0
	global_load_lds_dwordx4 v128, s[6:7]
	s_add_i32 m0, s76, 0xe000
	s_nop 0
	global_load_lds_dwordx4 v132, s[6:7]
	s_waitcnt vmcnt(8)
	s_waitcnt lgkmcnt(0)
	s_barrier
	s_setprio 1
	s_waitcnt lgkmcnt(0)
	v_mfma_f32_16x16x32_bf16 v[124:127], v[140:143], v[188:191], v[124:127]
	v_mfma_f32_16x16x32_bf16 v[120:123], v[164:167], v[188:191], v[120:123]
	v_mfma_f32_16x16x32_bf16 v[108:111], v[140:143], v[196:199], v[108:111]
	v_mfma_f32_16x16x32_bf16 v[104:107], v[164:167], v[196:199], v[104:107]
	v_mfma_f32_16x16x32_bf16 v[92:95], v[140:143], v[204:207], v[92:95]
	v_mfma_f32_16x16x32_bf16 v[88:91], v[164:167], v[204:207], v[88:91]
	v_mfma_f32_16x16x32_bf16 v[76:79], v[140:143], v[212:215], v[76:79]
	v_mfma_f32_16x16x32_bf16 v[72:75], v[164:167], v[212:215], v[72:75]
	v_mfma_f32_16x16x32_bf16 v[124:127], v[160:163], v[192:195], v[124:127]
	v_mfma_f32_16x16x32_bf16 v[120:123], v[168:171], v[192:195], v[120:123]
	v_mfma_f32_16x16x32_bf16 v[108:111], v[160:163], v[200:203], v[108:111]
	v_mfma_f32_16x16x32_bf16 v[104:107], v[168:171], v[200:203], v[104:107]
	v_mfma_f32_16x16x32_bf16 v[92:95], v[160:163], v[208:211], v[92:95]
	v_mfma_f32_16x16x32_bf16 v[88:91], v[168:171], v[208:211], v[88:91]
	v_mfma_f32_16x16x32_bf16 v[76:79], v[160:163], v[216:219], v[76:79]
	v_mfma_f32_16x16x32_bf16 v[72:75], v[168:171], v[216:219], v[72:75]
	s_setprio 0
	s_setprio 1
	v_mfma_f32_16x16x32_bf16 v[116:119], v[172:175], v[188:191], v[116:119]
	v_mfma_f32_16x16x32_bf16 v[112:115], v[180:183], v[188:191], v[112:115]
	v_mfma_f32_16x16x32_bf16 v[100:103], v[172:175], v[196:199], v[100:103]
	v_mfma_f32_16x16x32_bf16 v[96:99], v[180:183], v[196:199], v[96:99]
	v_mfma_f32_16x16x32_bf16 v[84:87], v[172:175], v[204:207], v[84:87]
	v_mfma_f32_16x16x32_bf16 v[80:83], v[180:183], v[204:207], v[80:83]
	v_mfma_f32_16x16x32_bf16 v[68:71], v[172:175], v[212:215], v[68:71]
	v_mfma_f32_16x16x32_bf16 v[64:67], v[180:183], v[212:215], v[64:67]
	v_mfma_f32_16x16x32_bf16 v[116:119], v[176:179], v[192:195], v[116:119]
	v_mfma_f32_16x16x32_bf16 v[112:115], v[184:187], v[192:195], v[112:115]
	v_mfma_f32_16x16x32_bf16 v[100:103], v[176:179], v[200:203], v[100:103]
	v_mfma_f32_16x16x32_bf16 v[96:99], v[184:187], v[200:203], v[96:99]
	v_mfma_f32_16x16x32_bf16 v[84:87], v[176:179], v[208:211], v[84:87]
	v_mfma_f32_16x16x32_bf16 v[80:83], v[184:187], v[208:211], v[80:83]
	v_mfma_f32_16x16x32_bf16 v[68:71], v[176:179], v[216:219], v[68:71]
	v_mfma_f32_16x16x32_bf16 v[64:67], v[184:187], v[216:219], v[64:67]
	s_setprio 0
	s_barrier
	s_mov_b64 s[6:7], s[70:71]
	s_add_i32 s38, s93, s75
	ds_read_b128 v[188:191], v149 offset:16384
	ds_read_b128 v[192:195], v149 offset:17408
	ds_read_b128 v[196:199], v149 offset:18432
	ds_read_b128 v[200:203], v149 offset:19456
	ds_read_b128 v[204:207], v149 offset:20480
	ds_read_b128 v[208:211], v149 offset:21504
	ds_read_b128 v[212:215], v149 offset:22528
	ds_read_b128 v[216:219], v149 offset:23552
	s_mov_b32 m0, s38
	s_nop 0
	global_load_lds_dwordx4 v130, s[6:7]
	s_add_i32 m0, s38, 0x2000
	s_nop 0
	global_load_lds_dwordx4 v134, s[6:7]
	s_add_u32 s6, s70, 0xb0000
	s_addc_u32 s7, s71, 0
	s_add_i32 s38, s94, s75
	s_mov_b32 m0, s38
	s_nop 0
	global_load_lds_dwordx4 v130, s[6:7]
	s_mov_b64 s[98:99], s[6:7]
	s_add_i32 m0, s38, 0x2000
	s_mov_b64 s[6:7], s[72:73]
	global_load_lds_dwordx4 v134, s[98:99]
	s_mov_b32 m0, s76
	s_nop 0
	global_load_lds_dwordx4 v128, s[6:7]
	s_mov_b32 m0, s77
	s_nop 0
	global_load_lds_dwordx4 v132, s[6:7]
	s_waitcnt vmcnt(8)
	s_waitcnt lgkmcnt(0)
	s_barrier
	s_setprio 1
	s_waitcnt lgkmcnt(0)
	v_mfma_f32_16x16x32_bf16 v[60:63], v[140:143], v[188:191], v[60:63]
	v_mfma_f32_16x16x32_bf16 v[56:59], v[164:167], v[188:191], v[56:59]
	v_mfma_f32_16x16x32_bf16 v[44:47], v[140:143], v[196:199], v[44:47]
	v_mfma_f32_16x16x32_bf16 v[40:43], v[164:167], v[196:199], v[40:43]
	v_mfma_f32_16x16x32_bf16 v[28:31], v[140:143], v[204:207], v[28:31]
	v_mfma_f32_16x16x32_bf16 v[24:27], v[164:167], v[204:207], v[24:27]
	v_mfma_f32_16x16x32_bf16 v[12:15], v[140:143], v[212:215], v[12:15]
	v_mfma_f32_16x16x32_bf16 v[8:11], v[164:167], v[212:215], v[8:11]
	v_mfma_f32_16x16x32_bf16 v[60:63], v[160:163], v[192:195], v[60:63]
	v_mfma_f32_16x16x32_bf16 v[56:59], v[168:171], v[192:195], v[56:59]
	v_mfma_f32_16x16x32_bf16 v[44:47], v[160:163], v[200:203], v[44:47]
	v_mfma_f32_16x16x32_bf16 v[40:43], v[168:171], v[200:203], v[40:43]
	v_mfma_f32_16x16x32_bf16 v[28:31], v[160:163], v[208:211], v[28:31]
	v_mfma_f32_16x16x32_bf16 v[24:27], v[168:171], v[208:211], v[24:27]
	v_mfma_f32_16x16x32_bf16 v[12:15], v[160:163], v[216:219], v[12:15]
	v_mfma_f32_16x16x32_bf16 v[8:11], v[168:171], v[216:219], v[8:11]
	s_setprio 0
	s_setprio 1
	v_mfma_f32_16x16x32_bf16 v[52:55], v[172:175], v[188:191], v[52:55]
	v_mfma_f32_16x16x32_bf16 v[48:51], v[180:183], v[188:191], v[48:51]
	v_mfma_f32_16x16x32_bf16 v[36:39], v[172:175], v[196:199], v[36:39]
	v_mfma_f32_16x16x32_bf16 v[32:35], v[180:183], v[196:199], v[32:35]
	v_mfma_f32_16x16x32_bf16 v[20:23], v[172:175], v[204:207], v[20:23]
	v_mfma_f32_16x16x32_bf16 v[16:19], v[180:183], v[204:207], v[16:19]
	v_mfma_f32_16x16x32_bf16 v[4:7], v[172:175], v[212:215], v[4:7]
	v_mfma_f32_16x16x32_bf16 v[0:3], v[180:183], v[212:215], v[0:3]
	v_mfma_f32_16x16x32_bf16 v[52:55], v[176:179], v[192:195], v[52:55]
	v_mfma_f32_16x16x32_bf16 v[48:51], v[184:187], v[192:195], v[48:51]
	v_mfma_f32_16x16x32_bf16 v[36:39], v[176:179], v[200:203], v[36:39]
	v_mfma_f32_16x16x32_bf16 v[32:35], v[184:187], v[200:203], v[32:35]
	v_mfma_f32_16x16x32_bf16 v[20:23], v[176:179], v[208:211], v[20:23]
	v_mfma_f32_16x16x32_bf16 v[16:19], v[184:187], v[208:211], v[16:19]
	v_mfma_f32_16x16x32_bf16 v[4:7], v[176:179], v[216:219], v[4:7]
	v_mfma_f32_16x16x32_bf16 v[0:3], v[184:187], v[216:219], v[0:3]
	s_setprio 0
	s_barrier
	s_add_i32 s38, 0, 0x18000
	v_add_u32_e32 v159, s38, v145
	s_add_i32 s39, 0, 0x1c000
	ds_read_b128 v[140:143], v159
	ds_read_b128 v[160:163], v159 offset:1024
	ds_read_b128 v[164:167], v159 offset:2048
	ds_read_b128 v[168:171], v159 offset:3072
	v_add_u32_e32 v159, s39, v145
	ds_read_b128 v[172:175], v159
	ds_read_b128 v[176:179], v159 offset:1024
	ds_read_b128 v[180:183], v159 offset:2048
	ds_read_b128 v[184:187], v159 offset:3072
	s_add_u32 s6, s72, 0xb0000
	s_addc_u32 s7, s73, 0
	s_mov_b32 m0, s78
	ds_read_b128 v[188:191], v149 offset:32768
	ds_read_b128 v[192:195], v149 offset:33792
	ds_read_b128 v[196:199], v149 offset:34816
	ds_read_b128 v[200:203], v149 offset:35840
	ds_read_b128 v[204:207], v149 offset:36864
	ds_read_b128 v[208:211], v149 offset:37888
	ds_read_b128 v[212:215], v149 offset:38912
	ds_read_b128 v[216:219], v149 offset:39936
	s_nop 0
	global_load_lds_dwordx4 v128, s[6:7]
	s_mov_b32 m0, s79
	s_nop 0
	global_load_lds_dwordx4 v132, s[6:7]
	s_waitcnt vmcnt(8)
	s_waitcnt lgkmcnt(0)
	s_barrier
	s_setprio 1
	s_waitcnt lgkmcnt(0)
	v_mfma_f32_16x16x32_bf16 v[124:127], v[140:143], v[188:191], v[124:127]
	v_mfma_f32_16x16x32_bf16 v[120:123], v[164:167], v[188:191], v[120:123]
	v_mfma_f32_16x16x32_bf16 v[108:111], v[140:143], v[196:199], v[108:111]
	v_mfma_f32_16x16x32_bf16 v[104:107], v[164:167], v[196:199], v[104:107]
	v_mfma_f32_16x16x32_bf16 v[92:95], v[140:143], v[204:207], v[92:95]
	v_mfma_f32_16x16x32_bf16 v[88:91], v[164:167], v[204:207], v[88:91]
	v_mfma_f32_16x16x32_bf16 v[76:79], v[140:143], v[212:215], v[76:79]
	v_mfma_f32_16x16x32_bf16 v[72:75], v[164:167], v[212:215], v[72:75]
	v_mfma_f32_16x16x32_bf16 v[124:127], v[160:163], v[192:195], v[124:127]
	v_mfma_f32_16x16x32_bf16 v[120:123], v[168:171], v[192:195], v[120:123]
	v_mfma_f32_16x16x32_bf16 v[108:111], v[160:163], v[200:203], v[108:111]
	v_mfma_f32_16x16x32_bf16 v[104:107], v[168:171], v[200:203], v[104:107]
	v_mfma_f32_16x16x32_bf16 v[92:95], v[160:163], v[208:211], v[92:95]
	v_mfma_f32_16x16x32_bf16 v[88:91], v[168:171], v[208:211], v[88:91]
	v_mfma_f32_16x16x32_bf16 v[76:79], v[160:163], v[216:219], v[76:79]
	v_mfma_f32_16x16x32_bf16 v[72:75], v[168:171], v[216:219], v[72:75]
	s_setprio 0
	s_setprio 1
	v_mfma_f32_16x16x32_bf16 v[116:119], v[172:175], v[188:191], v[116:119]
	v_mfma_f32_16x16x32_bf16 v[112:115], v[180:183], v[188:191], v[112:115]
	v_mfma_f32_16x16x32_bf16 v[100:103], v[172:175], v[196:199], v[100:103]
	v_mfma_f32_16x16x32_bf16 v[96:99], v[180:183], v[196:199], v[96:99]
	v_mfma_f32_16x16x32_bf16 v[84:87], v[172:175], v[204:207], v[84:87]
	v_mfma_f32_16x16x32_bf16 v[80:83], v[180:183], v[204:207], v[80:83]
	v_mfma_f32_16x16x32_bf16 v[68:71], v[172:175], v[212:215], v[68:71]
	v_mfma_f32_16x16x32_bf16 v[64:67], v[180:183], v[212:215], v[64:67]
	v_mfma_f32_16x16x32_bf16 v[116:119], v[176:179], v[192:195], v[116:119]
	v_mfma_f32_16x16x32_bf16 v[112:115], v[184:187], v[192:195], v[112:115]
	v_mfma_f32_16x16x32_bf16 v[100:103], v[176:179], v[200:203], v[100:103]
	v_mfma_f32_16x16x32_bf16 v[96:99], v[184:187], v[200:203], v[96:99]
	v_mfma_f32_16x16x32_bf16 v[84:87], v[176:179], v[208:211], v[84:87]
	v_mfma_f32_16x16x32_bf16 v[80:83], v[184:187], v[208:211], v[80:83]
	v_mfma_f32_16x16x32_bf16 v[68:71], v[176:179], v[216:219], v[68:71]
	v_mfma_f32_16x16x32_bf16 v[64:67], v[184:187], v[216:219], v[64:67]
	s_setprio 0
	s_barrier
	s_add_u32 s6, s70, 0x80
	s_addc_u32 s7, s71, 0
	s_add_i32 s38, s38, s75
	ds_read_b128 v[188:191], v149 offset:49152
	ds_read_b128 v[192:195], v149 offset:50176
	ds_read_b128 v[196:199], v149 offset:51200
	ds_read_b128 v[200:203], v149 offset:52224
	ds_read_b128 v[204:207], v149 offset:53248
	ds_read_b128 v[208:211], v149 offset:54272
	ds_read_b128 v[212:215], v149 offset:55296
	ds_read_b128 v[216:219], v149 offset:56320
	s_mov_b32 m0, s38
	s_nop 0
	global_load_lds_dwordx4 v130, s[6:7]
	s_add_i32 m0, s38, 0x2000
	s_nop 0
	global_load_lds_dwordx4 v134, s[6:7]
	s_add_u32 s6, s70, 0xb0080
	s_addc_u32 s7, s71, 0
	s_add_i32 s38, s39, s75
	s_mov_b32 m0, s38
	s_nop 0
	global_load_lds_dwordx4 v130, s[6:7]
	s_add_i32 m0, s38, 0x2000
	s_nop 0
	global_load_lds_dwordx4 v134, s[6:7]
	s_mov_b32 m0, s88
	s_nop 0
	global_load_lds_dwordx4 v128, s[42:43]
	s_mov_b32 m0, s89
	s_nop 0
	global_load_lds_dwordx4 v132, s[42:43]
	s_waitcnt vmcnt(8)
	s_waitcnt lgkmcnt(0)
	s_barrier
	s_setprio 1
	s_waitcnt lgkmcnt(0)
	v_mfma_f32_16x16x32_bf16 v[60:63], v[140:143], v[188:191], v[60:63]
	v_mfma_f32_16x16x32_bf16 v[56:59], v[164:167], v[188:191], v[56:59]
	v_mfma_f32_16x16x32_bf16 v[44:47], v[140:143], v[196:199], v[44:47]
	v_mfma_f32_16x16x32_bf16 v[40:43], v[164:167], v[196:199], v[40:43]
	v_mfma_f32_16x16x32_bf16 v[28:31], v[140:143], v[204:207], v[28:31]
	v_mfma_f32_16x16x32_bf16 v[24:27], v[164:167], v[204:207], v[24:27]
	v_mfma_f32_16x16x32_bf16 v[12:15], v[140:143], v[212:215], v[12:15]
	v_mfma_f32_16x16x32_bf16 v[8:11], v[164:167], v[212:215], v[8:11]
	v_mfma_f32_16x16x32_bf16 v[60:63], v[160:163], v[192:195], v[60:63]
	v_mfma_f32_16x16x32_bf16 v[56:59], v[168:171], v[192:195], v[56:59]
	v_mfma_f32_16x16x32_bf16 v[44:47], v[160:163], v[200:203], v[44:47]
	v_mfma_f32_16x16x32_bf16 v[40:43], v[168:171], v[200:203], v[40:43]
	v_mfma_f32_16x16x32_bf16 v[28:31], v[160:163], v[208:211], v[28:31]
	v_mfma_f32_16x16x32_bf16 v[24:27], v[168:171], v[208:211], v[24:27]
	v_mfma_f32_16x16x32_bf16 v[12:15], v[160:163], v[216:219], v[12:15]
	v_mfma_f32_16x16x32_bf16 v[8:11], v[168:171], v[216:219], v[8:11]
	s_setprio 0
	s_setprio 1
	v_mfma_f32_16x16x32_bf16 v[52:55], v[172:175], v[188:191], v[52:55]
	v_mfma_f32_16x16x32_bf16 v[48:51], v[180:183], v[188:191], v[48:51]
	v_mfma_f32_16x16x32_bf16 v[36:39], v[172:175], v[196:199], v[36:39]
	v_mfma_f32_16x16x32_bf16 v[32:35], v[180:183], v[196:199], v[32:35]
	v_mfma_f32_16x16x32_bf16 v[20:23], v[172:175], v[204:207], v[20:23]
	v_mfma_f32_16x16x32_bf16 v[16:19], v[180:183], v[204:207], v[16:19]
	v_mfma_f32_16x16x32_bf16 v[4:7], v[172:175], v[212:215], v[4:7]
	v_mfma_f32_16x16x32_bf16 v[0:3], v[180:183], v[212:215], v[0:3]
	v_mfma_f32_16x16x32_bf16 v[52:55], v[176:179], v[192:195], v[52:55]
	v_mfma_f32_16x16x32_bf16 v[48:51], v[184:187], v[192:195], v[48:51]
	v_mfma_f32_16x16x32_bf16 v[36:39], v[176:179], v[200:203], v[36:39]
	v_mfma_f32_16x16x32_bf16 v[32:35], v[184:187], v[200:203], v[32:35]
	v_mfma_f32_16x16x32_bf16 v[20:23], v[176:179], v[208:211], v[20:23]
	v_mfma_f32_16x16x32_bf16 v[16:19], v[184:187], v[208:211], v[16:19]
	v_mfma_f32_16x16x32_bf16 v[4:7], v[176:179], v[216:219], v[4:7]
	v_mfma_f32_16x16x32_bf16 v[0:3], v[184:187], v[216:219], v[0:3]
	s_setprio 0
	s_barrier
	s_add_i32 vcc_lo, vcc_lo, 2
	s_add_u32 s60, s60, 0x100
	s_addc_u32 s61, s61, 0
	s_cmp_gt_u32 vcc_lo, 41
	s_mov_b64 s[38:39], s[40:41]
	s_cbranch_scc0 .LBB0_1188
	s_and_b64 vcc, exec, s[22:23]
	s_cbranch_vccz .LBB0_1191
	s_barrier

; #define PG8_STAGE(bufoff, gbase, voff) do { const char* gb_ = (const char*)(gbase); asm volatile("" : "+s"(gb_));   \
;         _Pragma("unroll") for (int _i = 0; _i < 2; ++_i) \
;         __builtin_amdgcn_global_load_lds((const unsigned*)(gb_ + (voff)[_i]), (PG8_LAS unsigned*)(lds + (bufoff) + ldsw + _i * 8192), 16, 0, 0); } while (0)
; #define PG8_WAIT_V(n) asm volatile("s_waitcnt vmcnt(" #n ")" ::: "memory")
; #define PG8_WAIT_V8_RELAX() do { if constexpr (Epi::NSTORES + Epi::NPRE == 10) asm volatile("s_waitcnt vmcnt(18)" ::: "memory"); else if constexpr (Epi::NSTORES + Epi::NPRE == 18) asm volatile("s_waitcnt vmcnt(26)" ::: "memory"); else asm volatile("s_waitcnt vmcnt(8)" ::: "memory"); } while (0)
; #define PG8_BAR __builtin_amdgcn_s_barrier()
; template <class Epi, class Sched, bool ALIGN_EPI = false, bool SP2 = false>
; __device__ __forceinline__ void gemm_phase(PG8_LAS unsigned char* lds, const Gemm g, const Sched& S, const Epi& E, int wave_s) {
;     ...
;         PG8_STAGE(PG8_SB(0, 0), cB, voffB); PG8_STAGE(PG8_SB(0, 1), cB + hstep, voffB); PG8_STAGE(PG8_SA(0, 0), cA, voffA); PG8_STAGE(PG8_SA(0, 1), cA + hstep, voffA);
;         if (wr == 1) PG8_BAR;
;         PG8_WAIT_V(2); PG8_BAR;
;         PG8_STAGE(PG8_SB(1, 0), cB + kstep, voffB); PG8_STAGE(PG8_SA(1, 0), cA + kstep, voffA); PG8_STAGE(PG8_SB(1, 1), cB + hstep + kstep, voffB);
;         PG8_WAIT_V(6); PG8_BAR;
;     ...
;         cur = nxt; cA = nA; cB = nB; ++ui;
;         if constexpr (ALIGN_EPI) { if (wr == 1) PG8_BAR; }
;         if constexpr (Epi::NPRE > 0) E.prefetch(lds, wid, cur, wr, fr, fq);
;         if constexpr (SP2 && Epi::NSTORES > 0 && !Epi::AFTER_DRAIN) {
;             const char* a1 = cA + kstep; const char* a2 = cA + 2 * kstep; const char* b2 = cB + 2 * kstep; const char* a3 = a2 + kstep; const char* b3 = b2 + kstep;
;             PG8_SP2_PAIR(PG8_WAIT_V8_RELAX);
.LBB0_1272:
	s_lshl_b32 s7, s7, 5
	s_and_b32 s7, s7, 0x60
	s_lshl_b32 s9, s22, 13
	s_lshl_b32 s26, s7, 7
	s_add_u32 s22, s36, 0x80
	s_addc_u32 s23, s37, 0
	s_waitcnt vmcnt(2)
	s_barrier
	s_add_i32 m0, s77, 0x18000
	s_nop 0
	global_load_lds_dwordx4 v136, s[22:23]
	s_add_i32 m0, s77, 0x1a000
	s_nop 0
	global_load_lds_dwordx4 v132, s[22:23]
	s_add_u32 s22, s38, 0x80
	s_addc_u32 s23, s39, 0
	s_add_i32 s87, s77, 0x8000
	s_mov_b32 m0, s87
	s_add_i32 s88, s77, 0xa000
	global_load_lds_dwordx4 v138, s[22:23]
	s_mov_b64 s[98:99], s[22:23]
	s_add_u32 s22, s36, 0x40080
	s_mov_b32 m0, s88
	s_addc_u32 s23, s37, 0
	global_load_lds_dwordx4 v134, s[98:99]
	s_add_i32 m0, s77, 0x1c000
	s_nop 0
	global_load_lds_dwordx4 v136, s[22:23]
	s_add_i32 m0, s77, 0x1e000
	v_and_b32_e32 v0, 15, v2
	global_load_lds_dwordx4 v132, s[22:23]
	v_lshrrev_b32_e32 v2, 1, v2
	v_or_b32_e32 v144, s8, v0
	v_and_b32_e32 v2, 24, v2
	v_lshlrev_b32_e32 v3, 6, v144
	v_lshlrev_b32_e32 v4, 1, v2
	s_movk_i32 s8, 0x3c0
	v_lshlrev_b32_e32 v5, 2, v144
	v_and_or_b32 v3, v3, s8, v4
	v_and_b32_e32 v5, 32, v5
	v_lshlrev_b32_e32 v145, 2, v0
	v_bitop3_b32 v5, v3, s9, v5 bitop3:0xde
	v_lshl_or_b32 v3, v0, 6, v4
	v_and_b32_e32 v0, 32, v145
	v_bitop3_b32 v146, v3, s26, v0 bitop3:0xde
	s_waitcnt vmcnt(6)
	s_cmpk_lt_u32 s6, 0x100
	v_or_b32_e32 v147, s7, v2
	v_mov_b32_e32 v2, v1
	v_mov_b32_e32 v3, v1
	s_cselect_b64 s[22:23], -1, 0
	s_add_u32 s63, s63, s24
	v_mov_b32_e32 v0, v1
	v_add_u32_e32 v149, 0, v5
	v_mov_b64_e32 v[10:11], v[2:3]
	v_mov_b64_e32 v[18:19], v[2:3]
	v_mov_b64_e32 v[26:27], v[2:3]
	v_mov_b64_e32 v[34:35], v[2:3]
	v_mov_b64_e32 v[42:43], v[2:3]
	v_mov_b64_e32 v[50:51], v[2:3]
	v_mov_b64_e32 v[58:59], v[2:3]
	v_mov_b64_e32 v[74:75], v[2:3]
	v_mov_b64_e32 v[6:7], v[2:3]
	v_mov_b64_e32 v[14:15], v[2:3]
	v_mov_b64_e32 v[22:23], v[2:3]
	v_mov_b64_e32 v[30:31], v[2:3]
	v_mov_b64_e32 v[38:39], v[2:3]
	v_mov_b64_e32 v[46:47], v[2:3]
	v_mov_b64_e32 v[54:55], v[2:3]
	v_mov_b64_e32 v[66:67], v[2:3]
	v_mov_b64_e32 v[70:71], v[2:3]
	v_mov_b64_e32 v[82:83], v[2:3]
	v_mov_b64_e32 v[90:91], v[2:3]
	v_mov_b64_e32 v[98:99], v[2:3]
	v_mov_b64_e32 v[106:107], v[2:3]
	v_mov_b64_e32 v[114:115], v[2:3]
	v_mov_b64_e32 v[122:123], v[2:3]
	v_mov_b64_e32 v[130:131], v[2:3]
	v_mov_b64_e32 v[62:63], v[2:3]
	v_mov_b64_e32 v[78:79], v[2:3]
	v_mov_b64_e32 v[86:87], v[2:3]
	v_mov_b64_e32 v[94:95], v[2:3]
	v_mov_b64_e32 v[102:103], v[2:3]
	v_mov_b64_e32 v[110:111], v[2:3]
	v_mov_b64_e32 v[118:119], v[2:3]
	v_mov_b64_e32 v[126:127], v[2:3]
	s_sext_i32_i16 s35, s12
	s_mov_b32 s89, s46
	s_addc_u32 s74, s74, s25
	v_mov_b64_e32 v[140:141], 0x580
	v_mov_b64_e32 v[142:143], 0x57f
	s_add_i32 s90, 0, 0x10000
	s_add_i32 s91, 0, 0x14000
	s_movk_i32 s92, 0x1600
	v_mov_b32_e32 v148, 0x358637bd
	v_mov_b64_e32 v[8:9], v[0:1]
	v_mov_b64_e32 v[16:17], v[0:1]
	v_mov_b64_e32 v[24:25], v[0:1]
	v_mov_b64_e32 v[32:33], v[0:1]
	v_mov_b64_e32 v[40:41], v[0:1]
	v_mov_b64_e32 v[48:49], v[0:1]
	v_mov_b64_e32 v[56:57], v[0:1]
	v_mov_b64_e32 v[72:73], v[0:1]
	v_mov_b64_e32 v[4:5], v[0:1]
	v_mov_b64_e32 v[12:13], v[0:1]
	v_mov_b64_e32 v[20:21], v[0:1]
	v_mov_b64_e32 v[28:29], v[0:1]
	v_mov_b64_e32 v[36:37], v[0:1]
	v_mov_b64_e32 v[44:45], v[0:1]
	v_mov_b64_e32 v[52:53], v[0:1]
	v_mov_b64_e32 v[64:65], v[0:1]
	v_mov_b64_e32 v[68:69], v[0:1]
	v_mov_b64_e32 v[80:81], v[0:1]
	v_mov_b64_e32 v[88:89], v[0:1]
	v_mov_b64_e32 v[96:97], v[0:1]
	v_mov_b64_e32 v[104:105], v[0:1]
	v_mov_b64_e32 v[112:113], v[0:1]
	v_mov_b64_e32 v[120:121], v[0:1]
	v_mov_b64_e32 v[128:129], v[0:1]
	v_mov_b64_e32 v[60:61], v[0:1]
	v_mov_b64_e32 v[76:77], v[0:1]
	v_mov_b64_e32 v[84:85], v[0:1]
	v_mov_b64_e32 v[92:93], v[0:1]
	v_mov_b64_e32 v[100:101], v[0:1]
	v_mov_b64_e32 v[108:109], v[0:1]
	v_mov_b64_e32 v[116:117], v[0:1]
	v_mov_b64_e32 v[124:125], v[0:1]
	s_mov_b32 s12, s13
	s_mov_b32 s93, s13
	s_barrier
	s_branch .LBB0_1275
.LBB0_1273:
	s_lshl_b32 s6, s26, 8
	s_ashr_i32 s7, s6, 31
	s_lshl_b64 s[6:7], s[6:7], 2
	v_mbcnt_lo_u32_b32 v6, -1, 0
	v_mbcnt_hi_u32_b32 v6, -1, v6
	s_add_u32 s6, s63, s6
	v_and_b32_e32 v0, 15, v6
	v_lshlrev_b32_e32 v2, 2, v6
	v_and_b32_e32 v2, 0xffffff80, v2
	s_addc_u32 s7, s74, s7
	v_lshlrev_b32_e32 v0, 2, v0
	v_ashrrev_i32_e32 v3, 31, v2
	v_lshl_add_u64 v[4:5], s[6:7], 0, v[0:1]
	v_lshlrev_b32_e32 v0, 3, v6
	v_lshl_add_u64 v[2:3], v[2:3], 2, v[4:5]
	v_and_b32_e32 v0, 0x80, v0
	s_mov_b32 m0, s76
	v_lshl_add_u64 v[2:3], v[2:3], 0, v[0:1]
	global_load_lds_dword v[2:3], off
	v_lshl_add_u64 v[2:3], v[2:3], 0, 64
	s_add_i32 m0, s76, 0x100
	s_add_u32 s34, s28, 0x100
	global_load_lds_dword v[2:3], off
	ds_read_b128 v[2:5], v151
	ds_read_b128 v[6:9], v151 offset:1024
	ds_read_b128 v[10:13], v151 offset:2048
	ds_read_b128 v[14:17], v151 offset:3072
	ds_read_b128 v[18:21], v150
	ds_read_b128 v[22:25], v150 offset:1024
	ds_read_b128 v[26:29], v150 offset:2048
	ds_read_b128 v[30:33], v150 offset:3072
	s_addc_u32 s35, s29, 0
	s_add_u32 s8, s28, 0x180
	s_addc_u32 s9, s29, 0
	s_add_u32 s6, s30, 0x100
	s_addc_u32 s7, s31, 0
	s_add_u32 s36, s28, 0x40080
	s_addc_u32 s37, s29, 0
	s_mov_b32 m0, s94
	ds_read_b128 v[34:37], v149
	ds_read_b128 v[38:41], v149 offset:1024
	ds_read_b128 v[42:45], v149 offset:2048
	ds_read_b128 v[46:49], v149 offset:3072
	ds_read_b128 v[50:53], v149 offset:4096
	ds_read_b128 v[54:57], v149 offset:5120
	ds_read_b128 v[58:61], v149 offset:6144
	ds_read_b128 v[62:65], v149 offset:7168
	s_nop 0
	global_load_lds_dwordx4 v138, s[36:37]
	s_mov_b32 m0, s12
	s_nop 0
	global_load_lds_dwordx4 v134, s[36:37]
	s_waitcnt vmcnt(18)
	s_waitcnt lgkmcnt(0)
	s_barrier
	s_setprio 1
	s_waitcnt lgkmcnt(0)
	v_mfma_f32_16x16x32_bf16 v[90:93], v[2:5], v[58:61], 0
	v_mfma_f32_16x16x32_bf16 v[66:69], v[2:5], v[34:37], 0
	v_mfma_f32_16x16x32_bf16 v[70:73], v[10:13], v[34:37], 0
	v_mfma_f32_16x16x32_bf16 v[74:77], v[2:5], v[42:45], 0
	v_mfma_f32_16x16x32_bf16 v[78:81], v[10:13], v[42:45], 0
	v_mfma_f32_16x16x32_bf16 v[82:85], v[2:5], v[50:53], 0
	v_mfma_f32_16x16x32_bf16 v[86:89], v[10:13], v[50:53], 0
	v_mfma_f32_16x16x32_bf16 v[96:99], v[6:9], v[62:65], v[90:93]
	v_mfma_f32_16x16x32_bf16 v[90:93], v[10:13], v[58:61], 0
	v_mfma_f32_16x16x32_bf16 v[66:69], v[6:9], v[38:41], v[66:69]
	v_mfma_f32_16x16x32_bf16 v[70:73], v[14:17], v[38:41], v[70:73]
	v_mfma_f32_16x16x32_bf16 v[74:77], v[6:9], v[46:49], v[74:77]
	v_mfma_f32_16x16x32_bf16 v[78:81], v[14:17], v[46:49], v[78:81]
	v_mfma_f32_16x16x32_bf16 v[82:85], v[6:9], v[54:57], v[82:85]
	v_mfma_f32_16x16x32_bf16 v[86:89], v[14:17], v[54:57], v[86:89]
	v_mfma_f32_16x16x32_bf16 v[104:107], v[14:17], v[62:65], v[90:93]
	s_setprio 0
	s_setprio 1
	v_mfma_f32_16x16x32_bf16 v[90:93], v[18:21], v[34:37], 0
	v_mfma_f32_16x16x32_bf16 v[34:37], v[26:29], v[34:37], 0
	v_mfma_f32_16x16x32_bf16 v[112:115], v[22:25], v[38:41], v[90:93]
	v_mfma_f32_16x16x32_bf16 v[34:37], v[30:33], v[38:41], v[34:37]
	v_mfma_f32_16x16x32_bf16 v[38:41], v[18:21], v[42:45], 0
	v_mfma_f32_16x16x32_bf16 v[42:45], v[26:29], v[42:45], 0
	v_mfma_f32_16x16x32_bf16 v[38:41], v[22:25], v[46:49], v[38:41]
	v_mfma_f32_16x16x32_bf16 v[42:45], v[30:33], v[46:49], v[42:45]
	v_mfma_f32_16x16x32_bf16 v[46:49], v[18:21], v[50:53], 0
	v_mfma_f32_16x16x32_bf16 v[50:53], v[26:29], v[50:53], 0
	v_mfma_f32_16x16x32_bf16 v[46:49], v[22:25], v[54:57], v[46:49]
	v_mfma_f32_16x16x32_bf16 v[50:53], v[30:33], v[54:57], v[50:53]
	v_mfma_f32_16x16x32_bf16 v[54:57], v[18:21], v[58:61], 0
	v_mfma_f32_16x16x32_bf16 v[54:57], v[22:25], v[62:65], v[54:57]
	v_mfma_f32_16x16x32_bf16 v[58:61], v[26:29], v[58:61], 0
	v_mfma_f32_16x16x32_bf16 v[154:157], v[30:33], v[62:65], v[58:61]
	s_setprio 0
	s_barrier
	s_mov_b32 m0, s61
	s_nop 3
	ds_read_b128 v[58:61], v149 offset:16384
	ds_read_b128 v[62:65], v149 offset:17408
	ds_read_b128 v[90:93], v149 offset:18432
	ds_read_b128 v[100:103], v149 offset:19456
	ds_read_b128 v[108:111], v149 offset:20480
	ds_read_b128 v[116:119], v149 offset:21504
	ds_read_b128 v[120:123], v149 offset:22528
	ds_read_b128 v[124:127], v149 offset:23552
	s_nop 0
	global_load_lds_dwordx4 v136, s[6:7]
	s_mov_b64 s[98:99], s[6:7]
	s_add_u32 s6, s30, 0x40100
	s_mov_b32 m0, s25
	s_addc_u32 s7, s31, 0
	global_load_lds_dwordx4 v132, s[98:99]
	s_mov_b32 m0, s27
	s_nop 0
	global_load_lds_dwordx4 v136, s[6:7]
	s_mov_b32 m0, s60
	s_nop 0
	global_load_lds_dwordx4 v132, s[6:7]
	s_mov_b32 m0, s77
	s_nop 0
	global_load_lds_dwordx4 v138, s[34:35]
	s_mov_b32 m0, s78
	s_nop 0
	global_load_lds_dwordx4 v134, s[34:35]
	s_waitcnt vmcnt(18)
	s_waitcnt lgkmcnt(0)
	s_barrier
	s_setprio 1
	s_waitcnt lgkmcnt(0)
	v_mfma_f32_16x16x32_bf16 v[128:131], v[2:5], v[58:61], 0
	v_mfma_f32_16x16x32_bf16 v[158:161], v[6:9], v[62:65], v[128:131]
	v_mfma_f32_16x16x32_bf16 v[128:131], v[10:13], v[58:61], 0
	v_mfma_f32_16x16x32_bf16 v[162:165], v[14:17], v[62:65], v[128:131]
	v_mfma_f32_16x16x32_bf16 v[128:131], v[2:5], v[90:93], 0
	v_mfma_f32_16x16x32_bf16 v[166:169], v[6:9], v[100:103], v[128:131]
	v_mfma_f32_16x16x32_bf16 v[128:131], v[10:13], v[90:93], 0
	v_mfma_f32_16x16x32_bf16 v[170:173], v[14:17], v[100:103], v[128:131]
	v_mfma_f32_16x16x32_bf16 v[128:131], v[2:5], v[108:111], 0
	v_mfma_f32_16x16x32_bf16 v[2:5], v[2:5], v[120:123], 0
	v_mfma_f32_16x16x32_bf16 v[174:177], v[6:9], v[116:119], v[128:131]
	v_mfma_f32_16x16x32_bf16 v[2:5], v[6:9], v[124:127], v[2:5]
	v_mfma_f32_16x16x32_bf16 v[6:9], v[10:13], v[120:123], 0
	v_mfma_f32_16x16x32_bf16 v[128:131], v[10:13], v[108:111], 0
	v_mfma_f32_16x16x32_bf16 v[6:9], v[14:17], v[124:127], v[6:9]
	v_mfma_f32_16x16x32_bf16 v[178:181], v[14:17], v[116:119], v[128:131]
	s_setprio 0
	s_setprio 1
	v_mfma_f32_16x16x32_bf16 v[10:13], v[18:21], v[58:61], 0
	v_mfma_f32_16x16x32_bf16 v[182:185], v[22:25], v[62:65], v[10:13]
	v_mfma_f32_16x16x32_bf16 v[10:13], v[26:29], v[58:61], 0
	v_mfma_f32_16x16x32_bf16 v[186:189], v[30:33], v[62:65], v[10:13]
	v_mfma_f32_16x16x32_bf16 v[10:13], v[18:21], v[90:93], 0
	v_mfma_f32_16x16x32_bf16 v[190:193], v[22:25], v[100:103], v[10:13]
	v_mfma_f32_16x16x32_bf16 v[10:13], v[26:29], v[90:93], 0
	v_mfma_f32_16x16x32_bf16 v[194:197], v[30:33], v[100:103], v[10:13]
	v_mfma_f32_16x16x32_bf16 v[10:13], v[18:21], v[108:111], 0
	v_mfma_f32_16x16x32_bf16 v[198:201], v[22:25], v[116:119], v[10:13]
	v_mfma_f32_16x16x32_bf16 v[10:13], v[26:29], v[108:111], 0
	v_mfma_f32_16x16x32_bf16 v[202:205], v[30:33], v[116:119], v[10:13]
	v_mfma_f32_16x16x32_bf16 v[10:13], v[18:21], v[120:123], 0
	v_mfma_f32_16x16x32_bf16 v[16:19], v[22:25], v[124:127], v[10:13]
	v_mfma_f32_16x16x32_bf16 v[10:13], v[26:29], v[120:123], 0
	v_mfma_f32_16x16x32_bf16 v[206:209], v[30:33], v[124:127], v[10:13]
	s_setprio 0
	s_barrier
	s_nop 4
	ds_read_b128 v[10:13], v152
	ds_read_b128 v[24:27], v152 offset:1024
	ds_read_b128 v[210:213], v152 offset:2048
	ds_read_b128 v[214:217], v152 offset:3072
	ds_read_b128 v[218:221], v153
	ds_read_b128 v[222:225], v153 offset:1024
	ds_read_b128 v[226:229], v153 offset:2048
	ds_read_b128 v[150:153], v153 offset:3072
	s_add_u32 s6, s28, 0x40100
	s_addc_u32 s7, s29, 0
	s_mov_b32 m0, s79
	ds_read_b128 v[20:23], v149 offset:32768
	ds_read_b128 v[28:31], v149 offset:33792
	ds_read_b128 v[230:233], v149 offset:34816
	ds_read_b128 v[234:237], v149 offset:35840
	ds_read_b128 v[238:241], v149 offset:36864
	ds_read_b128 v[242:245], v149 offset:37888
	ds_read_b128 v[246:249], v149 offset:38912
	ds_read_b128 v[250:253], v149 offset:39936
	s_nop 0
	global_load_lds_dwordx4 v138, s[6:7]
	s_mov_b32 m0, s82
	s_nop 0
	global_load_lds_dwordx4 v134, s[6:7]
	s_waitcnt vmcnt(18)
	s_waitcnt lgkmcnt(0)
	s_barrier
	s_setprio 1
	s_waitcnt lgkmcnt(0)
	v_mfma_f32_16x16x32_bf16 v[58:61], v[10:13], v[20:23], v[66:69]
	v_mfma_f32_16x16x32_bf16 v[124:127], v[24:27], v[28:31], v[58:61]
	v_mfma_f32_16x16x32_bf16 v[58:61], v[210:213], v[20:23], v[70:73]
	v_mfma_f32_16x16x32_bf16 v[116:119], v[214:217], v[28:31], v[58:61]
	v_mfma_f32_16x16x32_bf16 v[58:61], v[10:13], v[230:233], v[74:77]
	v_mfma_f32_16x16x32_bf16 v[108:111], v[24:27], v[234:237], v[58:61]
	v_mfma_f32_16x16x32_bf16 v[58:61], v[210:213], v[230:233], v[78:81]
	v_mfma_f32_16x16x32_bf16 v[100:103], v[214:217], v[234:237], v[58:61]
	v_mfma_f32_16x16x32_bf16 v[58:61], v[10:13], v[238:241], v[82:85]
	v_mfma_f32_16x16x32_bf16 v[92:95], v[24:27], v[242:245], v[58:61]
	v_mfma_f32_16x16x32_bf16 v[58:61], v[210:213], v[238:241], v[86:89]
	v_mfma_f32_16x16x32_bf16 v[84:87], v[214:217], v[242:245], v[58:61]
	v_mfma_f32_16x16x32_bf16 v[58:61], v[10:13], v[246:249], v[96:99]
	v_mfma_f32_16x16x32_bf16 v[76:79], v[24:27], v[250:253], v[58:61]
	v_mfma_f32_16x16x32_bf16 v[58:61], v[210:213], v[246:249], v[104:107]
	v_mfma_f32_16x16x32_bf16 v[60:63], v[214:217], v[250:253], v[58:61]
	s_setprio 0
	s_setprio 1
	v_mfma_f32_16x16x32_bf16 v[64:67], v[218:221], v[20:23], v[112:115]
	v_mfma_f32_16x16x32_bf16 v[20:23], v[226:229], v[20:23], v[34:37]
	v_mfma_f32_16x16x32_bf16 v[120:123], v[150:153], v[28:31], v[20:23]
	v_mfma_f32_16x16x32_bf16 v[20:23], v[218:221], v[230:233], v[38:41]
	v_mfma_f32_16x16x32_bf16 v[112:115], v[222:225], v[234:237], v[20:23]
	v_mfma_f32_16x16x32_bf16 v[20:23], v[226:229], v[230:233], v[42:45]
	v_mfma_f32_16x16x32_bf16 v[104:107], v[150:153], v[234:237], v[20:23]
	v_mfma_f32_16x16x32_bf16 v[20:23], v[218:221], v[238:241], v[46:49]
	v_mfma_f32_16x16x32_bf16 v[96:99], v[222:225], v[242:245], v[20:23]
	v_mfma_f32_16x16x32_bf16 v[20:23], v[226:229], v[238:241], v[50:53]
	v_mfma_f32_16x16x32_bf16 v[88:91], v[150:153], v[242:245], v[20:23]
	v_mfma_f32_16x16x32_bf16 v[20:23], v[218:221], v[246:249], v[54:57]
	v_mfma_f32_16x16x32_bf16 v[80:83], v[222:225], v[250:253], v[20:23]
	v_mfma_f32_16x16x32_bf16 v[20:23], v[226:229], v[246:249], v[154:157]
	v_mfma_f32_16x16x32_bf16 v[128:131], v[222:225], v[28:31], v[64:67]
	v_mfma_f32_16x16x32_bf16 v[68:71], v[150:153], v[250:253], v[20:23]
	s_setprio 0
	s_barrier
	s_add_u32 s6, s30, 0x180
	s_addc_u32 s7, s31, 0
	s_mov_b32 m0, s43
	ds_read_b128 v[32:35], v149 offset:49152
	ds_read_b128 v[40:43], v149 offset:50176
	ds_read_b128 v[154:157], v149 offset:51200
	ds_read_b128 v[230:233], v149 offset:52224
	ds_read_b128 v[234:237], v149 offset:53248
	ds_read_b128 v[238:241], v149 offset:54272
	ds_read_b128 v[242:245], v149 offset:55296
	ds_read_b128 v[246:249], v149 offset:56320
	s_nop 0
	global_load_lds_dwordx4 v136, s[6:7]
	s_mov_b64 s[98:99], s[6:7]
	s_add_u32 s6, s30, 0x40180
	s_mov_b32 m0, s42
	s_addc_u32 s7, s31, 0
	global_load_lds_dwordx4 v132, s[98:99]
	s_mov_b32 m0, s40
	s_nop 0
	global_load_lds_dwordx4 v136, s[6:7]
	s_mov_b32 m0, s41
	s_nop 0
	global_load_lds_dwordx4 v132, s[6:7]
	s_mov_b32 m0, s87
	s_nop 0
	global_load_lds_dwordx4 v138, s[8:9]
	s_mov_b32 m0, s88
	s_nop 0
	global_load_lds_dwordx4 v134, s[8:9]
	s_waitcnt vmcnt(18)
	s_waitcnt lgkmcnt(0)
	s_barrier
	s_setprio 1
	s_waitcnt lgkmcnt(0)
	v_mfma_f32_16x16x32_bf16 v[20:23], v[10:13], v[32:35], v[158:161]
	v_mfma_f32_16x16x32_bf16 v[64:67], v[24:27], v[40:43], v[20:23]
	v_mfma_f32_16x16x32_bf16 v[20:23], v[210:213], v[32:35], v[162:165]
	v_mfma_f32_16x16x32_bf16 v[52:55], v[214:217], v[40:43], v[20:23]
	v_mfma_f32_16x16x32_bf16 v[20:23], v[10:13], v[154:157], v[166:169]
	v_mfma_f32_16x16x32_bf16 v[44:47], v[24:27], v[230:233], v[20:23]
	v_mfma_f32_16x16x32_bf16 v[20:23], v[210:213], v[154:157], v[170:173]
	v_mfma_f32_16x16x32_bf16 v[36:39], v[214:217], v[230:233], v[20:23]
	v_mfma_f32_16x16x32_bf16 v[20:23], v[10:13], v[234:237], v[174:177]
	v_mfma_f32_16x16x32_bf16 v[2:5], v[10:13], v[242:245], v[2:5]
	v_mfma_f32_16x16x32_bf16 v[28:31], v[24:27], v[238:241], v[20:23]
	v_mfma_f32_16x16x32_bf16 v[20:23], v[210:213], v[234:237], v[178:181]
	v_mfma_f32_16x16x32_bf16 v[12:15], v[24:27], v[246:249], v[2:5]
	v_mfma_f32_16x16x32_bf16 v[2:5], v[210:213], v[242:245], v[6:9]
	v_mfma_f32_16x16x32_bf16 v[20:23], v[214:217], v[238:241], v[20:23]
	v_mfma_f32_16x16x32_bf16 v[4:7], v[214:217], v[246:249], v[2:5]
	s_setprio 0
	s_setprio 1
	v_mfma_f32_16x16x32_bf16 v[8:11], v[218:221], v[32:35], v[182:185]
	v_mfma_f32_16x16x32_bf16 v[72:75], v[222:225], v[40:43], v[8:11]
	v_mfma_f32_16x16x32_bf16 v[8:11], v[226:229], v[32:35], v[186:189]
	v_mfma_f32_16x16x32_bf16 v[56:59], v[150:153], v[40:43], v[8:11]
	v_mfma_f32_16x16x32_bf16 v[8:11], v[218:221], v[154:157], v[190:193]
	v_mfma_f32_16x16x32_bf16 v[48:51], v[222:225], v[230:233], v[8:11]
	v_mfma_f32_16x16x32_bf16 v[8:11], v[226:229], v[154:157], v[194:197]
	v_mfma_f32_16x16x32_bf16 v[40:43], v[150:153], v[230:233], v[8:11]
	v_mfma_f32_16x16x32_bf16 v[8:11], v[218:221], v[234:237], v[198:201]
	v_mfma_f32_16x16x32_bf16 v[32:35], v[222:225], v[238:241], v[8:11]
	v_mfma_f32_16x16x32_bf16 v[8:11], v[226:229], v[234:237], v[202:205]
	v_mfma_f32_16x16x32_bf16 v[24:27], v[150:153], v[238:241], v[8:11]
	v_mfma_f32_16x16x32_bf16 v[8:11], v[218:221], v[242:245], v[16:19]
	v_mfma_f32_16x16x32_bf16 v[16:19], v[222:225], v[246:249], v[8:11]
	v_mfma_f32_16x16x32_bf16 v[8:11], v[226:229], v[242:245], v[206:209]
	v_mfma_f32_16x16x32_bf16 v[8:11], v[150:153], v[246:249], v[8:11]
	s_setprio 0
	s_barrier
	s_mov_b64 s[8:9], 0

; template <class Epi, class Sched, bool ALIGN_EPI = false, bool SP2 = false>
; __device__ __forceinline__ void gemm_phase(PG8_LAS unsigned char* lds, const Gemm g, const Sched& S, const Epi& E, int wave_s) {
;     ...
;         const bool has_next = S.next(ui + 1, nxt);
;         const char* nA = has_next ? (const char*)g.A + (size_t)nxt.pm * tstep : cA; const char* nB = has_next ? (const char*)g.Bt + (size_t)nxt.pn * tstep : cB;
;         for (int t = peeled ? 2 : 0; t < nt; t += 2) {
;             const bool last = (t == nt - 2);
;             const char* a1 = cA + (size_t)(t + 1) * kstep;
;             const char* a2 = last ? nA : cA + (size_t)(t + 2) * kstep; const char* b2 = last ? nB : cB + (size_t)(t + 2) * kstep;
;             const char* a3 = a2 + kstep; const char* b3 = b2 + kstep;
;             if (last && has_next) S.a_ready(nxt);
.LBB0_1278:
	v_add_u32_e32 v151, s90, v146
	v_add_u32_e32 v150, s91, v146
	ds_read_b128 v[152:155], v151
	ds_read_b128 v[156:159], v151 offset:1024
	ds_read_b128 v[160:163], v151 offset:2048
	ds_read_b128 v[164:167], v151 offset:3072
	ds_read_b128 v[168:171], v150
	ds_read_b128 v[172:175], v150 offset:1024
	ds_read_b128 v[176:179], v150 offset:2048
	ds_read_b128 v[180:183], v150 offset:3072
	s_add_u32 s36, s70, 0x100
	s_addc_u32 s37, s71, 0
	s_cmp_eq_u32 vcc_hi, 12
	s_cselect_b32 s42, s96, s36
	s_cselect_b32 s43, s95, s37
	s_cselect_b32 s40, vcc_lo, s6
	s_cselect_b32 s41, s97, s7
	s_add_u32 s38, s42, 0x80
	s_addc_u32 s39, s43, 0
	s_add_u32 s60, s70, 0x40080
	s_addc_u32 s61, s71, 0
	s_add_i32 s94, s77, 0xc000
	ds_read_b128 v[184:187], v149
	ds_read_b128 v[188:191], v149 offset:1024
	ds_read_b128 v[192:195], v149 offset:2048
	ds_read_b128 v[196:199], v149 offset:3072
	ds_read_b128 v[200:203], v149 offset:4096
	ds_read_b128 v[204:207], v149 offset:5120
	ds_read_b128 v[208:211], v149 offset:6144
	ds_read_b128 v[212:215], v149 offset:7168
	s_mov_b32 m0, s94
	s_add_i32 s12, s77, 0xe000
	global_load_lds_dwordx4 v138, s[60:61]
	s_mov_b32 m0, s12
	s_nop 0
	global_load_lds_dwordx4 v134, s[60:61]
	s_waitcnt vmcnt(8)
	s_waitcnt lgkmcnt(0)
	s_barrier
	s_setprio 1
	s_waitcnt lgkmcnt(0)
	v_mfma_f32_16x16x32_bf16 v[124:127], v[152:155], v[184:187], v[124:127]
	v_mfma_f32_16x16x32_bf16 v[116:119], v[160:163], v[184:187], v[116:119]
	v_mfma_f32_16x16x32_bf16 v[108:111], v[152:155], v[192:195], v[108:111]
	v_mfma_f32_16x16x32_bf16 v[100:103], v[160:163], v[192:195], v[100:103]
	v_mfma_f32_16x16x32_bf16 v[92:95], v[152:155], v[200:203], v[92:95]
	v_mfma_f32_16x16x32_bf16 v[84:87], v[160:163], v[200:203], v[84:87]
	v_mfma_f32_16x16x32_bf16 v[76:79], v[152:155], v[208:211], v[76:79]
	v_mfma_f32_16x16x32_bf16 v[60:63], v[160:163], v[208:211], v[60:63]
	v_mfma_f32_16x16x32_bf16 v[124:127], v[156:159], v[188:191], v[124:127]
	v_mfma_f32_16x16x32_bf16 v[116:119], v[164:167], v[188:191], v[116:119]
	v_mfma_f32_16x16x32_bf16 v[108:111], v[156:159], v[196:199], v[108:111]
	v_mfma_f32_16x16x32_bf16 v[100:103], v[164:167], v[196:199], v[100:103]
	v_mfma_f32_16x16x32_bf16 v[92:95], v[156:159], v[204:207], v[92:95]
	v_mfma_f32_16x16x32_bf16 v[84:87], v[164:167], v[204:207], v[84:87]
	v_mfma_f32_16x16x32_bf16 v[76:79], v[156:159], v[212:215], v[76:79]
	v_mfma_f32_16x16x32_bf16 v[60:63], v[164:167], v[212:215], v[60:63]
	s_setprio 0
	s_setprio 1
	v_mfma_f32_16x16x32_bf16 v[128:131], v[168:171], v[184:187], v[128:131]
	v_mfma_f32_16x16x32_bf16 v[120:123], v[176:179], v[184:187], v[120:123]
	v_mfma_f32_16x16x32_bf16 v[112:115], v[168:171], v[192:195], v[112:115]
	v_mfma_f32_16x16x32_bf16 v[104:107], v[176:179], v[192:195], v[104:107]
	v_mfma_f32_16x16x32_bf16 v[96:99], v[168:171], v[200:203], v[96:99]
	v_mfma_f32_16x16x32_bf16 v[88:91], v[176:179], v[200:203], v[88:91]
	v_mfma_f32_16x16x32_bf16 v[80:83], v[168:171], v[208:211], v[80:83]
	v_mfma_f32_16x16x32_bf16 v[68:71], v[176:179], v[208:211], v[68:71]
	v_mfma_f32_16x16x32_bf16 v[128:131], v[172:175], v[188:191], v[128:131]
	v_mfma_f32_16x16x32_bf16 v[120:123], v[180:183], v[188:191], v[120:123]
	v_mfma_f32_16x16x32_bf16 v[112:115], v[172:175], v[196:199], v[112:115]
	v_mfma_f32_16x16x32_bf16 v[104:107], v[180:183], v[196:199], v[104:107]
	v_mfma_f32_16x16x32_bf16 v[96:99], v[172:175], v[204:207], v[96:99]
	v_mfma_f32_16x16x32_bf16 v[88:91], v[180:183], v[204:207], v[88:91]
	v_mfma_f32_16x16x32_bf16 v[80:83], v[172:175], v[212:215], v[80:83]
	v_mfma_f32_16x16x32_bf16 v[68:71], v[180:183], v[212:215], v[68:71]
	s_setprio 0
	s_barrier
	s_mov_b64 s[70:71], s[40:41]
	s_add_i32 s61, s90, s72
	ds_read_b128 v[184:187], v149 offset:16384
	ds_read_b128 v[188:191], v149 offset:17408
	ds_read_b128 v[192:195], v149 offset:18432
	ds_read_b128 v[196:199], v149 offset:19456
	ds_read_b128 v[200:203], v149 offset:20480
	ds_read_b128 v[204:207], v149 offset:21504
	ds_read_b128 v[208:211], v149 offset:22528
	ds_read_b128 v[212:215], v149 offset:23552
	s_mov_b32 m0, s61
	s_add_i32 s25, s61, 0x2000
	global_load_lds_dwordx4 v136, s[70:71]
	s_mov_b64 s[98:99], s[70:71]
	s_add_u32 s70, s40, 0x40000
	s_mov_b32 m0, s25
	s_addc_u32 s71, s41, 0
	s_add_i32 s27, s91, s72
	global_load_lds_dwordx4 v132, s[98:99]
	s_mov_b32 m0, s27
	s_add_i32 s60, s27, 0x2000
	global_load_lds_dwordx4 v136, s[70:71]
	s_mov_b64 s[98:99], s[70:71]
	s_mov_b32 m0, s60
	s_mov_b64 s[70:71], s[42:43]
	global_load_lds_dwordx4 v132, s[98:99]
	s_mov_b32 m0, s77
	s_nop 0
	global_load_lds_dwordx4 v138, s[70:71]
	s_mov_b32 m0, s78
	s_nop 0
	global_load_lds_dwordx4 v134, s[70:71]
	s_waitcnt vmcnt(8)
	s_waitcnt lgkmcnt(0)
	s_barrier
	s_setprio 1
	s_waitcnt lgkmcnt(0)
	v_mfma_f32_16x16x32_bf16 v[64:67], v[152:155], v[184:187], v[64:67]
	v_mfma_f32_16x16x32_bf16 v[52:55], v[160:163], v[184:187], v[52:55]
	v_mfma_f32_16x16x32_bf16 v[44:47], v[152:155], v[192:195], v[44:47]
	v_mfma_f32_16x16x32_bf16 v[36:39], v[160:163], v[192:195], v[36:39]
	v_mfma_f32_16x16x32_bf16 v[28:31], v[152:155], v[200:203], v[28:31]
	v_mfma_f32_16x16x32_bf16 v[20:23], v[160:163], v[200:203], v[20:23]
	v_mfma_f32_16x16x32_bf16 v[12:15], v[152:155], v[208:211], v[12:15]
	v_mfma_f32_16x16x32_bf16 v[2:5], v[160:163], v[208:211], v[4:7]
	v_mfma_f32_16x16x32_bf16 v[64:67], v[156:159], v[188:191], v[64:67]
	v_mfma_f32_16x16x32_bf16 v[52:55], v[164:167], v[188:191], v[52:55]
	v_mfma_f32_16x16x32_bf16 v[44:47], v[156:159], v[196:199], v[44:47]
	v_mfma_f32_16x16x32_bf16 v[36:39], v[164:167], v[196:199], v[36:39]
	v_mfma_f32_16x16x32_bf16 v[28:31], v[156:159], v[204:207], v[28:31]
	v_mfma_f32_16x16x32_bf16 v[20:23], v[164:167], v[204:207], v[20:23]
	v_mfma_f32_16x16x32_bf16 v[12:15], v[156:159], v[212:215], v[12:15]
	v_mfma_f32_16x16x32_bf16 v[2:5], v[164:167], v[212:215], v[2:5]
	s_setprio 0
	s_setprio 1
	v_mfma_f32_16x16x32_bf16 v[72:75], v[168:171], v[184:187], v[72:75]
	v_mfma_f32_16x16x32_bf16 v[56:59], v[176:179], v[184:187], v[56:59]
	v_mfma_f32_16x16x32_bf16 v[48:51], v[168:171], v[192:195], v[48:51]
	v_mfma_f32_16x16x32_bf16 v[40:43], v[176:179], v[192:195], v[40:43]
	v_mfma_f32_16x16x32_bf16 v[32:35], v[168:171], v[200:203], v[32:35]
	v_mfma_f32_16x16x32_bf16 v[24:27], v[176:179], v[200:203], v[24:27]
	v_mfma_f32_16x16x32_bf16 v[16:19], v[168:171], v[208:211], v[16:19]
	v_mfma_f32_16x16x32_bf16 v[6:9], v[176:179], v[208:211], v[8:11]
	v_mfma_f32_16x16x32_bf16 v[72:75], v[172:175], v[188:191], v[72:75]
	v_mfma_f32_16x16x32_bf16 v[56:59], v[180:183], v[188:191], v[56:59]
	v_mfma_f32_16x16x32_bf16 v[48:51], v[172:175], v[196:199], v[48:51]
	v_mfma_f32_16x16x32_bf16 v[40:43], v[180:183], v[196:199], v[40:43]
	v_mfma_f32_16x16x32_bf16 v[32:35], v[172:175], v[204:207], v[32:35]
	v_mfma_f32_16x16x32_bf16 v[24:27], v[180:183], v[204:207], v[24:27]
	v_mfma_f32_16x16x32_bf16 v[16:19], v[172:175], v[212:215], v[16:19]
	v_mfma_f32_16x16x32_bf16 v[8:11], v[180:183], v[212:215], v[6:9]
	s_setprio 0
	s_barrier
	s_add_i32 s86, 0, 0x18000
	s_add_i32 s85, 0, 0x1c000
	v_add_u32_e32 v152, s86, v146
	v_add_u32_e32 v153, s85, v146
	ds_read_b128 v[154:157], v152
	ds_read_b128 v[158:161], v152 offset:1024
	ds_read_b128 v[162:165], v152 offset:2048
	ds_read_b128 v[166:169], v152 offset:3072
	ds_read_b128 v[170:173], v153
	ds_read_b128 v[174:177], v153 offset:1024
	ds_read_b128 v[178:181], v153 offset:2048
	ds_read_b128 v[182:185], v153 offset:3072
	s_add_u32 s42, s42, 0x40000
	s_addc_u32 s43, s43, 0
	s_mov_b32 m0, s79
	ds_read_b128 v[186:189], v149 offset:32768
	ds_read_b128 v[190:193], v149 offset:33792
	ds_read_b128 v[194:197], v149 offset:34816
	ds_read_b128 v[198:201], v149 offset:35840
	ds_read_b128 v[202:205], v149 offset:36864
	ds_read_b128 v[206:209], v149 offset:37888
	ds_read_b128 v[210:213], v149 offset:38912
	ds_read_b128 v[214:217], v149 offset:39936
	s_nop 0
	global_load_lds_dwordx4 v138, s[42:43]
	s_mov_b32 m0, s82
	s_nop 0
	global_load_lds_dwordx4 v134, s[42:43]
	s_waitcnt vmcnt(8)
	s_waitcnt lgkmcnt(0)
	s_barrier
	s_setprio 1
	s_waitcnt lgkmcnt(0)
	v_mfma_f32_16x16x32_bf16 v[124:127], v[154:157], v[186:189], v[124:127]
	v_mfma_f32_16x16x32_bf16 v[116:119], v[162:165], v[186:189], v[116:119]
	v_mfma_f32_16x16x32_bf16 v[108:111], v[154:157], v[194:197], v[108:111]
	v_mfma_f32_16x16x32_bf16 v[100:103], v[162:165], v[194:197], v[100:103]
	v_mfma_f32_16x16x32_bf16 v[92:95], v[154:157], v[202:205], v[92:95]
	v_mfma_f32_16x16x32_bf16 v[84:87], v[162:165], v[202:205], v[84:87]
	v_mfma_f32_16x16x32_bf16 v[76:79], v[154:157], v[210:213], v[76:79]
	v_mfma_f32_16x16x32_bf16 v[60:63], v[162:165], v[210:213], v[60:63]
	v_mfma_f32_16x16x32_bf16 v[124:127], v[158:161], v[190:193], v[124:127]
	v_mfma_f32_16x16x32_bf16 v[116:119], v[166:169], v[190:193], v[116:119]
	v_mfma_f32_16x16x32_bf16 v[108:111], v[158:161], v[198:201], v[108:111]
	v_mfma_f32_16x16x32_bf16 v[100:103], v[166:169], v[198:201], v[100:103]
	v_mfma_f32_16x16x32_bf16 v[92:95], v[158:161], v[206:209], v[92:95]
	v_mfma_f32_16x16x32_bf16 v[84:87], v[166:169], v[206:209], v[84:87]
	v_mfma_f32_16x16x32_bf16 v[76:79], v[158:161], v[214:217], v[76:79]
	v_mfma_f32_16x16x32_bf16 v[60:63], v[166:169], v[214:217], v[60:63]
	s_setprio 0
	s_setprio 1
	v_mfma_f32_16x16x32_bf16 v[128:131], v[170:173], v[186:189], v[128:131]
	v_mfma_f32_16x16x32_bf16 v[120:123], v[178:181], v[186:189], v[120:123]
	v_mfma_f32_16x16x32_bf16 v[112:115], v[170:173], v[194:197], v[112:115]
	v_mfma_f32_16x16x32_bf16 v[104:107], v[178:181], v[194:197], v[104:107]
	v_mfma_f32_16x16x32_bf16 v[96:99], v[170:173], v[202:205], v[96:99]
	v_mfma_f32_16x16x32_bf16 v[88:91], v[178:181], v[202:205], v[88:91]
	v_mfma_f32_16x16x32_bf16 v[80:83], v[170:173], v[210:213], v[80:83]
	v_mfma_f32_16x16x32_bf16 v[68:71], v[178:181], v[210:213], v[68:71]
	v_mfma_f32_16x16x32_bf16 v[128:131], v[174:177], v[190:193], v[128:131]
	v_mfma_f32_16x16x32_bf16 v[120:123], v[182:185], v[190:193], v[120:123]
	v_mfma_f32_16x16x32_bf16 v[112:115], v[174:177], v[198:201], v[112:115]
	v_mfma_f32_16x16x32_bf16 v[104:107], v[182:185], v[198:201], v[104:107]
	v_mfma_f32_16x16x32_bf16 v[96:99], v[174:177], v[206:209], v[96:99]
	v_mfma_f32_16x16x32_bf16 v[88:91], v[182:185], v[206:209], v[88:91]
	v_mfma_f32_16x16x32_bf16 v[80:83], v[174:177], v[214:217], v[80:83]
	v_mfma_f32_16x16x32_bf16 v[68:71], v[182:185], v[214:217], v[68:71]
	s_setprio 0
	s_barrier
	s_add_u32 s70, s40, 0x80
	s_addc_u32 s71, s41, 0
	s_add_i32 s43, s86, s72
	ds_read_b128 v[186:189], v149 offset:49152
	ds_read_b128 v[190:193], v149 offset:50176
	ds_read_b128 v[194:197], v149 offset:51200
	ds_read_b128 v[198:201], v149 offset:52224
	ds_read_b128 v[202:205], v149 offset:53248
	ds_read_b128 v[206:209], v149 offset:54272
	ds_read_b128 v[210:213], v149 offset:55296
	ds_read_b128 v[214:217], v149 offset:56320
	s_mov_b32 m0, s43
	s_add_i32 s42, s43, 0x2000
	global_load_lds_dwordx4 v136, s[70:71]
	s_mov_b64 s[98:99], s[70:71]
	s_add_u32 s70, s40, 0x40080
	s_mov_b32 m0, s42
	s_addc_u32 s71, s41, 0
	s_add_i32 s40, s85, s72
	global_load_lds_dwordx4 v132, s[98:99]
	s_mov_b32 m0, s40
	s_add_i32 s41, s40, 0x2000
	global_load_lds_dwordx4 v136, s[70:71]
	s_mov_b32 m0, s41
	s_nop 0
	global_load_lds_dwordx4 v132, s[70:71]
	s_mov_b32 m0, s87
	s_nop 0
	global_load_lds_dwordx4 v138, s[38:39]
	s_mov_b32 m0, s88
	s_nop 0
	global_load_lds_dwordx4 v134, s[38:39]
	s_waitcnt vmcnt(8)
	s_waitcnt lgkmcnt(0)
	s_barrier
	s_setprio 1
	s_waitcnt lgkmcnt(0)
	v_mfma_f32_16x16x32_bf16 v[64:67], v[154:157], v[186:189], v[64:67]
	v_mfma_f32_16x16x32_bf16 v[52:55], v[162:165], v[186:189], v[52:55]
	v_mfma_f32_16x16x32_bf16 v[44:47], v[154:157], v[194:197], v[44:47]
	v_mfma_f32_16x16x32_bf16 v[36:39], v[162:165], v[194:197], v[36:39]
	v_mfma_f32_16x16x32_bf16 v[28:31], v[154:157], v[202:205], v[28:31]
	v_mfma_f32_16x16x32_bf16 v[20:23], v[162:165], v[202:205], v[20:23]
	v_mfma_f32_16x16x32_bf16 v[12:15], v[154:157], v[210:213], v[12:15]
	v_mfma_f32_16x16x32_bf16 v[2:5], v[162:165], v[210:213], v[2:5]
	v_mfma_f32_16x16x32_bf16 v[64:67], v[158:161], v[190:193], v[64:67]
	v_mfma_f32_16x16x32_bf16 v[52:55], v[166:169], v[190:193], v[52:55]
	v_mfma_f32_16x16x32_bf16 v[44:47], v[158:161], v[198:201], v[44:47]
	v_mfma_f32_16x16x32_bf16 v[36:39], v[166:169], v[198:201], v[36:39]
	v_mfma_f32_16x16x32_bf16 v[28:31], v[158:161], v[206:209], v[28:31]
	v_mfma_f32_16x16x32_bf16 v[20:23], v[166:169], v[206:209], v[20:23]
	v_mfma_f32_16x16x32_bf16 v[12:15], v[158:161], v[214:217], v[12:15]
	v_mfma_f32_16x16x32_bf16 v[4:7], v[166:169], v[214:217], v[2:5]
	s_setprio 0
	s_setprio 1
	v_mfma_f32_16x16x32_bf16 v[72:75], v[170:173], v[186:189], v[72:75]
	v_mfma_f32_16x16x32_bf16 v[56:59], v[178:181], v[186:189], v[56:59]
	v_mfma_f32_16x16x32_bf16 v[48:51], v[170:173], v[194:197], v[48:51]
	v_mfma_f32_16x16x32_bf16 v[40:43], v[178:181], v[194:197], v[40:43]
	v_mfma_f32_16x16x32_bf16 v[32:35], v[170:173], v[202:205], v[32:35]
	v_mfma_f32_16x16x32_bf16 v[24:27], v[178:181], v[202:205], v[24:27]
	v_mfma_f32_16x16x32_bf16 v[16:19], v[170:173], v[210:213], v[16:19]
	v_mfma_f32_16x16x32_bf16 v[8:11], v[178:181], v[210:213], v[8:11]
	v_mfma_f32_16x16x32_bf16 v[72:75], v[174:177], v[190:193], v[72:75]
	v_mfma_f32_16x16x32_bf16 v[56:59], v[182:185], v[190:193], v[56:59]
	v_mfma_f32_16x16x32_bf16 v[48:51], v[174:177], v[198:201], v[48:51]
	v_mfma_f32_16x16x32_bf16 v[40:43], v[182:185], v[198:201], v[40:43]
	v_mfma_f32_16x16x32_bf16 v[32:35], v[174:177], v[206:209], v[32:35]
	v_mfma_f32_16x16x32_bf16 v[24:27], v[182:185], v[206:209], v[24:27]
	v_mfma_f32_16x16x32_bf16 v[16:19], v[174:177], v[214:217], v[16:19]
	v_mfma_f32_16x16x32_bf16 v[8:11], v[182:185], v[214:217], v[8:11]
	s_setprio 0
	s_barrier
	s_add_i32 vcc_hi, vcc_hi, 2
	s_add_u32 s6, s6, 0x100
	s_addc_u32 s7, s7, 0
	s_cmp_gt_u32 vcc_hi, 13
	s_mov_b64 s[70:71], s[36:37]
	s_cbranch_scc0 .LBB0_1278
	s_and_b64 vcc, exec, s[22:23]
	s_cbranch_vccz .LBB0_1281
	s_barrier

; __device__ __forceinline__ int lane_id_() { int l; asm volatile("v_mbcnt_lo_u32_b32 %0, -1, 0\n\tv_mbcnt_hi_u32_b32 %0, -1, %0" : "=v"(l)); return l; }
; #define PG8_LAS __attribute__((address_space(3)))
; #define PG8_STAGE(bufoff, gbase, voff) do { const char* gb_ = (const char*)(gbase); asm volatile("" : "+s"(gb_));   \
;         _Pragma("unroll") for (int _i = 0; _i < 2; ++_i) \
;         __builtin_amdgcn_global_load_lds((const unsigned*)(gb_ + (voff)[_i]), (PG8_LAS unsigned*)(lds + (bufoff) + ldsw + _i * 8192), 16, 0, 0); } while (0)
; #define PG8_WAIT_V(n) asm volatile("s_waitcnt vmcnt(" #n ")" ::: "memory")
; #define PG8_BAR __builtin_amdgcn_s_barrier()
;     __device__ __forceinline__ void operator()(const f32x4 (&acc)[2][2][4][2], const Unit& u, int wr, int wc, int fr, int fq, PG8_LAS unsigned char* lds, int wid) const {
;     ...
;                     if (fq == 0) *(PG8_LAS float*)(lds + PRE_SLOT + 4096 + ((wr * 64 + fr + ai * HALF + m * 16) * 4 + wc) * 4) = s; }
;             }
;         if (!LAST) {
;             asm volatile("s_waitcnt lgkmcnt(0)" ::: "memory"); __builtin_amdgcn_s_barrier(); asm volatile("" ::: "memory");
;             if (wid < 4) { const int r = wid * 64 + lane_id_();
;                 const f32x4 p = *(const PG8_LAS f32x4*)(lds + PRE_SLOT + 4096 + r * 16);
;                 __hip_atomic_fetch_add(ssq + u.pm * BM + r, (p[0] + p[1]) + (p[2] + p[3]), __ATOMIC_RELAXED, __HIP_MEMORY_SCOPE_AGENT); }
; template <class Epi, class Sched, bool ALIGN_EPI = false, bool SP2 = false>
; __device__ __forceinline__ void gemm_phase(PG8_LAS unsigned char* lds, const Gemm g, const Sched& S, const Epi& E, int wave_s) {
;     ...
;         PG8_STAGE(PG8_SB(0, 0), cB, voffB); PG8_STAGE(PG8_SB(0, 1), cB + hstep, voffB); PG8_STAGE(PG8_SA(0, 0), cA, voffA); PG8_STAGE(PG8_SA(0, 1), cA + hstep, voffA);
;         if (wr == 1) PG8_BAR;
;         PG8_WAIT_V(2); PG8_BAR;
;         PG8_STAGE(PG8_SB(1, 0), cB + kstep, voffB); PG8_STAGE(PG8_SA(1, 0), cA + kstep, voffA); PG8_STAGE(PG8_SB(1, 1), cB + hstep + kstep, voffB);
;         PG8_WAIT_V(6); PG8_BAR;
.LBB0_1652:
	s_and_b32 s10, s6, 3
	s_lshl_b32 s11, s7, 13
	s_lshl_b32 s12, s10, 12
	s_add_u32 s8, s34, 0x80
	s_addc_u32 s9, s35, 0
	s_waitcnt vmcnt(2)
	s_barrier
	s_add_i32 m0, s57, 0x18000
	s_nop 0
	global_load_lds_dwordx4 v130, s[8:9]
	s_add_i32 m0, s57, 0x1a000
	s_nop 0
	global_load_lds_dwordx4 v134, s[8:9]
	s_add_u32 s8, s30, 0x80
	s_addc_u32 s9, s31, 0
	s_add_i32 s66, s57, 0x8000
	s_mov_b32 m0, s66
	s_add_i32 s67, s57, 0xa000
	global_load_lds_dwordx4 v128, s[8:9]
	s_mov_b64 s[98:99], s[8:9]
	s_add_u32 s8, s34, 0xb0080
	s_mov_b32 m0, s67
	s_addc_u32 s9, s35, 0
	global_load_lds_dwordx4 v132, s[98:99]
	s_add_i32 m0, s57, 0x1c000
	s_nop 0
	global_load_lds_dwordx4 v130, s[8:9]
	s_add_i32 m0, s57, 0x1e000
	v_and_b32_e32 v1, 15, v0
	global_load_lds_dwordx4 v134, s[8:9]
	v_bfe_u32 v2, v0, 4, 2
	v_lshlrev_b32_e32 v4, 4, v2
	v_lshlrev_b32_e32 v0, 2, v0
	v_lshl_or_b32 v144, s7, 6, v1
	v_lshl_or_b32 v1, v1, 6, v4
	v_and_b32_e32 v0, 32, v0
	s_cmpk_lt_u32 s68, 0x100
	v_lshlrev_b32_e32 v3, 3, v2
	v_bitop3_b32 v4, v1, s11, v0 bitop3:0xde
	v_bitop3_b32 v145, v1, s12, v0 bitop3:0xde
	s_cselect_b64 s[16:17], -1, 0
	v_lshlrev_b32_e32 v0, 4, v144
	s_add_i32 s7, 0, 0x22400
	v_lshl_or_b32 v146, s10, 5, v3
	v_add_u32_e32 v1, s7, v0
	s_lshl_b32 s7, s10, 2
	s_add_i32 s10, 0, 0x22500
	v_cmp_eq_u32_e64 s[8:9], 0, v2
	v_add_u32_e32 v2, s10, v0
	s_add_i32 s10, 0, 0x22600
	v_add_u32_e32 v3, s10, v0
	s_add_i32 s10, 0, 0x22700
	v_add_u32_e32 v5, s10, v0
	s_add_i32 s10, 0, 0x22c00
	v_add_u32_e32 v6, s10, v0
	s_add_i32 s10, 0, 0x22d00
	v_add_u32_e32 v7, s10, v0
	s_add_i32 s10, 0, 0x22e00
	v_add_u32_e32 v8, s10, v0
	s_add_i32 s10, 0, 0x22f00
	s_waitcnt vmcnt(6)
	s_cmp_lt_i32 s6, 4
	v_add_u32_e32 v0, s10, v0
	s_cselect_b64 s[18:19], -1, 0
	s_add_i32 s71, 0, 0x10000
	s_add_i32 s72, 0, 0x14000
	s_andn2_b32 s68, s68, 63
	s_mov_b32 s69, s46
	s_ashr_i32 s70, s33, 31
	v_mov_b64_e32 v[136:137], 0x100
	v_mov_b64_e32 v[138:139], 0xff
	v_add_u32_e32 v147, s71, v145
	v_add_u32_e32 v148, s72, v145
	v_add_u32_e32 v149, 0, v4
	v_mbcnt_hi_u32_b32 v150, -1, v254
	v_add_u32_e32 v151, s7, v1
	v_add_u32_e32 v152, s7, v2
	v_add_u32_e32 v153, s7, v3
	v_add_u32_e32 v154, s7, v5
	s_mov_b64 s[20:21], 0x40000
	v_add_u32_e32 v155, s7, v6
	s_mov_b64 s[22:23], 0x48000
	v_add_u32_e32 v156, s7, v7
	s_mov_b64 s[24:25], 0x50000
	v_add_u32_e32 v157, s7, v8
	s_mov_b64 s[26:27], 0x58000
	v_add_u32_e32 v158, s7, v0
	s_barrier
	s_branch .LBB0_1655

.LBB0_1666:
	ds_read_b128 v[140:143], v147
	ds_read_b128 v[160:163], v147 offset:1024
	ds_read_b128 v[164:167], v147 offset:2048
	ds_read_b128 v[168:171], v147 offset:3072
	ds_read_b128 v[172:175], v148
	ds_read_b128 v[176:179], v148 offset:1024
	ds_read_b128 v[180:183], v148 offset:2048
	ds_read_b128 v[184:187], v148 offset:3072
	s_add_u32 s34, s30, 0x100
	s_addc_u32 s35, s31, 0
	s_cmp_eq_u32 s77, 40
	s_cselect_b32 s40, s12, s34
	s_cselect_b32 s41, s13, s35
	s_cselect_b32 s38, s28, s60
	s_cselect_b32 s39, s29, s61
	s_add_u32 s36, s40, 0x80
	s_addc_u32 s37, s41, 0
	s_add_u32 s6, s30, 0xb0080
	s_addc_u32 s7, s31, 0
	ds_read_b128 v[188:191], v149
	ds_read_b128 v[192:195], v149 offset:1024
	ds_read_b128 v[196:199], v149 offset:2048
	ds_read_b128 v[200:203], v149 offset:3072
	ds_read_b128 v[204:207], v149 offset:4096
	ds_read_b128 v[208:211], v149 offset:5120
	ds_read_b128 v[212:215], v149 offset:6144
	ds_read_b128 v[216:219], v149 offset:7168
	s_add_i32 m0, s57, 0xc000
	s_nop 0
	global_load_lds_dwordx4 v128, s[6:7]
	s_add_i32 m0, s57, 0xe000
	s_nop 0
	global_load_lds_dwordx4 v132, s[6:7]
	s_waitcnt vmcnt(8)
	s_waitcnt lgkmcnt(0)
	s_barrier
	s_setprio 1
	s_waitcnt lgkmcnt(0)
	v_mfma_f32_16x16x32_bf16 v[124:127], v[140:143], v[188:191], v[124:127]
	v_mfma_f32_16x16x32_bf16 v[120:123], v[164:167], v[188:191], v[120:123]
	v_mfma_f32_16x16x32_bf16 v[108:111], v[140:143], v[196:199], v[108:111]
	v_mfma_f32_16x16x32_bf16 v[104:107], v[164:167], v[196:199], v[104:107]
	v_mfma_f32_16x16x32_bf16 v[92:95], v[140:143], v[204:207], v[92:95]
	v_mfma_f32_16x16x32_bf16 v[88:91], v[164:167], v[204:207], v[88:91]
	v_mfma_f32_16x16x32_bf16 v[76:79], v[140:143], v[212:215], v[76:79]
	v_mfma_f32_16x16x32_bf16 v[72:75], v[164:167], v[212:215], v[72:75]
	v_mfma_f32_16x16x32_bf16 v[124:127], v[160:163], v[192:195], v[124:127]
	v_mfma_f32_16x16x32_bf16 v[120:123], v[168:171], v[192:195], v[120:123]
	v_mfma_f32_16x16x32_bf16 v[108:111], v[160:163], v[200:203], v[108:111]
	v_mfma_f32_16x16x32_bf16 v[104:107], v[168:171], v[200:203], v[104:107]
	v_mfma_f32_16x16x32_bf16 v[92:95], v[160:163], v[208:211], v[92:95]
	v_mfma_f32_16x16x32_bf16 v[88:91], v[168:171], v[208:211], v[88:91]
	v_mfma_f32_16x16x32_bf16 v[76:79], v[160:163], v[216:219], v[76:79]
	v_mfma_f32_16x16x32_bf16 v[72:75], v[168:171], v[216:219], v[72:75]
	s_setprio 0
	s_setprio 1
	v_mfma_f32_16x16x32_bf16 v[116:119], v[172:175], v[188:191], v[116:119]
	v_mfma_f32_16x16x32_bf16 v[112:115], v[180:183], v[188:191], v[112:115]
	v_mfma_f32_16x16x32_bf16 v[100:103], v[172:175], v[196:199], v[100:103]
	v_mfma_f32_16x16x32_bf16 v[96:99], v[180:183], v[196:199], v[96:99]
	v_mfma_f32_16x16x32_bf16 v[84:87], v[172:175], v[204:207], v[84:87]
	v_mfma_f32_16x16x32_bf16 v[80:83], v[180:183], v[204:207], v[80:83]
	v_mfma_f32_16x16x32_bf16 v[68:71], v[172:175], v[212:215], v[68:71]
	v_mfma_f32_16x16x32_bf16 v[64:67], v[180:183], v[212:215], v[64:67]
	v_mfma_f32_16x16x32_bf16 v[116:119], v[176:179], v[192:195], v[116:119]
	v_mfma_f32_16x16x32_bf16 v[112:115], v[184:187], v[192:195], v[112:115]
	v_mfma_f32_16x16x32_bf16 v[100:103], v[176:179], v[200:203], v[100:103]
	v_mfma_f32_16x16x32_bf16 v[96:99], v[184:187], v[200:203], v[96:99]
	v_mfma_f32_16x16x32_bf16 v[84:87], v[176:179], v[208:211], v[84:87]
	v_mfma_f32_16x16x32_bf16 v[80:83], v[184:187], v[208:211], v[80:83]
	v_mfma_f32_16x16x32_bf16 v[68:71], v[176:179], v[216:219], v[68:71]
	v_mfma_f32_16x16x32_bf16 v[64:67], v[184:187], v[216:219], v[64:67]
	s_setprio 0
	s_barrier
	s_mov_b64 s[6:7], s[38:39]
	s_add_i32 s30, s71, s56
	ds_read_b128 v[188:191], v149 offset:16384
	ds_read_b128 v[192:195], v149 offset:17408
	ds_read_b128 v[196:199], v149 offset:18432
	ds_read_b128 v[200:203], v149 offset:19456
	ds_read_b128 v[204:207], v149 offset:20480
	ds_read_b128 v[208:211], v149 offset:21504
	ds_read_b128 v[212:215], v149 offset:22528
	ds_read_b128 v[216:219], v149 offset:23552
	s_mov_b32 m0, s30
	s_nop 0
	global_load_lds_dwordx4 v130, s[6:7]
	s_add_i32 m0, s30, 0x2000
	s_nop 0
	global_load_lds_dwordx4 v134, s[6:7]
	s_add_u32 s6, s38, 0xb0000
	s_addc_u32 s7, s39, 0
	s_add_i32 s30, s72, s56
	s_mov_b32 m0, s30
	s_nop 0
	global_load_lds_dwordx4 v130, s[6:7]
	s_mov_b64 s[98:99], s[6:7]
	s_add_i32 m0, s30, 0x2000
	s_mov_b64 s[6:7], s[40:41]
	global_load_lds_dwordx4 v134, s[98:99]
	s_mov_b32 m0, s57
	s_nop 0
	global_load_lds_dwordx4 v128, s[6:7]
	s_mov_b32 m0, s62
	s_nop 0
	global_load_lds_dwordx4 v132, s[6:7]
	s_waitcnt vmcnt(8)
	s_waitcnt lgkmcnt(0)
	s_barrier
	s_setprio 1
	s_waitcnt lgkmcnt(0)
	v_mfma_f32_16x16x32_bf16 v[60:63], v[140:143], v[188:191], v[60:63]
	v_mfma_f32_16x16x32_bf16 v[56:59], v[164:167], v[188:191], v[56:59]
	v_mfma_f32_16x16x32_bf16 v[44:47], v[140:143], v[196:199], v[44:47]
	v_mfma_f32_16x16x32_bf16 v[40:43], v[164:167], v[196:199], v[40:43]
	v_mfma_f32_16x16x32_bf16 v[28:31], v[140:143], v[204:207], v[28:31]
	v_mfma_f32_16x16x32_bf16 v[24:27], v[164:167], v[204:207], v[24:27]
	v_mfma_f32_16x16x32_bf16 v[12:15], v[140:143], v[212:215], v[12:15]
	v_mfma_f32_16x16x32_bf16 v[8:11], v[164:167], v[212:215], v[8:11]
	v_mfma_f32_16x16x32_bf16 v[60:63], v[160:163], v[192:195], v[60:63]
	v_mfma_f32_16x16x32_bf16 v[56:59], v[168:171], v[192:195], v[56:59]
	v_mfma_f32_16x16x32_bf16 v[44:47], v[160:163], v[200:203], v[44:47]
	v_mfma_f32_16x16x32_bf16 v[40:43], v[168:171], v[200:203], v[40:43]
	v_mfma_f32_16x16x32_bf16 v[28:31], v[160:163], v[208:211], v[28:31]
	v_mfma_f32_16x16x32_bf16 v[24:27], v[168:171], v[208:211], v[24:27]
	v_mfma_f32_16x16x32_bf16 v[12:15], v[160:163], v[216:219], v[12:15]
	v_mfma_f32_16x16x32_bf16 v[8:11], v[168:171], v[216:219], v[8:11]
	s_setprio 0
	s_setprio 1
	v_mfma_f32_16x16x32_bf16 v[52:55], v[172:175], v[188:191], v[52:55]
	v_mfma_f32_16x16x32_bf16 v[48:51], v[180:183], v[188:191], v[48:51]
	v_mfma_f32_16x16x32_bf16 v[36:39], v[172:175], v[196:199], v[36:39]
	v_mfma_f32_16x16x32_bf16 v[32:35], v[180:183], v[196:199], v[32:35]
	v_mfma_f32_16x16x32_bf16 v[20:23], v[172:175], v[204:207], v[20:23]
	v_mfma_f32_16x16x32_bf16 v[16:19], v[180:183], v[204:207], v[16:19]
	v_mfma_f32_16x16x32_bf16 v[4:7], v[172:175], v[212:215], v[4:7]
	v_mfma_f32_16x16x32_bf16 v[0:3], v[180:183], v[212:215], v[0:3]
	v_mfma_f32_16x16x32_bf16 v[52:55], v[176:179], v[192:195], v[52:55]
	v_mfma_f32_16x16x32_bf16 v[48:51], v[184:187], v[192:195], v[48:51]
	v_mfma_f32_16x16x32_bf16 v[36:39], v[176:179], v[200:203], v[36:39]
	v_mfma_f32_16x16x32_bf16 v[32:35], v[184:187], v[200:203], v[32:35]
	v_mfma_f32_16x16x32_bf16 v[20:23], v[176:179], v[208:211], v[20:23]
	v_mfma_f32_16x16x32_bf16 v[16:19], v[184:187], v[208:211], v[16:19]
	v_mfma_f32_16x16x32_bf16 v[4:7], v[176:179], v[216:219], v[4:7]
	v_mfma_f32_16x16x32_bf16 v[0:3], v[184:187], v[216:219], v[0:3]
	s_setprio 0
	s_barrier
	s_add_i32 s30, 0, 0x18000
	v_add_u32_e32 v159, s30, v145
	s_add_i32 s31, 0, 0x1c000
	ds_read_b128 v[140:143], v159
	ds_read_b128 v[160:163], v159 offset:1024
	ds_read_b128 v[164:167], v159 offset:2048
	ds_read_b128 v[168:171], v159 offset:3072
	v_add_u32_e32 v159, s31, v145
	ds_read_b128 v[172:175], v159
	ds_read_b128 v[176:179], v159 offset:1024
	ds_read_b128 v[180:183], v159 offset:2048
	ds_read_b128 v[184:187], v159 offset:3072
	s_add_u32 s6, s40, 0xb0000
	s_addc_u32 s7, s41, 0
	s_mov_b32 m0, s63
	ds_read_b128 v[188:191], v149 offset:32768
	ds_read_b128 v[192:195], v149 offset:33792
	ds_read_b128 v[196:199], v149 offset:34816
	ds_read_b128 v[200:203], v149 offset:35840
	ds_read_b128 v[204:207], v149 offset:36864
	ds_read_b128 v[208:211], v149 offset:37888
	ds_read_b128 v[212:215], v149 offset:38912
	ds_read_b128 v[216:219], v149 offset:39936
	s_nop 0
	global_load_lds_dwordx4 v128, s[6:7]
	s_mov_b32 m0, s64
	s_nop 0
	global_load_lds_dwordx4 v132, s[6:7]
	s_waitcnt vmcnt(8)
	s_waitcnt lgkmcnt(0)
	s_barrier
	s_setprio 1
	s_waitcnt lgkmcnt(0)
	v_mfma_f32_16x16x32_bf16 v[124:127], v[140:143], v[188:191], v[124:127]
	v_mfma_f32_16x16x32_bf16 v[120:123], v[164:167], v[188:191], v[120:123]
	v_mfma_f32_16x16x32_bf16 v[108:111], v[140:143], v[196:199], v[108:111]
	v_mfma_f32_16x16x32_bf16 v[104:107], v[164:167], v[196:199], v[104:107]
	v_mfma_f32_16x16x32_bf16 v[92:95], v[140:143], v[204:207], v[92:95]
	v_mfma_f32_16x16x32_bf16 v[88:91], v[164:167], v[204:207], v[88:91]
	v_mfma_f32_16x16x32_bf16 v[76:79], v[140:143], v[212:215], v[76:79]
	v_mfma_f32_16x16x32_bf16 v[72:75], v[164:167], v[212:215], v[72:75]
	v_mfma_f32_16x16x32_bf16 v[124:127], v[160:163], v[192:195], v[124:127]
	v_mfma_f32_16x16x32_bf16 v[120:123], v[168:171], v[192:195], v[120:123]
	v_mfma_f32_16x16x32_bf16 v[108:111], v[160:163], v[200:203], v[108:111]
	v_mfma_f32_16x16x32_bf16 v[104:107], v[168:171], v[200:203], v[104:107]
	v_mfma_f32_16x16x32_bf16 v[92:95], v[160:163], v[208:211], v[92:95]
	v_mfma_f32_16x16x32_bf16 v[88:91], v[168:171], v[208:211], v[88:91]
	v_mfma_f32_16x16x32_bf16 v[76:79], v[160:163], v[216:219], v[76:79]
	v_mfma_f32_16x16x32_bf16 v[72:75], v[168:171], v[216:219], v[72:75]
	s_setprio 0
	s_setprio 1
	v_mfma_f32_16x16x32_bf16 v[116:119], v[172:175], v[188:191], v[116:119]
	v_mfma_f32_16x16x32_bf16 v[112:115], v[180:183], v[188:191], v[112:115]
	v_mfma_f32_16x16x32_bf16 v[100:103], v[172:175], v[196:199], v[100:103]
	v_mfma_f32_16x16x32_bf16 v[96:99], v[180:183], v[196:199], v[96:99]
	v_mfma_f32_16x16x32_bf16 v[84:87], v[172:175], v[204:207], v[84:87]
	v_mfma_f32_16x16x32_bf16 v[80:83], v[180:183], v[204:207], v[80:83]
	v_mfma_f32_16x16x32_bf16 v[68:71], v[172:175], v[212:215], v[68:71]
	v_mfma_f32_16x16x32_bf16 v[64:67], v[180:183], v[212:215], v[64:67]
	v_mfma_f32_16x16x32_bf16 v[116:119], v[176:179], v[192:195], v[116:119]
	v_mfma_f32_16x16x32_bf16 v[112:115], v[184:187], v[192:195], v[112:115]
	v_mfma_f32_16x16x32_bf16 v[100:103], v[176:179], v[200:203], v[100:103]
	v_mfma_f32_16x16x32_bf16 v[96:99], v[184:187], v[200:203], v[96:99]
	v_mfma_f32_16x16x32_bf16 v[84:87], v[176:179], v[208:211], v[84:87]
	v_mfma_f32_16x16x32_bf16 v[80:83], v[184:187], v[208:211], v[80:83]
	v_mfma_f32_16x16x32_bf16 v[68:71], v[176:179], v[216:219], v[68:71]
	v_mfma_f32_16x16x32_bf16 v[64:67], v[184:187], v[216:219], v[64:67]
	s_setprio 0
	s_barrier
	s_add_u32 s6, s38, 0x80
	s_addc_u32 s7, s39, 0
	s_add_i32 s30, s30, s56
	ds_read_b128 v[188:191], v149 offset:49152
	ds_read_b128 v[192:195], v149 offset:50176
	ds_read_b128 v[196:199], v149 offset:51200
	ds_read_b128 v[200:203], v149 offset:52224
	ds_read_b128 v[204:207], v149 offset:53248
	ds_read_b128 v[208:211], v149 offset:54272
	ds_read_b128 v[212:215], v149 offset:55296
	ds_read_b128 v[216:219], v149 offset:56320
	s_mov_b32 m0, s30
	s_nop 0
	global_load_lds_dwordx4 v130, s[6:7]
	s_add_i32 m0, s30, 0x2000
	s_nop 0
	global_load_lds_dwordx4 v134, s[6:7]
	s_add_u32 s6, s38, 0xb0080
	s_addc_u32 s7, s39, 0
	s_add_i32 s30, s31, s56
	s_mov_b32 m0, s30
	s_nop 0
	global_load_lds_dwordx4 v130, s[6:7]
	s_add_i32 m0, s30, 0x2000
	s_nop 0
	global_load_lds_dwordx4 v134, s[6:7]
	s_mov_b32 m0, s66
	s_nop 0
	global_load_lds_dwordx4 v128, s[36:37]
	s_mov_b32 m0, s67
	s_nop 0
	global_load_lds_dwordx4 v132, s[36:37]
	s_waitcnt vmcnt(8)
	s_waitcnt lgkmcnt(0)
	s_barrier
	s_setprio 1
	s_waitcnt lgkmcnt(0)
	v_mfma_f32_16x16x32_bf16 v[60:63], v[140:143], v[188:191], v[60:63]
	v_mfma_f32_16x16x32_bf16 v[56:59], v[164:167], v[188:191], v[56:59]
	v_mfma_f32_16x16x32_bf16 v[44:47], v[140:143], v[196:199], v[44:47]
	v_mfma_f32_16x16x32_bf16 v[40:43], v[164:167], v[196:199], v[40:43]
	v_mfma_f32_16x16x32_bf16 v[28:31], v[140:143], v[204:207], v[28:31]
	v_mfma_f32_16x16x32_bf16 v[24:27], v[164:167], v[204:207], v[24:27]
	v_mfma_f32_16x16x32_bf16 v[12:15], v[140:143], v[212:215], v[12:15]
	v_mfma_f32_16x16x32_bf16 v[8:11], v[164:167], v[212:215], v[8:11]
	v_mfma_f32_16x16x32_bf16 v[60:63], v[160:163], v[192:195], v[60:63]
	v_mfma_f32_16x16x32_bf16 v[56:59], v[168:171], v[192:195], v[56:59]
	v_mfma_f32_16x16x32_bf16 v[44:47], v[160:163], v[200:203], v[44:47]
	v_mfma_f32_16x16x32_bf16 v[40:43], v[168:171], v[200:203], v[40:43]
	v_mfma_f32_16x16x32_bf16 v[28:31], v[160:163], v[208:211], v[28:31]
	v_mfma_f32_16x16x32_bf16 v[24:27], v[168:171], v[208:211], v[24:27]
	v_mfma_f32_16x16x32_bf16 v[12:15], v[160:163], v[216:219], v[12:15]
	v_mfma_f32_16x16x32_bf16 v[8:11], v[168:171], v[216:219], v[8:11]
	s_setprio 0
	s_setprio 1
	v_mfma_f32_16x16x32_bf16 v[52:55], v[172:175], v[188:191], v[52:55]
	v_mfma_f32_16x16x32_bf16 v[48:51], v[180:183], v[188:191], v[48:51]
	v_mfma_f32_16x16x32_bf16 v[36:39], v[172:175], v[196:199], v[36:39]
	v_mfma_f32_16x16x32_bf16 v[32:35], v[180:183], v[196:199], v[32:35]
	v_mfma_f32_16x16x32_bf16 v[20:23], v[172:175], v[204:207], v[20:23]
	v_mfma_f32_16x16x32_bf16 v[16:19], v[180:183], v[204:207], v[16:19]
	v_mfma_f32_16x16x32_bf16 v[4:7], v[172:175], v[212:215], v[4:7]
	v_mfma_f32_16x16x32_bf16 v[0:3], v[180:183], v[212:215], v[0:3]
	v_mfma_f32_16x16x32_bf16 v[52:55], v[176:179], v[192:195], v[52:55]
	v_mfma_f32_16x16x32_bf16 v[48:51], v[184:187], v[192:195], v[48:51]
	v_mfma_f32_16x16x32_bf16 v[36:39], v[176:179], v[200:203], v[36:39]
	v_mfma_f32_16x16x32_bf16 v[32:35], v[184:187], v[200:203], v[32:35]
	v_mfma_f32_16x16x32_bf16 v[20:23], v[176:179], v[208:211], v[20:23]
	v_mfma_f32_16x16x32_bf16 v[16:19], v[184:187], v[208:211], v[16:19]
	v_mfma_f32_16x16x32_bf16 v[4:7], v[176:179], v[216:219], v[4:7]
	v_mfma_f32_16x16x32_bf16 v[0:3], v[184:187], v[216:219], v[0:3]
	s_setprio 0
	s_barrier
	s_add_i32 s77, s77, 2
	s_add_u32 s60, s60, 0x100
	s_addc_u32 s61, s61, 0
	s_cmp_gt_u32 s77, 41
	s_mov_b64 s[30:31], s[34:35]
	s_cbranch_scc0 .LBB0_1666
	s_and_b64 vcc, exec, s[16:17]
	s_cbranch_vccz .LBB0_1669
	s_barrier

; #define PG8_STAGE(bufoff, gbase, voff) do { const char* gb_ = (const char*)(gbase); asm volatile("" : "+s"(gb_));   \
;         _Pragma("unroll") for (int _i = 0; _i < 2; ++_i) \
;         __builtin_amdgcn_global_load_lds((const unsigned*)(gb_ + (voff)[_i]), (PG8_LAS unsigned*)(lds + (bufoff) + ldsw + _i * 8192), 16, 0, 0); } while (0)
; #define PG8_WAIT_V(n) asm volatile("s_waitcnt vmcnt(" #n ")" ::: "memory")
; #define PG8_BAR __builtin_amdgcn_s_barrier()
; template <class Epi, class Sched, bool ALIGN_EPI = false, bool SP2 = false>
; __device__ __forceinline__ void gemm_phase(PG8_LAS unsigned char* lds, const Gemm g, const Sched& S, const Epi& E, int wave_s) {
;     ...
;     f32x4 acc[2][2][4][2];
; #pragma unroll
;     for (int a = 0; a < 2; ++a)
; #pragma unroll
;         for (int b = 0; b < 2; ++b)
; #pragma unroll
;             for (int m = 0; m < 4; ++m)
; #pragma unroll
;                 for (int n = 0; n < 2; ++n) acc[a][b][m][n] = (f32x4){0.f, 0.f, 0.f, 0.f};
;     bf16x8 At[4][2], B0[2][2], B1[2][2];
;     const char* cA = (const char*)g.A + (size_t)cur.pm * tstep; const char* cB = (const char*)g.Bt + (size_t)cur.pn * tstep;
;     S.a_ready(cur);
;     if constexpr (SP2) {
;         PG8_STAGE(PG8_SB(0, 0), cB, voffB); PG8_STAGE(PG8_SB(0, 1), cB + hstep, voffB); PG8_STAGE(PG8_SA(0, 0), cA, voffA); PG8_STAGE(PG8_SA(0, 1), cA + hstep, voffA);
;         if (wr == 1) PG8_BAR;
;         PG8_WAIT_V(2); PG8_BAR;
;         PG8_STAGE(PG8_SB(1, 0), cB + kstep, voffB); PG8_STAGE(PG8_SA(1, 0), cA + kstep, voffA); PG8_STAGE(PG8_SB(1, 1), cB + hstep + kstep, voffB);
;         PG8_WAIT_V(6); PG8_BAR;
;     } else {
;         PG8_STAGE(PG8_SB(0, 0), cB, voffB); PG8_STAGE(PG8_SA(0, 0), cA, voffA); PG8_STAGE(PG8_SB(0, 1), cB + hstep, voffB); PG8_STAGE(PG8_SA(0, 1), cA + hstep, voffA);
;         if (wr == 1) PG8_BAR;
;         PG8_WAIT_V(4); PG8_BAR;
;         PG8_STAGE(PG8_SB(1, 0), cB + kstep, voffB); PG8_STAGE(PG8_SA(1, 0), cA + kstep, voffA); PG8_STAGE(PG8_SB(1, 1), cB + hstep + kstep, voffB);
;         PG8_WAIT_V(6); PG8_BAR;
.LBB0_1754:
	s_lshl_b32 s18, s18, 5
	s_and_b32 s20, s18, 0x60
	s_lshl_b32 s7, s7, 13
	s_lshl_b32 s21, s20, 7
	s_add_u32 s18, s10, 0x80
	s_addc_u32 s19, s11, 0
	s_waitcnt vmcnt(2)
	s_barrier
	s_add_i32 m0, s37, 0x18000
	s_nop 0
	global_load_lds_dwordx4 v134, s[18:19]
	s_add_i32 m0, s37, 0x1a000
	s_nop 0
	global_load_lds_dwordx4 v138, s[18:19]
	s_add_u32 s18, s40, 0x80
	s_addc_u32 s19, s41, 0
	s_add_i32 s68, s37, 0x8000
	s_mov_b32 m0, s68
	s_add_i32 s69, s37, 0xa000
	global_load_lds_dwordx4 v132, s[18:19]
	s_mov_b64 s[98:99], s[18:19]
	s_add_u32 s18, s10, 0x40080
	s_mov_b32 m0, s69
	s_addc_u32 s19, s11, 0
	global_load_lds_dwordx4 v136, s[98:99]
	s_add_i32 m0, s37, 0x1c000
	s_nop 0
	global_load_lds_dwordx4 v134, s[18:19]
	s_add_i32 m0, s37, 0x1e000
	v_and_b32_e32 v0, 15, v2
	global_load_lds_dwordx4 v138, s[18:19]
	v_lshrrev_b32_e32 v2, 1, v2
	v_or_b32_e32 v144, s12, v0
	v_and_b32_e32 v2, 24, v2
	v_lshlrev_b32_e32 v3, 6, v144
	v_lshlrev_b32_e32 v4, 1, v2
	s_movk_i32 s12, 0x3c0
	v_lshlrev_b32_e32 v5, 2, v144
	v_and_or_b32 v3, v3, s12, v4
	v_and_b32_e32 v5, 32, v5
	v_lshlrev_b32_e32 v145, 2, v0
	v_bitop3_b32 v5, v3, s7, v5 bitop3:0xde
	v_lshl_or_b32 v3, v0, 6, v4
	v_and_b32_e32 v0, 32, v145
	s_cmpk_lt_u32 s6, 0x100
	v_bitop3_b32 v146, v3, s21, v0 bitop3:0xde
	s_waitcnt vmcnt(6)
	s_cselect_b64 s[18:19], -1, 0
	s_ashr_i32 s71, s33, 31
	v_or_b32_e32 v147, s20, v2
	v_mov_b32_e32 v2, v1
	v_mov_b32_e32 v3, v1
	s_add_u32 s72, s42, s8
	v_mov_b32_e32 v0, v1
	v_add_u32_e32 v149, 0, v5
	v_mov_b64_e32 v[6:7], v[2:3]
	v_mov_b64_e32 v[10:11], v[2:3]
	v_mov_b64_e32 v[22:23], v[2:3]
	v_mov_b64_e32 v[26:27], v[2:3]
	v_mov_b64_e32 v[38:39], v[2:3]
	v_mov_b64_e32 v[42:43], v[2:3]
	v_mov_b64_e32 v[54:55], v[2:3]
	v_mov_b64_e32 v[58:59], v[2:3]
	v_mov_b64_e32 v[14:15], v[2:3]
	v_mov_b64_e32 v[18:19], v[2:3]
	v_mov_b64_e32 v[30:31], v[2:3]
	v_mov_b64_e32 v[34:35], v[2:3]
	v_mov_b64_e32 v[46:47], v[2:3]
	v_mov_b64_e32 v[50:51], v[2:3]
	v_mov_b64_e32 v[62:63], v[2:3]
	v_mov_b64_e32 v[66:67], v[2:3]
	v_mov_b64_e32 v[70:71], v[2:3]
	v_mov_b64_e32 v[74:75], v[2:3]
	v_mov_b64_e32 v[86:87], v[2:3]
	v_mov_b64_e32 v[90:91], v[2:3]
	v_mov_b64_e32 v[102:103], v[2:3]
	v_mov_b64_e32 v[106:107], v[2:3]
	v_mov_b64_e32 v[118:119], v[2:3]
	v_mov_b64_e32 v[122:123], v[2:3]
	v_mov_b64_e32 v[78:79], v[2:3]
	v_mov_b64_e32 v[82:83], v[2:3]
	v_mov_b64_e32 v[94:95], v[2:3]
	v_mov_b64_e32 v[98:99], v[2:3]
	v_mov_b64_e32 v[110:111], v[2:3]
	v_mov_b64_e32 v[114:115], v[2:3]
	v_mov_b64_e32 v[126:127], v[2:3]
	v_mov_b64_e32 v[130:131], v[2:3]
	s_mov_b32 s70, s46
	s_addc_u32 s73, s43, s9
	v_mov_b64_e32 v[140:141], 0x200
	v_mov_b64_e32 v[142:143], 0x1ff
	s_add_i32 s74, 0, 0x10000
	s_add_i32 s75, 0, 0x14000
	v_mov_b32_e32 v148, 0x358637bd
	s_mov_b64 s[20:21], 0x48000
	s_mov_b64 s[22:23], 0x50000
	s_mov_b64 s[24:25], 0x58000
	v_mov_b64_e32 v[4:5], v[0:1]
	v_mov_b64_e32 v[8:9], v[0:1]
	v_mov_b64_e32 v[20:21], v[0:1]
	v_mov_b64_e32 v[24:25], v[0:1]
	v_mov_b64_e32 v[36:37], v[0:1]
	v_mov_b64_e32 v[40:41], v[0:1]
	v_mov_b64_e32 v[52:53], v[0:1]
	v_mov_b64_e32 v[56:57], v[0:1]
	v_mov_b64_e32 v[12:13], v[0:1]
	v_mov_b64_e32 v[16:17], v[0:1]
	v_mov_b64_e32 v[28:29], v[0:1]
	v_mov_b64_e32 v[32:33], v[0:1]
	v_mov_b64_e32 v[44:45], v[0:1]
	v_mov_b64_e32 v[48:49], v[0:1]
	v_mov_b64_e32 v[60:61], v[0:1]
	v_mov_b64_e32 v[64:65], v[0:1]
	v_mov_b64_e32 v[68:69], v[0:1]
	v_mov_b64_e32 v[72:73], v[0:1]
	v_mov_b64_e32 v[84:85], v[0:1]
	v_mov_b64_e32 v[88:89], v[0:1]
	v_mov_b64_e32 v[100:101], v[0:1]
	v_mov_b64_e32 v[104:105], v[0:1]
	v_mov_b64_e32 v[116:117], v[0:1]
	v_mov_b64_e32 v[120:121], v[0:1]
	v_mov_b64_e32 v[76:77], v[0:1]
	v_mov_b64_e32 v[80:81], v[0:1]
	v_mov_b64_e32 v[92:93], v[0:1]
	v_mov_b64_e32 v[96:97], v[0:1]
	v_mov_b64_e32 v[108:109], v[0:1]
	v_mov_b64_e32 v[112:113], v[0:1]
	v_mov_b64_e32 v[124:125], v[0:1]
	v_mov_b64_e32 v[128:129], v[0:1]
	s_mov_b32 s12, s13
	s_mov_b32 s76, s13
	s_barrier
	s_branch .LBB0_1757
.LBB0_1755:
	s_lshl_b32 s6, s28, 8
	s_ashr_i32 s7, s6, 31
	s_lshl_b64 s[6:7], s[6:7], 2
	v_mbcnt_lo_u32_b32 v6, -1, 0
	v_mbcnt_hi_u32_b32 v6, -1, v6
	s_add_u32 s6, s72, s6
	v_and_b32_e32 v0, 15, v6
	v_lshlrev_b32_e32 v2, 2, v6
	v_and_b32_e32 v2, 0xffffff80, v2
	s_addc_u32 s7, s73, s7
	v_lshlrev_b32_e32 v0, 2, v0
	v_ashrrev_i32_e32 v3, 31, v2
	v_lshl_add_u64 v[4:5], s[6:7], 0, v[0:1]
	v_lshlrev_b32_e32 v0, 3, v6
	v_lshl_add_u64 v[2:3], v[2:3], 2, v[4:5]
	v_and_b32_e32 v0, 0x80, v0
	s_mov_b32 m0, s65
	v_lshl_add_u64 v[2:3], v[2:3], 0, v[0:1]
	global_load_lds_dword v[2:3], off
	v_lshl_add_u64 v[2:3], v[2:3], 0, 64
	s_add_i32 m0, s65, 0x100
	s_add_u32 s10, s30, 0x100
	global_load_lds_dword v[2:3], off
	ds_read_b128 v[2:5], v151
	ds_read_b128 v[6:9], v151 offset:1024
	ds_read_b128 v[10:13], v151 offset:2048
	ds_read_b128 v[14:17], v151 offset:3072
	ds_read_b128 v[18:21], v150
	ds_read_b128 v[22:25], v150 offset:1024
	ds_read_b128 v[26:29], v150 offset:2048
	ds_read_b128 v[30:33], v150 offset:3072
	s_addc_u32 s11, s31, 0
	s_add_u32 s8, s30, 0x180
	s_addc_u32 s9, s31, 0
	s_add_u32 s6, s34, 0x100
	s_addc_u32 s7, s35, 0
	s_add_u32 s40, s30, 0x40080
	s_addc_u32 s41, s31, 0
	s_mov_b32 m0, s85
	ds_read_b128 v[34:37], v149
	ds_read_b128 v[38:41], v149 offset:1024
	ds_read_b128 v[42:45], v149 offset:2048
	ds_read_b128 v[46:49], v149 offset:3072
	ds_read_b128 v[50:53], v149 offset:4096
	ds_read_b128 v[54:57], v149 offset:5120
	ds_read_b128 v[58:61], v149 offset:6144
	ds_read_b128 v[62:65], v149 offset:7168
	s_nop 0
	global_load_lds_dwordx4 v132, s[40:41]
	s_mov_b32 m0, s12
	s_nop 0
	global_load_lds_dwordx4 v136, s[40:41]
	s_waitcnt vmcnt(26)
	s_waitcnt lgkmcnt(0)
	s_barrier
	s_setprio 1
	s_waitcnt lgkmcnt(0)
	v_mfma_f32_16x16x32_bf16 v[90:93], v[2:5], v[58:61], 0
	v_mfma_f32_16x16x32_bf16 v[66:69], v[2:5], v[34:37], 0
	v_mfma_f32_16x16x32_bf16 v[70:73], v[10:13], v[34:37], 0
	v_mfma_f32_16x16x32_bf16 v[74:77], v[2:5], v[42:45], 0
	v_mfma_f32_16x16x32_bf16 v[78:81], v[10:13], v[42:45], 0
	v_mfma_f32_16x16x32_bf16 v[82:85], v[2:5], v[50:53], 0
	v_mfma_f32_16x16x32_bf16 v[86:89], v[10:13], v[50:53], 0
	v_mfma_f32_16x16x32_bf16 v[100:103], v[6:9], v[62:65], v[90:93]
	v_mfma_f32_16x16x32_bf16 v[90:93], v[10:13], v[58:61], 0
	v_mfma_f32_16x16x32_bf16 v[66:69], v[6:9], v[38:41], v[66:69]
	v_mfma_f32_16x16x32_bf16 v[70:73], v[14:17], v[38:41], v[70:73]
	v_mfma_f32_16x16x32_bf16 v[74:77], v[6:9], v[46:49], v[74:77]
	v_mfma_f32_16x16x32_bf16 v[78:81], v[14:17], v[46:49], v[78:81]
	v_mfma_f32_16x16x32_bf16 v[82:85], v[6:9], v[54:57], v[82:85]
	v_mfma_f32_16x16x32_bf16 v[86:89], v[14:17], v[54:57], v[86:89]
	v_mfma_f32_16x16x32_bf16 v[104:107], v[14:17], v[62:65], v[90:93]
	s_setprio 0
	s_setprio 1
	v_mfma_f32_16x16x32_bf16 v[90:93], v[18:21], v[34:37], 0
	v_mfma_f32_16x16x32_bf16 v[34:37], v[26:29], v[34:37], 0
	v_mfma_f32_16x16x32_bf16 v[116:119], v[22:25], v[38:41], v[90:93]
	v_mfma_f32_16x16x32_bf16 v[34:37], v[30:33], v[38:41], v[34:37]
	v_mfma_f32_16x16x32_bf16 v[38:41], v[18:21], v[42:45], 0
	v_mfma_f32_16x16x32_bf16 v[42:45], v[26:29], v[42:45], 0
	v_mfma_f32_16x16x32_bf16 v[38:41], v[22:25], v[46:49], v[38:41]
	v_mfma_f32_16x16x32_bf16 v[42:45], v[30:33], v[46:49], v[42:45]
	v_mfma_f32_16x16x32_bf16 v[46:49], v[18:21], v[50:53], 0
	v_mfma_f32_16x16x32_bf16 v[50:53], v[26:29], v[50:53], 0
	v_mfma_f32_16x16x32_bf16 v[46:49], v[22:25], v[54:57], v[46:49]
	v_mfma_f32_16x16x32_bf16 v[50:53], v[30:33], v[54:57], v[50:53]
	v_mfma_f32_16x16x32_bf16 v[54:57], v[18:21], v[58:61], 0
	v_mfma_f32_16x16x32_bf16 v[58:61], v[26:29], v[58:61], 0
	v_mfma_f32_16x16x32_bf16 v[54:57], v[22:25], v[62:65], v[54:57]
	v_mfma_f32_16x16x32_bf16 v[58:61], v[30:33], v[62:65], v[58:61]
	s_setprio 0
	s_barrier
	s_mov_b32 m0, s79
	ds_read_b128 v[62:65], v149 offset:16384
	ds_read_b128 v[90:93], v149 offset:17408
	ds_read_b128 v[94:97], v149 offset:18432
	ds_read_b128 v[108:111], v149 offset:19456
	ds_read_b128 v[112:115], v149 offset:20480
	ds_read_b128 v[120:123], v149 offset:21504
	ds_read_b128 v[124:127], v149 offset:22528
	ds_read_b128 v[128:131], v149 offset:23552
	s_nop 0
	global_load_lds_dwordx4 v134, s[6:7]
	s_mov_b64 s[98:99], s[6:7]
	s_add_u32 s6, s34, 0x40100
	s_mov_b32 m0, s27
	s_addc_u32 s7, s35, 0
	global_load_lds_dwordx4 v138, s[98:99]
	s_mov_b32 m0, s29
	s_nop 0
	global_load_lds_dwordx4 v134, s[6:7]
	s_mov_b32 m0, s77
	s_nop 0
	global_load_lds_dwordx4 v138, s[6:7]
	s_mov_b32 m0, s37
	s_nop 0
	global_load_lds_dwordx4 v132, s[10:11]
	s_mov_b32 m0, s39
	s_nop 0
	global_load_lds_dwordx4 v136, s[10:11]
	s_waitcnt vmcnt(26)
	s_waitcnt lgkmcnt(0)
	s_barrier
	s_setprio 1
	s_waitcnt lgkmcnt(0)
	v_mfma_f32_16x16x32_bf16 v[154:157], v[2:5], v[62:65], 0
	v_mfma_f32_16x16x32_bf16 v[162:165], v[2:5], v[94:97], 0
	v_mfma_f32_16x16x32_bf16 v[170:173], v[2:5], v[112:115], 0
	v_mfma_f32_16x16x32_bf16 v[2:5], v[2:5], v[124:127], 0
	v_mfma_f32_16x16x32_bf16 v[154:157], v[6:9], v[90:93], v[154:157]
	v_mfma_f32_16x16x32_bf16 v[162:165], v[6:9], v[108:111], v[162:165]
	v_mfma_f32_16x16x32_bf16 v[170:173], v[6:9], v[120:123], v[170:173]
	v_mfma_f32_16x16x32_bf16 v[2:5], v[6:9], v[128:131], v[2:5]
	v_mfma_f32_16x16x32_bf16 v[6:9], v[10:13], v[124:127], 0
	v_mfma_f32_16x16x32_bf16 v[158:161], v[10:13], v[62:65], 0
	v_mfma_f32_16x16x32_bf16 v[166:169], v[10:13], v[94:97], 0
	v_mfma_f32_16x16x32_bf16 v[174:177], v[10:13], v[112:115], 0
	v_mfma_f32_16x16x32_bf16 v[6:9], v[14:17], v[128:131], v[6:9]
	v_mfma_f32_16x16x32_bf16 v[158:161], v[14:17], v[90:93], v[158:161]
	v_mfma_f32_16x16x32_bf16 v[166:169], v[14:17], v[108:111], v[166:169]
	v_mfma_f32_16x16x32_bf16 v[174:177], v[14:17], v[120:123], v[174:177]
	s_setprio 0
	s_setprio 1
	v_mfma_f32_16x16x32_bf16 v[10:13], v[18:21], v[62:65], 0
	v_mfma_f32_16x16x32_bf16 v[178:181], v[22:25], v[90:93], v[10:13]
	v_mfma_f32_16x16x32_bf16 v[10:13], v[26:29], v[62:65], 0
	v_mfma_f32_16x16x32_bf16 v[182:185], v[30:33], v[90:93], v[10:13]
	v_mfma_f32_16x16x32_bf16 v[10:13], v[18:21], v[94:97], 0
	v_mfma_f32_16x16x32_bf16 v[186:189], v[22:25], v[108:111], v[10:13]
	v_mfma_f32_16x16x32_bf16 v[10:13], v[26:29], v[94:97], 0
	v_mfma_f32_16x16x32_bf16 v[190:193], v[30:33], v[108:111], v[10:13]
	v_mfma_f32_16x16x32_bf16 v[10:13], v[18:21], v[112:115], 0
	v_mfma_f32_16x16x32_bf16 v[194:197], v[22:25], v[120:123], v[10:13]
	v_mfma_f32_16x16x32_bf16 v[10:13], v[26:29], v[112:115], 0
	v_mfma_f32_16x16x32_bf16 v[198:201], v[30:33], v[120:123], v[10:13]
	v_mfma_f32_16x16x32_bf16 v[10:13], v[18:21], v[124:127], 0
	v_mfma_f32_16x16x32_bf16 v[202:205], v[22:25], v[128:131], v[10:13]
	v_mfma_f32_16x16x32_bf16 v[10:13], v[26:29], v[124:127], 0
	v_mfma_f32_16x16x32_bf16 v[206:209], v[30:33], v[128:131], v[10:13]
	s_setprio 0
	s_barrier
	s_nop 4
	ds_read_b128 v[10:13], v152
	ds_read_b128 v[14:17], v152 offset:1024
	ds_read_b128 v[20:23], v152 offset:2048
	ds_read_b128 v[24:27], v152 offset:3072
	ds_read_b128 v[210:213], v153
	ds_read_b128 v[214:217], v153 offset:1024
	ds_read_b128 v[218:221], v153 offset:2048
	ds_read_b128 v[150:153], v153 offset:3072
	s_add_u32 s6, s30, 0x40100
	s_addc_u32 s7, s31, 0
	s_mov_b32 m0, s66
	ds_read_b128 v[28:31], v149 offset:32768
	ds_read_b128 v[62:65], v149 offset:33792
	ds_read_b128 v[222:225], v149 offset:34816
	ds_read_b128 v[226:229], v149 offset:35840
	ds_read_b128 v[230:233], v149 offset:36864
	ds_read_b128 v[234:237], v149 offset:37888
	ds_read_b128 v[238:241], v149 offset:38912
	ds_read_b128 v[242:245], v149 offset:39936
	s_nop 0
	global_load_lds_dwordx4 v132, s[6:7]
	s_mov_b32 m0, s67
	s_nop 0
	global_load_lds_dwordx4 v136, s[6:7]
	s_waitcnt vmcnt(26)
	s_waitcnt lgkmcnt(0)
	s_barrier
	s_setprio 1
	s_waitcnt lgkmcnt(0)
	v_mfma_f32_16x16x32_bf16 v[66:69], v[10:13], v[28:31], v[66:69]
	v_mfma_f32_16x16x32_bf16 v[128:131], v[14:17], v[62:65], v[66:69]
	v_mfma_f32_16x16x32_bf16 v[66:69], v[20:23], v[28:31], v[70:73]
	v_mfma_f32_16x16x32_bf16 v[124:127], v[24:27], v[62:65], v[66:69]
	v_mfma_f32_16x16x32_bf16 v[66:69], v[10:13], v[222:225], v[74:77]
	v_mfma_f32_16x16x32_bf16 v[112:115], v[14:17], v[226:229], v[66:69]
	v_mfma_f32_16x16x32_bf16 v[66:69], v[20:23], v[222:225], v[78:81]
	v_mfma_f32_16x16x32_bf16 v[108:111], v[24:27], v[226:229], v[66:69]
	v_mfma_f32_16x16x32_bf16 v[66:69], v[10:13], v[230:233], v[82:85]
	v_mfma_f32_16x16x32_bf16 v[96:99], v[14:17], v[234:237], v[66:69]
	v_mfma_f32_16x16x32_bf16 v[66:69], v[20:23], v[230:233], v[86:89]
	v_mfma_f32_16x16x32_bf16 v[92:95], v[24:27], v[234:237], v[66:69]
	v_mfma_f32_16x16x32_bf16 v[66:69], v[10:13], v[238:241], v[100:103]
	v_mfma_f32_16x16x32_bf16 v[80:83], v[14:17], v[242:245], v[66:69]
	v_mfma_f32_16x16x32_bf16 v[66:69], v[20:23], v[238:241], v[104:107]
	v_mfma_f32_16x16x32_bf16 v[76:79], v[24:27], v[242:245], v[66:69]
	s_setprio 0
	s_setprio 1
	v_mfma_f32_16x16x32_bf16 v[66:69], v[210:213], v[28:31], v[116:119]
	v_mfma_f32_16x16x32_bf16 v[28:31], v[218:221], v[28:31], v[34:37]
	v_mfma_f32_16x16x32_bf16 v[116:119], v[150:153], v[62:65], v[28:31]
	v_mfma_f32_16x16x32_bf16 v[28:31], v[210:213], v[222:225], v[38:41]
	v_mfma_f32_16x16x32_bf16 v[104:107], v[214:217], v[226:229], v[28:31]
	v_mfma_f32_16x16x32_bf16 v[28:31], v[218:221], v[222:225], v[42:45]
	v_mfma_f32_16x16x32_bf16 v[100:103], v[150:153], v[226:229], v[28:31]
	v_mfma_f32_16x16x32_bf16 v[28:31], v[210:213], v[230:233], v[46:49]
	v_mfma_f32_16x16x32_bf16 v[88:91], v[214:217], v[234:237], v[28:31]
	v_mfma_f32_16x16x32_bf16 v[28:31], v[218:221], v[230:233], v[50:53]
	v_mfma_f32_16x16x32_bf16 v[84:87], v[150:153], v[234:237], v[28:31]
	v_mfma_f32_16x16x32_bf16 v[28:31], v[210:213], v[238:241], v[54:57]
	v_mfma_f32_16x16x32_bf16 v[72:75], v[214:217], v[242:245], v[28:31]
	v_mfma_f32_16x16x32_bf16 v[28:31], v[218:221], v[238:241], v[58:61]
	v_mfma_f32_16x16x32_bf16 v[120:123], v[214:217], v[62:65], v[66:69]
	v_mfma_f32_16x16x32_bf16 v[68:71], v[150:153], v[242:245], v[28:31]
	s_setprio 0
	s_barrier
	s_add_u32 s6, s34, 0x180
	s_addc_u32 s7, s35, 0
	s_mov_b32 m0, s86
	ds_read_b128 v[36:39], v149 offset:49152
	ds_read_b128 v[40:43], v149 offset:50176
	ds_read_b128 v[222:225], v149 offset:51200
	ds_read_b128 v[226:229], v149 offset:52224
	ds_read_b128 v[230:233], v149 offset:53248
	ds_read_b128 v[234:237], v149 offset:54272
	ds_read_b128 v[238:241], v149 offset:55296
	ds_read_b128 v[242:245], v149 offset:56320
	s_nop 0
	global_load_lds_dwordx4 v134, s[6:7]
	s_mov_b64 s[98:99], s[6:7]
	s_add_u32 s6, s34, 0x40180
	s_mov_b32 m0, s54
	s_addc_u32 s7, s35, 0
	global_load_lds_dwordx4 v138, s[98:99]
	s_mov_b32 m0, s55
	s_nop 0
	global_load_lds_dwordx4 v134, s[6:7]
	s_mov_b32 m0, s78
	s_nop 0
	global_load_lds_dwordx4 v138, s[6:7]
	s_mov_b32 m0, s68
	s_nop 0
	global_load_lds_dwordx4 v132, s[8:9]
	s_mov_b32 m0, s69
	s_nop 0
	global_load_lds_dwordx4 v136, s[8:9]
	s_waitcnt vmcnt(26)
	s_waitcnt lgkmcnt(0)
	s_barrier
	s_setprio 1
	s_waitcnt lgkmcnt(0)
	v_mfma_f32_16x16x32_bf16 v[28:31], v[10:13], v[36:39], v[154:157]
	v_mfma_f32_16x16x32_bf16 v[64:67], v[14:17], v[40:43], v[28:31]
	v_mfma_f32_16x16x32_bf16 v[28:31], v[20:23], v[36:39], v[158:161]
	v_mfma_f32_16x16x32_bf16 v[60:63], v[24:27], v[40:43], v[28:31]
	v_mfma_f32_16x16x32_bf16 v[28:31], v[10:13], v[222:225], v[162:165]
	v_mfma_f32_16x16x32_bf16 v[48:51], v[14:17], v[226:229], v[28:31]
	v_mfma_f32_16x16x32_bf16 v[28:31], v[20:23], v[222:225], v[166:169]
	v_mfma_f32_16x16x32_bf16 v[44:47], v[24:27], v[226:229], v[28:31]
	v_mfma_f32_16x16x32_bf16 v[28:31], v[10:13], v[230:233], v[170:173]
	v_mfma_f32_16x16x32_bf16 v[2:5], v[10:13], v[238:241], v[2:5]
	v_mfma_f32_16x16x32_bf16 v[32:35], v[14:17], v[234:237], v[28:31]
	v_mfma_f32_16x16x32_bf16 v[28:31], v[20:23], v[230:233], v[174:177]
	v_mfma_f32_16x16x32_bf16 v[16:19], v[14:17], v[242:245], v[2:5]
	v_mfma_f32_16x16x32_bf16 v[2:5], v[20:23], v[238:241], v[6:9]
	v_mfma_f32_16x16x32_bf16 v[28:31], v[24:27], v[234:237], v[28:31]
	v_mfma_f32_16x16x32_bf16 v[12:15], v[24:27], v[242:245], v[2:5]
	s_setprio 0
	s_setprio 1
	v_mfma_f32_16x16x32_bf16 v[2:5], v[210:213], v[36:39], v[178:181]
	v_mfma_f32_16x16x32_bf16 v[56:59], v[214:217], v[40:43], v[2:5]
	v_mfma_f32_16x16x32_bf16 v[2:5], v[218:221], v[36:39], v[182:185]
	v_mfma_f32_16x16x32_bf16 v[52:55], v[150:153], v[40:43], v[2:5]
	v_mfma_f32_16x16x32_bf16 v[2:5], v[210:213], v[222:225], v[186:189]
	v_mfma_f32_16x16x32_bf16 v[40:43], v[214:217], v[226:229], v[2:5]
	v_mfma_f32_16x16x32_bf16 v[2:5], v[218:221], v[222:225], v[190:193]
	v_mfma_f32_16x16x32_bf16 v[36:39], v[150:153], v[226:229], v[2:5]
	v_mfma_f32_16x16x32_bf16 v[2:5], v[210:213], v[230:233], v[194:197]
	v_mfma_f32_16x16x32_bf16 v[24:27], v[214:217], v[234:237], v[2:5]
	v_mfma_f32_16x16x32_bf16 v[2:5], v[218:221], v[230:233], v[198:201]
	v_mfma_f32_16x16x32_bf16 v[20:23], v[150:153], v[234:237], v[2:5]
	v_mfma_f32_16x16x32_bf16 v[2:5], v[210:213], v[238:241], v[202:205]
	v_mfma_f32_16x16x32_bf16 v[8:11], v[214:217], v[242:245], v[2:5]
	v_mfma_f32_16x16x32_bf16 v[2:5], v[218:221], v[238:241], v[206:209]
	v_mfma_f32_16x16x32_bf16 v[4:7], v[150:153], v[242:245], v[2:5]
	s_setprio 0
	s_barrier
	s_mov_b64 s[8:9], 0

; #define PG8_WAIT_V8_STRICT() asm volatile("s_waitcnt vmcnt(8)" ::: "memory")
; template <class Epi, class Sched, bool ALIGN_EPI = false, bool SP2 = false>
; __device__ __forceinline__ void gemm_phase(PG8_LAS unsigned char* lds, const Gemm g, const Sched& S, const Epi& E, int wave_s) {
;     ...
;         const bool has_next = S.next(ui + 1, nxt);
;         const char* nA = has_next ? (const char*)g.A + (size_t)nxt.pm * tstep : cA; const char* nB = has_next ? (const char*)g.Bt + (size_t)nxt.pn * tstep : cB;
;         for (int t = peeled ? 2 : 0; t < nt; t += 2) {
;             const bool last = (t == nt - 2);
;             const char* a1 = cA + (size_t)(t + 1) * kstep;
;             const char* a2 = last ? nA : cA + (size_t)(t + 2) * kstep; const char* b2 = last ? nB : cB + (size_t)(t + 2) * kstep;
;             const char* a3 = a2 + kstep; const char* b3 = b2 + kstep;
;             if (last && has_next) S.a_ready(nxt);
;             if constexpr (SP2) {
;             PG8_SP2_PAIR(PG8_WAIT_V8_STRICT);
.LBB0_1764:
	v_add_u32_e32 v151, s74, v146
	v_add_u32_e32 v150, s75, v146
	ds_read_b128 v[152:155], v151
	ds_read_b128 v[156:159], v151 offset:1024
	ds_read_b128 v[160:163], v151 offset:2048
	ds_read_b128 v[164:167], v151 offset:3072
	ds_read_b128 v[168:171], v150
	ds_read_b128 v[172:175], v150 offset:1024
	ds_read_b128 v[176:179], v150 offset:2048
	ds_read_b128 v[180:183], v150 offset:3072
	s_add_u32 s10, s56, 0x100
	s_addc_u32 s11, s57, 0
	s_cmp_eq_u32 s88, 12
	s_cselect_b32 s54, s61, s10
	s_cselect_b32 s55, s60, s11
	s_cselect_b32 s42, s87, s6
	s_cselect_b32 s43, s82, s7
	s_add_u32 s40, s54, 0x80
	s_addc_u32 s41, s55, 0
	s_add_u32 s56, s56, 0x40080
	s_addc_u32 s57, s57, 0
	s_add_i32 s85, s37, 0xc000
	ds_read_b128 v[184:187], v149
	ds_read_b128 v[188:191], v149 offset:1024
	ds_read_b128 v[192:195], v149 offset:2048
	ds_read_b128 v[196:199], v149 offset:3072
	ds_read_b128 v[200:203], v149 offset:4096
	ds_read_b128 v[204:207], v149 offset:5120
	ds_read_b128 v[208:211], v149 offset:6144
	ds_read_b128 v[212:215], v149 offset:7168
	s_mov_b32 m0, s85
	s_add_i32 s12, s37, 0xe000
	global_load_lds_dwordx4 v132, s[56:57]
	s_mov_b32 m0, s12
	s_nop 0
	global_load_lds_dwordx4 v136, s[56:57]
	s_waitcnt vmcnt(8)
	s_waitcnt lgkmcnt(0)
	s_barrier
	s_setprio 1
	s_waitcnt lgkmcnt(0)
	v_mfma_f32_16x16x32_bf16 v[128:131], v[152:155], v[184:187], v[128:131]
	v_mfma_f32_16x16x32_bf16 v[124:127], v[160:163], v[184:187], v[124:127]
	v_mfma_f32_16x16x32_bf16 v[112:115], v[152:155], v[192:195], v[112:115]
	v_mfma_f32_16x16x32_bf16 v[108:111], v[160:163], v[192:195], v[108:111]
	v_mfma_f32_16x16x32_bf16 v[96:99], v[152:155], v[200:203], v[96:99]
	v_mfma_f32_16x16x32_bf16 v[92:95], v[160:163], v[200:203], v[92:95]
	v_mfma_f32_16x16x32_bf16 v[80:83], v[152:155], v[208:211], v[80:83]
	v_mfma_f32_16x16x32_bf16 v[76:79], v[160:163], v[208:211], v[76:79]
	v_mfma_f32_16x16x32_bf16 v[128:131], v[156:159], v[188:191], v[128:131]
	v_mfma_f32_16x16x32_bf16 v[124:127], v[164:167], v[188:191], v[124:127]
	v_mfma_f32_16x16x32_bf16 v[112:115], v[156:159], v[196:199], v[112:115]
	v_mfma_f32_16x16x32_bf16 v[108:111], v[164:167], v[196:199], v[108:111]
	v_mfma_f32_16x16x32_bf16 v[96:99], v[156:159], v[204:207], v[96:99]
	v_mfma_f32_16x16x32_bf16 v[92:95], v[164:167], v[204:207], v[92:95]
	v_mfma_f32_16x16x32_bf16 v[80:83], v[156:159], v[212:215], v[80:83]
	v_mfma_f32_16x16x32_bf16 v[76:79], v[164:167], v[212:215], v[76:79]
	s_setprio 0
	s_setprio 1
	v_mfma_f32_16x16x32_bf16 v[120:123], v[168:171], v[184:187], v[120:123]
	v_mfma_f32_16x16x32_bf16 v[116:119], v[176:179], v[184:187], v[116:119]
	v_mfma_f32_16x16x32_bf16 v[104:107], v[168:171], v[192:195], v[104:107]
	v_mfma_f32_16x16x32_bf16 v[100:103], v[176:179], v[192:195], v[100:103]
	v_mfma_f32_16x16x32_bf16 v[88:91], v[168:171], v[200:203], v[88:91]
	v_mfma_f32_16x16x32_bf16 v[84:87], v[176:179], v[200:203], v[84:87]
	v_mfma_f32_16x16x32_bf16 v[72:75], v[168:171], v[208:211], v[72:75]
	v_mfma_f32_16x16x32_bf16 v[68:71], v[176:179], v[208:211], v[68:71]
	v_mfma_f32_16x16x32_bf16 v[120:123], v[172:175], v[188:191], v[120:123]
	v_mfma_f32_16x16x32_bf16 v[116:119], v[180:183], v[188:191], v[116:119]
	v_mfma_f32_16x16x32_bf16 v[104:107], v[172:175], v[196:199], v[104:107]
	v_mfma_f32_16x16x32_bf16 v[100:103], v[180:183], v[196:199], v[100:103]
	v_mfma_f32_16x16x32_bf16 v[88:91], v[172:175], v[204:207], v[88:91]
	v_mfma_f32_16x16x32_bf16 v[84:87], v[180:183], v[204:207], v[84:87]
	v_mfma_f32_16x16x32_bf16 v[72:75], v[172:175], v[212:215], v[72:75]
	v_mfma_f32_16x16x32_bf16 v[68:71], v[180:183], v[212:215], v[68:71]
	s_setprio 0
	s_barrier
	s_mov_b64 s[56:57], s[42:43]
	s_add_i32 s79, s74, s64
	ds_read_b128 v[184:187], v149 offset:16384
	ds_read_b128 v[188:191], v149 offset:17408
	ds_read_b128 v[192:195], v149 offset:18432
	ds_read_b128 v[196:199], v149 offset:19456
	ds_read_b128 v[200:203], v149 offset:20480
	ds_read_b128 v[204:207], v149 offset:21504
	ds_read_b128 v[208:211], v149 offset:22528
	ds_read_b128 v[212:215], v149 offset:23552
	s_mov_b32 m0, s79
	s_add_i32 s27, s79, 0x2000
	global_load_lds_dwordx4 v134, s[56:57]
	s_mov_b64 s[98:99], s[56:57]
	s_add_u32 s56, s42, 0x40000
	s_mov_b32 m0, s27
	s_addc_u32 s57, s43, 0
	s_add_i32 s29, s75, s64
	global_load_lds_dwordx4 v138, s[98:99]
	s_mov_b32 m0, s29
	s_add_i32 s77, s29, 0x2000
	global_load_lds_dwordx4 v134, s[56:57]
	s_mov_b64 s[98:99], s[56:57]
	s_mov_b32 m0, s77
	s_mov_b64 s[56:57], s[54:55]
	global_load_lds_dwordx4 v138, s[98:99]
	s_mov_b32 m0, s37
	s_nop 0
	global_load_lds_dwordx4 v132, s[56:57]
	s_mov_b32 m0, s39
	s_nop 0
	global_load_lds_dwordx4 v136, s[56:57]
	s_waitcnt vmcnt(8)
	s_waitcnt lgkmcnt(0)
	s_barrier
	s_setprio 1
	s_waitcnt lgkmcnt(0)
	v_mfma_f32_16x16x32_bf16 v[64:67], v[152:155], v[184:187], v[64:67]
	v_mfma_f32_16x16x32_bf16 v[60:63], v[160:163], v[184:187], v[60:63]
	v_mfma_f32_16x16x32_bf16 v[48:51], v[152:155], v[192:195], v[48:51]
	v_mfma_f32_16x16x32_bf16 v[44:47], v[160:163], v[192:195], v[44:47]
	v_mfma_f32_16x16x32_bf16 v[32:35], v[152:155], v[200:203], v[32:35]
	v_mfma_f32_16x16x32_bf16 v[28:31], v[160:163], v[200:203], v[28:31]
	v_mfma_f32_16x16x32_bf16 v[16:19], v[152:155], v[208:211], v[16:19]
	v_mfma_f32_16x16x32_bf16 v[12:15], v[160:163], v[208:211], v[12:15]
	v_mfma_f32_16x16x32_bf16 v[64:67], v[156:159], v[188:191], v[64:67]
	v_mfma_f32_16x16x32_bf16 v[60:63], v[164:167], v[188:191], v[60:63]
	v_mfma_f32_16x16x32_bf16 v[48:51], v[156:159], v[196:199], v[48:51]
	v_mfma_f32_16x16x32_bf16 v[44:47], v[164:167], v[196:199], v[44:47]
	v_mfma_f32_16x16x32_bf16 v[32:35], v[156:159], v[204:207], v[32:35]
	v_mfma_f32_16x16x32_bf16 v[28:31], v[164:167], v[204:207], v[28:31]
	v_mfma_f32_16x16x32_bf16 v[16:19], v[156:159], v[212:215], v[16:19]
	v_mfma_f32_16x16x32_bf16 v[12:15], v[164:167], v[212:215], v[12:15]
	s_setprio 0
	s_setprio 1
	v_mfma_f32_16x16x32_bf16 v[56:59], v[168:171], v[184:187], v[56:59]
	v_mfma_f32_16x16x32_bf16 v[52:55], v[176:179], v[184:187], v[52:55]
	v_mfma_f32_16x16x32_bf16 v[40:43], v[168:171], v[192:195], v[40:43]
	v_mfma_f32_16x16x32_bf16 v[36:39], v[176:179], v[192:195], v[36:39]
	v_mfma_f32_16x16x32_bf16 v[24:27], v[168:171], v[200:203], v[24:27]
	v_mfma_f32_16x16x32_bf16 v[20:23], v[176:179], v[200:203], v[20:23]
	v_mfma_f32_16x16x32_bf16 v[8:11], v[168:171], v[208:211], v[8:11]
	v_mfma_f32_16x16x32_bf16 v[2:5], v[176:179], v[208:211], v[4:7]
	v_mfma_f32_16x16x32_bf16 v[56:59], v[172:175], v[188:191], v[56:59]
	v_mfma_f32_16x16x32_bf16 v[52:55], v[180:183], v[188:191], v[52:55]
	v_mfma_f32_16x16x32_bf16 v[40:43], v[172:175], v[196:199], v[40:43]
	v_mfma_f32_16x16x32_bf16 v[36:39], v[180:183], v[196:199], v[36:39]
	v_mfma_f32_16x16x32_bf16 v[24:27], v[172:175], v[204:207], v[24:27]
	v_mfma_f32_16x16x32_bf16 v[20:23], v[180:183], v[204:207], v[20:23]
	v_mfma_f32_16x16x32_bf16 v[8:11], v[172:175], v[212:215], v[8:11]
	v_mfma_f32_16x16x32_bf16 v[2:5], v[180:183], v[212:215], v[2:5]
	s_setprio 0
	s_barrier
	s_add_i32 s86, 0, 0x18000
	s_add_i32 s56, 0, 0x1c000
	v_add_u32_e32 v152, s86, v146
	v_add_u32_e32 v153, s56, v146
	ds_read_b128 v[154:157], v152
	ds_read_b128 v[158:161], v152 offset:1024
	ds_read_b128 v[162:165], v152 offset:2048
	ds_read_b128 v[166:169], v152 offset:3072
	ds_read_b128 v[170:173], v153
	ds_read_b128 v[174:177], v153 offset:1024
	ds_read_b128 v[178:181], v153 offset:2048
	ds_read_b128 v[182:185], v153 offset:3072
	s_add_u32 s54, s54, 0x40000
	s_addc_u32 s55, s55, 0
	s_mov_b32 m0, s66
	ds_read_b128 v[186:189], v149 offset:32768
	ds_read_b128 v[190:193], v149 offset:33792
	ds_read_b128 v[194:197], v149 offset:34816
	ds_read_b128 v[198:201], v149 offset:35840
	ds_read_b128 v[202:205], v149 offset:36864
	ds_read_b128 v[206:209], v149 offset:37888
	ds_read_b128 v[210:213], v149 offset:38912
	ds_read_b128 v[214:217], v149 offset:39936
	s_nop 0
	global_load_lds_dwordx4 v132, s[54:55]
	s_mov_b32 m0, s67
	s_nop 0
	global_load_lds_dwordx4 v136, s[54:55]
	s_waitcnt vmcnt(8)
	s_waitcnt lgkmcnt(0)
	s_barrier
	s_setprio 1
	s_waitcnt lgkmcnt(0)
	v_mfma_f32_16x16x32_bf16 v[128:131], v[154:157], v[186:189], v[128:131]
	v_mfma_f32_16x16x32_bf16 v[124:127], v[162:165], v[186:189], v[124:127]
	v_mfma_f32_16x16x32_bf16 v[112:115], v[154:157], v[194:197], v[112:115]
	v_mfma_f32_16x16x32_bf16 v[108:111], v[162:165], v[194:197], v[108:111]
	v_mfma_f32_16x16x32_bf16 v[96:99], v[154:157], v[202:205], v[96:99]
	v_mfma_f32_16x16x32_bf16 v[92:95], v[162:165], v[202:205], v[92:95]
	v_mfma_f32_16x16x32_bf16 v[80:83], v[154:157], v[210:213], v[80:83]
	v_mfma_f32_16x16x32_bf16 v[76:79], v[162:165], v[210:213], v[76:79]
	v_mfma_f32_16x16x32_bf16 v[128:131], v[158:161], v[190:193], v[128:131]
	v_mfma_f32_16x16x32_bf16 v[124:127], v[166:169], v[190:193], v[124:127]
	v_mfma_f32_16x16x32_bf16 v[112:115], v[158:161], v[198:201], v[112:115]
	v_mfma_f32_16x16x32_bf16 v[108:111], v[166:169], v[198:201], v[108:111]
	v_mfma_f32_16x16x32_bf16 v[96:99], v[158:161], v[206:209], v[96:99]
	v_mfma_f32_16x16x32_bf16 v[92:95], v[166:169], v[206:209], v[92:95]
	v_mfma_f32_16x16x32_bf16 v[80:83], v[158:161], v[214:217], v[80:83]
	v_mfma_f32_16x16x32_bf16 v[76:79], v[166:169], v[214:217], v[76:79]
	s_setprio 0
	s_setprio 1
	v_mfma_f32_16x16x32_bf16 v[120:123], v[170:173], v[186:189], v[120:123]
	v_mfma_f32_16x16x32_bf16 v[116:119], v[178:181], v[186:189], v[116:119]
	v_mfma_f32_16x16x32_bf16 v[104:107], v[170:173], v[194:197], v[104:107]
	v_mfma_f32_16x16x32_bf16 v[100:103], v[178:181], v[194:197], v[100:103]
	v_mfma_f32_16x16x32_bf16 v[88:91], v[170:173], v[202:205], v[88:91]
	v_mfma_f32_16x16x32_bf16 v[84:87], v[178:181], v[202:205], v[84:87]
	v_mfma_f32_16x16x32_bf16 v[72:75], v[170:173], v[210:213], v[72:75]
	v_mfma_f32_16x16x32_bf16 v[68:71], v[178:181], v[210:213], v[68:71]
	v_mfma_f32_16x16x32_bf16 v[120:123], v[174:177], v[190:193], v[120:123]
	v_mfma_f32_16x16x32_bf16 v[116:119], v[182:185], v[190:193], v[116:119]
	v_mfma_f32_16x16x32_bf16 v[104:107], v[174:177], v[198:201], v[104:107]
	v_mfma_f32_16x16x32_bf16 v[100:103], v[182:185], v[198:201], v[100:103]
	v_mfma_f32_16x16x32_bf16 v[88:91], v[174:177], v[206:209], v[88:91]
	v_mfma_f32_16x16x32_bf16 v[84:87], v[182:185], v[206:209], v[84:87]
	v_mfma_f32_16x16x32_bf16 v[72:75], v[174:177], v[214:217], v[72:75]
	v_mfma_f32_16x16x32_bf16 v[68:71], v[182:185], v[214:217], v[68:71]
	s_setprio 0
	s_barrier
; #define PG8_LDA(dst, b, h) do { _Pragma("unroll") for (int m = 0; m < 4; ++m) _Pragma("unroll") for (int k = 0; k < 2; ++k) dst[m][k] = *(const PG8_LAS bf16x8*)(lds + PG8_SA(b, h) + aoff + m * 2048 + k * 1024); } while (0)
; #define PG8_WAIT_V(n) asm volatile("s_waitcnt vmcnt(" #n ")" ::: "memory")
; template <class Epi, class Sched, bool ALIGN_EPI = false, bool SP2 = false>
; __device__ __forceinline__ void gemm_phase(PG8_LAS unsigned char* lds, const Gemm g, const Sched& S, const Epi& E, int wave_s) {
;     ...
;         for (int t = peeled ? 2 : 0; t < nt; t += 2) {
;             const bool last = (t == nt - 2);
;             const char* a1 = cA + (size_t)(t + 1) * kstep;
;             const char* a2 = last ? nA : cA + (size_t)(t + 2) * kstep; const char* b2 = last ? nB : cB + (size_t)(t + 2) * kstep;
;             const char* a3 = a2 + kstep; const char* b3 = b2 + kstep;
;             if (last && has_next) S.a_ready(nxt);
;             if constexpr (SP2) {
;             PG8_SP2_PAIR(PG8_WAIT_V8_STRICT);
;             } else {
;             PG8_LDB(B0, 0, 0); PG8_SCHED; PG8_LDA(At, 0, 0); PG8_STAGE(PG8_SA(1, 1), a1 + hstep, voffA);
;             PG8_WAIT_L(8); PG8_BAR; PG8_WAIT_L(0); PG8_MMA(0, 0, At, B0); PG8_BAR; PG8_SCHED;
;             PG8_LDB(B1, 0, 1); PG8_STAGE(PG8_SB(0, 0), b2, voffB);
;             PG8_BAR; PG8_WAIT_L(0); PG8_MMA(0, 1, At, B1); PG8_BAR;
;             PG8_LDA(At, 0, 1); PG8_STAGE(PG8_SA(0, 0), a2, voffA);
;             PG8_BAR; PG8_WAIT_L(0); PG8_MMA(1, 0, At, B0); PG8_BAR; PG8_SCHED;
;             PG8_STAGE(PG8_SB(0, 1), b2 + hstep, voffB);
;             PG8_WAIT_V(6); PG8_BAR; PG8_MMA(1, 1, At, B1); PG8_BAR;
;             PG8_LDB(B0, 1, 0); PG8_SCHED; PG8_LDA(At, 1, 0); PG8_STAGE(PG8_SA(0, 1), a2 + hstep, voffA);
;             PG8_WAIT_L(8); PG8_BAR; PG8_WAIT_L(0); PG8_MMA(0, 0, At, B0); PG8_BAR; PG8_SCHED;
;             PG8_LDB(B1, 1, 1); PG8_STAGE(PG8_SB(1, 0), b3, voffB);
;             PG8_BAR; PG8_WAIT_L(0); PG8_MMA(0, 1, At, B1); PG8_BAR;
;             PG8_LDA(At, 1, 1); PG8_STAGE(PG8_SA(1, 0), a3, voffA);
;             PG8_BAR; PG8_WAIT_L(0); PG8_MMA(1, 0, At, B0); PG8_BAR; PG8_SCHED;
;             PG8_STAGE(PG8_SB(1, 1), b3 + hstep, voffB);
;             PG8_WAIT_V(6); PG8_BAR; PG8_MMA(1, 1, At, B1); PG8_BAR;
;             }
;         }
;         if constexpr (ALIGN_EPI) { if (wr == 0) PG8_BAR; }
	s_add_u32 s54, s42, 0x80
	s_addc_u32 s55, s43, 0
	s_add_i32 s86, s86, s64
	ds_read_b128 v[186:189], v149 offset:49152
	ds_read_b128 v[190:193], v149 offset:50176
	ds_read_b128 v[194:197], v149 offset:51200
	ds_read_b128 v[198:201], v149 offset:52224
	ds_read_b128 v[202:205], v149 offset:53248
	ds_read_b128 v[206:209], v149 offset:54272
	ds_read_b128 v[210:213], v149 offset:55296
	ds_read_b128 v[214:217], v149 offset:56320
	s_mov_b32 m0, s86
	s_nop 0
	global_load_lds_dwordx4 v134, s[54:55]
	s_mov_b64 s[98:99], s[54:55]
	s_add_i32 s54, s86, 0x2000
	s_add_u32 s42, s42, 0x40080
	s_mov_b32 m0, s54
	s_addc_u32 s43, s43, 0
	s_add_i32 s55, s56, s64
	global_load_lds_dwordx4 v138, s[98:99]
	s_mov_b32 m0, s55
	s_add_i32 s78, s55, 0x2000
	global_load_lds_dwordx4 v134, s[42:43]
	s_mov_b32 m0, s78
	s_nop 0
	global_load_lds_dwordx4 v138, s[42:43]
	s_mov_b32 m0, s68
	s_nop 0
	global_load_lds_dwordx4 v132, s[40:41]
	s_mov_b32 m0, s69
	s_nop 0
	global_load_lds_dwordx4 v136, s[40:41]
	s_waitcnt vmcnt(8)
	s_waitcnt lgkmcnt(0)
	s_barrier
	s_setprio 1
	s_waitcnt lgkmcnt(0)
	v_mfma_f32_16x16x32_bf16 v[64:67], v[154:157], v[186:189], v[64:67]
	v_mfma_f32_16x16x32_bf16 v[60:63], v[162:165], v[186:189], v[60:63]
	v_mfma_f32_16x16x32_bf16 v[48:51], v[154:157], v[194:197], v[48:51]
	v_mfma_f32_16x16x32_bf16 v[44:47], v[162:165], v[194:197], v[44:47]
	v_mfma_f32_16x16x32_bf16 v[32:35], v[154:157], v[202:205], v[32:35]
	v_mfma_f32_16x16x32_bf16 v[28:31], v[162:165], v[202:205], v[28:31]
	v_mfma_f32_16x16x32_bf16 v[16:19], v[154:157], v[210:213], v[16:19]
	v_mfma_f32_16x16x32_bf16 v[12:15], v[162:165], v[210:213], v[12:15]
	v_mfma_f32_16x16x32_bf16 v[64:67], v[158:161], v[190:193], v[64:67]
	v_mfma_f32_16x16x32_bf16 v[60:63], v[166:169], v[190:193], v[60:63]
	v_mfma_f32_16x16x32_bf16 v[48:51], v[158:161], v[198:201], v[48:51]
	v_mfma_f32_16x16x32_bf16 v[44:47], v[166:169], v[198:201], v[44:47]
	v_mfma_f32_16x16x32_bf16 v[32:35], v[158:161], v[206:209], v[32:35]
	v_mfma_f32_16x16x32_bf16 v[28:31], v[166:169], v[206:209], v[28:31]
	v_mfma_f32_16x16x32_bf16 v[16:19], v[158:161], v[214:217], v[16:19]
	v_mfma_f32_16x16x32_bf16 v[12:15], v[166:169], v[214:217], v[12:15]
	s_setprio 0
	s_setprio 1
	v_mfma_f32_16x16x32_bf16 v[56:59], v[170:173], v[186:189], v[56:59]
	v_mfma_f32_16x16x32_bf16 v[52:55], v[178:181], v[186:189], v[52:55]
	v_mfma_f32_16x16x32_bf16 v[40:43], v[170:173], v[194:197], v[40:43]
	v_mfma_f32_16x16x32_bf16 v[36:39], v[178:181], v[194:197], v[36:39]
	v_mfma_f32_16x16x32_bf16 v[24:27], v[170:173], v[202:205], v[24:27]
	v_mfma_f32_16x16x32_bf16 v[20:23], v[178:181], v[202:205], v[20:23]
	v_mfma_f32_16x16x32_bf16 v[6:9], v[170:173], v[210:213], v[8:11]
	v_mfma_f32_16x16x32_bf16 v[2:5], v[178:181], v[210:213], v[2:5]
	v_mfma_f32_16x16x32_bf16 v[56:59], v[174:177], v[190:193], v[56:59]
	v_mfma_f32_16x16x32_bf16 v[52:55], v[182:185], v[190:193], v[52:55]
	v_mfma_f32_16x16x32_bf16 v[40:43], v[174:177], v[198:201], v[40:43]
	v_mfma_f32_16x16x32_bf16 v[36:39], v[182:185], v[198:201], v[36:39]
	v_mfma_f32_16x16x32_bf16 v[24:27], v[174:177], v[206:209], v[24:27]
	v_mfma_f32_16x16x32_bf16 v[20:23], v[182:185], v[206:209], v[20:23]
	v_mfma_f32_16x16x32_bf16 v[8:11], v[174:177], v[214:217], v[6:9]
	v_mfma_f32_16x16x32_bf16 v[4:7], v[182:185], v[214:217], v[2:5]
	s_setprio 0
	s_barrier
	s_add_i32 s88, s88, 2
	s_add_u32 s6, s6, 0x100
	s_addc_u32 s7, s7, 0
	s_cmp_gt_u32 s88, 13
	s_mov_b64 s[56:57], s[10:11]
	s_cbranch_scc0 .LBB0_1764
	s_and_b64 vcc, exec, s[18:19]
	s_cbranch_vccz .LBB0_1767
	s_barrier

; __device__ __forceinline__ int lane_id_() { int l; asm volatile("v_mbcnt_lo_u32_b32 %0, -1, 0\n\tv_mbcnt_hi_u32_b32 %0, -1, %0" : "=v"(l)); return l; }
; #define PG8_LAS __attribute__((address_space(3)))
; #define PG8_STAGE(bufoff, gbase, voff) do { const char* gb_ = (const char*)(gbase); asm volatile("" : "+s"(gb_));   \
;         _Pragma("unroll") for (int _i = 0; _i < 2; ++_i) \
;         __builtin_amdgcn_global_load_lds((const unsigned*)(gb_ + (voff)[_i]), (PG8_LAS unsigned*)(lds + (bufoff) + ldsw + _i * 8192), 16, 0, 0); } while (0)
; #define PG8_WAIT_V(n) asm volatile("s_waitcnt vmcnt(" #n ")" ::: "memory")
; #define PG8_BAR __builtin_amdgcn_s_barrier()
;     __device__ __forceinline__ void operator()(const f32x4 (&acc)[2][2][4][2], const Unit& u, int wr, int wc, int fr, int fq, PG8_LAS unsigned char* lds, int wid) const {
;     ...
;                 }
;                 if (!LAST) { s += __shfl_xor(s, 16); s += __shfl_xor(s, 32);
;                     if (fq == 0) *(PG8_LAS float*)(lds + PRE_SLOT + 4096 + ((wr * 64 + fr + ai * HALF + m * 16) * 4 + wc) * 4) = s; }
;             }
;         if (!LAST) {
;             asm volatile("s_waitcnt lgkmcnt(0)" ::: "memory"); __builtin_amdgcn_s_barrier(); asm volatile("" ::: "memory");
;             if (wid < 4) { const int r = wid * 64 + lane_id_();
;                 const f32x4 p = *(const PG8_LAS f32x4*)(lds + PRE_SLOT + 4096 + r * 16);
;                 __hip_atomic_fetch_add(ssq + u.pm * BM + r, (p[0] + p[1]) + (p[2] + p[3]), __ATOMIC_RELAXED, __HIP_MEMORY_SCOPE_AGENT); }
; template <class Epi, class Sched, bool ALIGN_EPI = false, bool SP2 = false>
; __device__ __forceinline__ void gemm_phase(PG8_LAS unsigned char* lds, const Gemm g, const Sched& S, const Epi& E, int wave_s) {
;     ...
;         PG8_WAIT_V(2); PG8_BAR;
;         PG8_STAGE(PG8_SB(1, 0), cB + kstep, voffB); PG8_STAGE(PG8_SA(1, 0), cA + kstep, voffA); PG8_STAGE(PG8_SB(1, 1), cB + hstep + kstep, voffB);
;         PG8_WAIT_V(6); PG8_BAR;
.LBB0_2292:
	s_and_b32 s10, s6, 3
	s_lshl_b32 s11, s7, 13
	s_lshl_b32 s16, s10, 12
	s_add_u32 s8, s42, 0x80
	s_addc_u32 s9, s43, 0
	s_waitcnt vmcnt(2)
	s_barrier
	s_add_i32 m0, s65, 0x18000
	s_nop 0
	global_load_lds_dwordx4 v130, s[8:9]
	s_add_i32 m0, s65, 0x1a000
	s_nop 0
	global_load_lds_dwordx4 v134, s[8:9]
	s_add_u32 s8, s40, 0x80
	s_addc_u32 s9, s41, 0
	s_add_i32 s70, s65, 0x8000
	s_mov_b32 m0, s70
	s_add_i32 s71, s65, 0xa000
	global_load_lds_dwordx4 v128, s[8:9]
	s_mov_b64 s[98:99], s[8:9]
	s_add_u32 s8, s42, 0x40080
	s_mov_b32 m0, s71
	s_addc_u32 s9, s43, 0
	global_load_lds_dwordx4 v132, s[98:99]
	s_add_i32 m0, s65, 0x1c000
	s_nop 0
	global_load_lds_dwordx4 v130, s[8:9]
	s_add_i32 m0, s65, 0x1e000
	v_and_b32_e32 v1, 15, v0
	global_load_lds_dwordx4 v134, s[8:9]
	v_bfe_u32 v2, v0, 4, 2
	v_lshlrev_b32_e32 v4, 4, v2
	v_lshlrev_b32_e32 v0, 2, v0
	v_lshl_or_b32 v144, s7, 6, v1
	v_lshl_or_b32 v1, v1, 6, v4
	v_and_b32_e32 v0, 32, v0
	s_cmpk_lt_u32 s72, 0x100
	v_lshlrev_b32_e32 v3, 3, v2
	v_bitop3_b32 v4, v1, s11, v0 bitop3:0xde
	v_bitop3_b32 v145, v1, s16, v0 bitop3:0xde
	s_cselect_b64 s[16:17], -1, 0
	v_lshlrev_b32_e32 v0, 4, v144
	s_add_i32 s7, 0, 0x22400
	v_lshl_or_b32 v146, s10, 5, v3
	v_add_u32_e32 v1, s7, v0
	s_lshl_b32 s7, s10, 2
	s_add_i32 s10, 0, 0x22500
	v_cmp_eq_u32_e64 s[8:9], 0, v2
	v_add_u32_e32 v2, s10, v0
	s_add_i32 s10, 0, 0x22600
	v_add_u32_e32 v3, s10, v0
	s_add_i32 s10, 0, 0x22700
	v_add_u32_e32 v5, s10, v0
	s_add_i32 s10, 0, 0x22c00
	v_add_u32_e32 v6, s10, v0
	s_add_i32 s10, 0, 0x22d00
	v_add_u32_e32 v7, s10, v0
	s_add_i32 s10, 0, 0x22e00
	v_add_u32_e32 v8, s10, v0
	s_add_i32 s10, 0, 0x22f00
	s_waitcnt vmcnt(6)
	s_cmp_lt_i32 s6, 4
	v_add_u32_e32 v0, s10, v0
	s_cselect_b64 s[18:19], -1, 0
	s_add_i32 s75, 0, 0x10000
	s_add_i32 s76, 0, 0x14000
	s_andn2_b32 s72, s72, 63
	s_mov_b32 s73, s46
	s_ashr_i32 s74, s33, 31
	v_mov_b64_e32 v[136:137], 0x100
	v_mov_b64_e32 v[138:139], 0xff
	v_add_u32_e32 v147, s75, v145
	v_add_u32_e32 v148, s76, v145
	v_add_u32_e32 v149, 0, v4
	v_mbcnt_hi_u32_b32 v150, -1, v254
	v_add_u32_e32 v151, s7, v1
	v_add_u32_e32 v152, s7, v2
	v_add_u32_e32 v153, s7, v3
	v_add_u32_e32 v154, s7, v5
	v_add_u32_e32 v155, s7, v6
	s_mov_b64 s[20:21], 0x48000
	v_add_u32_e32 v156, s7, v7
	s_mov_b64 s[22:23], 0x50000
	v_add_u32_e32 v157, s7, v8
	s_mov_b64 s[24:25], 0x58000
	v_add_u32_e32 v158, s7, v0
	s_barrier
	s_branch .LBB0_2295

; template <class Epi, class Sched, bool ALIGN_EPI = false, bool SP2 = false>
; __device__ __forceinline__ void gemm_phase(PG8_LAS unsigned char* lds, const Gemm g, const Sched& S, const Epi& E, int wave_s) {
;     ...
;         const bool has_next = S.next(ui + 1, nxt);
;         const char* nA = has_next ? (const char*)g.A + (size_t)nxt.pm * tstep : cA; const char* nB = has_next ? (const char*)g.Bt + (size_t)nxt.pn * tstep : cB;
;         for (int t = peeled ? 2 : 0; t < nt; t += 2) {
;             const bool last = (t == nt - 2);
;             const char* a1 = cA + (size_t)(t + 1) * kstep;
;             const char* a2 = last ? nA : cA + (size_t)(t + 2) * kstep; const char* b2 = last ? nB : cB + (size_t)(t + 2) * kstep;
;             const char* a3 = a2 + kstep; const char* b3 = b2 + kstep;
;             if (last && has_next) S.a_ready(nxt);
.LBB0_2302:
	ds_read_b128 v[140:143], v147
	ds_read_b128 v[160:163], v147 offset:1024
	ds_read_b128 v[164:167], v147 offset:2048
	ds_read_b128 v[168:171], v147 offset:3072
	ds_read_b128 v[172:175], v148
	ds_read_b128 v[176:179], v148 offset:1024
	ds_read_b128 v[180:183], v148 offset:2048
	ds_read_b128 v[184:187], v148 offset:3072
	s_add_u32 s42, s40, 0x100
	s_addc_u32 s43, s41, 0
	s_cmp_eq_u32 s79, 12
	s_cselect_b32 s58, s37, s42
	s_cselect_b32 s59, s29, s43
	s_cselect_b32 s56, s39, s77
	s_cselect_b32 s57, s27, s78
	s_add_u32 s54, s58, 0x80
	s_addc_u32 s55, s59, 0
	s_add_u32 s6, s40, 0x40080
	s_addc_u32 s7, s41, 0
	ds_read_b128 v[188:191], v149
	ds_read_b128 v[192:195], v149 offset:1024
	ds_read_b128 v[196:199], v149 offset:2048
	ds_read_b128 v[200:203], v149 offset:3072
	ds_read_b128 v[204:207], v149 offset:4096
	ds_read_b128 v[208:211], v149 offset:5120
	ds_read_b128 v[212:215], v149 offset:6144
	ds_read_b128 v[216:219], v149 offset:7168
	s_add_i32 m0, s65, 0xc000
	s_nop 0
	global_load_lds_dwordx4 v128, s[6:7]
	s_add_i32 m0, s65, 0xe000
	s_nop 0
	global_load_lds_dwordx4 v132, s[6:7]
	s_waitcnt vmcnt(8)
	s_waitcnt lgkmcnt(0)
	s_barrier
	s_setprio 1
	s_waitcnt lgkmcnt(0)
	v_mfma_f32_16x16x32_bf16 v[124:127], v[140:143], v[188:191], v[124:127]
	v_mfma_f32_16x16x32_bf16 v[120:123], v[164:167], v[188:191], v[120:123]
	v_mfma_f32_16x16x32_bf16 v[108:111], v[140:143], v[196:199], v[108:111]
	v_mfma_f32_16x16x32_bf16 v[104:107], v[164:167], v[196:199], v[104:107]
	v_mfma_f32_16x16x32_bf16 v[92:95], v[140:143], v[204:207], v[92:95]
	v_mfma_f32_16x16x32_bf16 v[88:91], v[164:167], v[204:207], v[88:91]
	v_mfma_f32_16x16x32_bf16 v[76:79], v[140:143], v[212:215], v[76:79]
	v_mfma_f32_16x16x32_bf16 v[72:75], v[164:167], v[212:215], v[72:75]
	v_mfma_f32_16x16x32_bf16 v[124:127], v[160:163], v[192:195], v[124:127]
	v_mfma_f32_16x16x32_bf16 v[120:123], v[168:171], v[192:195], v[120:123]
	v_mfma_f32_16x16x32_bf16 v[108:111], v[160:163], v[200:203], v[108:111]
	v_mfma_f32_16x16x32_bf16 v[104:107], v[168:171], v[200:203], v[104:107]
	v_mfma_f32_16x16x32_bf16 v[92:95], v[160:163], v[208:211], v[92:95]
	v_mfma_f32_16x16x32_bf16 v[88:91], v[168:171], v[208:211], v[88:91]
	v_mfma_f32_16x16x32_bf16 v[76:79], v[160:163], v[216:219], v[76:79]
	v_mfma_f32_16x16x32_bf16 v[72:75], v[168:171], v[216:219], v[72:75]
	s_setprio 0
	s_setprio 1
	v_mfma_f32_16x16x32_bf16 v[116:119], v[172:175], v[188:191], v[116:119]
	v_mfma_f32_16x16x32_bf16 v[112:115], v[180:183], v[188:191], v[112:115]
	v_mfma_f32_16x16x32_bf16 v[100:103], v[172:175], v[196:199], v[100:103]
	v_mfma_f32_16x16x32_bf16 v[96:99], v[180:183], v[196:199], v[96:99]
	v_mfma_f32_16x16x32_bf16 v[84:87], v[172:175], v[204:207], v[84:87]
	v_mfma_f32_16x16x32_bf16 v[80:83], v[180:183], v[204:207], v[80:83]
	v_mfma_f32_16x16x32_bf16 v[68:71], v[172:175], v[212:215], v[68:71]
	v_mfma_f32_16x16x32_bf16 v[64:67], v[180:183], v[212:215], v[64:67]
	v_mfma_f32_16x16x32_bf16 v[116:119], v[176:179], v[192:195], v[116:119]
	v_mfma_f32_16x16x32_bf16 v[112:115], v[184:187], v[192:195], v[112:115]
	v_mfma_f32_16x16x32_bf16 v[100:103], v[176:179], v[200:203], v[100:103]
	v_mfma_f32_16x16x32_bf16 v[96:99], v[184:187], v[200:203], v[96:99]
	v_mfma_f32_16x16x32_bf16 v[84:87], v[176:179], v[208:211], v[84:87]
	v_mfma_f32_16x16x32_bf16 v[80:83], v[184:187], v[208:211], v[80:83]
	v_mfma_f32_16x16x32_bf16 v[68:71], v[176:179], v[216:219], v[68:71]
	v_mfma_f32_16x16x32_bf16 v[64:67], v[184:187], v[216:219], v[64:67]
	s_setprio 0
	s_barrier
	s_mov_b64 s[6:7], s[56:57]
	s_add_i32 s40, s75, s64
	ds_read_b128 v[188:191], v149 offset:16384
	ds_read_b128 v[192:195], v149 offset:17408
	ds_read_b128 v[196:199], v149 offset:18432
	ds_read_b128 v[200:203], v149 offset:19456
	ds_read_b128 v[204:207], v149 offset:20480
	ds_read_b128 v[208:211], v149 offset:21504
	ds_read_b128 v[212:215], v149 offset:22528
	ds_read_b128 v[216:219], v149 offset:23552
	s_mov_b32 m0, s40
	s_nop 0
	global_load_lds_dwordx4 v130, s[6:7]
	s_add_i32 m0, s40, 0x2000
	s_nop 0
	global_load_lds_dwordx4 v134, s[6:7]
	s_add_u32 s6, s56, 0x40000
	s_addc_u32 s7, s57, 0
	s_add_i32 s40, s76, s64
	s_mov_b32 m0, s40
	s_nop 0
	global_load_lds_dwordx4 v130, s[6:7]
	s_mov_b64 s[98:99], s[6:7]
	s_add_i32 m0, s40, 0x2000
	s_mov_b64 s[6:7], s[58:59]
	global_load_lds_dwordx4 v134, s[98:99]
	s_mov_b32 m0, s65
	s_nop 0
	global_load_lds_dwordx4 v128, s[6:7]
	s_mov_b32 m0, s66
	s_nop 0
	global_load_lds_dwordx4 v132, s[6:7]
	s_waitcnt vmcnt(8)
	s_waitcnt lgkmcnt(0)
	s_barrier
	s_setprio 1
	s_waitcnt lgkmcnt(0)
	v_mfma_f32_16x16x32_bf16 v[60:63], v[140:143], v[188:191], v[60:63]
	v_mfma_f32_16x16x32_bf16 v[56:59], v[164:167], v[188:191], v[56:59]
	v_mfma_f32_16x16x32_bf16 v[44:47], v[140:143], v[196:199], v[44:47]
	v_mfma_f32_16x16x32_bf16 v[40:43], v[164:167], v[196:199], v[40:43]
	v_mfma_f32_16x16x32_bf16 v[28:31], v[140:143], v[204:207], v[28:31]
	v_mfma_f32_16x16x32_bf16 v[24:27], v[164:167], v[204:207], v[24:27]
	v_mfma_f32_16x16x32_bf16 v[12:15], v[140:143], v[212:215], v[12:15]
	v_mfma_f32_16x16x32_bf16 v[8:11], v[164:167], v[212:215], v[8:11]
	v_mfma_f32_16x16x32_bf16 v[60:63], v[160:163], v[192:195], v[60:63]
	v_mfma_f32_16x16x32_bf16 v[56:59], v[168:171], v[192:195], v[56:59]
	v_mfma_f32_16x16x32_bf16 v[44:47], v[160:163], v[200:203], v[44:47]
	v_mfma_f32_16x16x32_bf16 v[40:43], v[168:171], v[200:203], v[40:43]
	v_mfma_f32_16x16x32_bf16 v[28:31], v[160:163], v[208:211], v[28:31]
	v_mfma_f32_16x16x32_bf16 v[24:27], v[168:171], v[208:211], v[24:27]
	v_mfma_f32_16x16x32_bf16 v[12:15], v[160:163], v[216:219], v[12:15]
	v_mfma_f32_16x16x32_bf16 v[8:11], v[168:171], v[216:219], v[8:11]
	s_setprio 0
	s_setprio 1
	v_mfma_f32_16x16x32_bf16 v[52:55], v[172:175], v[188:191], v[52:55]
	v_mfma_f32_16x16x32_bf16 v[48:51], v[180:183], v[188:191], v[48:51]
	v_mfma_f32_16x16x32_bf16 v[36:39], v[172:175], v[196:199], v[36:39]
	v_mfma_f32_16x16x32_bf16 v[32:35], v[180:183], v[196:199], v[32:35]
	v_mfma_f32_16x16x32_bf16 v[20:23], v[172:175], v[204:207], v[20:23]
	v_mfma_f32_16x16x32_bf16 v[16:19], v[180:183], v[204:207], v[16:19]
	v_mfma_f32_16x16x32_bf16 v[4:7], v[172:175], v[212:215], v[4:7]
	v_mfma_f32_16x16x32_bf16 v[0:3], v[180:183], v[212:215], v[0:3]
	v_mfma_f32_16x16x32_bf16 v[52:55], v[176:179], v[192:195], v[52:55]
	v_mfma_f32_16x16x32_bf16 v[48:51], v[184:187], v[192:195], v[48:51]
	v_mfma_f32_16x16x32_bf16 v[36:39], v[176:179], v[200:203], v[36:39]
	v_mfma_f32_16x16x32_bf16 v[32:35], v[184:187], v[200:203], v[32:35]
	v_mfma_f32_16x16x32_bf16 v[20:23], v[176:179], v[208:211], v[20:23]
	v_mfma_f32_16x16x32_bf16 v[16:19], v[184:187], v[208:211], v[16:19]
	v_mfma_f32_16x16x32_bf16 v[4:7], v[176:179], v[216:219], v[4:7]
	v_mfma_f32_16x16x32_bf16 v[0:3], v[184:187], v[216:219], v[0:3]
	s_setprio 0
	s_barrier
; #define PG8_LDA(dst, b, h) do { _Pragma("unroll") for (int m = 0; m < 4; ++m) _Pragma("unroll") for (int k = 0; k < 2; ++k) dst[m][k] = *(const PG8_LAS bf16x8*)(lds + PG8_SA(b, h) + aoff + m * 2048 + k * 1024); } while (0)
; #define PG8_WAIT_V(n) asm volatile("s_waitcnt vmcnt(" #n ")" ::: "memory")
; template <class Epi, class Sched, bool ALIGN_EPI = false, bool SP2 = false>
; __device__ __forceinline__ void gemm_phase(PG8_LAS unsigned char* lds, const Gemm g, const Sched& S, const Epi& E, int wave_s) {
;     ...
;         for (int t = peeled ? 2 : 0; t < nt; t += 2) {
;             const bool last = (t == nt - 2);
;             const char* a1 = cA + (size_t)(t + 1) * kstep;
;             const char* a2 = last ? nA : cA + (size_t)(t + 2) * kstep; const char* b2 = last ? nB : cB + (size_t)(t + 2) * kstep;
;             const char* a3 = a2 + kstep; const char* b3 = b2 + kstep;
;             if (last && has_next) S.a_ready(nxt);
;             if constexpr (SP2) {
;             PG8_SP2_PAIR(PG8_WAIT_V8_STRICT);
;             } else {
;             PG8_LDB(B0, 0, 0); PG8_SCHED; PG8_LDA(At, 0, 0); PG8_STAGE(PG8_SA(1, 1), a1 + hstep, voffA);
;             PG8_WAIT_L(8); PG8_BAR; PG8_WAIT_L(0); PG8_MMA(0, 0, At, B0); PG8_BAR; PG8_SCHED;
;             PG8_LDB(B1, 0, 1); PG8_STAGE(PG8_SB(0, 0), b2, voffB);
;             PG8_BAR; PG8_WAIT_L(0); PG8_MMA(0, 1, At, B1); PG8_BAR;
;             PG8_LDA(At, 0, 1); PG8_STAGE(PG8_SA(0, 0), a2, voffA);
;             PG8_BAR; PG8_WAIT_L(0); PG8_MMA(1, 0, At, B0); PG8_BAR; PG8_SCHED;
;             PG8_STAGE(PG8_SB(0, 1), b2 + hstep, voffB);
;             PG8_WAIT_V(6); PG8_BAR; PG8_MMA(1, 1, At, B1); PG8_BAR;
;             PG8_LDB(B0, 1, 0); PG8_SCHED; PG8_LDA(At, 1, 0); PG8_STAGE(PG8_SA(0, 1), a2 + hstep, voffA);
;             PG8_WAIT_L(8); PG8_BAR; PG8_WAIT_L(0); PG8_MMA(0, 0, At, B0); PG8_BAR; PG8_SCHED;
;             PG8_LDB(B1, 1, 1); PG8_STAGE(PG8_SB(1, 0), b3, voffB);
;             PG8_BAR; PG8_WAIT_L(0); PG8_MMA(0, 1, At, B1); PG8_BAR;
;             PG8_LDA(At, 1, 1); PG8_STAGE(PG8_SA(1, 0), a3, voffA);
;             PG8_BAR; PG8_WAIT_L(0); PG8_MMA(1, 0, At, B0); PG8_BAR; PG8_SCHED;
;             PG8_STAGE(PG8_SB(1, 1), b3 + hstep, voffB);
;             PG8_WAIT_V(6); PG8_BAR; PG8_MMA(1, 1, At, B1); PG8_BAR;
;             }
;         }
;         if constexpr (ALIGN_EPI) { if (wr == 0) PG8_BAR; }
	s_add_i32 s40, 0, 0x18000
	v_add_u32_e32 v159, s40, v145
	s_add_i32 s41, 0, 0x1c000
	ds_read_b128 v[140:143], v159
	ds_read_b128 v[160:163], v159 offset:1024
	ds_read_b128 v[164:167], v159 offset:2048
	ds_read_b128 v[168:171], v159 offset:3072
	v_add_u32_e32 v159, s41, v145
	ds_read_b128 v[172:175], v159
	ds_read_b128 v[176:179], v159 offset:1024
	ds_read_b128 v[180:183], v159 offset:2048
	ds_read_b128 v[184:187], v159 offset:3072
	s_add_u32 s6, s58, 0x40000
	s_addc_u32 s7, s59, 0
	s_mov_b32 m0, s67
	ds_read_b128 v[188:191], v149 offset:32768
	ds_read_b128 v[192:195], v149 offset:33792
	ds_read_b128 v[196:199], v149 offset:34816
	ds_read_b128 v[200:203], v149 offset:35840
	ds_read_b128 v[204:207], v149 offset:36864
	ds_read_b128 v[208:211], v149 offset:37888
	ds_read_b128 v[212:215], v149 offset:38912
	ds_read_b128 v[216:219], v149 offset:39936
	s_nop 0
	global_load_lds_dwordx4 v128, s[6:7]
	s_mov_b32 m0, s68
	s_nop 0
	global_load_lds_dwordx4 v132, s[6:7]
	s_waitcnt vmcnt(8)
	s_waitcnt lgkmcnt(0)
	s_barrier
	s_setprio 1
	s_waitcnt lgkmcnt(0)
	v_mfma_f32_16x16x32_bf16 v[124:127], v[140:143], v[188:191], v[124:127]
	v_mfma_f32_16x16x32_bf16 v[120:123], v[164:167], v[188:191], v[120:123]
	v_mfma_f32_16x16x32_bf16 v[108:111], v[140:143], v[196:199], v[108:111]
	v_mfma_f32_16x16x32_bf16 v[104:107], v[164:167], v[196:199], v[104:107]
	v_mfma_f32_16x16x32_bf16 v[92:95], v[140:143], v[204:207], v[92:95]
	v_mfma_f32_16x16x32_bf16 v[88:91], v[164:167], v[204:207], v[88:91]
	v_mfma_f32_16x16x32_bf16 v[76:79], v[140:143], v[212:215], v[76:79]
	v_mfma_f32_16x16x32_bf16 v[72:75], v[164:167], v[212:215], v[72:75]
	v_mfma_f32_16x16x32_bf16 v[124:127], v[160:163], v[192:195], v[124:127]
	v_mfma_f32_16x16x32_bf16 v[120:123], v[168:171], v[192:195], v[120:123]
	v_mfma_f32_16x16x32_bf16 v[108:111], v[160:163], v[200:203], v[108:111]
	v_mfma_f32_16x16x32_bf16 v[104:107], v[168:171], v[200:203], v[104:107]
	v_mfma_f32_16x16x32_bf16 v[92:95], v[160:163], v[208:211], v[92:95]
	v_mfma_f32_16x16x32_bf16 v[88:91], v[168:171], v[208:211], v[88:91]
	v_mfma_f32_16x16x32_bf16 v[76:79], v[160:163], v[216:219], v[76:79]
	v_mfma_f32_16x16x32_bf16 v[72:75], v[168:171], v[216:219], v[72:75]
	s_setprio 0
	s_setprio 1
	v_mfma_f32_16x16x32_bf16 v[116:119], v[172:175], v[188:191], v[116:119]
	v_mfma_f32_16x16x32_bf16 v[112:115], v[180:183], v[188:191], v[112:115]
	v_mfma_f32_16x16x32_bf16 v[100:103], v[172:175], v[196:199], v[100:103]
	v_mfma_f32_16x16x32_bf16 v[96:99], v[180:183], v[196:199], v[96:99]
	v_mfma_f32_16x16x32_bf16 v[84:87], v[172:175], v[204:207], v[84:87]
	v_mfma_f32_16x16x32_bf16 v[80:83], v[180:183], v[204:207], v[80:83]
	v_mfma_f32_16x16x32_bf16 v[68:71], v[172:175], v[212:215], v[68:71]
	v_mfma_f32_16x16x32_bf16 v[64:67], v[180:183], v[212:215], v[64:67]
	v_mfma_f32_16x16x32_bf16 v[116:119], v[176:179], v[192:195], v[116:119]
	v_mfma_f32_16x16x32_bf16 v[112:115], v[184:187], v[192:195], v[112:115]
	v_mfma_f32_16x16x32_bf16 v[100:103], v[176:179], v[200:203], v[100:103]
	v_mfma_f32_16x16x32_bf16 v[96:99], v[184:187], v[200:203], v[96:99]
	v_mfma_f32_16x16x32_bf16 v[84:87], v[176:179], v[208:211], v[84:87]
	v_mfma_f32_16x16x32_bf16 v[80:83], v[184:187], v[208:211], v[80:83]
	v_mfma_f32_16x16x32_bf16 v[68:71], v[176:179], v[216:219], v[68:71]
	v_mfma_f32_16x16x32_bf16 v[64:67], v[184:187], v[216:219], v[64:67]
	s_setprio 0
	s_barrier
	s_add_u32 s6, s56, 0x80
	s_addc_u32 s7, s57, 0
	s_add_i32 s40, s40, s64
	ds_read_b128 v[188:191], v149 offset:49152
	ds_read_b128 v[192:195], v149 offset:50176
	ds_read_b128 v[196:199], v149 offset:51200
	ds_read_b128 v[200:203], v149 offset:52224
	ds_read_b128 v[204:207], v149 offset:53248
	ds_read_b128 v[208:211], v149 offset:54272
	ds_read_b128 v[212:215], v149 offset:55296
	ds_read_b128 v[216:219], v149 offset:56320
	s_mov_b32 m0, s40
	s_nop 0
	global_load_lds_dwordx4 v130, s[6:7]
	s_add_i32 m0, s40, 0x2000
	s_nop 0
	global_load_lds_dwordx4 v134, s[6:7]
	s_add_u32 s6, s56, 0x40080
	s_addc_u32 s7, s57, 0
	s_add_i32 s40, s41, s64
	s_mov_b32 m0, s40
	s_nop 0
	global_load_lds_dwordx4 v130, s[6:7]
	s_add_i32 m0, s40, 0x2000
	s_nop 0
	global_load_lds_dwordx4 v134, s[6:7]
	s_mov_b32 m0, s70
	s_nop 0
	global_load_lds_dwordx4 v128, s[54:55]
	s_mov_b32 m0, s71
	s_nop 0
	global_load_lds_dwordx4 v132, s[54:55]
	s_waitcnt vmcnt(8)
	s_waitcnt lgkmcnt(0)
	s_barrier
	s_setprio 1
	s_waitcnt lgkmcnt(0)
	v_mfma_f32_16x16x32_bf16 v[60:63], v[140:143], v[188:191], v[60:63]
	v_mfma_f32_16x16x32_bf16 v[56:59], v[164:167], v[188:191], v[56:59]
	v_mfma_f32_16x16x32_bf16 v[44:47], v[140:143], v[196:199], v[44:47]
	v_mfma_f32_16x16x32_bf16 v[40:43], v[164:167], v[196:199], v[40:43]
	v_mfma_f32_16x16x32_bf16 v[28:31], v[140:143], v[204:207], v[28:31]
	v_mfma_f32_16x16x32_bf16 v[24:27], v[164:167], v[204:207], v[24:27]
	v_mfma_f32_16x16x32_bf16 v[12:15], v[140:143], v[212:215], v[12:15]
	v_mfma_f32_16x16x32_bf16 v[8:11], v[164:167], v[212:215], v[8:11]
	v_mfma_f32_16x16x32_bf16 v[60:63], v[160:163], v[192:195], v[60:63]
	v_mfma_f32_16x16x32_bf16 v[56:59], v[168:171], v[192:195], v[56:59]
	v_mfma_f32_16x16x32_bf16 v[44:47], v[160:163], v[200:203], v[44:47]
	v_mfma_f32_16x16x32_bf16 v[40:43], v[168:171], v[200:203], v[40:43]
	v_mfma_f32_16x16x32_bf16 v[28:31], v[160:163], v[208:211], v[28:31]
	v_mfma_f32_16x16x32_bf16 v[24:27], v[168:171], v[208:211], v[24:27]
	v_mfma_f32_16x16x32_bf16 v[12:15], v[160:163], v[216:219], v[12:15]
	v_mfma_f32_16x16x32_bf16 v[8:11], v[168:171], v[216:219], v[8:11]
	s_setprio 0
	s_setprio 1
	v_mfma_f32_16x16x32_bf16 v[52:55], v[172:175], v[188:191], v[52:55]
	v_mfma_f32_16x16x32_bf16 v[48:51], v[180:183], v[188:191], v[48:51]
	v_mfma_f32_16x16x32_bf16 v[36:39], v[172:175], v[196:199], v[36:39]
	v_mfma_f32_16x16x32_bf16 v[32:35], v[180:183], v[196:199], v[32:35]
	v_mfma_f32_16x16x32_bf16 v[20:23], v[172:175], v[204:207], v[20:23]
	v_mfma_f32_16x16x32_bf16 v[16:19], v[180:183], v[204:207], v[16:19]
	v_mfma_f32_16x16x32_bf16 v[4:7], v[172:175], v[212:215], v[4:7]
	v_mfma_f32_16x16x32_bf16 v[0:3], v[180:183], v[212:215], v[0:3]
	v_mfma_f32_16x16x32_bf16 v[52:55], v[176:179], v[192:195], v[52:55]
	v_mfma_f32_16x16x32_bf16 v[48:51], v[184:187], v[192:195], v[48:51]
	v_mfma_f32_16x16x32_bf16 v[36:39], v[176:179], v[200:203], v[36:39]
	v_mfma_f32_16x16x32_bf16 v[32:35], v[184:187], v[200:203], v[32:35]
	v_mfma_f32_16x16x32_bf16 v[20:23], v[176:179], v[208:211], v[20:23]
	v_mfma_f32_16x16x32_bf16 v[16:19], v[184:187], v[208:211], v[16:19]
	v_mfma_f32_16x16x32_bf16 v[4:7], v[176:179], v[216:219], v[4:7]
	v_mfma_f32_16x16x32_bf16 v[0:3], v[184:187], v[216:219], v[0:3]
	s_setprio 0
	s_barrier
	s_add_i32 s79, s79, 2
	s_add_u32 s77, s77, 0x100
	s_addc_u32 s78, s78, 0
	s_cmp_gt_u32 s79, 13
	s_mov_b64 s[40:41], s[42:43]
	s_cbranch_scc0 .LBB0_2302
	s_and_b64 vcc, exec, s[16:17]
	s_cbranch_vccz .LBB0_2305
	s_barrier

; __device__ __forceinline__ int lane_id_() { int l; asm volatile("v_mbcnt_lo_u32_b32 %0, -1, 0\n\tv_mbcnt_hi_u32_b32 %0, -1, %0" : "=v"(l)); return l; }
; #define PG8_LAS __attribute__((address_space(3)))
; #define PG8_STAGE(bufoff, gbase, voff) do { const char* gb_ = (const char*)(gbase); asm volatile("" : "+s"(gb_));   \
;         _Pragma("unroll") for (int _i = 0; _i < 2; ++_i) \
;         __builtin_amdgcn_global_load_lds((const unsigned*)(gb_ + (voff)[_i]), (PG8_LAS unsigned*)(lds + (bufoff) + ldsw + _i * 8192), 16, 0, 0); } while (0)
; #define PG8_WAIT_V(n) asm volatile("s_waitcnt vmcnt(" #n ")" ::: "memory")
; #define PG8_BAR __builtin_amdgcn_s_barrier()
;     __device__ __forceinline__ void prefetch(PG8_LAS unsigned char* lds, int wid, const Unit& u, int wr, int fr, int fq) const {
;         { const int l_ = lane_id_(); fr = l_ & 15; fq = l_ >> 4; }
; #pragma unroll
;         for (int j = 0; j < 2; ++j) { const int i = 2 * fq + j;
;             __builtin_amdgcn_global_load_lds((const unsigned*)(ssq + u.pm * BM + wr * 64 + fr + (i >> 2) * HALF + (i & 3) * 16), (PG8_LAS unsigned*)(lds + PRE_SLOT + wid * 512 + j * 256), 4, 0, 0); }
;     }
; template <class Epi, class Sched, bool ALIGN_EPI = false, bool SP2 = false>
; __device__ __forceinline__ void gemm_phase(PG8_LAS unsigned char* lds, const Gemm g, const Sched& S, const Epi& E, int wave_s) {
;     ...
;     f32x4 acc[2][2][4][2];
; #pragma unroll
;     for (int a = 0; a < 2; ++a)
; #pragma unroll
;         for (int b = 0; b < 2; ++b)
; #pragma unroll
;             for (int m = 0; m < 4; ++m)
; #pragma unroll
;                 for (int n = 0; n < 2; ++n) acc[a][b][m][n] = (f32x4){0.f, 0.f, 0.f, 0.f};
;     bf16x8 At[4][2], B0[2][2], B1[2][2];
;     const char* cA = (const char*)g.A + (size_t)cur.pm * tstep; const char* cB = (const char*)g.Bt + (size_t)cur.pn * tstep;
;     S.a_ready(cur);
;     if constexpr (SP2) {
;         PG8_STAGE(PG8_SB(0, 0), cB, voffB); PG8_STAGE(PG8_SB(0, 1), cB + hstep, voffB); PG8_STAGE(PG8_SA(0, 0), cA, voffA); PG8_STAGE(PG8_SA(0, 1), cA + hstep, voffA);
;         if (wr == 1) PG8_BAR;
;         PG8_WAIT_V(2); PG8_BAR;
;         PG8_STAGE(PG8_SB(1, 0), cB + kstep, voffB); PG8_STAGE(PG8_SA(1, 0), cA + kstep, voffA); PG8_STAGE(PG8_SB(1, 1), cB + hstep + kstep, voffB);
;         PG8_WAIT_V(6); PG8_BAR;
.LBB0_2384:
	s_lshl_b32 s13, s13, 5
	s_and_b32 s18, s13, 0x60
	s_lshl_b32 s7, s16, 13
	s_lshl_b32 s13, s18, 7
	s_add_u32 s16, s24, 0x80
	s_addc_u32 s17, s25, 0
	s_waitcnt vmcnt(2)
	s_barrier
	s_add_i32 m0, s42, 0x18000
	s_nop 0
	global_load_lds_dwordx4 v136, s[16:17]
	s_add_i32 m0, s42, 0x1a000
	s_nop 0
	global_load_lds_dwordx4 v132, s[16:17]
	s_add_u32 s16, s26, 0x80
	s_addc_u32 s17, s27, 0
	s_add_i32 s54, s42, 0x8000
	s_mov_b32 m0, s54
	s_add_i32 s55, s42, 0xa000
	global_load_lds_dwordx4 v138, s[16:17]
	s_mov_b64 s[98:99], s[16:17]
	s_add_u32 s16, s24, 0x40080
	s_mov_b32 m0, s55
	s_addc_u32 s17, s25, 0
	global_load_lds_dwordx4 v134, s[98:99]
	s_add_i32 m0, s42, 0x1c000
	s_nop 0
	global_load_lds_dwordx4 v136, s[16:17]
	s_add_i32 m0, s42, 0x1e000
	v_and_b32_e32 v0, 15, v2
	global_load_lds_dwordx4 v132, s[16:17]
	v_lshrrev_b32_e32 v2, 1, v2
	v_or_b32_e32 v144, s6, v0
	v_and_b32_e32 v2, 24, v2
	v_lshlrev_b32_e32 v3, 6, v144
	v_lshlrev_b32_e32 v4, 1, v2
	s_movk_i32 s6, 0x3c0
	v_lshlrev_b32_e32 v5, 2, v144
	v_and_or_b32 v3, v3, s6, v4
	v_and_b32_e32 v5, 32, v5
	v_lshlrev_b32_e32 v145, 2, v0
	v_bitop3_b32 v5, v3, s7, v5 bitop3:0xde
	v_lshl_or_b32 v3, v0, 6, v4
	v_and_b32_e32 v0, 32, v145
	v_bitop3_b32 v146, v3, s13, v0 bitop3:0xde
	s_waitcnt vmcnt(6)
	s_cmpk_lt_u32 s12, 0x100
	v_or_b32_e32 v147, s18, v2
	v_mov_b32_e32 v2, v1
	v_mov_b32_e32 v3, v1
	s_cselect_b64 s[12:13], -1, 0
	s_add_u32 s57, s60, s14
	v_mov_b32_e32 v0, v1
	v_add_u32_e32 v149, 0, v5
	v_mov_b64_e32 v[10:11], v[2:3]
	v_mov_b64_e32 v[18:19], v[2:3]
	v_mov_b64_e32 v[26:27], v[2:3]
	s_waitcnt vmcnt(0)
	v_mov_b64_e32 v[34:35], v[2:3]
	v_mov_b64_e32 v[42:43], v[2:3]
	v_mov_b64_e32 v[50:51], v[2:3]
	v_mov_b64_e32 v[58:59], v[2:3]
	v_mov_b64_e32 v[74:75], v[2:3]
	v_mov_b64_e32 v[6:7], v[2:3]
	v_mov_b64_e32 v[14:15], v[2:3]
	v_mov_b64_e32 v[22:23], v[2:3]
	v_mov_b64_e32 v[30:31], v[2:3]
	v_mov_b64_e32 v[38:39], v[2:3]
	v_mov_b64_e32 v[46:47], v[2:3]
	v_mov_b64_e32 v[54:55], v[2:3]
	v_mov_b64_e32 v[66:67], v[2:3]
	v_mov_b64_e32 v[70:71], v[2:3]
	v_mov_b64_e32 v[82:83], v[2:3]
	v_mov_b64_e32 v[90:91], v[2:3]
	v_mov_b64_e32 v[98:99], v[2:3]
	v_mov_b64_e32 v[106:107], v[2:3]
	v_mov_b64_e32 v[114:115], v[2:3]
	v_mov_b64_e32 v[122:123], v[2:3]
	v_mov_b64_e32 v[130:131], v[2:3]
	v_mov_b64_e32 v[62:63], v[2:3]
	v_mov_b64_e32 v[78:79], v[2:3]
	v_mov_b64_e32 v[86:87], v[2:3]
	v_mov_b64_e32 v[94:95], v[2:3]
	v_mov_b64_e32 v[102:103], v[2:3]
	v_mov_b64_e32 v[110:111], v[2:3]
	v_mov_b64_e32 v[118:119], v[2:3]
	v_mov_b64_e32 v[126:127], v[2:3]
	s_sext_i32_i16 s23, s8
	s_mov_b32 s56, s46
	s_addc_u32 s58, s61, s15
	v_mov_b64_e32 v[140:141], 0x580
	v_mov_b64_e32 v[142:143], 0x57f
	s_add_i32 s59, 0, 0x10000
	s_add_i32 s60, 0, 0x14000
	s_movk_i32 s61, 0x1600
	v_mov_b32_e32 v148, 0x358637bd
	v_mov_b64_e32 v[8:9], v[0:1]
	v_mov_b64_e32 v[16:17], v[0:1]
	v_mov_b64_e32 v[24:25], v[0:1]
	v_mov_b64_e32 v[32:33], v[0:1]
	v_mov_b64_e32 v[40:41], v[0:1]
	v_mov_b64_e32 v[48:49], v[0:1]
	v_mov_b64_e32 v[56:57], v[0:1]
	v_mov_b64_e32 v[72:73], v[0:1]
	v_mov_b64_e32 v[4:5], v[0:1]
	v_mov_b64_e32 v[12:13], v[0:1]
	v_mov_b64_e32 v[20:21], v[0:1]
	v_mov_b64_e32 v[28:29], v[0:1]
	v_mov_b64_e32 v[36:37], v[0:1]
	v_mov_b64_e32 v[44:45], v[0:1]
	v_mov_b64_e32 v[52:53], v[0:1]
	v_mov_b64_e32 v[64:65], v[0:1]
	v_mov_b64_e32 v[68:69], v[0:1]
	v_mov_b64_e32 v[80:81], v[0:1]
	v_mov_b64_e32 v[88:89], v[0:1]
	v_mov_b64_e32 v[96:97], v[0:1]
	v_mov_b64_e32 v[104:105], v[0:1]
	v_mov_b64_e32 v[112:113], v[0:1]
	v_mov_b64_e32 v[120:121], v[0:1]
	v_mov_b64_e32 v[128:129], v[0:1]
	v_mov_b64_e32 v[60:61], v[0:1]
	v_mov_b64_e32 v[76:77], v[0:1]
	v_mov_b64_e32 v[84:85], v[0:1]
	v_mov_b64_e32 v[92:93], v[0:1]
	v_mov_b64_e32 v[100:101], v[0:1]
	v_mov_b64_e32 v[108:109], v[0:1]
	v_mov_b64_e32 v[116:117], v[0:1]
	v_mov_b64_e32 v[124:125], v[0:1]
	s_mov_b32 s8, s9
	s_mov_b32 s62, s9
	s_barrier
	s_branch .LBB0_2387
.LBB0_2385:
	s_lshl_b32 s6, s16, 8
	s_ashr_i32 s7, s6, 31
	s_lshl_b64 s[6:7], s[6:7], 2
	v_mbcnt_lo_u32_b32 v6, -1, 0
	v_mbcnt_hi_u32_b32 v6, -1, v6
	s_add_u32 s6, s57, s6
	v_and_b32_e32 v0, 15, v6
	v_lshlrev_b32_e32 v2, 2, v6
	v_and_b32_e32 v2, 0xffffff80, v2
	s_addc_u32 s7, s58, s7
	v_lshlrev_b32_e32 v0, 2, v0
	v_ashrrev_i32_e32 v3, 31, v2
	v_lshl_add_u64 v[4:5], s[6:7], 0, v[0:1]
	v_lshlrev_b32_e32 v0, 3, v6
	v_lshl_add_u64 v[2:3], v[2:3], 2, v[4:5]
	v_and_b32_e32 v0, 0x80, v0
	s_mov_b32 m0, s41
	v_lshl_add_u64 v[2:3], v[2:3], 0, v[0:1]
	global_load_lds_dword v[2:3], off
	v_lshl_add_u64 v[2:3], v[2:3], 0, 64
	s_add_i32 m0, s41, 0x100
	s_add_u32 s22, s18, 0x100
	global_load_lds_dword v[2:3], off
	ds_read_b128 v[2:5], v151
	ds_read_b128 v[6:9], v151 offset:1024
	ds_read_b128 v[10:13], v151 offset:2048
	ds_read_b128 v[14:17], v151 offset:3072
	ds_read_b128 v[18:21], v150
	ds_read_b128 v[22:25], v150 offset:1024
	ds_read_b128 v[26:29], v150 offset:2048
	ds_read_b128 v[30:33], v150 offset:3072
	s_addc_u32 s23, s19, 0
	s_add_u32 s6, s18, 0x180
	s_addc_u32 s7, s19, 0
	s_add_u32 s24, s20, 0x100
	s_addc_u32 s25, s21, 0
	s_add_u32 s26, s18, 0x40080
	s_addc_u32 s27, s19, 0
	s_mov_b32 m0, s65
	ds_read_b128 v[34:37], v149
	ds_read_b128 v[38:41], v149 offset:1024
	ds_read_b128 v[42:45], v149 offset:2048
	ds_read_b128 v[46:49], v149 offset:3072
	ds_read_b128 v[50:53], v149 offset:4096
	ds_read_b128 v[54:57], v149 offset:5120
	ds_read_b128 v[58:61], v149 offset:6144
	ds_read_b128 v[62:65], v149 offset:7168
	s_nop 0
	global_load_lds_dwordx4 v138, s[26:27]
	s_mov_b32 m0, s8
	s_nop 0
	global_load_lds_dwordx4 v134, s[26:27]
	s_waitcnt vmcnt(18)
	s_waitcnt lgkmcnt(0)
	s_barrier
	s_setprio 1
	s_waitcnt lgkmcnt(0)
	v_mfma_f32_16x16x32_bf16 v[90:93], v[2:5], v[58:61], 0
	v_mfma_f32_16x16x32_bf16 v[66:69], v[2:5], v[34:37], 0
	v_mfma_f32_16x16x32_bf16 v[70:73], v[10:13], v[34:37], 0
	v_mfma_f32_16x16x32_bf16 v[74:77], v[2:5], v[42:45], 0
	v_mfma_f32_16x16x32_bf16 v[78:81], v[10:13], v[42:45], 0
	v_mfma_f32_16x16x32_bf16 v[82:85], v[2:5], v[50:53], 0
	v_mfma_f32_16x16x32_bf16 v[86:89], v[10:13], v[50:53], 0
	v_mfma_f32_16x16x32_bf16 v[96:99], v[6:9], v[62:65], v[90:93]
	v_mfma_f32_16x16x32_bf16 v[90:93], v[10:13], v[58:61], 0
	v_mfma_f32_16x16x32_bf16 v[66:69], v[6:9], v[38:41], v[66:69]
	v_mfma_f32_16x16x32_bf16 v[70:73], v[14:17], v[38:41], v[70:73]
	v_mfma_f32_16x16x32_bf16 v[74:77], v[6:9], v[46:49], v[74:77]
	v_mfma_f32_16x16x32_bf16 v[78:81], v[14:17], v[46:49], v[78:81]
	v_mfma_f32_16x16x32_bf16 v[82:85], v[6:9], v[54:57], v[82:85]
	v_mfma_f32_16x16x32_bf16 v[86:89], v[14:17], v[54:57], v[86:89]
	v_mfma_f32_16x16x32_bf16 v[104:107], v[14:17], v[62:65], v[90:93]
	s_setprio 0
	s_setprio 1
	v_mfma_f32_16x16x32_bf16 v[90:93], v[18:21], v[34:37], 0
	v_mfma_f32_16x16x32_bf16 v[34:37], v[26:29], v[34:37], 0
	v_mfma_f32_16x16x32_bf16 v[112:115], v[22:25], v[38:41], v[90:93]
	v_mfma_f32_16x16x32_bf16 v[34:37], v[30:33], v[38:41], v[34:37]
	v_mfma_f32_16x16x32_bf16 v[38:41], v[18:21], v[42:45], 0
	v_mfma_f32_16x16x32_bf16 v[42:45], v[26:29], v[42:45], 0
	v_mfma_f32_16x16x32_bf16 v[38:41], v[22:25], v[46:49], v[38:41]
	v_mfma_f32_16x16x32_bf16 v[42:45], v[30:33], v[46:49], v[42:45]
	v_mfma_f32_16x16x32_bf16 v[46:49], v[18:21], v[50:53], 0
	v_mfma_f32_16x16x32_bf16 v[50:53], v[26:29], v[50:53], 0
	v_mfma_f32_16x16x32_bf16 v[46:49], v[22:25], v[54:57], v[46:49]
	v_mfma_f32_16x16x32_bf16 v[50:53], v[30:33], v[54:57], v[50:53]
	v_mfma_f32_16x16x32_bf16 v[54:57], v[18:21], v[58:61], 0
	v_mfma_f32_16x16x32_bf16 v[54:57], v[22:25], v[62:65], v[54:57]
	v_mfma_f32_16x16x32_bf16 v[58:61], v[26:29], v[58:61], 0
	v_mfma_f32_16x16x32_bf16 v[154:157], v[30:33], v[62:65], v[58:61]
	s_setprio 0
	s_barrier
	s_mov_b32 m0, s64
	s_nop 3
	ds_read_b128 v[58:61], v149 offset:16384
	ds_read_b128 v[62:65], v149 offset:17408
	ds_read_b128 v[90:93], v149 offset:18432
	ds_read_b128 v[100:103], v149 offset:19456
	ds_read_b128 v[108:111], v149 offset:20480
	ds_read_b128 v[116:119], v149 offset:21504
	ds_read_b128 v[120:123], v149 offset:22528
	ds_read_b128 v[124:127], v149 offset:23552
	s_nop 0
	global_load_lds_dwordx4 v136, s[24:25]
	s_mov_b64 s[98:99], s[24:25]
	s_add_u32 s24, s20, 0x40100
	s_mov_b32 m0, s15
	s_addc_u32 s25, s21, 0
	global_load_lds_dwordx4 v132, s[98:99]
	s_mov_b32 m0, s17
	s_nop 0
	global_load_lds_dwordx4 v136, s[24:25]
	s_mov_b32 m0, s63
	s_nop 0
	global_load_lds_dwordx4 v132, s[24:25]
	s_mov_b32 m0, s42
	s_nop 0
	global_load_lds_dwordx4 v138, s[22:23]
	s_mov_b32 m0, s43
	s_nop 0
	global_load_lds_dwordx4 v134, s[22:23]
	s_waitcnt vmcnt(18)
	s_waitcnt lgkmcnt(0)
	s_barrier
	s_setprio 1
	s_waitcnt lgkmcnt(0)
	v_mfma_f32_16x16x32_bf16 v[128:131], v[2:5], v[58:61], 0
	v_mfma_f32_16x16x32_bf16 v[158:161], v[6:9], v[62:65], v[128:131]
	v_mfma_f32_16x16x32_bf16 v[128:131], v[10:13], v[58:61], 0
	v_mfma_f32_16x16x32_bf16 v[162:165], v[14:17], v[62:65], v[128:131]
	v_mfma_f32_16x16x32_bf16 v[128:131], v[2:5], v[90:93], 0
	v_mfma_f32_16x16x32_bf16 v[166:169], v[6:9], v[100:103], v[128:131]
	v_mfma_f32_16x16x32_bf16 v[128:131], v[10:13], v[90:93], 0
	v_mfma_f32_16x16x32_bf16 v[170:173], v[14:17], v[100:103], v[128:131]
	v_mfma_f32_16x16x32_bf16 v[128:131], v[2:5], v[108:111], 0
	v_mfma_f32_16x16x32_bf16 v[2:5], v[2:5], v[120:123], 0
	v_mfma_f32_16x16x32_bf16 v[174:177], v[6:9], v[116:119], v[128:131]
	v_mfma_f32_16x16x32_bf16 v[2:5], v[6:9], v[124:127], v[2:5]
	v_mfma_f32_16x16x32_bf16 v[6:9], v[10:13], v[120:123], 0
	v_mfma_f32_16x16x32_bf16 v[128:131], v[10:13], v[108:111], 0
	v_mfma_f32_16x16x32_bf16 v[6:9], v[14:17], v[124:127], v[6:9]
	v_mfma_f32_16x16x32_bf16 v[178:181], v[14:17], v[116:119], v[128:131]
	s_setprio 0
	s_setprio 1
	v_mfma_f32_16x16x32_bf16 v[10:13], v[18:21], v[58:61], 0
	v_mfma_f32_16x16x32_bf16 v[182:185], v[22:25], v[62:65], v[10:13]
	v_mfma_f32_16x16x32_bf16 v[10:13], v[26:29], v[58:61], 0
	v_mfma_f32_16x16x32_bf16 v[186:189], v[30:33], v[62:65], v[10:13]
	v_mfma_f32_16x16x32_bf16 v[10:13], v[18:21], v[90:93], 0
	v_mfma_f32_16x16x32_bf16 v[190:193], v[22:25], v[100:103], v[10:13]
	v_mfma_f32_16x16x32_bf16 v[10:13], v[26:29], v[90:93], 0
	v_mfma_f32_16x16x32_bf16 v[194:197], v[30:33], v[100:103], v[10:13]
	v_mfma_f32_16x16x32_bf16 v[10:13], v[18:21], v[108:111], 0
	v_mfma_f32_16x16x32_bf16 v[198:201], v[22:25], v[116:119], v[10:13]
	v_mfma_f32_16x16x32_bf16 v[10:13], v[26:29], v[108:111], 0
	v_mfma_f32_16x16x32_bf16 v[202:205], v[30:33], v[116:119], v[10:13]
	v_mfma_f32_16x16x32_bf16 v[10:13], v[18:21], v[120:123], 0
	v_mfma_f32_16x16x32_bf16 v[16:19], v[22:25], v[124:127], v[10:13]
	v_mfma_f32_16x16x32_bf16 v[10:13], v[26:29], v[120:123], 0
	v_mfma_f32_16x16x32_bf16 v[206:209], v[30:33], v[124:127], v[10:13]
	s_setprio 0
	s_barrier
	s_nop 4
	ds_read_b128 v[10:13], v152
	ds_read_b128 v[24:27], v152 offset:1024
	ds_read_b128 v[210:213], v152 offset:2048
	ds_read_b128 v[214:217], v152 offset:3072
	ds_read_b128 v[218:221], v153
	ds_read_b128 v[222:225], v153 offset:1024
	ds_read_b128 v[226:229], v153 offset:2048
	ds_read_b128 v[150:153], v153 offset:3072
	s_add_u32 s22, s18, 0x40100
	s_addc_u32 s23, s19, 0
	s_mov_b32 m0, s52
	ds_read_b128 v[20:23], v149 offset:32768
	ds_read_b128 v[28:31], v149 offset:33792
	ds_read_b128 v[230:233], v149 offset:34816
	ds_read_b128 v[234:237], v149 offset:35840
	ds_read_b128 v[238:241], v149 offset:36864
	ds_read_b128 v[242:245], v149 offset:37888
	ds_read_b128 v[246:249], v149 offset:38912
	ds_read_b128 v[250:253], v149 offset:39936
	s_nop 0
	global_load_lds_dwordx4 v138, s[22:23]
	s_mov_b32 m0, s53
	s_nop 0
	global_load_lds_dwordx4 v134, s[22:23]
	s_waitcnt vmcnt(18)
	s_waitcnt lgkmcnt(0)
	s_barrier
	s_setprio 1
	s_waitcnt lgkmcnt(0)
	v_mfma_f32_16x16x32_bf16 v[58:61], v[10:13], v[20:23], v[66:69]
	v_mfma_f32_16x16x32_bf16 v[124:127], v[24:27], v[28:31], v[58:61]
	v_mfma_f32_16x16x32_bf16 v[58:61], v[210:213], v[20:23], v[70:73]
	v_mfma_f32_16x16x32_bf16 v[116:119], v[214:217], v[28:31], v[58:61]
	v_mfma_f32_16x16x32_bf16 v[58:61], v[10:13], v[230:233], v[74:77]
	v_mfma_f32_16x16x32_bf16 v[108:111], v[24:27], v[234:237], v[58:61]
	v_mfma_f32_16x16x32_bf16 v[58:61], v[210:213], v[230:233], v[78:81]
	v_mfma_f32_16x16x32_bf16 v[100:103], v[214:217], v[234:237], v[58:61]
	v_mfma_f32_16x16x32_bf16 v[58:61], v[10:13], v[238:241], v[82:85]
	v_mfma_f32_16x16x32_bf16 v[92:95], v[24:27], v[242:245], v[58:61]
	v_mfma_f32_16x16x32_bf16 v[58:61], v[210:213], v[238:241], v[86:89]
	v_mfma_f32_16x16x32_bf16 v[84:87], v[214:217], v[242:245], v[58:61]
	v_mfma_f32_16x16x32_bf16 v[58:61], v[10:13], v[246:249], v[96:99]
	v_mfma_f32_16x16x32_bf16 v[76:79], v[24:27], v[250:253], v[58:61]
	v_mfma_f32_16x16x32_bf16 v[58:61], v[210:213], v[246:249], v[104:107]
	v_mfma_f32_16x16x32_bf16 v[60:63], v[214:217], v[250:253], v[58:61]
	s_setprio 0
	s_setprio 1
	v_mfma_f32_16x16x32_bf16 v[64:67], v[218:221], v[20:23], v[112:115]
	v_mfma_f32_16x16x32_bf16 v[20:23], v[226:229], v[20:23], v[34:37]
	v_mfma_f32_16x16x32_bf16 v[120:123], v[150:153], v[28:31], v[20:23]
	v_mfma_f32_16x16x32_bf16 v[20:23], v[218:221], v[230:233], v[38:41]
	v_mfma_f32_16x16x32_bf16 v[112:115], v[222:225], v[234:237], v[20:23]
	v_mfma_f32_16x16x32_bf16 v[20:23], v[226:229], v[230:233], v[42:45]
	v_mfma_f32_16x16x32_bf16 v[104:107], v[150:153], v[234:237], v[20:23]
	v_mfma_f32_16x16x32_bf16 v[20:23], v[218:221], v[238:241], v[46:49]
	v_mfma_f32_16x16x32_bf16 v[96:99], v[222:225], v[242:245], v[20:23]
	v_mfma_f32_16x16x32_bf16 v[20:23], v[226:229], v[238:241], v[50:53]
	v_mfma_f32_16x16x32_bf16 v[88:91], v[150:153], v[242:245], v[20:23]
	v_mfma_f32_16x16x32_bf16 v[20:23], v[218:221], v[246:249], v[54:57]
	v_mfma_f32_16x16x32_bf16 v[80:83], v[222:225], v[250:253], v[20:23]
	v_mfma_f32_16x16x32_bf16 v[20:23], v[226:229], v[246:249], v[154:157]
	v_mfma_f32_16x16x32_bf16 v[128:131], v[222:225], v[28:31], v[64:67]
	v_mfma_f32_16x16x32_bf16 v[68:71], v[150:153], v[250:253], v[20:23]
	s_setprio 0
	s_barrier
	s_add_u32 s22, s20, 0x180
	s_addc_u32 s23, s21, 0
	s_mov_b32 m0, s31
	ds_read_b128 v[32:35], v149 offset:49152
	ds_read_b128 v[40:43], v149 offset:50176
	ds_read_b128 v[154:157], v149 offset:51200
	ds_read_b128 v[230:233], v149 offset:52224
	ds_read_b128 v[234:237], v149 offset:53248
	ds_read_b128 v[238:241], v149 offset:54272
	ds_read_b128 v[242:245], v149 offset:55296
	ds_read_b128 v[246:249], v149 offset:56320
	s_nop 0
	global_load_lds_dwordx4 v136, s[22:23]
	s_mov_b64 s[98:99], s[22:23]
	s_add_u32 s22, s20, 0x40180
	s_mov_b32 m0, s30
	s_addc_u32 s23, s21, 0
	global_load_lds_dwordx4 v132, s[98:99]
	s_mov_b32 m0, s28
	s_nop 0
	global_load_lds_dwordx4 v136, s[22:23]
	s_mov_b32 m0, s29
	s_nop 0
	global_load_lds_dwordx4 v132, s[22:23]
	s_mov_b32 m0, s54
	s_nop 0
	global_load_lds_dwordx4 v138, s[6:7]
	s_mov_b32 m0, s55
	s_nop 0
	global_load_lds_dwordx4 v134, s[6:7]
	s_waitcnt vmcnt(18)
	s_waitcnt lgkmcnt(0)
	s_barrier
	s_setprio 1
	s_waitcnt lgkmcnt(0)
	v_mfma_f32_16x16x32_bf16 v[20:23], v[10:13], v[32:35], v[158:161]
	v_mfma_f32_16x16x32_bf16 v[64:67], v[24:27], v[40:43], v[20:23]
	v_mfma_f32_16x16x32_bf16 v[20:23], v[210:213], v[32:35], v[162:165]
	v_mfma_f32_16x16x32_bf16 v[52:55], v[214:217], v[40:43], v[20:23]
	v_mfma_f32_16x16x32_bf16 v[20:23], v[10:13], v[154:157], v[166:169]
	v_mfma_f32_16x16x32_bf16 v[44:47], v[24:27], v[230:233], v[20:23]
	v_mfma_f32_16x16x32_bf16 v[20:23], v[210:213], v[154:157], v[170:173]
	v_mfma_f32_16x16x32_bf16 v[36:39], v[214:217], v[230:233], v[20:23]
	v_mfma_f32_16x16x32_bf16 v[20:23], v[10:13], v[234:237], v[174:177]
	v_mfma_f32_16x16x32_bf16 v[2:5], v[10:13], v[242:245], v[2:5]
	v_mfma_f32_16x16x32_bf16 v[28:31], v[24:27], v[238:241], v[20:23]
	v_mfma_f32_16x16x32_bf16 v[20:23], v[210:213], v[234:237], v[178:181]
	v_mfma_f32_16x16x32_bf16 v[12:15], v[24:27], v[246:249], v[2:5]
	v_mfma_f32_16x16x32_bf16 v[2:5], v[210:213], v[242:245], v[6:9]
	v_mfma_f32_16x16x32_bf16 v[20:23], v[214:217], v[238:241], v[20:23]
	v_mfma_f32_16x16x32_bf16 v[4:7], v[214:217], v[246:249], v[2:5]
	s_setprio 0
	s_setprio 1
	v_mfma_f32_16x16x32_bf16 v[8:11], v[218:221], v[32:35], v[182:185]
	v_mfma_f32_16x16x32_bf16 v[72:75], v[222:225], v[40:43], v[8:11]
	v_mfma_f32_16x16x32_bf16 v[8:11], v[226:229], v[32:35], v[186:189]
	v_mfma_f32_16x16x32_bf16 v[56:59], v[150:153], v[40:43], v[8:11]
	v_mfma_f32_16x16x32_bf16 v[8:11], v[218:221], v[154:157], v[190:193]
	v_mfma_f32_16x16x32_bf16 v[48:51], v[222:225], v[230:233], v[8:11]
	v_mfma_f32_16x16x32_bf16 v[8:11], v[226:229], v[154:157], v[194:197]
	v_mfma_f32_16x16x32_bf16 v[40:43], v[150:153], v[230:233], v[8:11]
	v_mfma_f32_16x16x32_bf16 v[8:11], v[218:221], v[234:237], v[198:201]
	v_mfma_f32_16x16x32_bf16 v[32:35], v[222:225], v[238:241], v[8:11]
	v_mfma_f32_16x16x32_bf16 v[8:11], v[226:229], v[234:237], v[202:205]
	v_mfma_f32_16x16x32_bf16 v[24:27], v[150:153], v[238:241], v[8:11]
	v_mfma_f32_16x16x32_bf16 v[8:11], v[218:221], v[242:245], v[16:19]
	v_mfma_f32_16x16x32_bf16 v[16:19], v[222:225], v[246:249], v[8:11]
	v_mfma_f32_16x16x32_bf16 v[8:11], v[226:229], v[242:245], v[206:209]
	v_mfma_f32_16x16x32_bf16 v[8:11], v[150:153], v[246:249], v[8:11]
	s_setprio 0
	s_barrier
	s_mov_b64 s[6:7], 0

; #define PG8_WAIT_V8_STRICT() asm volatile("s_waitcnt vmcnt(8)" ::: "memory")
; template <class Epi, class Sched, bool ALIGN_EPI = false, bool SP2 = false>
; __device__ __forceinline__ void gemm_phase(PG8_LAS unsigned char* lds, const Gemm g, const Sched& S, const Epi& E, int wave_s) {
;     ...
;         const bool has_next = S.next(ui + 1, nxt);
;         const char* nA = has_next ? (const char*)g.A + (size_t)nxt.pm * tstep : cA; const char* nB = has_next ? (const char*)g.Bt + (size_t)nxt.pn * tstep : cB;
;         for (int t = peeled ? 2 : 0; t < nt; t += 2) {
;             const bool last = (t == nt - 2);
;             const char* a1 = cA + (size_t)(t + 1) * kstep;
;             const char* a2 = last ? nA : cA + (size_t)(t + 2) * kstep; const char* b2 = last ? nB : cB + (size_t)(t + 2) * kstep;
;             const char* a3 = a2 + kstep; const char* b3 = b2 + kstep;
;             if (last && has_next) S.a_ready(nxt);
;             if constexpr (SP2) {
;             PG8_SP2_PAIR(PG8_WAIT_V8_STRICT);
.LBB0_2390:
	v_add_u32_e32 v151, s59, v146
	v_add_u32_e32 v150, s60, v146
	ds_read_b128 v[152:155], v151
	ds_read_b128 v[156:159], v151 offset:1024
	ds_read_b128 v[160:163], v151 offset:2048
	ds_read_b128 v[164:167], v151 offset:3072
	ds_read_b128 v[168:171], v150
	ds_read_b128 v[172:175], v150 offset:1024
	ds_read_b128 v[176:179], v150 offset:2048
	ds_read_b128 v[180:183], v150 offset:3072
	s_add_u32 s24, s34, 0x100
	s_addc_u32 s25, s35, 0
	s_cmp_eq_u32 s70, 12
	s_cselect_b32 s30, s67, s24
	s_cselect_b32 s31, s66, s25
	s_cselect_b32 s28, s69, s71
	s_cselect_b32 s29, s68, s72
	s_add_u32 s26, s30, 0x80
	s_addc_u32 s27, s31, 0
	s_add_u32 s34, s34, 0x40080
	s_addc_u32 s35, s35, 0
	s_add_i32 s65, s42, 0xc000
	ds_read_b128 v[184:187], v149
	ds_read_b128 v[188:191], v149 offset:1024
	ds_read_b128 v[192:195], v149 offset:2048
	ds_read_b128 v[196:199], v149 offset:3072
	ds_read_b128 v[200:203], v149 offset:4096
	ds_read_b128 v[204:207], v149 offset:5120
	ds_read_b128 v[208:211], v149 offset:6144
	ds_read_b128 v[212:215], v149 offset:7168
	s_mov_b32 m0, s65
	s_add_i32 s8, s42, 0xe000
	global_load_lds_dwordx4 v138, s[34:35]
	s_mov_b32 m0, s8
	s_nop 0
	global_load_lds_dwordx4 v134, s[34:35]
	s_waitcnt vmcnt(8)
	s_waitcnt lgkmcnt(0)
	s_barrier
	s_setprio 1
	s_waitcnt lgkmcnt(0)
	v_mfma_f32_16x16x32_bf16 v[124:127], v[152:155], v[184:187], v[124:127]
	v_mfma_f32_16x16x32_bf16 v[116:119], v[160:163], v[184:187], v[116:119]
	v_mfma_f32_16x16x32_bf16 v[108:111], v[152:155], v[192:195], v[108:111]
	v_mfma_f32_16x16x32_bf16 v[100:103], v[160:163], v[192:195], v[100:103]
	v_mfma_f32_16x16x32_bf16 v[92:95], v[152:155], v[200:203], v[92:95]
	v_mfma_f32_16x16x32_bf16 v[84:87], v[160:163], v[200:203], v[84:87]
	v_mfma_f32_16x16x32_bf16 v[76:79], v[152:155], v[208:211], v[76:79]
	v_mfma_f32_16x16x32_bf16 v[60:63], v[160:163], v[208:211], v[60:63]
	v_mfma_f32_16x16x32_bf16 v[124:127], v[156:159], v[188:191], v[124:127]
	v_mfma_f32_16x16x32_bf16 v[116:119], v[164:167], v[188:191], v[116:119]
	v_mfma_f32_16x16x32_bf16 v[108:111], v[156:159], v[196:199], v[108:111]
	v_mfma_f32_16x16x32_bf16 v[100:103], v[164:167], v[196:199], v[100:103]
	v_mfma_f32_16x16x32_bf16 v[92:95], v[156:159], v[204:207], v[92:95]
	v_mfma_f32_16x16x32_bf16 v[84:87], v[164:167], v[204:207], v[84:87]
	v_mfma_f32_16x16x32_bf16 v[76:79], v[156:159], v[212:215], v[76:79]
	v_mfma_f32_16x16x32_bf16 v[60:63], v[164:167], v[212:215], v[60:63]
	s_setprio 0
	s_setprio 1
	v_mfma_f32_16x16x32_bf16 v[128:131], v[168:171], v[184:187], v[128:131]
	v_mfma_f32_16x16x32_bf16 v[120:123], v[176:179], v[184:187], v[120:123]
	v_mfma_f32_16x16x32_bf16 v[112:115], v[168:171], v[192:195], v[112:115]
	v_mfma_f32_16x16x32_bf16 v[104:107], v[176:179], v[192:195], v[104:107]
	v_mfma_f32_16x16x32_bf16 v[96:99], v[168:171], v[200:203], v[96:99]
	v_mfma_f32_16x16x32_bf16 v[88:91], v[176:179], v[200:203], v[88:91]
	v_mfma_f32_16x16x32_bf16 v[80:83], v[168:171], v[208:211], v[80:83]
	v_mfma_f32_16x16x32_bf16 v[68:71], v[176:179], v[208:211], v[68:71]
	v_mfma_f32_16x16x32_bf16 v[128:131], v[172:175], v[188:191], v[128:131]
	v_mfma_f32_16x16x32_bf16 v[120:123], v[180:183], v[188:191], v[120:123]
	v_mfma_f32_16x16x32_bf16 v[112:115], v[172:175], v[196:199], v[112:115]
	v_mfma_f32_16x16x32_bf16 v[104:107], v[180:183], v[196:199], v[104:107]
	v_mfma_f32_16x16x32_bf16 v[96:99], v[172:175], v[204:207], v[96:99]
	v_mfma_f32_16x16x32_bf16 v[88:91], v[180:183], v[204:207], v[88:91]
	v_mfma_f32_16x16x32_bf16 v[80:83], v[172:175], v[212:215], v[80:83]
	v_mfma_f32_16x16x32_bf16 v[68:71], v[180:183], v[212:215], v[68:71]
	s_setprio 0
	s_barrier
	s_mov_b64 s[34:35], s[28:29]
	s_add_i32 s64, s59, s38
	ds_read_b128 v[184:187], v149 offset:16384
	ds_read_b128 v[188:191], v149 offset:17408
	ds_read_b128 v[192:195], v149 offset:18432
	ds_read_b128 v[196:199], v149 offset:19456
	ds_read_b128 v[200:203], v149 offset:20480
	ds_read_b128 v[204:207], v149 offset:21504
	ds_read_b128 v[208:211], v149 offset:22528
	ds_read_b128 v[212:215], v149 offset:23552
	s_mov_b32 m0, s64
	s_add_i32 s15, s64, 0x2000
	global_load_lds_dwordx4 v136, s[34:35]
	s_mov_b64 s[98:99], s[34:35]
	s_add_u32 s34, s28, 0x40000
	s_mov_b32 m0, s15
	s_addc_u32 s35, s29, 0
	s_add_i32 s17, s60, s38
	global_load_lds_dwordx4 v132, s[98:99]
	s_mov_b32 m0, s17
	s_add_i32 s63, s17, 0x2000
	global_load_lds_dwordx4 v136, s[34:35]
	s_mov_b64 s[98:99], s[34:35]
	s_mov_b32 m0, s63
	s_mov_b64 s[34:35], s[30:31]
	global_load_lds_dwordx4 v132, s[98:99]
	s_mov_b32 m0, s42
	s_nop 0
	global_load_lds_dwordx4 v138, s[34:35]
	s_mov_b32 m0, s43
	s_nop 0
	global_load_lds_dwordx4 v134, s[34:35]
	s_waitcnt vmcnt(8)
	s_waitcnt lgkmcnt(0)
	s_barrier
	s_setprio 1
	s_waitcnt lgkmcnt(0)
	v_mfma_f32_16x16x32_bf16 v[64:67], v[152:155], v[184:187], v[64:67]
	v_mfma_f32_16x16x32_bf16 v[52:55], v[160:163], v[184:187], v[52:55]
	v_mfma_f32_16x16x32_bf16 v[44:47], v[152:155], v[192:195], v[44:47]
	v_mfma_f32_16x16x32_bf16 v[36:39], v[160:163], v[192:195], v[36:39]
	v_mfma_f32_16x16x32_bf16 v[28:31], v[152:155], v[200:203], v[28:31]
	v_mfma_f32_16x16x32_bf16 v[20:23], v[160:163], v[200:203], v[20:23]
	v_mfma_f32_16x16x32_bf16 v[12:15], v[152:155], v[208:211], v[12:15]
	v_mfma_f32_16x16x32_bf16 v[2:5], v[160:163], v[208:211], v[4:7]
	v_mfma_f32_16x16x32_bf16 v[64:67], v[156:159], v[188:191], v[64:67]
	v_mfma_f32_16x16x32_bf16 v[52:55], v[164:167], v[188:191], v[52:55]
	v_mfma_f32_16x16x32_bf16 v[44:47], v[156:159], v[196:199], v[44:47]
	v_mfma_f32_16x16x32_bf16 v[36:39], v[164:167], v[196:199], v[36:39]
	v_mfma_f32_16x16x32_bf16 v[28:31], v[156:159], v[204:207], v[28:31]
	v_mfma_f32_16x16x32_bf16 v[20:23], v[164:167], v[204:207], v[20:23]
	v_mfma_f32_16x16x32_bf16 v[12:15], v[156:159], v[212:215], v[12:15]
	v_mfma_f32_16x16x32_bf16 v[2:5], v[164:167], v[212:215], v[2:5]
	s_setprio 0
	s_setprio 1
	v_mfma_f32_16x16x32_bf16 v[72:75], v[168:171], v[184:187], v[72:75]
	v_mfma_f32_16x16x32_bf16 v[56:59], v[176:179], v[184:187], v[56:59]
	v_mfma_f32_16x16x32_bf16 v[48:51], v[168:171], v[192:195], v[48:51]
	v_mfma_f32_16x16x32_bf16 v[40:43], v[176:179], v[192:195], v[40:43]
	v_mfma_f32_16x16x32_bf16 v[32:35], v[168:171], v[200:203], v[32:35]
	v_mfma_f32_16x16x32_bf16 v[24:27], v[176:179], v[200:203], v[24:27]
	v_mfma_f32_16x16x32_bf16 v[16:19], v[168:171], v[208:211], v[16:19]
	v_mfma_f32_16x16x32_bf16 v[6:9], v[176:179], v[208:211], v[8:11]
	v_mfma_f32_16x16x32_bf16 v[72:75], v[172:175], v[188:191], v[72:75]
	v_mfma_f32_16x16x32_bf16 v[56:59], v[180:183], v[188:191], v[56:59]
	v_mfma_f32_16x16x32_bf16 v[48:51], v[172:175], v[196:199], v[48:51]
	v_mfma_f32_16x16x32_bf16 v[40:43], v[180:183], v[196:199], v[40:43]
	v_mfma_f32_16x16x32_bf16 v[32:35], v[172:175], v[204:207], v[32:35]
	v_mfma_f32_16x16x32_bf16 v[24:27], v[180:183], v[204:207], v[24:27]
	v_mfma_f32_16x16x32_bf16 v[16:19], v[172:175], v[212:215], v[16:19]
	v_mfma_f32_16x16x32_bf16 v[8:11], v[180:183], v[212:215], v[6:9]
	s_setprio 0
	s_barrier
	s_add_i32 s73, 0, 0x18000
	s_add_i32 s74, 0, 0x1c000
	v_add_u32_e32 v152, s73, v146
	v_add_u32_e32 v153, s74, v146
	ds_read_b128 v[154:157], v152
	ds_read_b128 v[158:161], v152 offset:1024
	ds_read_b128 v[162:165], v152 offset:2048
	ds_read_b128 v[166:169], v152 offset:3072
	ds_read_b128 v[170:173], v153
	ds_read_b128 v[174:177], v153 offset:1024
	ds_read_b128 v[178:181], v153 offset:2048
	ds_read_b128 v[182:185], v153 offset:3072
	s_add_u32 s30, s30, 0x40000
	s_addc_u32 s31, s31, 0
	s_mov_b32 m0, s52
	ds_read_b128 v[186:189], v149 offset:32768
	ds_read_b128 v[190:193], v149 offset:33792
	ds_read_b128 v[194:197], v149 offset:34816
	ds_read_b128 v[198:201], v149 offset:35840
	ds_read_b128 v[202:205], v149 offset:36864
	ds_read_b128 v[206:209], v149 offset:37888
	ds_read_b128 v[210:213], v149 offset:38912
	ds_read_b128 v[214:217], v149 offset:39936
	s_nop 0
	global_load_lds_dwordx4 v138, s[30:31]
	s_mov_b32 m0, s53
	s_nop 0
	global_load_lds_dwordx4 v134, s[30:31]
	s_waitcnt vmcnt(8)
	s_waitcnt lgkmcnt(0)
	s_barrier
	s_setprio 1
	s_waitcnt lgkmcnt(0)
	v_mfma_f32_16x16x32_bf16 v[124:127], v[154:157], v[186:189], v[124:127]
	v_mfma_f32_16x16x32_bf16 v[116:119], v[162:165], v[186:189], v[116:119]
	v_mfma_f32_16x16x32_bf16 v[108:111], v[154:157], v[194:197], v[108:111]
	v_mfma_f32_16x16x32_bf16 v[100:103], v[162:165], v[194:197], v[100:103]
	v_mfma_f32_16x16x32_bf16 v[92:95], v[154:157], v[202:205], v[92:95]
	v_mfma_f32_16x16x32_bf16 v[84:87], v[162:165], v[202:205], v[84:87]
	v_mfma_f32_16x16x32_bf16 v[76:79], v[154:157], v[210:213], v[76:79]
	v_mfma_f32_16x16x32_bf16 v[60:63], v[162:165], v[210:213], v[60:63]
	v_mfma_f32_16x16x32_bf16 v[124:127], v[158:161], v[190:193], v[124:127]
	v_mfma_f32_16x16x32_bf16 v[116:119], v[166:169], v[190:193], v[116:119]
	v_mfma_f32_16x16x32_bf16 v[108:111], v[158:161], v[198:201], v[108:111]
	v_mfma_f32_16x16x32_bf16 v[100:103], v[166:169], v[198:201], v[100:103]
	v_mfma_f32_16x16x32_bf16 v[92:95], v[158:161], v[206:209], v[92:95]
	v_mfma_f32_16x16x32_bf16 v[84:87], v[166:169], v[206:209], v[84:87]
	v_mfma_f32_16x16x32_bf16 v[76:79], v[158:161], v[214:217], v[76:79]
	v_mfma_f32_16x16x32_bf16 v[60:63], v[166:169], v[214:217], v[60:63]
	s_setprio 0
	s_setprio 1
	v_mfma_f32_16x16x32_bf16 v[128:131], v[170:173], v[186:189], v[128:131]
	v_mfma_f32_16x16x32_bf16 v[120:123], v[178:181], v[186:189], v[120:123]
	v_mfma_f32_16x16x32_bf16 v[112:115], v[170:173], v[194:197], v[112:115]
	v_mfma_f32_16x16x32_bf16 v[104:107], v[178:181], v[194:197], v[104:107]
	v_mfma_f32_16x16x32_bf16 v[96:99], v[170:173], v[202:205], v[96:99]
	v_mfma_f32_16x16x32_bf16 v[88:91], v[178:181], v[202:205], v[88:91]
	v_mfma_f32_16x16x32_bf16 v[80:83], v[170:173], v[210:213], v[80:83]
	v_mfma_f32_16x16x32_bf16 v[68:71], v[178:181], v[210:213], v[68:71]
	v_mfma_f32_16x16x32_bf16 v[128:131], v[174:177], v[190:193], v[128:131]
	v_mfma_f32_16x16x32_bf16 v[120:123], v[182:185], v[190:193], v[120:123]
	v_mfma_f32_16x16x32_bf16 v[112:115], v[174:177], v[198:201], v[112:115]
	v_mfma_f32_16x16x32_bf16 v[104:107], v[182:185], v[198:201], v[104:107]
	v_mfma_f32_16x16x32_bf16 v[96:99], v[174:177], v[206:209], v[96:99]
	v_mfma_f32_16x16x32_bf16 v[88:91], v[182:185], v[206:209], v[88:91]
	v_mfma_f32_16x16x32_bf16 v[80:83], v[174:177], v[214:217], v[80:83]
	v_mfma_f32_16x16x32_bf16 v[68:71], v[182:185], v[214:217], v[68:71]
	s_setprio 0
	s_barrier
; #define PG8_LDA(dst, b, h) do { _Pragma("unroll") for (int m = 0; m < 4; ++m) _Pragma("unroll") for (int k = 0; k < 2; ++k) dst[m][k] = *(const PG8_LAS bf16x8*)(lds + PG8_SA(b, h) + aoff + m * 2048 + k * 1024); } while (0)
; #define PG8_WAIT_V(n) asm volatile("s_waitcnt vmcnt(" #n ")" ::: "memory")
; template <class Epi, class Sched, bool ALIGN_EPI = false, bool SP2 = false>
; __device__ __forceinline__ void gemm_phase(PG8_LAS unsigned char* lds, const Gemm g, const Sched& S, const Epi& E, int wave_s) {
;     ...
;         for (int t = peeled ? 2 : 0; t < nt; t += 2) {
;             const bool last = (t == nt - 2);
;             const char* a1 = cA + (size_t)(t + 1) * kstep;
;             const char* a2 = last ? nA : cA + (size_t)(t + 2) * kstep; const char* b2 = last ? nB : cB + (size_t)(t + 2) * kstep;
;             const char* a3 = a2 + kstep; const char* b3 = b2 + kstep;
;             if (last && has_next) S.a_ready(nxt);
;             if constexpr (SP2) {
;             PG8_SP2_PAIR(PG8_WAIT_V8_STRICT);
;             } else {
;             PG8_LDB(B0, 0, 0); PG8_SCHED; PG8_LDA(At, 0, 0); PG8_STAGE(PG8_SA(1, 1), a1 + hstep, voffA);
;             PG8_WAIT_L(8); PG8_BAR; PG8_WAIT_L(0); PG8_MMA(0, 0, At, B0); PG8_BAR; PG8_SCHED;
;             PG8_LDB(B1, 0, 1); PG8_STAGE(PG8_SB(0, 0), b2, voffB);
;             PG8_BAR; PG8_WAIT_L(0); PG8_MMA(0, 1, At, B1); PG8_BAR;
;             PG8_LDA(At, 0, 1); PG8_STAGE(PG8_SA(0, 0), a2, voffA);
;             PG8_BAR; PG8_WAIT_L(0); PG8_MMA(1, 0, At, B0); PG8_BAR; PG8_SCHED;
;             PG8_STAGE(PG8_SB(0, 1), b2 + hstep, voffB);
;             PG8_WAIT_V(6); PG8_BAR; PG8_MMA(1, 1, At, B1); PG8_BAR;
;             PG8_LDB(B0, 1, 0); PG8_SCHED; PG8_LDA(At, 1, 0); PG8_STAGE(PG8_SA(0, 1), a2 + hstep, voffA);
;             PG8_WAIT_L(8); PG8_BAR; PG8_WAIT_L(0); PG8_MMA(0, 0, At, B0); PG8_BAR; PG8_SCHED;
;             PG8_LDB(B1, 1, 1); PG8_STAGE(PG8_SB(1, 0), b3, voffB);
;             PG8_BAR; PG8_WAIT_L(0); PG8_MMA(0, 1, At, B1); PG8_BAR;
;             PG8_LDA(At, 1, 1); PG8_STAGE(PG8_SA(1, 0), a3, voffA);
;             PG8_BAR; PG8_WAIT_L(0); PG8_MMA(1, 0, At, B0); PG8_BAR; PG8_SCHED;
;             PG8_STAGE(PG8_SB(1, 1), b3 + hstep, voffB);
;             PG8_WAIT_V(6); PG8_BAR; PG8_MMA(1, 1, At, B1); PG8_BAR;
;             }
;         }
;         if constexpr (ALIGN_EPI) { if (wr == 0) PG8_BAR; }
	s_add_u32 s34, s28, 0x80
	s_addc_u32 s35, s29, 0
	s_add_i32 s31, s73, s38
	ds_read_b128 v[186:189], v149 offset:49152
	ds_read_b128 v[190:193], v149 offset:50176
	ds_read_b128 v[194:197], v149 offset:51200
	ds_read_b128 v[198:201], v149 offset:52224
	ds_read_b128 v[202:205], v149 offset:53248
	ds_read_b128 v[206:209], v149 offset:54272
	ds_read_b128 v[210:213], v149 offset:55296
	ds_read_b128 v[214:217], v149 offset:56320
	s_mov_b32 m0, s31
	s_add_i32 s30, s31, 0x2000
	global_load_lds_dwordx4 v136, s[34:35]
	s_mov_b64 s[98:99], s[34:35]
	s_add_u32 s34, s28, 0x40080
	s_mov_b32 m0, s30
	s_addc_u32 s35, s29, 0
	s_add_i32 s28, s74, s38
	global_load_lds_dwordx4 v132, s[98:99]
	s_mov_b32 m0, s28
	s_add_i32 s29, s28, 0x2000
	global_load_lds_dwordx4 v136, s[34:35]
	s_mov_b32 m0, s29
	s_nop 0
	global_load_lds_dwordx4 v132, s[34:35]
	s_mov_b32 m0, s54
	s_nop 0
	global_load_lds_dwordx4 v138, s[26:27]
	s_mov_b32 m0, s55
	s_nop 0
	global_load_lds_dwordx4 v134, s[26:27]
	s_waitcnt vmcnt(8)
	s_waitcnt lgkmcnt(0)
	s_barrier
	s_setprio 1
	s_waitcnt lgkmcnt(0)
	v_mfma_f32_16x16x32_bf16 v[64:67], v[154:157], v[186:189], v[64:67]
	v_mfma_f32_16x16x32_bf16 v[52:55], v[162:165], v[186:189], v[52:55]
	v_mfma_f32_16x16x32_bf16 v[44:47], v[154:157], v[194:197], v[44:47]
	v_mfma_f32_16x16x32_bf16 v[36:39], v[162:165], v[194:197], v[36:39]
	v_mfma_f32_16x16x32_bf16 v[28:31], v[154:157], v[202:205], v[28:31]
	v_mfma_f32_16x16x32_bf16 v[20:23], v[162:165], v[202:205], v[20:23]
	v_mfma_f32_16x16x32_bf16 v[12:15], v[154:157], v[210:213], v[12:15]
	v_mfma_f32_16x16x32_bf16 v[2:5], v[162:165], v[210:213], v[2:5]
	v_mfma_f32_16x16x32_bf16 v[64:67], v[158:161], v[190:193], v[64:67]
	v_mfma_f32_16x16x32_bf16 v[52:55], v[166:169], v[190:193], v[52:55]
	v_mfma_f32_16x16x32_bf16 v[44:47], v[158:161], v[198:201], v[44:47]
	v_mfma_f32_16x16x32_bf16 v[36:39], v[166:169], v[198:201], v[36:39]
	v_mfma_f32_16x16x32_bf16 v[28:31], v[158:161], v[206:209], v[28:31]
	v_mfma_f32_16x16x32_bf16 v[20:23], v[166:169], v[206:209], v[20:23]
	v_mfma_f32_16x16x32_bf16 v[12:15], v[158:161], v[214:217], v[12:15]
	v_mfma_f32_16x16x32_bf16 v[4:7], v[166:169], v[214:217], v[2:5]
	s_setprio 0
	s_setprio 1
	v_mfma_f32_16x16x32_bf16 v[72:75], v[170:173], v[186:189], v[72:75]
	v_mfma_f32_16x16x32_bf16 v[56:59], v[178:181], v[186:189], v[56:59]
	v_mfma_f32_16x16x32_bf16 v[48:51], v[170:173], v[194:197], v[48:51]
	v_mfma_f32_16x16x32_bf16 v[40:43], v[178:181], v[194:197], v[40:43]
	v_mfma_f32_16x16x32_bf16 v[32:35], v[170:173], v[202:205], v[32:35]
	v_mfma_f32_16x16x32_bf16 v[24:27], v[178:181], v[202:205], v[24:27]
	v_mfma_f32_16x16x32_bf16 v[16:19], v[170:173], v[210:213], v[16:19]
	v_mfma_f32_16x16x32_bf16 v[8:11], v[178:181], v[210:213], v[8:11]
	v_mfma_f32_16x16x32_bf16 v[72:75], v[174:177], v[190:193], v[72:75]
	v_mfma_f32_16x16x32_bf16 v[56:59], v[182:185], v[190:193], v[56:59]
	v_mfma_f32_16x16x32_bf16 v[48:51], v[174:177], v[198:201], v[48:51]
	v_mfma_f32_16x16x32_bf16 v[40:43], v[182:185], v[198:201], v[40:43]
	v_mfma_f32_16x16x32_bf16 v[32:35], v[174:177], v[206:209], v[32:35]
	v_mfma_f32_16x16x32_bf16 v[24:27], v[182:185], v[206:209], v[24:27]
	v_mfma_f32_16x16x32_bf16 v[16:19], v[174:177], v[214:217], v[16:19]
	v_mfma_f32_16x16x32_bf16 v[8:11], v[182:185], v[214:217], v[8:11]
	s_setprio 0
	s_barrier
	s_add_i32 s70, s70, 2
	s_add_u32 s71, s71, 0x100
	s_addc_u32 s72, s72, 0
	s_cmp_gt_u32 s70, 13
	s_mov_b64 s[34:35], s[24:25]
	s_cbranch_scc0 .LBB0_2390
	s_and_b64 vcc, exec, s[12:13]
	s_cbranch_vccz .LBB0_2393
	s_barrier

; #define PG8_STAGE(bufoff, gbase, voff) do { const char* gb_ = (const char*)(gbase); asm volatile("" : "+s"(gb_));   \
;         _Pragma("unroll") for (int _i = 0; _i < 2; ++_i) \
;         __builtin_amdgcn_global_load_lds((const unsigned*)(gb_ + (voff)[_i]), (PG8_LAS unsigned*)(lds + (bufoff) + ldsw + _i * 8192), 16, 0, 0); } while (0)
; #define PG8_WAIT_V(n) asm volatile("s_waitcnt vmcnt(" #n ")" ::: "memory")
; #define PG8_BAR __builtin_amdgcn_s_barrier()
; template <class Epi, class Sched, bool ALIGN_EPI = false, bool SP2 = false>
; __device__ __forceinline__ void gemm_phase(PG8_LAS unsigned char* lds, const Gemm g, const Sched& S, const Epi& E, int wave_s) {
;     ...
;     const unsigned ldsw = (unsigned)wid * 1024u;
;     const int aoff = lds_byte(wr * 64 + fr, fq * 8), boff = lds_byte(wc * 32 + fr, fq * 8);
;     ...
;         PG8_WAIT_V(2); PG8_BAR;
;         PG8_STAGE(PG8_SB(1, 0), cB + kstep, voffB); PG8_STAGE(PG8_SA(1, 0), cA + kstep, voffA); PG8_STAGE(PG8_SB(1, 1), cB + hstep + kstep, voffB);
;         PG8_WAIT_V(6); PG8_BAR;
.LBB0_2458:
	s_lshl_b32 s2, s2, 5
	s_and_b32 s10, s2, 0x60
	s_lshl_b32 s9, s0, 13
	s_lshl_b32 s11, s10, 7
	s_add_u32 s2, s22, 0x80
	s_addc_u32 s3, s23, 0
	s_waitcnt vmcnt(2)
	s_barrier
	s_add_i32 m0, s36, 0x18000
	s_nop 0
	global_load_lds_dwordx4 v130, s[2:3]
	s_add_i32 m0, s36, 0x1a000
	s_nop 0
	global_load_lds_dwordx4 v134, s[2:3]
	s_add_u32 s2, s20, 0x80
	s_addc_u32 s3, s21, 0
	s_add_i32 s41, s36, 0x8000
	s_mov_b32 m0, s41
	s_add_i32 s42, s36, 0xa000
	global_load_lds_dwordx4 v128, s[2:3]
	s_mov_b64 s[98:99], s[2:3]
	s_add_u32 s2, s22, 0xb0080
	s_mov_b32 m0, s42
	s_addc_u32 s3, s23, 0
	global_load_lds_dwordx4 v132, s[98:99]
	s_add_i32 m0, s36, 0x1c000
	s_nop 0
	global_load_lds_dwordx4 v130, s[2:3]
	s_add_i32 m0, s36, 0x1e000
	v_and_b32_e32 v1, 15, v0
	global_load_lds_dwordx4 v134, s[2:3]
	v_lshrrev_b32_e32 v2, 1, v0
	v_and_b32_e32 v2, 24, v2
	v_lshlrev_b32_e32 v3, 1, v2
	v_lshlrev_b32_e32 v0, 2, v0
	v_lshl_or_b32 v146, s0, 6, v1
	v_lshl_or_b32 v1, v1, 6, v3
	v_and_b32_e32 v0, 32, v0
	s_waitcnt vmcnt(6)
	s_cmpk_lt_u32 s8, 0x100
	v_bitop3_b32 v3, v1, s9, v0 bitop3:0xde
	v_bitop3_b32 v147, v1, s11, v0 bitop3:0xde
	s_cselect_b64 s[8:9], -1, 0
	s_add_i32 s43, 0, 0x10000
	s_add_i32 s44, 0, 0x14000
	s_sext_i32_i8 s53, s1
	v_or_b32_e32 v148, s10, v2
	v_mov_b64_e32 v[136:137], 0x100
	v_mov_b64_e32 v[138:139], 0xff
	v_add_u32_e32 v149, s43, v147
	v_add_u32_e32 v150, s44, v147
	v_add_u32_e32 v151, 0, v3
	s_mov_b64 s[10:11], 0x20000
	s_mov_b64 s[12:13], 0x24000
	s_mov_b64 s[14:15], 0x28000
	s_mov_b64 s[16:17], 0x2c000
	s_barrier
	s_branch .LBB0_2461

; template <class Epi, class Sched, bool ALIGN_EPI = false, bool SP2 = false>
; __device__ __forceinline__ void gemm_phase(PG8_LAS unsigned char* lds, const Gemm g, const Sched& S, const Epi& E, int wave_s) {
;     ...
;         const bool has_next = S.next(ui + 1, nxt);
;         const char* nA = has_next ? (const char*)g.A + (size_t)nxt.pm * tstep : cA; const char* nB = has_next ? (const char*)g.Bt + (size_t)nxt.pn * tstep : cB;
;         for (int t = peeled ? 2 : 0; t < nt; t += 2) {
;             const bool last = (t == nt - 2);
;             const char* a1 = cA + (size_t)(t + 1) * kstep;
;             const char* a2 = last ? nA : cA + (size_t)(t + 2) * kstep; const char* b2 = last ? nB : cB + (size_t)(t + 2) * kstep;
;             const char* a3 = a2 + kstep; const char* b3 = b2 + kstep;
;             if (last && has_next) S.a_ready(nxt);
.LBB0_2472:
	ds_read_b128 v[140:143], v149
	ds_read_b128 v[152:155], v149 offset:1024
	ds_read_b128 v[156:159], v149 offset:2048
	ds_read_b128 v[160:163], v149 offset:3072
	ds_read_b128 v[164:167], v150
	ds_read_b128 v[168:171], v150 offset:1024
	ds_read_b128 v[172:175], v150 offset:2048
	ds_read_b128 v[176:179], v150 offset:3072
	s_add_u32 s22, s20, 0x100
	s_addc_u32 s23, s21, 0
	s_cmp_eq_u32 s56, 40
	s_cselect_b32 s28, s2, s22
	s_cselect_b32 s29, s3, s23
	s_cselect_b32 s26, s18, s54
	s_cselect_b32 s27, s19, s55
	s_add_u32 s24, s28, 0x80
	s_addc_u32 s25, s29, 0
	s_add_u32 s20, s20, 0xb0080
	s_addc_u32 s21, s21, 0
	ds_read_b128 v[180:183], v151
	ds_read_b128 v[184:187], v151 offset:1024
	ds_read_b128 v[188:191], v151 offset:2048
	ds_read_b128 v[192:195], v151 offset:3072
	ds_read_b128 v[196:199], v151 offset:4096
	ds_read_b128 v[200:203], v151 offset:5120
	ds_read_b128 v[204:207], v151 offset:6144
	ds_read_b128 v[208:211], v151 offset:7168
	s_add_i32 m0, s36, 0xc000
	s_nop 0
	global_load_lds_dwordx4 v128, s[20:21]
	s_add_i32 m0, s36, 0xe000
	s_nop 0
	global_load_lds_dwordx4 v132, s[20:21]
	s_waitcnt vmcnt(8)
	s_waitcnt lgkmcnt(0)
	s_barrier
	s_setprio 1
	s_waitcnt lgkmcnt(0)
	v_mfma_f32_16x16x32_bf16 v[124:127], v[140:143], v[180:183], v[124:127]
	v_mfma_f32_16x16x32_bf16 v[120:123], v[156:159], v[180:183], v[120:123]
	v_mfma_f32_16x16x32_bf16 v[108:111], v[140:143], v[188:191], v[108:111]
	v_mfma_f32_16x16x32_bf16 v[104:107], v[156:159], v[188:191], v[104:107]
	v_mfma_f32_16x16x32_bf16 v[92:95], v[140:143], v[196:199], v[92:95]
	v_mfma_f32_16x16x32_bf16 v[88:91], v[156:159], v[196:199], v[88:91]
	v_mfma_f32_16x16x32_bf16 v[76:79], v[140:143], v[204:207], v[76:79]
	v_mfma_f32_16x16x32_bf16 v[72:75], v[156:159], v[204:207], v[72:75]
	v_mfma_f32_16x16x32_bf16 v[124:127], v[152:155], v[184:187], v[124:127]
	v_mfma_f32_16x16x32_bf16 v[120:123], v[160:163], v[184:187], v[120:123]
	v_mfma_f32_16x16x32_bf16 v[108:111], v[152:155], v[192:195], v[108:111]
	v_mfma_f32_16x16x32_bf16 v[104:107], v[160:163], v[192:195], v[104:107]
	v_mfma_f32_16x16x32_bf16 v[92:95], v[152:155], v[200:203], v[92:95]
	v_mfma_f32_16x16x32_bf16 v[88:91], v[160:163], v[200:203], v[88:91]
	v_mfma_f32_16x16x32_bf16 v[76:79], v[152:155], v[208:211], v[76:79]
	v_mfma_f32_16x16x32_bf16 v[72:75], v[160:163], v[208:211], v[72:75]
	s_setprio 0
	s_setprio 1
	v_mfma_f32_16x16x32_bf16 v[116:119], v[164:167], v[180:183], v[116:119]
	v_mfma_f32_16x16x32_bf16 v[112:115], v[172:175], v[180:183], v[112:115]
	v_mfma_f32_16x16x32_bf16 v[100:103], v[164:167], v[188:191], v[100:103]
	v_mfma_f32_16x16x32_bf16 v[96:99], v[172:175], v[188:191], v[96:99]
	v_mfma_f32_16x16x32_bf16 v[84:87], v[164:167], v[196:199], v[84:87]
	v_mfma_f32_16x16x32_bf16 v[80:83], v[172:175], v[196:199], v[80:83]
	v_mfma_f32_16x16x32_bf16 v[68:71], v[164:167], v[204:207], v[68:71]
	v_mfma_f32_16x16x32_bf16 v[64:67], v[172:175], v[204:207], v[64:67]
	v_mfma_f32_16x16x32_bf16 v[116:119], v[168:171], v[184:187], v[116:119]
	v_mfma_f32_16x16x32_bf16 v[112:115], v[176:179], v[184:187], v[112:115]
	v_mfma_f32_16x16x32_bf16 v[100:103], v[168:171], v[192:195], v[100:103]
	v_mfma_f32_16x16x32_bf16 v[96:99], v[176:179], v[192:195], v[96:99]
	v_mfma_f32_16x16x32_bf16 v[84:87], v[168:171], v[200:203], v[84:87]
	v_mfma_f32_16x16x32_bf16 v[80:83], v[176:179], v[200:203], v[80:83]
	v_mfma_f32_16x16x32_bf16 v[68:71], v[168:171], v[208:211], v[68:71]
	v_mfma_f32_16x16x32_bf16 v[64:67], v[176:179], v[208:211], v[64:67]
	s_setprio 0
	s_barrier
	s_mov_b64 s[20:21], s[26:27]
	s_add_i32 s57, s43, s35
	ds_read_b128 v[180:183], v151 offset:16384
	ds_read_b128 v[184:187], v151 offset:17408
	ds_read_b128 v[188:191], v151 offset:18432
	ds_read_b128 v[192:195], v151 offset:19456
	ds_read_b128 v[196:199], v151 offset:20480
	ds_read_b128 v[200:203], v151 offset:21504
	ds_read_b128 v[204:207], v151 offset:22528
	ds_read_b128 v[208:211], v151 offset:23552
	s_mov_b32 m0, s57
	s_nop 0
	global_load_lds_dwordx4 v130, s[20:21]
	s_add_i32 m0, s57, 0x2000
	s_nop 0
	global_load_lds_dwordx4 v134, s[20:21]
	s_add_u32 s20, s26, 0xb0000
	s_addc_u32 s21, s27, 0
	s_add_i32 s57, s44, s35
	s_mov_b32 m0, s57
	s_nop 0
	global_load_lds_dwordx4 v130, s[20:21]
	s_mov_b64 s[98:99], s[20:21]
	s_add_i32 m0, s57, 0x2000
	s_mov_b64 s[20:21], s[28:29]
	global_load_lds_dwordx4 v134, s[98:99]
	s_mov_b32 m0, s36
	s_nop 0
	global_load_lds_dwordx4 v128, s[20:21]
	s_mov_b32 m0, s37
	s_nop 0
	global_load_lds_dwordx4 v132, s[20:21]
	s_waitcnt vmcnt(8)
	s_waitcnt lgkmcnt(0)
	s_barrier
	s_setprio 1
	s_waitcnt lgkmcnt(0)
	v_mfma_f32_16x16x32_bf16 v[60:63], v[140:143], v[180:183], v[60:63]
	v_mfma_f32_16x16x32_bf16 v[56:59], v[156:159], v[180:183], v[56:59]
	v_mfma_f32_16x16x32_bf16 v[44:47], v[140:143], v[188:191], v[44:47]
	v_mfma_f32_16x16x32_bf16 v[40:43], v[156:159], v[188:191], v[40:43]
	v_mfma_f32_16x16x32_bf16 v[28:31], v[140:143], v[196:199], v[28:31]
	v_mfma_f32_16x16x32_bf16 v[24:27], v[156:159], v[196:199], v[24:27]
	v_mfma_f32_16x16x32_bf16 v[12:15], v[140:143], v[204:207], v[12:15]
	v_mfma_f32_16x16x32_bf16 v[8:11], v[156:159], v[204:207], v[8:11]
	v_mfma_f32_16x16x32_bf16 v[60:63], v[152:155], v[184:187], v[60:63]
	v_mfma_f32_16x16x32_bf16 v[56:59], v[160:163], v[184:187], v[56:59]
	v_mfma_f32_16x16x32_bf16 v[44:47], v[152:155], v[192:195], v[44:47]
	v_mfma_f32_16x16x32_bf16 v[40:43], v[160:163], v[192:195], v[40:43]
	v_mfma_f32_16x16x32_bf16 v[28:31], v[152:155], v[200:203], v[28:31]
	v_mfma_f32_16x16x32_bf16 v[24:27], v[160:163], v[200:203], v[24:27]
	v_mfma_f32_16x16x32_bf16 v[12:15], v[152:155], v[208:211], v[12:15]
	v_mfma_f32_16x16x32_bf16 v[8:11], v[160:163], v[208:211], v[8:11]
	s_setprio 0
	s_setprio 1
	v_mfma_f32_16x16x32_bf16 v[52:55], v[164:167], v[180:183], v[52:55]
	v_mfma_f32_16x16x32_bf16 v[48:51], v[172:175], v[180:183], v[48:51]
	v_mfma_f32_16x16x32_bf16 v[36:39], v[164:167], v[188:191], v[36:39]
	v_mfma_f32_16x16x32_bf16 v[32:35], v[172:175], v[188:191], v[32:35]
	v_mfma_f32_16x16x32_bf16 v[20:23], v[164:167], v[196:199], v[20:23]
	v_mfma_f32_16x16x32_bf16 v[16:19], v[172:175], v[196:199], v[16:19]
	v_mfma_f32_16x16x32_bf16 v[4:7], v[164:167], v[204:207], v[4:7]
	v_mfma_f32_16x16x32_bf16 v[0:3], v[172:175], v[204:207], v[0:3]
	v_mfma_f32_16x16x32_bf16 v[52:55], v[168:171], v[184:187], v[52:55]
	v_mfma_f32_16x16x32_bf16 v[48:51], v[176:179], v[184:187], v[48:51]
	v_mfma_f32_16x16x32_bf16 v[36:39], v[168:171], v[192:195], v[36:39]
	v_mfma_f32_16x16x32_bf16 v[32:35], v[176:179], v[192:195], v[32:35]
	v_mfma_f32_16x16x32_bf16 v[20:23], v[168:171], v[200:203], v[20:23]
	v_mfma_f32_16x16x32_bf16 v[16:19], v[176:179], v[200:203], v[16:19]
	v_mfma_f32_16x16x32_bf16 v[4:7], v[168:171], v[208:211], v[4:7]
	v_mfma_f32_16x16x32_bf16 v[0:3], v[176:179], v[208:211], v[0:3]
	s_setprio 0
	s_barrier
	s_add_i32 s57, 0, 0x18000
	v_add_u32_e32 v144, s57, v147
	s_add_i32 s58, 0, 0x1c000
	ds_read_b128 v[140:143], v144
	ds_read_b128 v[152:155], v144 offset:1024
	ds_read_b128 v[156:159], v144 offset:2048
	ds_read_b128 v[160:163], v144 offset:3072
	v_add_u32_e32 v144, s58, v147
	ds_read_b128 v[164:167], v144
	ds_read_b128 v[168:171], v144 offset:1024
	ds_read_b128 v[172:175], v144 offset:2048
	ds_read_b128 v[176:179], v144 offset:3072
	s_add_u32 s20, s28, 0xb0000
	s_addc_u32 s21, s29, 0
	s_mov_b32 m0, s38
	ds_read_b128 v[180:183], v151 offset:32768
	ds_read_b128 v[184:187], v151 offset:33792
	ds_read_b128 v[188:191], v151 offset:34816
	ds_read_b128 v[192:195], v151 offset:35840
	ds_read_b128 v[196:199], v151 offset:36864
	ds_read_b128 v[200:203], v151 offset:37888
	ds_read_b128 v[204:207], v151 offset:38912
	ds_read_b128 v[208:211], v151 offset:39936
	s_nop 0
	global_load_lds_dwordx4 v128, s[20:21]
	s_mov_b32 m0, s39
	s_nop 0
	global_load_lds_dwordx4 v132, s[20:21]
	s_waitcnt vmcnt(8)
	s_waitcnt lgkmcnt(0)
	s_barrier
	s_setprio 1
	s_waitcnt lgkmcnt(0)
	v_mfma_f32_16x16x32_bf16 v[124:127], v[140:143], v[180:183], v[124:127]
	v_mfma_f32_16x16x32_bf16 v[120:123], v[156:159], v[180:183], v[120:123]
	v_mfma_f32_16x16x32_bf16 v[108:111], v[140:143], v[188:191], v[108:111]
	v_mfma_f32_16x16x32_bf16 v[104:107], v[156:159], v[188:191], v[104:107]
	v_mfma_f32_16x16x32_bf16 v[92:95], v[140:143], v[196:199], v[92:95]
	v_mfma_f32_16x16x32_bf16 v[88:91], v[156:159], v[196:199], v[88:91]
	v_mfma_f32_16x16x32_bf16 v[76:79], v[140:143], v[204:207], v[76:79]
	v_mfma_f32_16x16x32_bf16 v[72:75], v[156:159], v[204:207], v[72:75]
	v_mfma_f32_16x16x32_bf16 v[124:127], v[152:155], v[184:187], v[124:127]
	v_mfma_f32_16x16x32_bf16 v[120:123], v[160:163], v[184:187], v[120:123]
	v_mfma_f32_16x16x32_bf16 v[108:111], v[152:155], v[192:195], v[108:111]
	v_mfma_f32_16x16x32_bf16 v[104:107], v[160:163], v[192:195], v[104:107]
	v_mfma_f32_16x16x32_bf16 v[92:95], v[152:155], v[200:203], v[92:95]
	v_mfma_f32_16x16x32_bf16 v[88:91], v[160:163], v[200:203], v[88:91]
	v_mfma_f32_16x16x32_bf16 v[76:79], v[152:155], v[208:211], v[76:79]
	v_mfma_f32_16x16x32_bf16 v[72:75], v[160:163], v[208:211], v[72:75]
	s_setprio 0
	s_setprio 1
	v_mfma_f32_16x16x32_bf16 v[116:119], v[164:167], v[180:183], v[116:119]
	v_mfma_f32_16x16x32_bf16 v[112:115], v[172:175], v[180:183], v[112:115]
	v_mfma_f32_16x16x32_bf16 v[100:103], v[164:167], v[188:191], v[100:103]
	v_mfma_f32_16x16x32_bf16 v[96:99], v[172:175], v[188:191], v[96:99]
	v_mfma_f32_16x16x32_bf16 v[84:87], v[164:167], v[196:199], v[84:87]
	v_mfma_f32_16x16x32_bf16 v[80:83], v[172:175], v[196:199], v[80:83]
	v_mfma_f32_16x16x32_bf16 v[68:71], v[164:167], v[204:207], v[68:71]
	v_mfma_f32_16x16x32_bf16 v[64:67], v[172:175], v[204:207], v[64:67]
	v_mfma_f32_16x16x32_bf16 v[116:119], v[168:171], v[184:187], v[116:119]
	v_mfma_f32_16x16x32_bf16 v[112:115], v[176:179], v[184:187], v[112:115]
	v_mfma_f32_16x16x32_bf16 v[100:103], v[168:171], v[192:195], v[100:103]
	v_mfma_f32_16x16x32_bf16 v[96:99], v[176:179], v[192:195], v[96:99]
	v_mfma_f32_16x16x32_bf16 v[84:87], v[168:171], v[200:203], v[84:87]
	v_mfma_f32_16x16x32_bf16 v[80:83], v[176:179], v[200:203], v[80:83]
	v_mfma_f32_16x16x32_bf16 v[68:71], v[168:171], v[208:211], v[68:71]
	v_mfma_f32_16x16x32_bf16 v[64:67], v[176:179], v[208:211], v[64:67]
	s_setprio 0
	s_barrier
; #define PG8_LDA(dst, b, h) do { _Pragma("unroll") for (int m = 0; m < 4; ++m) _Pragma("unroll") for (int k = 0; k < 2; ++k) dst[m][k] = *(const PG8_LAS bf16x8*)(lds + PG8_SA(b, h) + aoff + m * 2048 + k * 1024); } while (0)
; #define PG8_WAIT_V(n) asm volatile("s_waitcnt vmcnt(" #n ")" ::: "memory")
; template <class Epi, class Sched, bool ALIGN_EPI = false, bool SP2 = false>
; __device__ __forceinline__ void gemm_phase(PG8_LAS unsigned char* lds, const Gemm g, const Sched& S, const Epi& E, int wave_s) {
;     ...
;         for (int t = peeled ? 2 : 0; t < nt; t += 2) {
;             const bool last = (t == nt - 2);
;             const char* a1 = cA + (size_t)(t + 1) * kstep;
;             const char* a2 = last ? nA : cA + (size_t)(t + 2) * kstep; const char* b2 = last ? nB : cB + (size_t)(t + 2) * kstep;
;             const char* a3 = a2 + kstep; const char* b3 = b2 + kstep;
;             if (last && has_next) S.a_ready(nxt);
;             if constexpr (SP2) {
;             PG8_SP2_PAIR(PG8_WAIT_V8_STRICT);
;             } else {
;             PG8_LDB(B0, 0, 0); PG8_SCHED; PG8_LDA(At, 0, 0); PG8_STAGE(PG8_SA(1, 1), a1 + hstep, voffA);
;             PG8_WAIT_L(8); PG8_BAR; PG8_WAIT_L(0); PG8_MMA(0, 0, At, B0); PG8_BAR; PG8_SCHED;
;             PG8_LDB(B1, 0, 1); PG8_STAGE(PG8_SB(0, 0), b2, voffB);
;             PG8_BAR; PG8_WAIT_L(0); PG8_MMA(0, 1, At, B1); PG8_BAR;
;             PG8_LDA(At, 0, 1); PG8_STAGE(PG8_SA(0, 0), a2, voffA);
;             PG8_BAR; PG8_WAIT_L(0); PG8_MMA(1, 0, At, B0); PG8_BAR; PG8_SCHED;
;             PG8_STAGE(PG8_SB(0, 1), b2 + hstep, voffB);
;             PG8_WAIT_V(6); PG8_BAR; PG8_MMA(1, 1, At, B1); PG8_BAR;
;             PG8_LDB(B0, 1, 0); PG8_SCHED; PG8_LDA(At, 1, 0); PG8_STAGE(PG8_SA(0, 1), a2 + hstep, voffA);
;             PG8_WAIT_L(8); PG8_BAR; PG8_WAIT_L(0); PG8_MMA(0, 0, At, B0); PG8_BAR; PG8_SCHED;
;             PG8_LDB(B1, 1, 1); PG8_STAGE(PG8_SB(1, 0), b3, voffB);
;             PG8_BAR; PG8_WAIT_L(0); PG8_MMA(0, 1, At, B1); PG8_BAR;
;             PG8_LDA(At, 1, 1); PG8_STAGE(PG8_SA(1, 0), a3, voffA);
;             PG8_BAR; PG8_WAIT_L(0); PG8_MMA(1, 0, At, B0); PG8_BAR; PG8_SCHED;
;             PG8_STAGE(PG8_SB(1, 1), b3 + hstep, voffB);
;             PG8_WAIT_V(6); PG8_BAR; PG8_MMA(1, 1, At, B1); PG8_BAR;
;             }
;         }
;         if constexpr (ALIGN_EPI) { if (wr == 0) PG8_BAR; }
	s_add_u32 s20, s26, 0x80
	s_addc_u32 s21, s27, 0
	s_add_i32 s28, s57, s35
	ds_read_b128 v[180:183], v151 offset:49152
	ds_read_b128 v[184:187], v151 offset:50176
	ds_read_b128 v[188:191], v151 offset:51200
	ds_read_b128 v[192:195], v151 offset:52224
	ds_read_b128 v[196:199], v151 offset:53248
	ds_read_b128 v[200:203], v151 offset:54272
	ds_read_b128 v[204:207], v151 offset:55296
	ds_read_b128 v[208:211], v151 offset:56320
	s_mov_b32 m0, s28
	s_nop 0
	global_load_lds_dwordx4 v130, s[20:21]
	s_add_i32 m0, s28, 0x2000
	s_nop 0
	global_load_lds_dwordx4 v134, s[20:21]
	s_add_u32 s20, s26, 0xb0080
	s_addc_u32 s21, s27, 0
	s_add_i32 s26, s58, s35
	s_mov_b32 m0, s26
	s_nop 0
	global_load_lds_dwordx4 v130, s[20:21]
	s_add_i32 m0, s26, 0x2000
	s_nop 0
	global_load_lds_dwordx4 v134, s[20:21]
	s_mov_b32 m0, s41
	s_nop 0
	global_load_lds_dwordx4 v128, s[24:25]
	s_mov_b32 m0, s42
	s_nop 0
	global_load_lds_dwordx4 v132, s[24:25]
	s_waitcnt vmcnt(8)
	s_waitcnt lgkmcnt(0)
	s_barrier
	s_setprio 1
	s_waitcnt lgkmcnt(0)
	v_mfma_f32_16x16x32_bf16 v[60:63], v[140:143], v[180:183], v[60:63]
	v_mfma_f32_16x16x32_bf16 v[56:59], v[156:159], v[180:183], v[56:59]
	v_mfma_f32_16x16x32_bf16 v[44:47], v[140:143], v[188:191], v[44:47]
	v_mfma_f32_16x16x32_bf16 v[40:43], v[156:159], v[188:191], v[40:43]
	v_mfma_f32_16x16x32_bf16 v[28:31], v[140:143], v[196:199], v[28:31]
	v_mfma_f32_16x16x32_bf16 v[24:27], v[156:159], v[196:199], v[24:27]
	v_mfma_f32_16x16x32_bf16 v[12:15], v[140:143], v[204:207], v[12:15]
	v_mfma_f32_16x16x32_bf16 v[8:11], v[156:159], v[204:207], v[8:11]
	v_mfma_f32_16x16x32_bf16 v[60:63], v[152:155], v[184:187], v[60:63]
	v_mfma_f32_16x16x32_bf16 v[56:59], v[160:163], v[184:187], v[56:59]
	v_mfma_f32_16x16x32_bf16 v[44:47], v[152:155], v[192:195], v[44:47]
	v_mfma_f32_16x16x32_bf16 v[40:43], v[160:163], v[192:195], v[40:43]
	v_mfma_f32_16x16x32_bf16 v[28:31], v[152:155], v[200:203], v[28:31]
	v_mfma_f32_16x16x32_bf16 v[24:27], v[160:163], v[200:203], v[24:27]
	v_mfma_f32_16x16x32_bf16 v[12:15], v[152:155], v[208:211], v[12:15]
	v_mfma_f32_16x16x32_bf16 v[8:11], v[160:163], v[208:211], v[8:11]
	s_setprio 0
	s_setprio 1
	v_mfma_f32_16x16x32_bf16 v[52:55], v[164:167], v[180:183], v[52:55]
	v_mfma_f32_16x16x32_bf16 v[48:51], v[172:175], v[180:183], v[48:51]
	v_mfma_f32_16x16x32_bf16 v[36:39], v[164:167], v[188:191], v[36:39]
	v_mfma_f32_16x16x32_bf16 v[32:35], v[172:175], v[188:191], v[32:35]
	v_mfma_f32_16x16x32_bf16 v[20:23], v[164:167], v[196:199], v[20:23]
	v_mfma_f32_16x16x32_bf16 v[16:19], v[172:175], v[196:199], v[16:19]
	v_mfma_f32_16x16x32_bf16 v[4:7], v[164:167], v[204:207], v[4:7]
	v_mfma_f32_16x16x32_bf16 v[0:3], v[172:175], v[204:207], v[0:3]
	v_mfma_f32_16x16x32_bf16 v[52:55], v[168:171], v[184:187], v[52:55]
	v_mfma_f32_16x16x32_bf16 v[48:51], v[176:179], v[184:187], v[48:51]
	v_mfma_f32_16x16x32_bf16 v[36:39], v[168:171], v[192:195], v[36:39]
	v_mfma_f32_16x16x32_bf16 v[32:35], v[176:179], v[192:195], v[32:35]
	v_mfma_f32_16x16x32_bf16 v[20:23], v[168:171], v[200:203], v[20:23]
	v_mfma_f32_16x16x32_bf16 v[16:19], v[176:179], v[200:203], v[16:19]
	v_mfma_f32_16x16x32_bf16 v[4:7], v[168:171], v[208:211], v[4:7]
	v_mfma_f32_16x16x32_bf16 v[0:3], v[176:179], v[208:211], v[0:3]
	s_setprio 0
	s_barrier
	s_add_i32 s56, s56, 2
	s_add_u32 s54, s54, 0x100
	s_addc_u32 s55, s55, 0
	s_cmp_gt_u32 s56, 41
	s_mov_b64 s[20:21], s[22:23]
	s_cbranch_scc0 .LBB0_2472
	s_and_b64 vcc, exec, s[8:9]
	s_cbranch_vccz .LBB0_2475
	s_barrier
